# strategy 4: per-interval s_setprio flips deleted from the GEMM mainloops, one static s_setprio 1 for the stagger-barrier half (waves 4-7) per GEMM phase
# baseline (speedup 1.0000x reference)
; __global__ void __launch_bounds__(512, 2) mega_fwd(Params p) {
;     ...
;             int q = ph - 1, layer = 0, op = 0;
; #pragma unroll 1
;             for (layer = 0; layer < 4; ++layer) { const int np = (layer & 1) ? 6 : 5; if (q < np) break; q -= np; }
;             const bool dil = layer & 1; const int j = layer >> 1;
;             op = dil ? q : (q < 2 ? q : q + 1);
;             if (op == OP_QKV) {
;                 if (!dil) { pg8::Gemm gm{xb, (const u16*)(ws + W_SBQKV) + (size_t)j * NQKV_SB * DM, T_TOK, NQKV_SB, DM};
;                     S.init(gm.M, gm.N, gridDim.x, blockIdx.x); pg8::EpiBf16 E{qkv, NQKV_SB}; pg8::gemm_phase(lds, gm, S, E); }
;                 else { pg8::Gemm gm{xb, (const u16*)(ws + W_DQKV) + (size_t)j * NQKV_DIL * DM, T_TOK, NQKV_DIL, DM};
;                     S.init(gm.M, gm.N, gridDim.x, blockIdx.x); pg8::EpiRope E{qkv, cs, sn}; pg8::gemm_phase(lds, gm, S, E); }
;             } else if (op == OP_ATT) {
;                 if (!dil) sb_attn_phase(lds, qkv, ob); else dil_attn_phase(lds, qkv, ob, lse);
;             } else if (op == OP_COMB) {
;                 dil_combine_phase(lse, ob);
;             } else if (op == OP_OPROJ) {
;                 const int lp = layer > 0 ? layer - 1 : 0;
;                 pg8::EpiRes E{ya, layer == 0 ? p.x : yb, layer == 0 ? nullptr : st2, p.ln_ffn_g + lp * DM, p.ln_ffn_b + lp * DM};
;                 if (!dil) { pg8::Gemm gm{ob, (const u16*)(ws + W_SBO) + (size_t)j * DM * DM, T_TOK, DM, DM};
;                     S.init(gm.M, gm.N, gridDim.x, blockIdx.x); pg8::gemm_phase(lds, gm, S, E); }
;                 else { pg8::Gemm gm{ob, (const u16*)(ws + W_DO) + (size_t)j * DM * WDIL, T_TOK, DM, WDIL};
;                     S.init(gm.M, gm.N, gridDim.x, blockIdx.x); pg8::gemm_phase(lds, gm, S, E); }
;                 panel_ln_tail(cntw + (2 * layer) * 64 * 16, S, ya, p.ln_mix_g + layer * DM, p.ln_mix_b + layer * DM, nullptr, xb, st1);
;             } else if (op == OP_GU) {
;                 pg8::Gemm gm{xb, (const u16*)(ws + W_GU) + (size_t)layer * 2 * DFF * DM, T_TOK, 2 * DFF, DM};
;                 S.init(gm.M, gm.N, gridDim.x, blockIdx.x); pg8::EpiGU E{hb}; pg8::gemm_phase(lds, gm, S, E);
.LBB0_26:
	v_writelane_b32 v255, s33, 40
	s_mov_b64 s[12:13], 0
	v_readlane_b32 s33, v255, 39
	s_and_b32 s3, s33, 1
	s_cmp_eq_u32 s3, 0
	s_cselect_b64 s[4:5], -1, 0
	s_cmp_eq_u32 s3, 1
	s_cselect_b64 s[6:7], -1, 0
	v_writelane_b32 v255, s6, 41
	s_nop 1
	v_writelane_b32 v255, s7, 42
	s_lshr_b32 s6, s33, 1
	v_writelane_b32 v255, s6, 43
	s_cmp_gt_i32 s2, 1
	s_nop 0
	v_writelane_b32 v255, s7, 44
	s_cselect_b64 s[6:7], -1, 0
	s_and_b64 s[4:5], s[4:5], s[6:7]
	s_cmp_lg_u64 s[4:5], 0
	s_addc_u32 s2, s2, 0
	v_writelane_b32 v255, s2, 45
	s_cmp_lt_i32 s2, 2
	s_mov_b64 s[2:3], 0
	v_writelane_b32 v255, s2, 46
	s_mov_b64 s[6:7], -1
	s_movk_i32 s5, 0x48
	v_writelane_b32 v255, s3, 47
	s_cbranch_scc1 .LBB0_51
	v_readlane_b32 s2, v255, 45
	s_cmp_gt_i32 s2, 2
	s_cbranch_scc0 .LBB0_49
	s_cmp_gt_i32 s2, 3
	s_cbranch_scc0 .LBB0_59
	s_cmp_eq_u32 s2, 4
	s_mov_b64 s[2:3], -1
	s_cbranch_scc0 .LBB0_43
	v_readlane_b32 s2, v253, 12
	v_mov_b32_e32 v0, v156
	v_readlane_b32 s3, v253, 13
	s_andn2_b64 vcc, exec, s[2:3]
	v_readfirstlane_b32 s24, v0
	s_cbranch_vccnz .LBB0_42
	v_lshlrev_b32_e32 v5, 4, v0
	v_add_u32_e32 v2, 0x2000, v5
	v_ashrrev_i32_e32 v1, 31, v2
	v_lshrrev_b32_e32 v1, 22, v1
	v_add_u32_e32 v1, v2, v1
	v_ashrrev_i32_e32 v1, 10, v1
	v_lshlrev_b32_e32 v3, 5, v1
	v_and_b32_e32 v4, 32, v3
	v_mul_i32_i24_e32 v3, 0x400, v1
	v_sub_u32_e32 v2, v2, v3
	v_lshrrev_b32_e32 v3, 4, v2
	v_bitop3_b32 v3, v3, v2, 32 bitop3:0x6c
	v_ashrrev_i32_e32 v2, 31, v3
	v_lshrrev_b32_e32 v2, 26, v2
	v_add_u32_e32 v6, v3, v2
	v_ashrrev_i32_e32 v2, 6, v6
	v_and_b32_e32 v6, 0xc0, v6
	v_sub_u32_e32 v3, v3, v6
	v_ashrrev_i16_sdwa v3, v252, sext(v3) dst_sel:DWORD dst_unused:UNUSED_PAD src0_sel:DWORD src1_sel:BYTE_0
	v_lshlrev_b32_e32 v6, 3, v1
	v_bfe_i32 v3, v3, 0, 16
	v_and_b32_e32 v6, 0xffff0, v6
	v_add_u32_e32 v4, v4, v3
	v_add_lshl_u32 v6, v2, v6, 12
	v_lshl_add_u32 v128, v4, 1, v6
	v_ashrrev_i32_e32 v4, 31, v0
	v_lshrrev_b32_e32 v4, 26, v4
	v_add_u32_e32 v4, v0, v4
	v_ashrrev_i32_e32 v4, 6, v4
	v_lshlrev_b32_e32 v6, 5, v4
	v_and_b32_e32 v7, 32, v6
	v_bfe_i32 v6, v0, 27, 1
	v_lshrrev_b32_e32 v6, 22, v6
	v_add_u32_e32 v6, v5, v6
	v_and_b32_e32 v6, 0xfffffc00, v6
	v_sub_u32_e32 v5, v5, v6
	v_lshrrev_b32_e32 v6, 4, v5
	v_bitop3_b32 v6, v6, v5, 32 bitop3:0x6c
	v_ashrrev_i32_e32 v5, 31, v5
	v_lshrrev_b32_e32 v5, 26, v5
	v_add_u32_e32 v5, v6, v5
	s_lshl_b32 s2, s33, 1
	s_mul_i32 s3, s33, 0x2c00000
	v_readlane_b32 s4, v253, 10
	v_ashrrev_i32_e32 v5, 6, v5
	s_mul_hi_u32 s2, s2, 0x1600000
	s_add_u32 s25, s4, s3
	v_readlane_b32 s3, v253, 11
	v_mul_i32_i24_e32 v8, 64, v5
	s_addc_u32 s26, s3, s2
	s_ashr_i32 s3, s24, 6
	v_sub_u32_e32 v6, v6, v8
	s_ashr_i32 s2, s24, 8
	s_lshl_b32 s27, s3, 10
	v_ashrrev_i16_sdwa v6, v252, sext(v6) dst_sel:DWORD dst_unused:UNUSED_PAD src0_sel:DWORD src1_sel:BYTE_0
	v_lshlrev_b32_e32 v8, 3, v4
	v_readlane_b32 s4, v254, 13
	v_bfe_i32 v6, v6, 0, 16
	v_and_b32_e32 v8, 0xffff0, v8
	v_readlane_b32 s5, v254, 14
	s_add_u32 s20, s25, s4
	v_add_u32_e32 v7, v7, v6
	v_add_lshl_u32 v8, v5, v8, 12
	s_addc_u32 s21, s26, s5
	s_add_i32 s28, s27, 0
	v_lshl_add_u32 v158, v7, 1, v8
	s_add_i32 m0, s28, 0x10000
	v_readlane_b32 s4, v254, 17
	global_load_lds_dwordx4 v158, s[20:21]
	s_add_i32 m0, s28, 0x12000
	v_readlane_b32 s5, v254, 18
	global_load_lds_dwordx4 v128, s[20:21]
	s_mov_b32 m0, s28
	s_add_i32 s29, s28, 0x2000
	s_nop 1
	global_load_lds_dwordx4 v158, s[4:5]
	s_mov_b32 m0, s29
	s_nop 0
	global_load_lds_dwordx4 v128, s[4:5]
	s_add_u32 s4, s20, 0x80000
	s_addc_u32 s5, s21, 0
	s_add_i32 m0, s28, 0x14000
	s_add_i32 s30, s28, 0x4000
	global_load_lds_dwordx4 v158, s[4:5]
	s_add_i32 m0, s28, 0x16000
	s_add_i32 s31, s28, 0x6000
	global_load_lds_dwordx4 v128, s[4:5]
	v_readlane_b32 s4, v254, 19
	s_mov_b32 m0, s30
	v_readlane_b32 s5, v254, 20
	s_cmp_lg_u32 s2, 1
	s_nop 3
	global_load_lds_dwordx4 v158, s[4:5]
	s_mov_b32 m0, s31
	s_nop 0
	global_load_lds_dwordx4 v128, s[4:5]
	s_cbranch_scc1 .LBB0_33
	s_setprio 1
	s_barrier

; #define PG8_STAGE(bufoff, gbase) do { _Pragma("unroll") for (int _i = 0; _i < 2; ++_i) \
;         __builtin_amdgcn_global_load_lds((const unsigned*)((const char*)(gbase) + voff[_i]), (LAS unsigned*)(lds + (bufoff) + ldsw + _i * 8192), 16, 0, 0); } while (0)
; #define PG8_LDA(dst, b, h) do { _Pragma("unroll") for (int m = 0; m < 4; ++m) _Pragma("unroll") for (int k = 0; k < 2; ++k) dst[m][k] = *(const LAS bf16x8*)(lds + PG8_SA(b, h) + aoff + m * 2048 + k * 1024); } while (0)
; #define PG8_LDB(dst, b, h) do { _Pragma("unroll") for (int n = 0; n < 2; ++n) _Pragma("unroll") for (int k = 0; k < 2; ++k) dst[n][k] = *(const LAS bf16x8*)(lds + PG8_SB(b, h) + boff + n * 2048 + k * 1024); } while (0)
; #define PG8_MMA(ai, bj, At, Bt) do { __builtin_amdgcn_s_setprio(1); _Pragma("unroll") for (int m = 0; m < 4; ++m) _Pragma("unroll") for (int n = 0; n < 2; ++n) _Pragma("unroll") for (int k = 0; k < 2; ++k) \
;         acc[ai][bj][m][n] = __builtin_amdgcn_mfma_f32_16x16x32_bf16(Bt[n][k], At[m][k], acc[ai][bj][m][n], 0, 0, 0); __builtin_amdgcn_s_setprio(0); } while (0)
; #define PG8_WAIT_V(n) asm volatile("s_waitcnt vmcnt(" #n ")" ::: "memory")
; #define PG8_WAIT_L(n) asm volatile("s_waitcnt lgkmcnt(" #n ")" ::: "memory")
; #define PG8_BAR __builtin_amdgcn_s_barrier()
; #define PG8_SCHED __builtin_amdgcn_sched_barrier(0)
; template <class Epi>
; DI void gemm_phase(LAS unsigned char* lds, const Gemm g, const StaticOrder& S, const Epi& E) {
;     ...
;         for (int t = 0; t < nt; t += 2) {
;             const bool last = (t == nt - 2);
;             const char* a1 = cA + (size_t)(t + 1) * kstep;
;             const char* a2 = last ? nA : cA + (size_t)(t + 2) * kstep; const char* b2 = last ? nB : cB + (size_t)(t + 2) * kstep;
;             const char* a3 = a2 + kstep; const char* b3 = b2 + kstep;
;             PG8_LDB(B0, 0, 0); PG8_SCHED; PG8_LDA(At, 0, 0); PG8_STAGE(PG8_SA(1, 1), a1 + hstep);
;             PG8_WAIT_L(8); PG8_BAR; PG8_WAIT_L(0); PG8_MMA(0, 0, At, B0); PG8_BAR; PG8_SCHED;
;             PG8_LDB(B1, 0, 1); PG8_STAGE(PG8_SB(0, 0), b2);
;             PG8_BAR; PG8_WAIT_L(0); PG8_MMA(0, 1, At, B1); PG8_BAR;
;             PG8_LDA(At, 0, 1); PG8_STAGE(PG8_SA(0, 0), a2);
;             PG8_BAR; PG8_WAIT_L(0); PG8_MMA(1, 0, At, B0); PG8_BAR; PG8_SCHED;
;             PG8_STAGE(PG8_SB(0, 1), b2 + hstep);
;             PG8_WAIT_V(6); PG8_BAR; PG8_MMA(1, 1, At, B1); PG8_BAR;
.LBB0_37:
	ds_read_b128 v[138:141], v135
	ds_read_b128 v[142:145], v135 offset:1024
	ds_read_b128 v[146:149], v135 offset:2048
	ds_read_b128 v[150:153], v135 offset:3072
	ds_read_b128 v[186:189], v137
	ds_read_b128 v[190:193], v137 offset:1024
	ds_read_b128 v[194:197], v137 offset:2048
	ds_read_b128 v[198:201], v137 offset:3072
	ds_read_b128 v[202:205], v137 offset:4096
	ds_read_b128 v[206:209], v137 offset:5120
	ds_read_b128 v[210:213], v137 offset:6144
	ds_read_b128 v[214:217], v137 offset:7168
	s_add_u32 s20, s18, 0xfff80080
	s_addc_u32 s21, s19, -1
	s_add_i32 s39, 0, 0x10000
	s_cmp_eq_u32 s38, 28
	s_cselect_b32 s23, s4, s21
	s_cselect_b32 s22, s5, s20
	s_cselect_b32 s21, s9, s37
	s_cselect_b32 s20, s11, s33
	s_add_i32 m0, s28, 0xc000
	s_nop 0
	global_load_lds_dwordx4 v130, s[18:19]
	s_add_i32 m0, s28, 0xe000
	s_nop 0
	global_load_lds_dwordx4 v132, s[18:19]
	s_waitcnt lgkmcnt(8)
	s_barrier
	s_waitcnt lgkmcnt(0)
	v_mfma_f32_16x16x32_bf16 v[124:127], v[138:141], v[186:189], v[124:127]
	v_mfma_f32_16x16x32_bf16 v[120:123], v[146:149], v[186:189], v[120:123]
	v_mfma_f32_16x16x32_bf16 v[108:111], v[138:141], v[194:197], v[108:111]
	v_mfma_f32_16x16x32_bf16 v[104:107], v[146:149], v[194:197], v[104:107]
	v_mfma_f32_16x16x32_bf16 v[92:95], v[138:141], v[202:205], v[92:95]
	v_mfma_f32_16x16x32_bf16 v[88:91], v[146:149], v[202:205], v[88:91]
	v_mfma_f32_16x16x32_bf16 v[76:79], v[138:141], v[210:213], v[76:79]
	v_mfma_f32_16x16x32_bf16 v[72:75], v[146:149], v[210:213], v[72:75]
	v_mfma_f32_16x16x32_bf16 v[124:127], v[142:145], v[190:193], v[124:127]
	v_mfma_f32_16x16x32_bf16 v[120:123], v[150:153], v[190:193], v[120:123]
	v_mfma_f32_16x16x32_bf16 v[108:111], v[142:145], v[198:201], v[108:111]
	v_mfma_f32_16x16x32_bf16 v[104:107], v[150:153], v[198:201], v[104:107]
	v_mfma_f32_16x16x32_bf16 v[92:95], v[142:145], v[206:209], v[92:95]
	v_mfma_f32_16x16x32_bf16 v[88:91], v[150:153], v[206:209], v[88:91]
	v_mfma_f32_16x16x32_bf16 v[76:79], v[142:145], v[214:217], v[76:79]
	v_mfma_f32_16x16x32_bf16 v[72:75], v[150:153], v[214:217], v[72:75]
	s_barrier
	ds_read_b128 v[226:229], v135 offset:16384
	ds_read_b128 v[230:233], v135 offset:17408
	ds_read_b128 v[234:237], v135 offset:18432
	ds_read_b128 v[238:241], v135 offset:19456
	s_add_i32 s42, 0, 0x14000
	s_add_i32 s39, s39, s27
	s_mov_b32 m0, s39
	s_nop 0
	global_load_lds_dwordx4 v158, s[20:21]
	s_add_i32 m0, s39, 0x2000
	s_nop 0
	global_load_lds_dwordx4 v128, s[20:21]
	s_waitcnt lgkmcnt(0)
	s_barrier
	v_mfma_f32_16x16x32_bf16 v[116:119], v[226:229], v[186:189], v[116:119]
	v_mfma_f32_16x16x32_bf16 v[112:115], v[234:237], v[186:189], v[112:115]
	v_mfma_f32_16x16x32_bf16 v[100:103], v[226:229], v[194:197], v[100:103]
	v_mfma_f32_16x16x32_bf16 v[96:99], v[234:237], v[194:197], v[96:99]
	v_mfma_f32_16x16x32_bf16 v[84:87], v[226:229], v[202:205], v[84:87]
	v_mfma_f32_16x16x32_bf16 v[80:83], v[234:237], v[202:205], v[80:83]
	v_mfma_f32_16x16x32_bf16 v[68:71], v[226:229], v[210:213], v[68:71]
	v_mfma_f32_16x16x32_bf16 v[64:67], v[234:237], v[210:213], v[64:67]
	v_mfma_f32_16x16x32_bf16 v[116:119], v[230:233], v[190:193], v[116:119]
	s_mov_b32 m0, s28
	v_mfma_f32_16x16x32_bf16 v[112:115], v[238:241], v[190:193], v[112:115]
	v_mfma_f32_16x16x32_bf16 v[100:103], v[230:233], v[198:201], v[100:103]
	v_mfma_f32_16x16x32_bf16 v[96:99], v[238:241], v[198:201], v[96:99]
	v_mfma_f32_16x16x32_bf16 v[84:87], v[230:233], v[206:209], v[84:87]
	v_mfma_f32_16x16x32_bf16 v[80:83], v[238:241], v[206:209], v[80:83]
	v_mfma_f32_16x16x32_bf16 v[68:71], v[230:233], v[214:217], v[68:71]
	v_mfma_f32_16x16x32_bf16 v[64:67], v[238:241], v[214:217], v[64:67]
	s_barrier
	ds_read_b128 v[186:189], v137 offset:16384
	ds_read_b128 v[190:193], v137 offset:17408
	ds_read_b128 v[194:197], v137 offset:18432
	ds_read_b128 v[198:201], v137 offset:19456
	ds_read_b128 v[202:205], v137 offset:20480
	ds_read_b128 v[206:209], v137 offset:21504
	ds_read_b128 v[210:213], v137 offset:22528
	ds_read_b128 v[214:217], v137 offset:23552
	global_load_lds_dwordx4 v158, s[22:23]
	s_mov_b64 s[100:101], s[22:23]
	s_mov_b32 m0, s29
	s_nop 0
	global_load_lds_dwordx4 v128, s[22:23]
	s_waitcnt lgkmcnt(0)
	s_barrier
	v_mfma_f32_16x16x32_bf16 v[60:63], v[138:141], v[186:189], v[60:63]
	v_mfma_f32_16x16x32_bf16 v[56:59], v[146:149], v[186:189], v[56:59]
	v_mfma_f32_16x16x32_bf16 v[44:47], v[138:141], v[194:197], v[44:47]
	v_mfma_f32_16x16x32_bf16 v[40:43], v[146:149], v[194:197], v[40:43]
	v_mfma_f32_16x16x32_bf16 v[28:31], v[138:141], v[202:205], v[28:31]
	v_mfma_f32_16x16x32_bf16 v[24:27], v[146:149], v[202:205], v[24:27]
	v_mfma_f32_16x16x32_bf16 v[12:15], v[138:141], v[210:213], v[12:15]
	v_mfma_f32_16x16x32_bf16 v[8:11], v[146:149], v[210:213], v[8:11]
	v_mfma_f32_16x16x32_bf16 v[60:63], v[142:145], v[190:193], v[60:63]
	v_mfma_f32_16x16x32_bf16 v[56:59], v[150:153], v[190:193], v[56:59]
	v_mfma_f32_16x16x32_bf16 v[44:47], v[142:145], v[198:201], v[44:47]
	v_mfma_f32_16x16x32_bf16 v[40:43], v[150:153], v[198:201], v[40:43]
	v_mfma_f32_16x16x32_bf16 v[28:31], v[142:145], v[206:209], v[28:31]
	v_mfma_f32_16x16x32_bf16 v[24:27], v[150:153], v[206:209], v[24:27]
	v_mfma_f32_16x16x32_bf16 v[12:15], v[142:145], v[214:217], v[12:15]
	v_mfma_f32_16x16x32_bf16 v[8:11], v[150:153], v[214:217], v[8:11]
	s_barrier
	s_add_u32 s40, s20, 0x80000
	s_addc_u32 s41, s21, 0
	s_add_i32 s39, s42, s27
	s_mov_b32 m0, s39
	s_nop 0
	global_load_lds_dwordx4 v158, s[40:41]
	s_add_i32 m0, s39, 0x2000
	s_nop 0
	global_load_lds_dwordx4 v128, s[40:41]
	s_waitcnt vmcnt(6)
	s_barrier
; #define PG8_STAGE(bufoff, gbase) do { _Pragma("unroll") for (int _i = 0; _i < 2; ++_i) \
;         __builtin_amdgcn_global_load_lds((const unsigned*)((const char*)(gbase) + voff[_i]), (LAS unsigned*)(lds + (bufoff) + ldsw + _i * 8192), 16, 0, 0); } while (0)
; #define PG8_LDA(dst, b, h) do { _Pragma("unroll") for (int m = 0; m < 4; ++m) _Pragma("unroll") for (int k = 0; k < 2; ++k) dst[m][k] = *(const LAS bf16x8*)(lds + PG8_SA(b, h) + aoff + m * 2048 + k * 1024); } while (0)
; #define PG8_LDB(dst, b, h) do { _Pragma("unroll") for (int n = 0; n < 2; ++n) _Pragma("unroll") for (int k = 0; k < 2; ++k) dst[n][k] = *(const LAS bf16x8*)(lds + PG8_SB(b, h) + boff + n * 2048 + k * 1024); } while (0)
; #define PG8_MMA(ai, bj, At, Bt) do { __builtin_amdgcn_s_setprio(1); _Pragma("unroll") for (int m = 0; m < 4; ++m) _Pragma("unroll") for (int n = 0; n < 2; ++n) _Pragma("unroll") for (int k = 0; k < 2; ++k) \
;         acc[ai][bj][m][n] = __builtin_amdgcn_mfma_f32_16x16x32_bf16(Bt[n][k], At[m][k], acc[ai][bj][m][n], 0, 0, 0); __builtin_amdgcn_s_setprio(0); } while (0)
; #define PG8_WAIT_V(n) asm volatile("s_waitcnt vmcnt(" #n ")" ::: "memory")
; #define PG8_WAIT_L(n) asm volatile("s_waitcnt lgkmcnt(" #n ")" ::: "memory")
; #define PG8_BAR __builtin_amdgcn_s_barrier()
; #define PG8_SCHED __builtin_amdgcn_sched_barrier(0)
; template <class Epi>
; DI void gemm_phase(LAS unsigned char* lds, const Gemm g, const StaticOrder& S, const Epi& E) {
;     ...
;             PG8_WAIT_V(6); PG8_BAR; PG8_MMA(1, 1, At, B1); PG8_BAR;
;             PG8_LDB(B0, 1, 0); PG8_SCHED; PG8_LDA(At, 1, 0); PG8_STAGE(PG8_SA(0, 1), a2 + hstep);
;             PG8_WAIT_L(8); PG8_BAR; PG8_WAIT_L(0); PG8_MMA(0, 0, At, B0); PG8_BAR; PG8_SCHED;
;             PG8_LDB(B1, 1, 1); PG8_STAGE(PG8_SB(1, 0), b3);
;             PG8_BAR; PG8_WAIT_L(0); PG8_MMA(0, 1, At, B1); PG8_BAR;
;             PG8_LDA(At, 1, 1); PG8_STAGE(PG8_SA(1, 0), a3);
	v_mfma_f32_16x16x32_bf16 v[52:55], v[226:229], v[186:189], v[52:55]
	v_mfma_f32_16x16x32_bf16 v[48:51], v[234:237], v[186:189], v[48:51]
	v_mfma_f32_16x16x32_bf16 v[36:39], v[226:229], v[194:197], v[36:39]
	v_mfma_f32_16x16x32_bf16 v[32:35], v[234:237], v[194:197], v[32:35]
	v_mfma_f32_16x16x32_bf16 v[20:23], v[226:229], v[202:205], v[20:23]
	v_mfma_f32_16x16x32_bf16 v[16:19], v[234:237], v[202:205], v[16:19]
	v_mfma_f32_16x16x32_bf16 v[4:7], v[226:229], v[210:213], v[4:7]
	v_mfma_f32_16x16x32_bf16 v[0:3], v[234:237], v[210:213], v[0:3]
	v_mfma_f32_16x16x32_bf16 v[52:55], v[230:233], v[190:193], v[52:55]
	s_add_i32 s39, 0, 0x18000
	v_mfma_f32_16x16x32_bf16 v[48:51], v[238:241], v[190:193], v[48:51]
	v_mfma_f32_16x16x32_bf16 v[36:39], v[230:233], v[198:201], v[36:39]
	v_mfma_f32_16x16x32_bf16 v[32:35], v[238:241], v[198:201], v[32:35]
	v_mfma_f32_16x16x32_bf16 v[20:23], v[230:233], v[206:209], v[20:23]
	v_mfma_f32_16x16x32_bf16 v[16:19], v[238:241], v[206:209], v[16:19]
	v_mfma_f32_16x16x32_bf16 v[4:7], v[230:233], v[214:217], v[4:7]
	v_mfma_f32_16x16x32_bf16 v[0:3], v[238:241], v[214:217], v[0:3]
	s_barrier
	ds_read_b128 v[138:141], v135 offset:32768
	ds_read_b128 v[142:145], v135 offset:33792
	ds_read_b128 v[146:149], v135 offset:34816
	ds_read_b128 v[150:153], v135 offset:35840
	ds_read_b128 v[186:189], v137 offset:32768
	ds_read_b128 v[190:193], v137 offset:33792
	ds_read_b128 v[194:197], v137 offset:34816
	ds_read_b128 v[198:201], v137 offset:35840
	ds_read_b128 v[202:205], v137 offset:36864
	ds_read_b128 v[206:209], v137 offset:37888
	ds_read_b128 v[210:213], v137 offset:38912
	ds_read_b128 v[214:217], v137 offset:39936
	s_add_u32 s22, s22, 0x80000
	s_addc_u32 s23, s23, 0
	s_mov_b32 m0, s30
	s_nop 0
	global_load_lds_dwordx4 v158, s[22:23]
	s_mov_b32 m0, s31
	s_nop 0
	global_load_lds_dwordx4 v128, s[22:23]
	s_waitcnt lgkmcnt(8)
	s_barrier
	s_waitcnt lgkmcnt(0)
	v_mfma_f32_16x16x32_bf16 v[124:127], v[138:141], v[186:189], v[124:127]
	v_mfma_f32_16x16x32_bf16 v[120:123], v[146:149], v[186:189], v[120:123]
	v_mfma_f32_16x16x32_bf16 v[108:111], v[138:141], v[194:197], v[108:111]
	v_mfma_f32_16x16x32_bf16 v[104:107], v[146:149], v[194:197], v[104:107]
	v_mfma_f32_16x16x32_bf16 v[92:95], v[138:141], v[202:205], v[92:95]
	v_mfma_f32_16x16x32_bf16 v[88:91], v[146:149], v[202:205], v[88:91]
	v_mfma_f32_16x16x32_bf16 v[76:79], v[138:141], v[210:213], v[76:79]
	v_mfma_f32_16x16x32_bf16 v[72:75], v[146:149], v[210:213], v[72:75]
	v_mfma_f32_16x16x32_bf16 v[124:127], v[142:145], v[190:193], v[124:127]
	v_mfma_f32_16x16x32_bf16 v[120:123], v[150:153], v[190:193], v[120:123]
	v_mfma_f32_16x16x32_bf16 v[108:111], v[142:145], v[198:201], v[108:111]
	v_mfma_f32_16x16x32_bf16 v[104:107], v[150:153], v[198:201], v[104:107]
	v_mfma_f32_16x16x32_bf16 v[92:95], v[142:145], v[206:209], v[92:95]
	v_mfma_f32_16x16x32_bf16 v[88:91], v[150:153], v[206:209], v[88:91]
	v_mfma_f32_16x16x32_bf16 v[76:79], v[142:145], v[214:217], v[76:79]
	v_mfma_f32_16x16x32_bf16 v[72:75], v[150:153], v[214:217], v[72:75]
	s_barrier
	ds_read_b128 v[226:229], v135 offset:49152
	ds_read_b128 v[230:233], v135 offset:50176
	ds_read_b128 v[234:237], v135 offset:51200
	ds_read_b128 v[238:241], v135 offset:52224
	s_add_i32 s22, 0, 0x1c000
	s_add_i32 s23, s39, s27
	s_add_i32 m0, s23, 0xffffff80
	s_nop 0
	global_load_lds_dwordx4 v158, s[20:21] offset:128
	s_add_i32 m0, s23, 0x1f80
	s_nop 0
	global_load_lds_dwordx4 v128, s[20:21] offset:128
	s_waitcnt lgkmcnt(0)
	s_barrier
	v_mfma_f32_16x16x32_bf16 v[116:119], v[226:229], v[186:189], v[116:119]
	v_mfma_f32_16x16x32_bf16 v[112:115], v[234:237], v[186:189], v[112:115]
	v_mfma_f32_16x16x32_bf16 v[100:103], v[226:229], v[194:197], v[100:103]
	v_mfma_f32_16x16x32_bf16 v[96:99], v[234:237], v[194:197], v[96:99]
	v_mfma_f32_16x16x32_bf16 v[84:87], v[226:229], v[202:205], v[84:87]
	v_mfma_f32_16x16x32_bf16 v[80:83], v[234:237], v[202:205], v[80:83]
	v_mfma_f32_16x16x32_bf16 v[68:71], v[226:229], v[210:213], v[68:71]
	v_mfma_f32_16x16x32_bf16 v[64:67], v[234:237], v[210:213], v[64:67]
	v_mfma_f32_16x16x32_bf16 v[116:119], v[230:233], v[190:193], v[116:119]
	s_add_i32 m0, s34, 0xffffff80
	v_mfma_f32_16x16x32_bf16 v[112:115], v[238:241], v[190:193], v[112:115]
	v_mfma_f32_16x16x32_bf16 v[100:103], v[230:233], v[198:201], v[100:103]
	v_mfma_f32_16x16x32_bf16 v[96:99], v[238:241], v[198:201], v[96:99]
	v_mfma_f32_16x16x32_bf16 v[84:87], v[230:233], v[206:209], v[84:87]
	v_mfma_f32_16x16x32_bf16 v[80:83], v[238:241], v[206:209], v[80:83]
	v_mfma_f32_16x16x32_bf16 v[68:71], v[230:233], v[214:217], v[68:71]
	v_mfma_f32_16x16x32_bf16 v[64:67], v[238:241], v[214:217], v[64:67]
	s_barrier
	ds_read_b128 v[186:189], v137 offset:49152
	ds_read_b128 v[190:193], v137 offset:50176
	ds_read_b128 v[194:197], v137 offset:51200
	ds_read_b128 v[198:201], v137 offset:52224
	ds_read_b128 v[202:205], v137 offset:53248
	ds_read_b128 v[206:209], v137 offset:54272
	ds_read_b128 v[210:213], v137 offset:55296
	ds_read_b128 v[214:217], v137 offset:56320
	global_load_lds_dwordx4 v158, s[100:101] offset:128
	s_add_i32 m0, s35, 0xffffff80
	s_nop 0
	global_load_lds_dwordx4 v128, s[100:101] offset:128
	s_waitcnt lgkmcnt(0)
	s_barrier
; #define PG8_STAGE(bufoff, gbase) do { _Pragma("unroll") for (int _i = 0; _i < 2; ++_i) \
;         __builtin_amdgcn_global_load_lds((const unsigned*)((const char*)(gbase) + voff[_i]), (LAS unsigned*)(lds + (bufoff) + ldsw + _i * 8192), 16, 0, 0); } while (0)
; #define PG8_MMA(ai, bj, At, Bt) do { __builtin_amdgcn_s_setprio(1); _Pragma("unroll") for (int m = 0; m < 4; ++m) _Pragma("unroll") for (int n = 0; n < 2; ++n) _Pragma("unroll") for (int k = 0; k < 2; ++k) \
;         acc[ai][bj][m][n] = __builtin_amdgcn_mfma_f32_16x16x32_bf16(Bt[n][k], At[m][k], acc[ai][bj][m][n], 0, 0, 0); __builtin_amdgcn_s_setprio(0); } while (0)
; #define PG8_WAIT_V(n) asm volatile("s_waitcnt vmcnt(" #n ")" ::: "memory")
; #define PG8_WAIT_L(n) asm volatile("s_waitcnt lgkmcnt(" #n ")" ::: "memory")
; #define PG8_BAR __builtin_amdgcn_s_barrier()
; #define PG8_SCHED __builtin_amdgcn_sched_barrier(0)
; template <class Epi>
; DI void gemm_phase(LAS unsigned char* lds, const Gemm g, const StaticOrder& S, const Epi& E) {
;     ...
;             PG8_BAR; PG8_WAIT_L(0); PG8_MMA(1, 0, At, B0); PG8_BAR; PG8_SCHED;
;             PG8_STAGE(PG8_SB(1, 1), b3 + hstep);
;             PG8_WAIT_V(6); PG8_BAR; PG8_MMA(1, 1, At, B1); PG8_BAR;
;         }
;     DI void operator()(const f32x4 (&acc)[2][2][4][2], const Unit& u, int wr, int wc, int fr, int fq) const {
;         const int row0 = u.pm * BM + wr * 64 + fr, col0 = u.pn * HALF + wc * 32 + 8 * fq;
; #pragma unroll
;         for (int ai = 0; ai < 2; ++ai)
; #pragma unroll
;             for (int m = 0; m < 4; ++m) { float hv[8];
; #pragma unroll
;                 for (int n = 0; n < 2; ++n)
; #pragma unroll
;                     for (int e = 0; e < 4; ++e) { const float gt = acc[ai][0][m][n][e], up = acc[ai][1][m][n][e];
;                         hv[n * 4 + e] = gt * __builtin_amdgcn_rcpf(1.f + __builtin_amdgcn_exp2f(-1.4426950408889634f * gt)) * up; }
;                 *(u32x4*)(H + (size_t)(row0 + ai * HALF + m * 16) * DFF + col0) = (u32x4){pk(hv[0], hv[1]), pk(hv[2], hv[3]), pk(hv[4], hv[5]), pk(hv[6], hv[7])}; }
	v_mfma_f32_16x16x32_bf16 v[60:63], v[138:141], v[186:189], v[60:63]
	v_mfma_f32_16x16x32_bf16 v[56:59], v[146:149], v[186:189], v[56:59]
	v_mfma_f32_16x16x32_bf16 v[44:47], v[138:141], v[194:197], v[44:47]
	v_mfma_f32_16x16x32_bf16 v[40:43], v[146:149], v[194:197], v[40:43]
	v_mfma_f32_16x16x32_bf16 v[28:31], v[138:141], v[202:205], v[28:31]
	v_mfma_f32_16x16x32_bf16 v[24:27], v[146:149], v[202:205], v[24:27]
	v_mfma_f32_16x16x32_bf16 v[12:15], v[138:141], v[210:213], v[12:15]
	v_mfma_f32_16x16x32_bf16 v[8:11], v[146:149], v[210:213], v[8:11]
	v_mfma_f32_16x16x32_bf16 v[60:63], v[142:145], v[190:193], v[60:63]
	v_mfma_f32_16x16x32_bf16 v[56:59], v[150:153], v[190:193], v[56:59]
	v_mfma_f32_16x16x32_bf16 v[44:47], v[142:145], v[198:201], v[44:47]
	v_mfma_f32_16x16x32_bf16 v[40:43], v[150:153], v[198:201], v[40:43]
	v_mfma_f32_16x16x32_bf16 v[28:31], v[142:145], v[206:209], v[28:31]
	v_mfma_f32_16x16x32_bf16 v[24:27], v[150:153], v[206:209], v[24:27]
	v_mfma_f32_16x16x32_bf16 v[12:15], v[142:145], v[214:217], v[12:15]
	v_mfma_f32_16x16x32_bf16 v[8:11], v[150:153], v[214:217], v[8:11]
	s_barrier
	s_add_u32 s20, s20, 0x80080
	s_addc_u32 s21, s21, 0
	s_add_i32 s22, s22, s27
	s_mov_b32 m0, s22
	s_nop 0
	global_load_lds_dwordx4 v158, s[20:21]
	s_add_i32 m0, s22, 0x2000
	s_nop 0
	global_load_lds_dwordx4 v128, s[20:21]
	s_waitcnt vmcnt(6)
	s_barrier
	v_mfma_f32_16x16x32_bf16 v[52:55], v[226:229], v[186:189], v[52:55]
	v_mfma_f32_16x16x32_bf16 v[48:51], v[234:237], v[186:189], v[48:51]
	v_mfma_f32_16x16x32_bf16 v[36:39], v[226:229], v[194:197], v[36:39]
	v_mfma_f32_16x16x32_bf16 v[32:35], v[234:237], v[194:197], v[32:35]
	v_mfma_f32_16x16x32_bf16 v[20:23], v[226:229], v[202:205], v[20:23]
	v_mfma_f32_16x16x32_bf16 v[16:19], v[234:237], v[202:205], v[16:19]
	v_mfma_f32_16x16x32_bf16 v[4:7], v[226:229], v[210:213], v[4:7]
	v_mfma_f32_16x16x32_bf16 v[0:3], v[234:237], v[210:213], v[0:3]
	v_mfma_f32_16x16x32_bf16 v[52:55], v[230:233], v[190:193], v[52:55]
	s_add_i32 s38, s38, 2
	v_mfma_f32_16x16x32_bf16 v[48:51], v[238:241], v[190:193], v[48:51]
	s_add_u32 s18, s18, 0x100
	v_mfma_f32_16x16x32_bf16 v[36:39], v[230:233], v[198:201], v[36:39]
	s_addc_u32 s19, s19, 0
	v_mfma_f32_16x16x32_bf16 v[32:35], v[238:241], v[198:201], v[32:35]
	s_add_u32 s33, s33, 0x100
	v_mfma_f32_16x16x32_bf16 v[20:23], v[230:233], v[206:209], v[20:23]
	s_addc_u32 s37, s37, 0
	v_mfma_f32_16x16x32_bf16 v[16:19], v[238:241], v[206:209], v[16:19]
	s_cmp_gt_u32 s38, 29
	v_mfma_f32_16x16x32_bf16 v[4:7], v[230:233], v[214:217], v[4:7]
	v_mfma_f32_16x16x32_bf16 v[0:3], v[238:241], v[214:217], v[0:3]
	s_barrier
	s_cbranch_scc0 .LBB0_37
	v_mul_f32_e32 v139, 0xbfb8aa3b, v124
	v_exp_f32_e32 v139, v139
	v_lshl_or_b32 v140, s2, 7, v136
	v_lshl_add_u32 v138, s3, 8, v134
	v_ashrrev_i32_e32 v141, 31, v140
	v_add_f32_e32 v139, 1.0, v139
	v_rcp_f32_e32 v142, v139
	v_mul_f32_e32 v139, 0xbfb8aa3b, v125
	v_exp_f32_e32 v139, v139
	s_movk_i32 s4, 0x2c00
	s_and_b64 vcc, exec, s[6:7]
	s_mov_b64 s[20:21], s[16:17]
	v_add_f32_e32 v139, 1.0, v139
	v_rcp_f32_e32 v143, v139
	v_mul_f32_e32 v139, 0xbfb8aa3b, v126
	v_exp_f32_e32 v139, v139
	s_mov_b64 s[18:19], s[14:15]
	v_pk_mul_f32 v[124:125], v[124:125], v[142:143]
	v_add_f32_e32 v139, 1.0, v139
	v_rcp_f32_e32 v144, v139
	v_mul_f32_e32 v139, 0xbfb8aa3b, v127
	v_exp_f32_e32 v139, v139
	v_pk_mul_f32 v[116:117], v[124:125], v[116:117]
	v_add_f32_e32 v139, 1.0, v139
	v_rcp_f32_e32 v145, v139
	v_mul_f32_e32 v139, 0xbfb8aa3b, v120
	v_exp_f32_e32 v139, v139
	v_cvt_pk_bf16_f32 v116, v116, v117
	v_pk_mul_f32 v[124:125], v[126:127], v[144:145]
	v_add_f32_e32 v139, 1.0, v139
	v_rcp_f32_e32 v146, v139
	v_mul_f32_e32 v139, 0xbfb8aa3b, v121
	v_exp_f32_e32 v139, v139
	v_pk_mul_f32 v[118:119], v[124:125], v[118:119]
	v_add_f32_e32 v139, 1.0, v139
	v_rcp_f32_e32 v147, v139
	v_mul_f32_e32 v139, 0xbfb8aa3b, v122
	v_exp_f32_e32 v139, v139
	v_cvt_pk_bf16_f32 v117, v118, v119
	v_pk_mul_f32 v[118:119], v[120:121], v[146:147]
	v_add_f32_e32 v139, 1.0, v139
	v_rcp_f32_e32 v148, v139
	v_mul_f32_e32 v139, 0xbfb8aa3b, v123
	v_exp_f32_e32 v139, v139
	v_pk_mul_f32 v[112:113], v[118:119], v[112:113]
	v_add_f32_e32 v139, 1.0, v139
	v_rcp_f32_e32 v149, v139
	v_cvt_pk_bf16_f32 v118, v112, v113
	v_pk_mul_f32 v[112:113], v[122:123], v[148:149]
	s_nop 0
	v_pk_mul_f32 v[112:113], v[112:113], v[114:115]
	v_lshlrev_b64 v[114:115], 1, v[140:141]
	v_cvt_pk_bf16_f32 v119, v112, v113
	v_mov_b64_e32 v[112:113], s[54:55]
	v_mad_i64_i32 v[120:121], s[2:3], v138, s4, v[112:113]
	v_lshl_add_u64 v[120:121], v[120:121], 0, v[114:115]
	global_store_dwordx4 v[120:121], v[116:119], off
	v_mul_f32_e32 v120, 0xbfb8aa3b, v104
	v_mul_f32_e32 v121, 0xbfb8aa3b, v105
	v_mul_f32_e32 v116, 0xbfb8aa3b, v108
	v_mul_f32_e32 v117, 0xbfb8aa3b, v109
	v_exp_f32_e32 v116, v116
	v_exp_f32_e32 v117, v117
	v_mul_f32_e32 v118, 0xbfb8aa3b, v110
	v_mul_f32_e32 v119, 0xbfb8aa3b, v111
	v_exp_f32_e32 v118, v118
	v_exp_f32_e32 v119, v119
	v_exp_f32_e32 v120, v120
	v_exp_f32_e32 v121, v121
	v_add_f32_e32 v116, 1.0, v116
	v_add_f32_e32 v117, 1.0, v117
	v_mul_f32_e32 v122, 0xbfb8aa3b, v106
	v_mul_f32_e32 v123, 0xbfb8aa3b, v107
	v_rcp_f32_e32 v116, v116
	v_rcp_f32_e32 v117, v117
	v_add_f32_e32 v118, 1.0, v118
	v_add_f32_e32 v119, 1.0, v119
	v_exp_f32_e32 v122, v122
	v_exp_f32_e32 v123, v123
	v_rcp_f32_e32 v118, v118
	v_rcp_f32_e32 v119, v119
	v_add_f32_e32 v120, 1.0, v120
	v_add_f32_e32 v121, 1.0, v121
	v_rcp_f32_e32 v120, v120
	v_rcp_f32_e32 v121, v121
	v_add_f32_e32 v122, 1.0, v122
	v_add_f32_e32 v123, 1.0, v123
	v_pk_mul_f32 v[108:109], v[108:109], v[116:117]
	v_rcp_f32_e32 v122, v122
	v_rcp_f32_e32 v123, v123
	v_pk_mul_f32 v[100:101], v[108:109], v[100:101]
;     DI void operator()(const f32x4 (&acc)[2][2][4][2], const Unit& u, int wr, int wc, int fr, int fq) const {
;         const int row0 = u.pm * BM + wr * 64 + fr, col0 = u.pn * HALF + wc * 32 + 8 * fq;
; #pragma unroll
;         for (int ai = 0; ai < 2; ++ai)
; #pragma unroll
;             for (int m = 0; m < 4; ++m) { float hv[8];
; #pragma unroll
;                 for (int n = 0; n < 2; ++n)
; #pragma unroll
;                     for (int e = 0; e < 4; ++e) { const float gt = acc[ai][0][m][n][e], up = acc[ai][1][m][n][e];
;                         hv[n * 4 + e] = gt * __builtin_amdgcn_rcpf(1.f + __builtin_amdgcn_exp2f(-1.4426950408889634f * gt)) * up; }
;                 *(u32x4*)(H + (size_t)(row0 + ai * HALF + m * 16) * DFF + col0) = (u32x4){pk(hv[0], hv[1]), pk(hv[2], hv[3]), pk(hv[4], hv[5]), pk(hv[6], hv[7])}; }
	v_pk_mul_f32 v[108:109], v[110:111], v[118:119]
	v_cvt_pk_bf16_f32 v100, v100, v101
	v_pk_mul_f32 v[102:103], v[108:109], v[102:103]
	s_nop 0
	v_cvt_pk_bf16_f32 v101, v102, v103
	v_pk_mul_f32 v[102:103], v[104:105], v[120:121]
	s_nop 0
	v_pk_mul_f32 v[96:97], v[102:103], v[96:97]
	s_nop 0
	v_cvt_pk_bf16_f32 v102, v96, v97
	v_pk_mul_f32 v[96:97], v[106:107], v[122:123]
	s_nop 0
	v_pk_mul_f32 v[96:97], v[96:97], v[98:99]
	v_mul_f32_e32 v98, 0xbfb8aa3b, v94
	v_cvt_pk_bf16_f32 v103, v96, v97
	v_or_b32_e32 v96, 16, v138
	v_mad_i64_i32 v[96:97], s[2:3], v96, s4, v[112:113]
	v_lshl_add_u64 v[96:97], v[96:97], 0, v[114:115]
	global_store_dwordx4 v[96:97], v[100:103], off
	v_mul_f32_e32 v96, 0xbfb8aa3b, v92
	v_mul_f32_e32 v97, 0xbfb8aa3b, v93
	v_exp_f32_e32 v96, v96
	v_exp_f32_e32 v97, v97
	v_mul_f32_e32 v99, 0xbfb8aa3b, v95
	v_exp_f32_e32 v98, v98
	v_exp_f32_e32 v99, v99
	v_mul_f32_e32 v100, 0xbfb8aa3b, v88
	v_mul_f32_e32 v101, 0xbfb8aa3b, v89
	v_exp_f32_e32 v100, v100
	v_exp_f32_e32 v101, v101
	v_add_f32_e32 v96, 1.0, v96
	v_add_f32_e32 v97, 1.0, v97
	v_mul_f32_e32 v102, 0xbfb8aa3b, v90
	v_mul_f32_e32 v103, 0xbfb8aa3b, v91
	v_rcp_f32_e32 v96, v96
	v_rcp_f32_e32 v97, v97
	v_add_f32_e32 v98, 1.0, v98
	v_add_f32_e32 v99, 1.0, v99
	v_exp_f32_e32 v102, v102
	v_exp_f32_e32 v103, v103
	v_rcp_f32_e32 v98, v98
	v_rcp_f32_e32 v99, v99
	v_add_f32_e32 v100, 1.0, v100
	v_add_f32_e32 v101, 1.0, v101
	v_rcp_f32_e32 v100, v100
	v_rcp_f32_e32 v101, v101
	v_add_f32_e32 v102, 1.0, v102
	v_add_f32_e32 v103, 1.0, v103
	v_pk_mul_f32 v[92:93], v[92:93], v[96:97]
	v_rcp_f32_e32 v102, v102
	v_rcp_f32_e32 v103, v103
	v_pk_mul_f32 v[84:85], v[92:93], v[84:85]
	v_pk_mul_f32 v[92:93], v[94:95], v[98:99]
	v_cvt_pk_bf16_f32 v84, v84, v85
	v_pk_mul_f32 v[86:87], v[92:93], v[86:87]
	s_nop 0
	v_cvt_pk_bf16_f32 v85, v86, v87
	v_pk_mul_f32 v[86:87], v[88:89], v[100:101]
	s_nop 0
	v_pk_mul_f32 v[80:81], v[86:87], v[80:81]
	s_nop 0
	v_cvt_pk_bf16_f32 v86, v80, v81
	v_pk_mul_f32 v[80:81], v[90:91], v[102:103]
	s_nop 0
	v_pk_mul_f32 v[80:81], v[80:81], v[82:83]
	v_mul_f32_e32 v82, 0xbfb8aa3b, v78
	v_cvt_pk_bf16_f32 v87, v80, v81
	v_or_b32_e32 v80, 32, v138
	v_mad_i64_i32 v[80:81], s[2:3], v80, s4, v[112:113]
	v_lshl_add_u64 v[80:81], v[80:81], 0, v[114:115]
	global_store_dwordx4 v[80:81], v[84:87], off
	v_mul_f32_e32 v80, 0xbfb8aa3b, v76
	v_mul_f32_e32 v81, 0xbfb8aa3b, v77
	v_exp_f32_e32 v80, v80
	v_exp_f32_e32 v81, v81
	v_mul_f32_e32 v83, 0xbfb8aa3b, v79
	v_exp_f32_e32 v82, v82
	v_exp_f32_e32 v83, v83
	v_mul_f32_e32 v84, 0xbfb8aa3b, v72
	v_mul_f32_e32 v85, 0xbfb8aa3b, v73
	v_exp_f32_e32 v84, v84
	v_exp_f32_e32 v85, v85
	v_add_f32_e32 v80, 1.0, v80
	v_add_f32_e32 v81, 1.0, v81
	v_mul_f32_e32 v86, 0xbfb8aa3b, v74
	v_mul_f32_e32 v87, 0xbfb8aa3b, v75
	v_rcp_f32_e32 v80, v80
	v_rcp_f32_e32 v81, v81
	v_add_f32_e32 v82, 1.0, v82
	v_add_f32_e32 v83, 1.0, v83
	v_exp_f32_e32 v86, v86
	v_exp_f32_e32 v87, v87
	v_rcp_f32_e32 v82, v82
	v_rcp_f32_e32 v83, v83
	v_add_f32_e32 v84, 1.0, v84
	v_add_f32_e32 v85, 1.0, v85
	v_rcp_f32_e32 v84, v84
	v_rcp_f32_e32 v85, v85
	v_add_f32_e32 v86, 1.0, v86
	v_add_f32_e32 v87, 1.0, v87
	v_pk_mul_f32 v[76:77], v[76:77], v[80:81]
	v_rcp_f32_e32 v86, v86
	v_rcp_f32_e32 v87, v87
	v_pk_mul_f32 v[68:69], v[76:77], v[68:69]
	v_pk_mul_f32 v[76:77], v[78:79], v[82:83]
	v_cvt_pk_bf16_f32 v68, v68, v69
	v_pk_mul_f32 v[70:71], v[76:77], v[70:71]
	s_nop 0
	v_cvt_pk_bf16_f32 v69, v70, v71
	v_pk_mul_f32 v[70:71], v[72:73], v[84:85]
	v_add_u32_e32 v72, 0x80, v138
	v_pk_mul_f32 v[64:65], v[70:71], v[64:65]
	s_nop 0
	v_cvt_pk_bf16_f32 v70, v64, v65
	v_pk_mul_f32 v[64:65], v[74:75], v[86:87]
	s_nop 0
	v_pk_mul_f32 v[64:65], v[64:65], v[66:67]
	v_mul_f32_e32 v66, 0xbfb8aa3b, v62
	v_cvt_pk_bf16_f32 v71, v64, v65
	v_or_b32_e32 v64, 48, v138
	v_mad_i64_i32 v[64:65], s[2:3], v64, s4, v[112:113]
	v_lshl_add_u64 v[64:65], v[64:65], 0, v[114:115]
	global_store_dwordx4 v[64:65], v[68:71], off
	v_mul_f32_e32 v64, 0xbfb8aa3b, v60
	v_mul_f32_e32 v65, 0xbfb8aa3b, v61
	v_exp_f32_e32 v64, v64
	v_exp_f32_e32 v65, v65
	v_mul_f32_e32 v67, 0xbfb8aa3b, v63
	v_exp_f32_e32 v66, v66
	v_exp_f32_e32 v67, v67
	v_mul_f32_e32 v68, 0xbfb8aa3b, v56
	v_mul_f32_e32 v69, 0xbfb8aa3b, v57
	v_exp_f32_e32 v68, v68
	v_exp_f32_e32 v69, v69
	v_add_f32_e32 v64, 1.0, v64
	v_add_f32_e32 v65, 1.0, v65
	v_mul_f32_e32 v70, 0xbfb8aa3b, v58
	v_mul_f32_e32 v71, 0xbfb8aa3b, v59
	v_rcp_f32_e32 v64, v64
	v_rcp_f32_e32 v65, v65
	v_add_f32_e32 v66, 1.0, v66
	v_add_f32_e32 v67, 1.0, v67
	v_exp_f32_e32 v70, v70
	v_exp_f32_e32 v71, v71
	v_rcp_f32_e32 v66, v66
	v_rcp_f32_e32 v67, v67
	v_add_f32_e32 v68, 1.0, v68
	v_add_f32_e32 v69, 1.0, v69
	v_rcp_f32_e32 v68, v68
	v_rcp_f32_e32 v69, v69
	v_add_f32_e32 v70, 1.0, v70
	v_add_f32_e32 v71, 1.0, v71
	v_pk_mul_f32 v[60:61], v[60:61], v[64:65]
	v_rcp_f32_e32 v70, v70
	v_rcp_f32_e32 v71, v71
	v_pk_mul_f32 v[52:53], v[60:61], v[52:53]
	v_pk_mul_f32 v[60:61], v[62:63], v[66:67]
	v_cvt_pk_bf16_f32 v52, v52, v53
	v_pk_mul_f32 v[54:55], v[60:61], v[54:55]
	s_nop 0
	v_cvt_pk_bf16_f32 v53, v54, v55
	v_pk_mul_f32 v[54:55], v[56:57], v[68:69]
	s_nop 0
	v_pk_mul_f32 v[48:49], v[54:55], v[48:49]
	s_nop 0
	v_cvt_pk_bf16_f32 v54, v48, v49
; #define PG8_WAIT_V(n) asm volatile("s_waitcnt vmcnt(" #n ")" ::: "memory")
; #define PG8_BAR __builtin_amdgcn_s_barrier()
; template <class Epi>
; DI void gemm_phase(LAS unsigned char* lds, const Gemm g, const StaticOrder& S, const Epi& E) {
;     ...
;         E(acc, cur, wr, wc, fr, fq);
;         if (!has_next) break;
; #pragma unroll
;         for (int a = 0; a < 2; ++a)
; #pragma unroll
;             for (int b = 0; b < 2; ++b)
; #pragma unroll
;                 for (int m = 0; m < 4; ++m)
; #pragma unroll
;                     for (int n = 0; n < 2; ++n) acc[a][b][m][n] = (f32x4){0.f, 0.f, 0.f, 0.f};
;         cur = nxt; cA = nA; cB = nB; ++ui;
;     }
;     PG8_WAIT_V(0);
;     if (wr == 0) PG8_BAR;
;     PG8_BAR;
;     DI void operator()(const f32x4 (&acc)[2][2][4][2], const Unit& u, int wr, int wc, int fr, int fq) const {
;         const int row0 = u.pm * BM + wr * 64 + fr, col0 = u.pn * HALF + wc * 32 + 8 * fq;
; #pragma unroll
;         for (int ai = 0; ai < 2; ++ai)
; #pragma unroll
;             for (int m = 0; m < 4; ++m) { float hv[8];
; #pragma unroll
;                 for (int n = 0; n < 2; ++n)
; #pragma unroll
;                     for (int e = 0; e < 4; ++e) { const float gt = acc[ai][0][m][n][e], up = acc[ai][1][m][n][e];
;                         hv[n * 4 + e] = gt * __builtin_amdgcn_rcpf(1.f + __builtin_amdgcn_exp2f(-1.4426950408889634f * gt)) * up; }
;                 *(u32x4*)(H + (size_t)(row0 + ai * HALF + m * 16) * DFF + col0) = (u32x4){pk(hv[0], hv[1]), pk(hv[2], hv[3]), pk(hv[4], hv[5]), pk(hv[6], hv[7])}; }
	v_pk_mul_f32 v[48:49], v[58:59], v[70:71]
	s_nop 0
	v_pk_mul_f32 v[48:49], v[48:49], v[50:51]
	v_mul_f32_e32 v50, 0xbfb8aa3b, v46
	v_cvt_pk_bf16_f32 v55, v48, v49
	v_mad_i64_i32 v[48:49], s[2:3], v72, s4, v[112:113]
	v_lshl_add_u64 v[48:49], v[48:49], 0, v[114:115]
	global_store_dwordx4 v[48:49], v[52:55], off
	v_mul_f32_e32 v48, 0xbfb8aa3b, v44
	v_mul_f32_e32 v49, 0xbfb8aa3b, v45
	v_exp_f32_e32 v48, v48
	v_exp_f32_e32 v49, v49
	v_mul_f32_e32 v51, 0xbfb8aa3b, v47
	v_exp_f32_e32 v50, v50
	v_exp_f32_e32 v51, v51
	v_mul_f32_e32 v52, 0xbfb8aa3b, v40
	v_mul_f32_e32 v53, 0xbfb8aa3b, v41
	v_exp_f32_e32 v52, v52
	v_exp_f32_e32 v53, v53
	v_add_f32_e32 v48, 1.0, v48
	v_add_f32_e32 v49, 1.0, v49
	v_mul_f32_e32 v54, 0xbfb8aa3b, v42
	v_mul_f32_e32 v55, 0xbfb8aa3b, v43
	v_rcp_f32_e32 v48, v48
	v_rcp_f32_e32 v49, v49
	v_add_f32_e32 v50, 1.0, v50
	v_add_f32_e32 v51, 1.0, v51
	v_exp_f32_e32 v54, v54
	v_exp_f32_e32 v55, v55
	v_rcp_f32_e32 v50, v50
	v_rcp_f32_e32 v51, v51
	v_add_f32_e32 v52, 1.0, v52
	v_add_f32_e32 v53, 1.0, v53
	v_rcp_f32_e32 v52, v52
	v_rcp_f32_e32 v53, v53
	v_add_f32_e32 v54, 1.0, v54
	v_add_f32_e32 v55, 1.0, v55
	v_pk_mul_f32 v[44:45], v[44:45], v[48:49]
	v_rcp_f32_e32 v54, v54
	v_rcp_f32_e32 v55, v55
	v_pk_mul_f32 v[36:37], v[44:45], v[36:37]
	v_pk_mul_f32 v[44:45], v[46:47], v[50:51]
	v_cvt_pk_bf16_f32 v36, v36, v37
	v_pk_mul_f32 v[38:39], v[44:45], v[38:39]
	s_nop 0
	v_cvt_pk_bf16_f32 v37, v38, v39
	v_pk_mul_f32 v[38:39], v[40:41], v[52:53]
	s_nop 0
	v_pk_mul_f32 v[32:33], v[38:39], v[32:33]
	s_nop 0
	v_cvt_pk_bf16_f32 v38, v32, v33
	v_pk_mul_f32 v[32:33], v[42:43], v[54:55]
	s_nop 0
	v_pk_mul_f32 v[32:33], v[32:33], v[34:35]
	v_mul_f32_e32 v34, 0xbfb8aa3b, v30
	v_cvt_pk_bf16_f32 v39, v32, v33
	v_add_u32_e32 v32, 0x90, v138
	v_mad_i64_i32 v[32:33], s[2:3], v32, s4, v[112:113]
	v_lshl_add_u64 v[32:33], v[32:33], 0, v[114:115]
	global_store_dwordx4 v[32:33], v[36:39], off
	v_mul_f32_e32 v32, 0xbfb8aa3b, v28
	v_mul_f32_e32 v33, 0xbfb8aa3b, v29
	v_exp_f32_e32 v32, v32
	v_exp_f32_e32 v33, v33
	v_mul_f32_e32 v35, 0xbfb8aa3b, v31
	v_exp_f32_e32 v34, v34
	v_exp_f32_e32 v35, v35
	v_mul_f32_e32 v36, 0xbfb8aa3b, v24
	v_mul_f32_e32 v37, 0xbfb8aa3b, v25
	v_exp_f32_e32 v36, v36
	v_exp_f32_e32 v37, v37
	v_add_f32_e32 v32, 1.0, v32
	v_add_f32_e32 v33, 1.0, v33
	v_mul_f32_e32 v38, 0xbfb8aa3b, v26
	v_mul_f32_e32 v39, 0xbfb8aa3b, v27
	v_rcp_f32_e32 v32, v32
	v_rcp_f32_e32 v33, v33
	v_add_f32_e32 v34, 1.0, v34
	v_add_f32_e32 v35, 1.0, v35
	v_exp_f32_e32 v38, v38
	v_exp_f32_e32 v39, v39
	v_rcp_f32_e32 v34, v34
	v_rcp_f32_e32 v35, v35
	v_add_f32_e32 v36, 1.0, v36
	v_add_f32_e32 v37, 1.0, v37
	v_rcp_f32_e32 v36, v36
	v_rcp_f32_e32 v37, v37
	v_add_f32_e32 v38, 1.0, v38
	v_add_f32_e32 v39, 1.0, v39
	v_pk_mul_f32 v[28:29], v[28:29], v[32:33]
	v_rcp_f32_e32 v38, v38
	v_rcp_f32_e32 v39, v39
	v_pk_mul_f32 v[20:21], v[28:29], v[20:21]
	v_pk_mul_f32 v[28:29], v[30:31], v[34:35]
	v_cvt_pk_bf16_f32 v20, v20, v21
	v_pk_mul_f32 v[22:23], v[28:29], v[22:23]
	s_nop 0
	v_cvt_pk_bf16_f32 v21, v22, v23
	v_pk_mul_f32 v[22:23], v[24:25], v[36:37]
	s_nop 0
	v_pk_mul_f32 v[16:17], v[22:23], v[16:17]
	s_nop 0
	v_cvt_pk_bf16_f32 v22, v16, v17
	v_pk_mul_f32 v[16:17], v[26:27], v[38:39]
	s_nop 0
	v_pk_mul_f32 v[16:17], v[16:17], v[18:19]
	v_mul_f32_e32 v18, 0xbfb8aa3b, v14
	v_cvt_pk_bf16_f32 v23, v16, v17
	v_add_u32_e32 v16, 0xa0, v138
	v_mad_i64_i32 v[16:17], s[2:3], v16, s4, v[112:113]
	v_lshl_add_u64 v[16:17], v[16:17], 0, v[114:115]
	global_store_dwordx4 v[16:17], v[20:23], off
	v_mul_f32_e32 v16, 0xbfb8aa3b, v12
	v_mul_f32_e32 v17, 0xbfb8aa3b, v13
	v_exp_f32_e32 v16, v16
	v_exp_f32_e32 v17, v17
	v_mul_f32_e32 v19, 0xbfb8aa3b, v15
	v_exp_f32_e32 v18, v18
	v_exp_f32_e32 v19, v19
	v_mul_f32_e32 v20, 0xbfb8aa3b, v8
	v_mul_f32_e32 v21, 0xbfb8aa3b, v9
	v_exp_f32_e32 v20, v20
	v_exp_f32_e32 v21, v21
	v_add_f32_e32 v16, 1.0, v16
	v_add_f32_e32 v17, 1.0, v17
	v_mul_f32_e32 v22, 0xbfb8aa3b, v10
	v_mul_f32_e32 v23, 0xbfb8aa3b, v11
	v_rcp_f32_e32 v16, v16
	v_rcp_f32_e32 v17, v17
	v_add_f32_e32 v18, 1.0, v18
	v_add_f32_e32 v19, 1.0, v19
	v_exp_f32_e32 v22, v22
	v_exp_f32_e32 v23, v23
	v_rcp_f32_e32 v18, v18
	v_rcp_f32_e32 v19, v19
	v_add_f32_e32 v20, 1.0, v20
	v_add_f32_e32 v21, 1.0, v21
	v_rcp_f32_e32 v20, v20
	v_rcp_f32_e32 v21, v21
	v_add_f32_e32 v22, 1.0, v22
	v_add_f32_e32 v23, 1.0, v23
	v_pk_mul_f32 v[12:13], v[12:13], v[16:17]
	v_rcp_f32_e32 v22, v22
	v_rcp_f32_e32 v23, v23
	v_pk_mul_f32 v[4:5], v[12:13], v[4:5]
	v_pk_mul_f32 v[12:13], v[14:15], v[18:19]
	v_cvt_pk_bf16_f32 v4, v4, v5
	v_pk_mul_f32 v[6:7], v[12:13], v[6:7]
	s_nop 0
	v_cvt_pk_bf16_f32 v5, v6, v7
	v_pk_mul_f32 v[6:7], v[8:9], v[20:21]
	s_nop 0
	v_pk_mul_f32 v[0:1], v[6:7], v[0:1]
	s_nop 0
	v_cvt_pk_bf16_f32 v6, v0, v1
	v_pk_mul_f32 v[0:1], v[10:11], v[22:23]
	s_nop 0
	v_pk_mul_f32 v[0:1], v[0:1], v[2:3]
	s_nop 0
	v_cvt_pk_bf16_f32 v7, v0, v1
	v_add_u32_e32 v0, 0xb0, v138
	v_mad_i64_i32 v[0:1], s[2:3], v0, s4, v[112:113]
	v_lshl_add_u64 v[0:1], v[0:1], 0, v[114:115]
	s_mov_b32 s2, s8
	s_mov_b32 s3, s10
	global_store_dwordx4 v[0:1], v[4:7], off
	s_cbranch_vccz .LBB0_34
	s_waitcnt vmcnt(0)
	s_cmpk_gt_u32 s24, 0xff
	s_cbranch_scc1 .LBB0_41
	s_barrier

; __device__ __forceinline__ int opaque_tid() { int t = threadIdx.x; asm volatile("" : "+v"(t)); return t; }
; #define PG8_BAR __builtin_amdgcn_s_barrier()
; template <class Epi>
; DI void gemm_phase(LAS unsigned char* lds, const Gemm g, const StaticOrder& S, const Epi& E) {
;     const int tid = opaque_tid(), wid = __builtin_amdgcn_readfirstlane(tid >> 6), lane = tid & 63, wr = wid >> 2, wc = wid & 3, fr = lane & 15, fq = lane >> 4;
;     const int K = g.K, nt = K / BK;
;     unsigned voff[2];
; #pragma unroll
;     for (int i = 0; i < 2; ++i) { int R, C; stage_rc(tid * 16 + i * 8192, R, C); voff[i] = (unsigned)(R * K + C) * 2u; }
;     const size_t kstep = (size_t)(BK * 2);
;     const size_t hstep = (size_t)HALF * K * 2;
;     const size_t tstep = 2 * hstep;
;     const unsigned ldsw = (unsigned)wid * 1024u;
;     const int aoff = lds_byte(wr * 64 + fr, fq * 8), boff = lds_byte(wc * 32 + fr, fq * 8);
;     ...
;     Unit cur, nxt; int ui = 0;
;     if (!S.next(0, cur)) return;
;     f32x4 acc[2][2][4][2];
; #pragma unroll
;     for (int a = 0; a < 2; ++a)
; #pragma unroll
;         for (int b = 0; b < 2; ++b)
; #pragma unroll
;             for (int m = 0; m < 4; ++m)
; #pragma unroll
;                 for (int n = 0; n < 2; ++n) acc[a][b][m][n] = (f32x4){0.f, 0.f, 0.f, 0.f};
;     bf16x8 At[4][2], B0[2][2], B1[2][2];
;     const char* cA = (const char*)g.A + (size_t)cur.pm * tstep; const char* cB = (const char*)g.Bt + (size_t)cur.pn * tstep;
;     PG8_STAGE(PG8_SB(0, 0), cB); PG8_STAGE(PG8_SA(0, 0), cA); PG8_STAGE(PG8_SB(0, 1), cB + hstep); PG8_STAGE(PG8_SA(0, 1), cA + hstep);
;     if (wr == 1) PG8_BAR;
; __global__ void __launch_bounds__(512, 2) mega_fwd(Params p) {
;     ...
;             } else if (op == OP_OPROJ) {
;                 const int lp = layer > 0 ? layer - 1 : 0;
;                 pg8::EpiRes E{ya, layer == 0 ? p.x : yb, layer == 0 ? nullptr : st2, p.ln_ffn_g + lp * DM, p.ln_ffn_b + lp * DM};
;                 if (!dil) { pg8::Gemm gm{ob, (const u16*)(ws + W_SBO) + (size_t)j * DM * DM, T_TOK, DM, DM};
;                     S.init(gm.M, gm.N, gridDim.x, blockIdx.x); pg8::gemm_phase(lds, gm, S, E); }
;                 else { pg8::Gemm gm{ob, (const u16*)(ws + W_DO) + (size_t)j * DM * WDIL, T_TOK, DM, WDIL};
;                     S.init(gm.M, gm.N, gridDim.x, blockIdx.x); pg8::gemm_phase(lds, gm, S, E); }
.LBB0_59:
	s_mov_b64 s[2:3], 0
	v_writelane_b32 v255, s2, 46
	s_nop 1
	v_writelane_b32 v255, s3, 47
	s_and_b64 vcc, exec, s[6:7]
	s_cbranch_vccz .LBB0_44
	s_load_dwordx8 s[4:11], s[0:1], 0x0
	v_sub_u32_e64 v0, s33, 1 clamp
	s_cmp_lg_u32 s33, 0
	v_readfirstlane_b32 s2, v0
	s_waitcnt lgkmcnt(0)
	s_load_dwordx4 s[4:7], s[0:1], 0x20
	s_cselect_b64 s[14:15], -1, 0
	s_lshl_b32 s76, s2, 11
	s_lshl_b64 s[2:3], s[76:77], 2
	s_add_u32 s16, s10, s2
	s_addc_u32 s17, s11, s3
	s_waitcnt lgkmcnt(0)
	s_add_u32 s18, s4, s2
	s_addc_u32 s19, s5, s3
	v_readlane_b32 s2, v255, 43
	v_readlane_b32 s3, v255, 44
	s_mov_b32 s3, s77
	v_writelane_b32 v255, s2, 43
	s_mov_b64 s[6:7], -1
	s_nop 0
	v_writelane_b32 v255, s3, 44
	s_nop 0
	v_readlane_b32 s2, v255, 41
	v_readlane_b32 s3, v255, 42
	s_and_b64 vcc, exec, s[2:3]
	s_cbranch_vccz .LBB0_307
	v_readlane_b32 s2, v254, 46
	v_mov_b32_e32 v0, v156
	v_readlane_b32 s3, v254, 47
	s_andn2_b64 vcc, exec, s[2:3]
	v_readfirstlane_b32 s28, v0
	s_cbranch_vccnz .LBB0_306
	v_lshlrev_b32_e32 v5, 4, v0
	v_add_u32_e32 v2, 0x2000, v5
	v_ashrrev_i32_e32 v1, 31, v2
	v_lshrrev_b32_e32 v1, 22, v1
	v_add_u32_e32 v1, v2, v1
	v_ashrrev_i32_e32 v1, 10, v1
	v_mul_i32_i24_e32 v3, 0x400, v1
	v_sub_u32_e32 v2, v2, v3
	v_lshrrev_b32_e32 v3, 4, v2
	v_bitop3_b32 v4, v3, v2, 32 bitop3:0x6c
	v_ashrrev_i32_e32 v2, 31, v4
	v_lshrrev_b32_e32 v2, 26, v2
	v_add_u32_e32 v6, v4, v2
	v_ashrrev_i32_e32 v2, 6, v6
	v_and_b32_e32 v6, 0xc0, v6
	v_sub_u32_e32 v4, v4, v6
	v_bfe_i32 v6, v0, 27, 1
	v_lshrrev_b32_e32 v6, 22, v6
	v_add_u32_e32 v6, v5, v6
	v_and_b32_e32 v6, 0xfffffc00, v6
	v_readlane_b32 s4, v255, 43
	v_lshlrev_b32_e32 v3, 3, v1
	v_sub_u32_e32 v5, v5, v6
	s_mul_hi_u32 s2, s4, 0x900000
	s_mul_i32 s3, s4, 0x900000
	v_readlane_b32 s4, v253, 14
	v_and_b32_e32 v3, 0xfffff0, v3
	v_lshrrev_b32_e32 v6, 4, v5
	s_add_u32 s29, s4, s3
	v_add_u32_e32 v3, v2, v3
	s_movk_i32 s4, 0x900
	v_bitop3_b32 v8, v6, v5, 32 bitop3:0x6c
	v_ashrrev_i32_e32 v6, 31, v0
	v_mul_lo_u32 v7, v3, s4
	v_lshlrev_b32_e32 v3, 5, v1
	v_lshrrev_b32_e32 v6, 26, v6
	v_and_b32_e32 v3, 32, v3
	v_ashrrev_i16_sdwa v4, v252, sext(v4) dst_sel:DWORD dst_unused:UNUSED_PAD src0_sel:DWORD src1_sel:BYTE_0
	v_ashrrev_i32_e32 v5, 31, v5
	v_add_u32_e32 v6, v0, v6
	v_or_b32_e32 v7, v7, v3
	v_bfe_i32 v4, v4, 0, 16
	v_lshrrev_b32_e32 v5, 26, v5
	v_ashrrev_i32_e32 v6, 6, v6
	v_add_lshl_u32 v186, v7, v4, 1
	v_add_u32_e32 v5, v8, v5
	v_lshlrev_b32_e32 v7, 3, v6
	v_readlane_b32 s5, v255, 44
	v_readlane_b32 s3, v253, 15
	v_ashrrev_i32_e32 v5, 6, v5
	v_and_b32_e32 v7, 0xfffff0, v7
	s_addc_u32 s30, s3, s2
	s_ashr_i32 s3, s28, 6
	v_add_u32_e32 v7, v5, v7
	v_mul_i32_i24_e32 v10, 64, v5
	v_readlane_b32 s5, v254, 31
	s_ashr_i32 s2, s28, 8
	s_lshl_b32 s31, s3, 10
	v_mul_lo_u32 v9, v7, s4
	v_lshlrev_b32_e32 v7, 5, v6
	v_sub_u32_e32 v8, v8, v10
	s_mul_i32 s4, s5, 0x120000
	v_and_b32_e32 v7, 32, v7
	v_ashrrev_i16_sdwa v8, v252, sext(v8) dst_sel:DWORD dst_unused:UNUSED_PAD src0_sel:DWORD src1_sel:BYTE_0
	s_add_u32 s22, s29, s4
	s_mul_hi_i32 s4, s5, 0x120000
	v_or_b32_e32 v9, v9, v7
	v_bfe_i32 v8, v8, 0, 16
	s_addc_u32 s23, s30, s4
	s_add_i32 s34, s31, 0
	v_add_lshl_u32 v188, v9, v8, 1
	s_add_i32 m0, s34, 0x10000
	v_readlane_b32 s4, v254, 21
	global_load_lds_dwordx4 v188, s[22:23]
	s_add_i32 m0, s34, 0x12000
	v_readlane_b32 s5, v254, 22
	global_load_lds_dwordx4 v186, s[22:23]
	s_mov_b32 m0, s34
	s_add_i32 s35, s34, 0x2000
	s_nop 1
	global_load_lds_dwordx4 v188, s[4:5]
	s_mov_b32 m0, s35
	s_nop 0
	global_load_lds_dwordx4 v186, s[4:5]
	s_add_u32 s4, s22, 0x90000
	s_addc_u32 s5, s23, 0
	s_add_i32 m0, s34, 0x14000
	s_add_i32 s36, s34, 0x4000
	global_load_lds_dwordx4 v188, s[4:5]
	s_add_i32 m0, s34, 0x16000
	s_add_i32 s37, s34, 0x6000
	global_load_lds_dwordx4 v186, s[4:5]
	v_readlane_b32 s4, v254, 23
	s_mov_b32 m0, s36
	v_readlane_b32 s5, v254, 24
	s_cmp_lg_u32 s2, 1
	s_nop 3
	global_load_lds_dwordx4 v188, s[4:5]
	s_mov_b32 m0, s37
	s_nop 0
	global_load_lds_dwordx4 v186, s[4:5]
	s_cbranch_scc1 .LBB0_64
	s_setprio 1
	s_barrier

; #define PG8_STAGE(bufoff, gbase) do { _Pragma("unroll") for (int _i = 0; _i < 2; ++_i) \
;         __builtin_amdgcn_global_load_lds((const unsigned*)((const char*)(gbase) + voff[_i]), (LAS unsigned*)(lds + (bufoff) + ldsw + _i * 8192), 16, 0, 0); } while (0)
; #define PG8_LDA(dst, b, h) do { _Pragma("unroll") for (int m = 0; m < 4; ++m) _Pragma("unroll") for (int k = 0; k < 2; ++k) dst[m][k] = *(const LAS bf16x8*)(lds + PG8_SA(b, h) + aoff + m * 2048 + k * 1024); } while (0)
; #define PG8_LDB(dst, b, h) do { _Pragma("unroll") for (int n = 0; n < 2; ++n) _Pragma("unroll") for (int k = 0; k < 2; ++k) dst[n][k] = *(const LAS bf16x8*)(lds + PG8_SB(b, h) + boff + n * 2048 + k * 1024); } while (0)
; #define PG8_MMA(ai, bj, At, Bt) do { __builtin_amdgcn_s_setprio(1); _Pragma("unroll") for (int m = 0; m < 4; ++m) _Pragma("unroll") for (int n = 0; n < 2; ++n) _Pragma("unroll") for (int k = 0; k < 2; ++k) \
;         acc[ai][bj][m][n] = __builtin_amdgcn_mfma_f32_16x16x32_bf16(Bt[n][k], At[m][k], acc[ai][bj][m][n], 0, 0, 0); __builtin_amdgcn_s_setprio(0); } while (0)
; #define PG8_WAIT_V(n) asm volatile("s_waitcnt vmcnt(" #n ")" ::: "memory")
; #define PG8_WAIT_L(n) asm volatile("s_waitcnt lgkmcnt(" #n ")" ::: "memory")
; #define PG8_BAR __builtin_amdgcn_s_barrier()
; #define PG8_SCHED __builtin_amdgcn_sched_barrier(0)
; template <class Epi>
; DI void gemm_phase(LAS unsigned char* lds, const Gemm g, const StaticOrder& S, const Epi& E) {
;     ...
;         for (int t = 0; t < nt; t += 2) {
;             const bool last = (t == nt - 2);
;             const char* a1 = cA + (size_t)(t + 1) * kstep;
;             const char* a2 = last ? nA : cA + (size_t)(t + 2) * kstep; const char* b2 = last ? nB : cB + (size_t)(t + 2) * kstep;
;             const char* a3 = a2 + kstep; const char* b3 = b2 + kstep;
;             PG8_LDB(B0, 0, 0); PG8_SCHED; PG8_LDA(At, 0, 0); PG8_STAGE(PG8_SA(1, 1), a1 + hstep);
;             PG8_WAIT_L(8); PG8_BAR; PG8_WAIT_L(0); PG8_MMA(0, 0, At, B0); PG8_BAR; PG8_SCHED;
;             PG8_LDB(B1, 0, 1); PG8_STAGE(PG8_SB(0, 0), b2);
;             PG8_BAR; PG8_WAIT_L(0); PG8_MMA(0, 1, At, B1); PG8_BAR;
;             PG8_LDA(At, 0, 1); PG8_STAGE(PG8_SA(0, 0), a2);
;             PG8_BAR; PG8_WAIT_L(0); PG8_MMA(1, 0, At, B0); PG8_BAR; PG8_SCHED;
;             PG8_STAGE(PG8_SB(0, 1), b2 + hstep);
;             PG8_WAIT_V(6); PG8_BAR; PG8_MMA(1, 1, At, B1); PG8_BAR;
.LBB0_77:
	ds_read_b128 v[128:131], v226
	ds_read_b128 v[132:135], v226 offset:1024
	ds_read_b128 v[136:139], v226 offset:2048
	ds_read_b128 v[140:143], v226 offset:3072
	ds_read_b128 v[144:147], v228
	ds_read_b128 v[148:151], v228 offset:1024
	ds_read_b128 v[152:155], v228 offset:2048
	ds_read_b128 v[194:197], v228 offset:3072
	ds_read_b128 v[198:201], v228 offset:4096
	ds_read_b128 v[202:205], v228 offset:5120
	ds_read_b128 v[206:209], v228 offset:6144
	ds_read_b128 v[210:213], v228 offset:7168
	s_add_u32 s22, s20, 0x100
	s_addc_u32 s23, s21, 0
	s_add_i32 s43, 0, 0x10000
	s_cmp_eq_u32 s33, 32
	s_cselect_b32 s27, s9, s23
	s_cselect_b32 s26, s8, s22
	s_cselect_b32 s25, s11, s5
	s_cselect_b32 s24, s10, s4
	s_add_i32 m0, s34, 0xc000
	s_nop 0
	global_load_lds_dwordx4 v190, s[20:21]
	s_add_i32 m0, s34, 0xe000
	s_nop 0
	global_load_lds_dwordx4 v192, s[20:21]
	s_waitcnt lgkmcnt(8)
	s_barrier
	s_waitcnt lgkmcnt(0)
	v_mfma_f32_16x16x32_bf16 v[124:127], v[128:131], v[144:147], v[124:127]
	v_mfma_f32_16x16x32_bf16 v[120:123], v[136:139], v[144:147], v[120:123]
	v_mfma_f32_16x16x32_bf16 v[116:119], v[128:131], v[152:155], v[116:119]
	v_mfma_f32_16x16x32_bf16 v[112:115], v[136:139], v[152:155], v[112:115]
	v_mfma_f32_16x16x32_bf16 v[108:111], v[128:131], v[198:201], v[108:111]
	v_mfma_f32_16x16x32_bf16 v[104:107], v[136:139], v[198:201], v[104:107]
	v_mfma_f32_16x16x32_bf16 v[100:103], v[128:131], v[206:209], v[100:103]
	v_mfma_f32_16x16x32_bf16 v[96:99], v[136:139], v[206:209], v[96:99]
	v_mfma_f32_16x16x32_bf16 v[124:127], v[132:135], v[148:151], v[124:127]
	v_mfma_f32_16x16x32_bf16 v[120:123], v[140:143], v[148:151], v[120:123]
	v_mfma_f32_16x16x32_bf16 v[116:119], v[132:135], v[194:197], v[116:119]
	v_mfma_f32_16x16x32_bf16 v[112:115], v[140:143], v[194:197], v[112:115]
	v_mfma_f32_16x16x32_bf16 v[108:111], v[132:135], v[202:205], v[108:111]
	v_mfma_f32_16x16x32_bf16 v[104:107], v[140:143], v[202:205], v[104:107]
	v_mfma_f32_16x16x32_bf16 v[100:103], v[132:135], v[210:213], v[100:103]
	v_mfma_f32_16x16x32_bf16 v[96:99], v[140:143], v[210:213], v[96:99]
	s_barrier
	ds_read_b128 v[214:217], v226 offset:16384
	ds_read_b128 v[230:233], v226 offset:17408
	ds_read_b128 v[234:237], v226 offset:18432
	ds_read_b128 v[238:241], v226 offset:19456
	s_add_i32 s44, 0, 0x14000
	s_add_i32 s20, s43, s31
	s_mov_b32 m0, s20
	s_nop 0
	global_load_lds_dwordx4 v188, s[24:25]
	s_add_i32 m0, s20, 0x2000
	s_nop 0
	global_load_lds_dwordx4 v186, s[24:25]
	s_waitcnt lgkmcnt(0)
	s_barrier
	v_mfma_f32_16x16x32_bf16 v[60:63], v[214:217], v[144:147], v[60:63]
	v_mfma_f32_16x16x32_bf16 v[56:59], v[234:237], v[144:147], v[56:59]
	v_mfma_f32_16x16x32_bf16 v[52:55], v[214:217], v[152:155], v[52:55]
	v_mfma_f32_16x16x32_bf16 v[48:51], v[234:237], v[152:155], v[48:51]
	v_mfma_f32_16x16x32_bf16 v[44:47], v[214:217], v[198:201], v[44:47]
	v_mfma_f32_16x16x32_bf16 v[40:43], v[234:237], v[198:201], v[40:43]
	v_mfma_f32_16x16x32_bf16 v[36:39], v[214:217], v[206:209], v[36:39]
	v_mfma_f32_16x16x32_bf16 v[32:35], v[234:237], v[206:209], v[32:35]
	v_mfma_f32_16x16x32_bf16 v[60:63], v[230:233], v[148:151], v[60:63]
	s_mov_b32 m0, s34
	v_mfma_f32_16x16x32_bf16 v[56:59], v[238:241], v[148:151], v[56:59]
	v_mfma_f32_16x16x32_bf16 v[52:55], v[230:233], v[194:197], v[52:55]
	v_mfma_f32_16x16x32_bf16 v[48:51], v[238:241], v[194:197], v[48:51]
	v_mfma_f32_16x16x32_bf16 v[44:47], v[230:233], v[202:205], v[44:47]
	v_mfma_f32_16x16x32_bf16 v[40:43], v[238:241], v[202:205], v[40:43]
	v_mfma_f32_16x16x32_bf16 v[36:39], v[230:233], v[210:213], v[36:39]
	v_mfma_f32_16x16x32_bf16 v[32:35], v[238:241], v[210:213], v[32:35]
	s_barrier
	ds_read_b128 v[144:147], v228 offset:16384
	ds_read_b128 v[148:151], v228 offset:17408
	ds_read_b128 v[152:155], v228 offset:18432
	ds_read_b128 v[194:197], v228 offset:19456
	ds_read_b128 v[198:201], v228 offset:20480
	ds_read_b128 v[202:205], v228 offset:21504
	ds_read_b128 v[206:209], v228 offset:22528
	ds_read_b128 v[210:213], v228 offset:23552
	global_load_lds_dwordx4 v188, s[26:27]
	s_mov_b64 s[100:101], s[26:27]
	s_mov_b32 m0, s35
	s_nop 0
	global_load_lds_dwordx4 v186, s[26:27]
	s_waitcnt lgkmcnt(0)
	s_barrier
	v_mfma_f32_16x16x32_bf16 v[92:95], v[128:131], v[144:147], v[92:95]
	v_mfma_f32_16x16x32_bf16 v[88:91], v[136:139], v[144:147], v[88:91]
	v_mfma_f32_16x16x32_bf16 v[84:87], v[128:131], v[152:155], v[84:87]
	v_mfma_f32_16x16x32_bf16 v[80:83], v[136:139], v[152:155], v[80:83]
	v_mfma_f32_16x16x32_bf16 v[76:79], v[128:131], v[198:201], v[76:79]
	v_mfma_f32_16x16x32_bf16 v[72:75], v[136:139], v[198:201], v[72:75]
	v_mfma_f32_16x16x32_bf16 v[68:71], v[128:131], v[206:209], v[68:71]
	v_mfma_f32_16x16x32_bf16 v[64:67], v[136:139], v[206:209], v[64:67]
	v_mfma_f32_16x16x32_bf16 v[92:95], v[132:135], v[148:151], v[92:95]
	v_mfma_f32_16x16x32_bf16 v[88:91], v[140:143], v[148:151], v[88:91]
	v_mfma_f32_16x16x32_bf16 v[84:87], v[132:135], v[194:197], v[84:87]
	v_mfma_f32_16x16x32_bf16 v[80:83], v[140:143], v[194:197], v[80:83]
	v_mfma_f32_16x16x32_bf16 v[76:79], v[132:135], v[202:205], v[76:79]
	v_mfma_f32_16x16x32_bf16 v[72:75], v[140:143], v[202:205], v[72:75]
	v_mfma_f32_16x16x32_bf16 v[68:71], v[132:135], v[210:213], v[68:71]
	v_mfma_f32_16x16x32_bf16 v[64:67], v[140:143], v[210:213], v[64:67]
	s_barrier
	s_add_u32 s20, s24, 0x90000
	s_addc_u32 s21, s25, 0
	s_add_i32 s43, s44, s31
	s_mov_b32 m0, s43
	s_nop 0
	global_load_lds_dwordx4 v188, s[20:21]
	s_add_i32 m0, s43, 0x2000
	s_nop 0
	global_load_lds_dwordx4 v186, s[20:21]
	s_waitcnt vmcnt(6)
	s_barrier
; #define PG8_STAGE(bufoff, gbase) do { _Pragma("unroll") for (int _i = 0; _i < 2; ++_i) \
;         __builtin_amdgcn_global_load_lds((const unsigned*)((const char*)(gbase) + voff[_i]), (LAS unsigned*)(lds + (bufoff) + ldsw + _i * 8192), 16, 0, 0); } while (0)
; #define PG8_LDA(dst, b, h) do { _Pragma("unroll") for (int m = 0; m < 4; ++m) _Pragma("unroll") for (int k = 0; k < 2; ++k) dst[m][k] = *(const LAS bf16x8*)(lds + PG8_SA(b, h) + aoff + m * 2048 + k * 1024); } while (0)
; #define PG8_LDB(dst, b, h) do { _Pragma("unroll") for (int n = 0; n < 2; ++n) _Pragma("unroll") for (int k = 0; k < 2; ++k) dst[n][k] = *(const LAS bf16x8*)(lds + PG8_SB(b, h) + boff + n * 2048 + k * 1024); } while (0)
; #define PG8_MMA(ai, bj, At, Bt) do { __builtin_amdgcn_s_setprio(1); _Pragma("unroll") for (int m = 0; m < 4; ++m) _Pragma("unroll") for (int n = 0; n < 2; ++n) _Pragma("unroll") for (int k = 0; k < 2; ++k) \
;         acc[ai][bj][m][n] = __builtin_amdgcn_mfma_f32_16x16x32_bf16(Bt[n][k], At[m][k], acc[ai][bj][m][n], 0, 0, 0); __builtin_amdgcn_s_setprio(0); } while (0)
; #define PG8_WAIT_V(n) asm volatile("s_waitcnt vmcnt(" #n ")" ::: "memory")
; #define PG8_WAIT_L(n) asm volatile("s_waitcnt lgkmcnt(" #n ")" ::: "memory")
; #define PG8_BAR __builtin_amdgcn_s_barrier()
; #define PG8_SCHED __builtin_amdgcn_sched_barrier(0)
; template <class Epi>
; DI void gemm_phase(LAS unsigned char* lds, const Gemm g, const StaticOrder& S, const Epi& E) {
;     ...
;             PG8_WAIT_V(6); PG8_BAR; PG8_MMA(1, 1, At, B1); PG8_BAR;
;             PG8_LDB(B0, 1, 0); PG8_SCHED; PG8_LDA(At, 1, 0); PG8_STAGE(PG8_SA(0, 1), a2 + hstep);
;             PG8_WAIT_L(8); PG8_BAR; PG8_WAIT_L(0); PG8_MMA(0, 0, At, B0); PG8_BAR; PG8_SCHED;
;             PG8_LDB(B1, 1, 1); PG8_STAGE(PG8_SB(1, 0), b3);
;             PG8_BAR; PG8_WAIT_L(0); PG8_MMA(0, 1, At, B1); PG8_BAR;
;             PG8_LDA(At, 1, 1); PG8_STAGE(PG8_SA(1, 0), a3);
	v_mfma_f32_16x16x32_bf16 v[28:31], v[214:217], v[144:147], v[28:31]
	v_mfma_f32_16x16x32_bf16 v[24:27], v[234:237], v[144:147], v[24:27]
	v_mfma_f32_16x16x32_bf16 v[20:23], v[214:217], v[152:155], v[20:23]
	v_mfma_f32_16x16x32_bf16 v[16:19], v[234:237], v[152:155], v[16:19]
	v_mfma_f32_16x16x32_bf16 v[12:15], v[214:217], v[198:201], v[12:15]
	v_mfma_f32_16x16x32_bf16 v[8:11], v[234:237], v[198:201], v[8:11]
	v_mfma_f32_16x16x32_bf16 v[4:7], v[214:217], v[206:209], v[4:7]
	v_mfma_f32_16x16x32_bf16 v[0:3], v[234:237], v[206:209], v[0:3]
	v_mfma_f32_16x16x32_bf16 v[28:31], v[230:233], v[148:151], v[28:31]
	s_add_i32 s43, 0, 0x18000
	v_mfma_f32_16x16x32_bf16 v[24:27], v[238:241], v[148:151], v[24:27]
	v_mfma_f32_16x16x32_bf16 v[20:23], v[230:233], v[194:197], v[20:23]
	v_mfma_f32_16x16x32_bf16 v[16:19], v[238:241], v[194:197], v[16:19]
	v_mfma_f32_16x16x32_bf16 v[12:15], v[230:233], v[202:205], v[12:15]
	v_mfma_f32_16x16x32_bf16 v[8:11], v[238:241], v[202:205], v[8:11]
	v_mfma_f32_16x16x32_bf16 v[4:7], v[230:233], v[210:213], v[4:7]
	v_mfma_f32_16x16x32_bf16 v[0:3], v[238:241], v[210:213], v[0:3]
	s_barrier
	ds_read_b128 v[128:131], v226 offset:32768
	ds_read_b128 v[132:135], v226 offset:33792
	ds_read_b128 v[136:139], v226 offset:34816
	ds_read_b128 v[140:143], v226 offset:35840
	ds_read_b128 v[144:147], v228 offset:32768
	ds_read_b128 v[148:151], v228 offset:33792
	ds_read_b128 v[152:155], v228 offset:34816
	ds_read_b128 v[194:197], v228 offset:35840
	ds_read_b128 v[198:201], v228 offset:36864
	ds_read_b128 v[202:205], v228 offset:37888
	ds_read_b128 v[206:209], v228 offset:38912
	ds_read_b128 v[210:213], v228 offset:39936
	s_add_u32 s20, s26, 0x90000
	s_addc_u32 s21, s27, 0
	s_mov_b32 m0, s36
	s_nop 0
	global_load_lds_dwordx4 v188, s[20:21]
	s_mov_b32 m0, s37
	s_nop 0
	global_load_lds_dwordx4 v186, s[20:21]
	s_waitcnt lgkmcnt(8)
	s_barrier
	s_waitcnt lgkmcnt(0)
	v_mfma_f32_16x16x32_bf16 v[124:127], v[128:131], v[144:147], v[124:127]
	v_mfma_f32_16x16x32_bf16 v[120:123], v[136:139], v[144:147], v[120:123]
	v_mfma_f32_16x16x32_bf16 v[116:119], v[128:131], v[152:155], v[116:119]
	v_mfma_f32_16x16x32_bf16 v[112:115], v[136:139], v[152:155], v[112:115]
	v_mfma_f32_16x16x32_bf16 v[108:111], v[128:131], v[198:201], v[108:111]
	v_mfma_f32_16x16x32_bf16 v[104:107], v[136:139], v[198:201], v[104:107]
	v_mfma_f32_16x16x32_bf16 v[100:103], v[128:131], v[206:209], v[100:103]
	v_mfma_f32_16x16x32_bf16 v[96:99], v[136:139], v[206:209], v[96:99]
	v_mfma_f32_16x16x32_bf16 v[124:127], v[132:135], v[148:151], v[124:127]
	v_mfma_f32_16x16x32_bf16 v[120:123], v[140:143], v[148:151], v[120:123]
	v_mfma_f32_16x16x32_bf16 v[116:119], v[132:135], v[194:197], v[116:119]
	v_mfma_f32_16x16x32_bf16 v[112:115], v[140:143], v[194:197], v[112:115]
	v_mfma_f32_16x16x32_bf16 v[108:111], v[132:135], v[202:205], v[108:111]
	v_mfma_f32_16x16x32_bf16 v[104:107], v[140:143], v[202:205], v[104:107]
	v_mfma_f32_16x16x32_bf16 v[100:103], v[132:135], v[210:213], v[100:103]
	v_mfma_f32_16x16x32_bf16 v[96:99], v[140:143], v[210:213], v[96:99]
	s_barrier
	ds_read_b128 v[214:217], v226 offset:49152
	ds_read_b128 v[230:233], v226 offset:50176
	ds_read_b128 v[234:237], v226 offset:51200
	ds_read_b128 v[238:241], v226 offset:52224
	s_add_i32 s26, 0, 0x1c000
	s_add_i32 s20, s43, s31
	s_add_i32 m0, s20, 0xffffff80
	s_nop 0
	global_load_lds_dwordx4 v188, s[24:25] offset:128
	s_add_i32 m0, s20, 0x1f80
	s_nop 0
	global_load_lds_dwordx4 v186, s[24:25] offset:128
	s_waitcnt lgkmcnt(0)
	s_barrier
	v_mfma_f32_16x16x32_bf16 v[60:63], v[214:217], v[144:147], v[60:63]
	v_mfma_f32_16x16x32_bf16 v[56:59], v[234:237], v[144:147], v[56:59]
	v_mfma_f32_16x16x32_bf16 v[52:55], v[214:217], v[152:155], v[52:55]
	v_mfma_f32_16x16x32_bf16 v[48:51], v[234:237], v[152:155], v[48:51]
	v_mfma_f32_16x16x32_bf16 v[44:47], v[214:217], v[198:201], v[44:47]
	v_mfma_f32_16x16x32_bf16 v[40:43], v[234:237], v[198:201], v[40:43]
	v_mfma_f32_16x16x32_bf16 v[36:39], v[214:217], v[206:209], v[36:39]
	v_mfma_f32_16x16x32_bf16 v[32:35], v[234:237], v[206:209], v[32:35]
	v_mfma_f32_16x16x32_bf16 v[60:63], v[230:233], v[148:151], v[60:63]
	s_add_i32 m0, s38, 0xffffff80
	v_mfma_f32_16x16x32_bf16 v[56:59], v[238:241], v[148:151], v[56:59]
	v_mfma_f32_16x16x32_bf16 v[52:55], v[230:233], v[194:197], v[52:55]
	v_mfma_f32_16x16x32_bf16 v[48:51], v[238:241], v[194:197], v[48:51]
	v_mfma_f32_16x16x32_bf16 v[44:47], v[230:233], v[202:205], v[44:47]
	v_mfma_f32_16x16x32_bf16 v[40:43], v[238:241], v[202:205], v[40:43]
	v_mfma_f32_16x16x32_bf16 v[36:39], v[230:233], v[210:213], v[36:39]
	v_mfma_f32_16x16x32_bf16 v[32:35], v[238:241], v[210:213], v[32:35]
	s_barrier
	ds_read_b128 v[144:147], v228 offset:49152
	ds_read_b128 v[148:151], v228 offset:50176
	ds_read_b128 v[152:155], v228 offset:51200
	ds_read_b128 v[194:197], v228 offset:52224
	ds_read_b128 v[198:201], v228 offset:53248
	ds_read_b128 v[202:205], v228 offset:54272
	ds_read_b128 v[206:209], v228 offset:55296
	ds_read_b128 v[210:213], v228 offset:56320
	global_load_lds_dwordx4 v188, s[100:101] offset:128
	s_add_i32 m0, s39, 0xffffff80
	s_nop 0
	global_load_lds_dwordx4 v186, s[100:101] offset:128
	s_waitcnt lgkmcnt(0)
	s_barrier
; #define PG8_WAIT_V(n) asm volatile("s_waitcnt vmcnt(" #n ")" ::: "memory")
; #define PG8_BAR __builtin_amdgcn_s_barrier()
; template <class Epi>
; DI void gemm_phase(LAS unsigned char* lds, const Gemm g, const StaticOrder& S, const Epi& E) {
;     ...
;             PG8_BAR; PG8_WAIT_L(0); PG8_MMA(1, 0, At, B0); PG8_BAR; PG8_SCHED;
;             PG8_STAGE(PG8_SB(1, 1), b3 + hstep);
;             PG8_WAIT_V(6); PG8_BAR; PG8_MMA(1, 1, At, B1); PG8_BAR;
;         }
;     template <bool LN, int BJ, int LO, int HI> DI void batch(const f32x4 (&acc)[2][2][4][2], unsigned row0, unsigned col0, const f32x4 (&gv)[2], const f32x4 (&bv)[2]) const {
;         f32x4 r[HI - LO]; float mean[(HI - LO) / 2], rstd[(HI - LO) / 2];
; #pragma unroll
;         for (int i = LO; i < HI; ++i) { const int ai = i >> 3, m = (i >> 1) & 3, n = i & 1; const unsigned row = row0 + ai * HALF + m * 16;
;             if (n == 0) { mean[(i - LO) >> 1] = 0.f; rstd[(i - LO) >> 1] = 1.f;
;                 if (LN) { const float2 st = *(const float2*)(stats + row * 2u); mean[(i - LO) >> 1] = st.x; rstd[(i - LO) >> 1] = st.y; } }
;             r[i - LO] = *(const f32x4*)(src + (row * (unsigned)DM + col0 + BJ * HALF + n * 16)); }
; #pragma unroll
;         for (int i = LO; i < HI; ++i) { const int ai = i >> 3, m = (i >> 1) & 3, n = i & 1; const unsigned row = row0 + ai * HALF + m * 16;
;             *(f32x4*)(Y + (row * (unsigned)DM + col0 + BJ * HALF + n * 16)) = acc[ai][BJ][m][n] + ((r[i - LO] - mean[(i - LO) >> 1]) * rstd[(i - LO) >> 1]) * gv[n] + bv[n]; }
;         __builtin_amdgcn_sched_barrier(0);
;     }
;     template <bool LN, int BJ> DI void load_gb(unsigned col0, f32x4 (&gv)[2], f32x4 (&bv)[2]) const {
; #pragma unroll
;         for (int n = 0; n < 2; ++n) {
;             if (LN) { gv[n] = *(const f32x4*)(gam + col0 + BJ * HALF + n * 16) * ALPHA; bv[n] = *(const f32x4*)(bet + col0 + BJ * HALF + n * 16) * ALPHA; }
;             else { gv[n] = (f32x4){ALPHA, ALPHA, ALPHA, ALPHA}; bv[n] = (f32x4){0.f, 0.f, 0.f, 0.f}; }
;         }
;     }
;     template <bool LN> DI void run(const f32x4 (&acc)[2][2][4][2], const Unit& u, int wr, int wc, int fr, int fq) const {
;         const unsigned row0 = u.pm * BM + wr * 64 + fr, col0 = u.pn * BM + wc * 32 + 4 * fq;
;         f32x4 gv[2], bv[2];
;         load_gb<LN, 0>(col0, gv, bv);
;         batch<LN, 0, 0, 4>(acc, row0, col0, gv, bv);
	v_mfma_f32_16x16x32_bf16 v[92:95], v[128:131], v[144:147], v[92:95]
	v_mfma_f32_16x16x32_bf16 v[88:91], v[136:139], v[144:147], v[88:91]
	v_mfma_f32_16x16x32_bf16 v[84:87], v[128:131], v[152:155], v[84:87]
	v_mfma_f32_16x16x32_bf16 v[80:83], v[136:139], v[152:155], v[80:83]
	v_mfma_f32_16x16x32_bf16 v[76:79], v[128:131], v[198:201], v[76:79]
	v_mfma_f32_16x16x32_bf16 v[72:75], v[136:139], v[198:201], v[72:75]
	v_mfma_f32_16x16x32_bf16 v[68:71], v[128:131], v[206:209], v[68:71]
	v_mfma_f32_16x16x32_bf16 v[64:67], v[136:139], v[206:209], v[64:67]
	v_mfma_f32_16x16x32_bf16 v[92:95], v[132:135], v[148:151], v[92:95]
	v_mfma_f32_16x16x32_bf16 v[88:91], v[140:143], v[148:151], v[88:91]
	v_mfma_f32_16x16x32_bf16 v[84:87], v[132:135], v[194:197], v[84:87]
	v_mfma_f32_16x16x32_bf16 v[80:83], v[140:143], v[194:197], v[80:83]
	v_mfma_f32_16x16x32_bf16 v[76:79], v[132:135], v[202:205], v[76:79]
	v_mfma_f32_16x16x32_bf16 v[72:75], v[140:143], v[202:205], v[72:75]
	v_mfma_f32_16x16x32_bf16 v[68:71], v[132:135], v[210:213], v[68:71]
	v_mfma_f32_16x16x32_bf16 v[64:67], v[140:143], v[210:213], v[64:67]
	s_barrier
	s_add_u32 s20, s24, 0x90080
	s_addc_u32 s21, s25, 0
	s_add_i32 s24, s26, s31
	s_mov_b32 m0, s24
	s_nop 0
	global_load_lds_dwordx4 v188, s[20:21]
	s_add_i32 m0, s24, 0x2000
	s_nop 0
	global_load_lds_dwordx4 v186, s[20:21]
	s_waitcnt vmcnt(6)
	s_barrier
	v_mfma_f32_16x16x32_bf16 v[28:31], v[214:217], v[144:147], v[28:31]
	v_mfma_f32_16x16x32_bf16 v[24:27], v[234:237], v[144:147], v[24:27]
	v_mfma_f32_16x16x32_bf16 v[20:23], v[214:217], v[152:155], v[20:23]
	v_mfma_f32_16x16x32_bf16 v[16:19], v[234:237], v[152:155], v[16:19]
	v_mfma_f32_16x16x32_bf16 v[12:15], v[214:217], v[198:201], v[12:15]
	v_mfma_f32_16x16x32_bf16 v[8:11], v[234:237], v[198:201], v[8:11]
	v_mfma_f32_16x16x32_bf16 v[4:7], v[214:217], v[206:209], v[4:7]
	v_mfma_f32_16x16x32_bf16 v[0:3], v[234:237], v[206:209], v[0:3]
	v_mfma_f32_16x16x32_bf16 v[28:31], v[230:233], v[148:151], v[28:31]
	s_add_i32 s33, s33, 2
	v_mfma_f32_16x16x32_bf16 v[24:27], v[238:241], v[148:151], v[24:27]
	s_add_u32 s4, s4, 0x100
	v_mfma_f32_16x16x32_bf16 v[20:23], v[230:233], v[194:197], v[20:23]
	s_addc_u32 s5, s5, 0
	v_mfma_f32_16x16x32_bf16 v[16:19], v[238:241], v[194:197], v[16:19]
	s_cmp_gt_u32 s33, 33
	v_mfma_f32_16x16x32_bf16 v[12:15], v[230:233], v[202:205], v[12:15]
	s_mov_b64 s[20:21], s[22:23]
	v_mfma_f32_16x16x32_bf16 v[8:11], v[238:241], v[202:205], v[8:11]
	v_mfma_f32_16x16x32_bf16 v[4:7], v[230:233], v[210:213], v[4:7]
	v_mfma_f32_16x16x32_bf16 v[0:3], v[238:241], v[210:213], v[0:3]
	s_barrier
	s_cbranch_scc0 .LBB0_77
	v_lshl_add_u32 v206, s3, 8, v225
	v_lshl_or_b32 v158, s2, 8, v227
	v_lshlrev_b32_e32 v232, 11, v206
	s_andn2_b64 vcc, exec, s[14:15]
	v_or_b32_e32 v231, 16, v158
	v_add_u32_e32 v194, v232, v158
	v_or_b32_e32 v230, 0x80, v158
	v_or_b32_e32 v229, 0x90, v158
	s_cbranch_vccnz .LBB0_80
	v_lshlrev_b64 v[132:133], 2, v[158:159]
	v_lshl_add_u64 v[140:141], s[16:17], 0, v[132:133]
	global_load_dwordx4 v[128:131], v[140:141], off
	v_lshl_add_u64 v[142:143], s[18:19], 0, v[132:133]
	v_readlane_b32 s2, v253, 8
	v_mov_b32_e32 v195, v159
	v_lshlrev_b32_e32 v136, 1, v206
	v_mov_b32_e32 v137, v159
	v_readlane_b32 s3, v253, 9
	v_lshlrev_b64 v[212:213], 2, v[194:195]
	v_add_u32_e32 v146, v232, v231
	v_lshl_add_u64 v[144:145], v[136:137], 2, s[2:3]
	v_lshl_add_u64 v[136:137], s[88:89], 0, v[212:213]
	v_mov_b32_e32 v147, v159
	v_lshl_add_u64 v[146:147], v[146:147], 2, s[88:89]
	v_or_b32_e32 v195, 16, v206
	v_mov_b32_e32 v201, v159
	v_mov_b32_e32 v209, v159
	v_lshl_add_u64 v[212:213], s[90:91], 0, v[212:213]
	s_waitcnt vmcnt(0)
	v_pk_mul_f32 v[152:153], v[130:131], s[78:79] op_sel_hi:[1,0]
	v_pk_mul_f32 v[154:155], v[128:129], s[78:79] op_sel_hi:[1,0]
	global_load_dwordx4 v[132:135], v[142:143], off
	global_load_dwordx4 v[128:131], v[140:141], off offset:64
	global_load_dwordx2 v[204:205], v[144:145], off
	global_load_dwordx4 v[196:199], v[146:147], off
	v_lshlrev_b32_e32 v146, 1, v195
	global_load_dwordx4 v[136:139], v[136:137], off
	v_lshlrev_b32_e32 v195, 11, v195
	v_mov_b32_e32 v147, v159
	v_add_u32_e32 v200, v195, v158
	v_lshl_add_u64 v[146:147], v[146:147], 2, s[2:3]
	v_lshl_add_u64 v[200:201], v[200:201], 2, s[88:89]
	global_load_dwordx2 v[214:215], v[146:147], off
	v_add_u32_e32 v208, v195, v231
	global_load_dwordx4 v[200:203], v[200:201], off
	v_lshl_add_u64 v[208:209], v[208:209], 2, s[88:89]
	global_load_dwordx4 v[208:211], v[208:209], off
	s_waitcnt vmcnt(0)
	v_pk_mul_f32 v[148:149], v[130:131], s[78:79] op_sel_hi:[1,0]
	v_pk_mul_f32 v[150:151], v[128:129], s[78:79] op_sel_hi:[1,0]
	global_load_dwordx4 v[128:131], v[142:143], off offset:64
	v_sub_f32_e32 v137, v137, v204
	v_sub_f32_e32 v136, v136, v204
	v_sub_f32_e32 v139, v139, v204
	v_sub_f32_e32 v138, v138, v204
	v_pk_mul_f32 v[138:139], v[204:205], v[138:139] op_sel:[1,0]
	v_pk_mul_f32 v[136:137], v[204:205], v[136:137] op_sel:[1,0]
	v_pk_fma_f32 v[138:139], v[152:153], v[138:139], v[126:127]
	v_pk_fma_f32 v[136:137], v[154:155], v[136:137], v[124:125]
	v_pk_fma_f32 v[138:139], v[134:135], s[78:79], v[138:139] op_sel_hi:[1,0,1]
	v_pk_fma_f32 v[136:137], v[132:133], s[78:79], v[136:137] op_sel_hi:[1,0,1]
	global_store_dwordx4 v[212:213], v[136:139], off
	s_nop 1
	v_sub_f32_e32 v137, v197, v204
	v_sub_f32_e32 v136, v196, v204
	v_sub_f32_e32 v139, v199, v204
	v_sub_f32_e32 v138, v198, v204
	v_pk_mul_f32 v[138:139], v[204:205], v[138:139] op_sel:[1,0]
	v_pk_mul_f32 v[136:137], v[204:205], v[136:137] op_sel:[1,0]
	v_pk_fma_f32 v[138:139], v[148:149], v[138:139], v[122:123]
	v_pk_fma_f32 v[136:137], v[150:151], v[136:137], v[120:121]
	v_or_b32_e32 v196, 16, v194
	v_mov_b32_e32 v197, v159
	v_lshl_add_u64 v[196:197], v[196:197], 2, s[90:91]
	s_waitcnt vmcnt(0)
;     template <bool LN, int BJ, int LO, int HI> DI void batch(const f32x4 (&acc)[2][2][4][2], unsigned row0, unsigned col0, const f32x4 (&gv)[2], const f32x4 (&bv)[2]) const {
;         f32x4 r[HI - LO]; float mean[(HI - LO) / 2], rstd[(HI - LO) / 2];
; #pragma unroll
;         for (int i = LO; i < HI; ++i) { const int ai = i >> 3, m = (i >> 1) & 3, n = i & 1; const unsigned row = row0 + ai * HALF + m * 16;
;             if (n == 0) { mean[(i - LO) >> 1] = 0.f; rstd[(i - LO) >> 1] = 1.f;
;                 if (LN) { const float2 st = *(const float2*)(stats + row * 2u); mean[(i - LO) >> 1] = st.x; rstd[(i - LO) >> 1] = st.y; } }
;             r[i - LO] = *(const f32x4*)(src + (row * (unsigned)DM + col0 + BJ * HALF + n * 16)); }
; #pragma unroll
;         for (int i = LO; i < HI; ++i) { const int ai = i >> 3, m = (i >> 1) & 3, n = i & 1; const unsigned row = row0 + ai * HALF + m * 16;
;             *(f32x4*)(Y + (row * (unsigned)DM + col0 + BJ * HALF + n * 16)) = acc[ai][BJ][m][n] + ((r[i - LO] - mean[(i - LO) >> 1]) * rstd[(i - LO) >> 1]) * gv[n] + bv[n]; }
;         __builtin_amdgcn_sched_barrier(0);
;     }
;     template <bool LN, int BJ> DI void load_gb(unsigned col0, f32x4 (&gv)[2], f32x4 (&bv)[2]) const {
; #pragma unroll
;         for (int n = 0; n < 2; ++n) {
;             if (LN) { gv[n] = *(const f32x4*)(gam + col0 + BJ * HALF + n * 16) * ALPHA; bv[n] = *(const f32x4*)(bet + col0 + BJ * HALF + n * 16) * ALPHA; }
;             else { gv[n] = (f32x4){ALPHA, ALPHA, ALPHA, ALPHA}; bv[n] = (f32x4){0.f, 0.f, 0.f, 0.f}; }
;         }
;     }
;     template <bool LN> DI void run(const f32x4 (&acc)[2][2][4][2], const Unit& u, int wr, int wc, int fr, int fq) const {
;         const unsigned row0 = u.pm * BM + wr * 64 + fr, col0 = u.pn * BM + wc * 32 + 4 * fq;
;         f32x4 gv[2], bv[2];
;         load_gb<LN, 0>(col0, gv, bv);
;         batch<LN, 0, 0, 4>(acc, row0, col0, gv, bv);
;         batch<LN, 0, 4, 8>(acc, row0, col0, gv, bv);
;         batch<LN, 0, 8, 12>(acc, row0, col0, gv, bv);
;         batch<LN, 0, 12, 16>(acc, row0, col0, gv, bv);
	v_pk_fma_f32 v[138:139], v[130:131], s[78:79], v[138:139] op_sel_hi:[1,0,1]
	v_pk_fma_f32 v[136:137], v[128:129], s[78:79], v[136:137] op_sel_hi:[1,0,1]
	global_store_dwordx4 v[196:197], v[136:139], off
	v_add_u32_e32 v196, 0x8000, v194
	v_mov_b32_e32 v197, v159
	v_sub_f32_e32 v137, v201, v214
	v_sub_f32_e32 v136, v200, v214
	v_sub_f32_e32 v139, v203, v214
	v_sub_f32_e32 v138, v202, v214
	v_pk_mul_f32 v[138:139], v[214:215], v[138:139] op_sel:[1,0]
	v_pk_mul_f32 v[136:137], v[214:215], v[136:137] op_sel:[1,0]
	v_pk_fma_f32 v[138:139], v[152:153], v[138:139], v[118:119]
	v_pk_fma_f32 v[136:137], v[154:155], v[136:137], v[116:117]
	v_pk_fma_f32 v[138:139], v[134:135], s[78:79], v[138:139] op_sel_hi:[1,0,1]
	v_pk_fma_f32 v[136:137], v[132:133], s[78:79], v[136:137] op_sel_hi:[1,0,1]
	v_lshl_add_u64 v[196:197], v[196:197], 2, s[90:91]
	global_store_dwordx4 v[196:197], v[136:139], off
	v_add_u32_e32 v196, 0x8010, v194
	v_mov_b32_e32 v197, v159
	v_sub_f32_e32 v137, v209, v214
	v_sub_f32_e32 v136, v208, v214
	v_sub_f32_e32 v139, v211, v214
	v_sub_f32_e32 v138, v210, v214
	v_pk_mul_f32 v[138:139], v[214:215], v[138:139] op_sel:[1,0]
	v_pk_mul_f32 v[136:137], v[214:215], v[136:137] op_sel:[1,0]
	v_pk_fma_f32 v[138:139], v[148:149], v[138:139], v[114:115]
	v_pk_fma_f32 v[136:137], v[150:151], v[136:137], v[112:113]
	v_pk_fma_f32 v[138:139], v[130:131], s[78:79], v[138:139] op_sel_hi:[1,0,1]
	v_pk_fma_f32 v[136:137], v[128:129], s[78:79], v[136:137] op_sel_hi:[1,0,1]
	v_lshl_add_u64 v[196:197], v[196:197], 2, s[90:91]
	global_store_dwordx4 v[196:197], v[136:139], off
	s_nop 1
	v_or_b32_e32 v138, 32, v206
	v_lshlrev_b32_e32 v136, 1, v138
	v_mov_b32_e32 v137, v159
	v_lshlrev_b32_e32 v236, 11, v138
	v_lshl_add_u64 v[200:201], v[136:137], 2, s[2:3]
	v_add_u32_e32 v136, v236, v158
	v_lshl_add_u64 v[136:137], v[136:137], 2, s[88:89]
	global_load_dwordx2 v[204:205], v[200:201], off
	v_add_u32_e32 v196, v236, v231
	global_load_dwordx4 v[136:139], v[136:137], off
	v_mov_b32_e32 v197, v159
	v_lshl_add_u64 v[196:197], v[196:197], 2, s[88:89]
	global_load_dwordx4 v[196:199], v[196:197], off
	v_or_b32_e32 v207, 48, v206
	v_lshlrev_b32_e32 v235, 11, v207
	v_lshlrev_b32_e32 v202, 1, v207
	v_mov_b32_e32 v203, v159
	v_add_u32_e32 v208, v235, v158
	v_mov_b32_e32 v209, v159
	v_lshl_add_u64 v[202:203], v[202:203], 2, s[2:3]
	v_lshl_add_u64 v[208:209], v[208:209], 2, s[88:89]
	global_load_dwordx2 v[216:217], v[202:203], off
	v_add_u32_e32 v212, v235, v231
	global_load_dwordx4 v[208:211], v[208:209], off
	v_mov_b32_e32 v213, v159
	v_lshl_add_u64 v[212:213], v[212:213], 2, s[88:89]
	global_load_dwordx4 v[212:215], v[212:213], off
	v_add_u32_e32 v218, 0x10000, v194
	v_mov_b32_e32 v219, v159
	v_lshl_add_u64 v[218:219], v[218:219], 2, s[90:91]
	s_waitcnt vmcnt(0)
	v_sub_f32_e32 v137, v137, v204
	v_sub_f32_e32 v136, v136, v204
	v_sub_f32_e32 v139, v139, v204
	v_sub_f32_e32 v138, v138, v204
	v_pk_mul_f32 v[138:139], v[204:205], v[138:139] op_sel:[1,0]
	v_pk_mul_f32 v[136:137], v[204:205], v[136:137] op_sel:[1,0]
	v_pk_fma_f32 v[138:139], v[152:153], v[138:139], v[110:111]
	v_pk_fma_f32 v[136:137], v[154:155], v[136:137], v[108:109]
	v_pk_fma_f32 v[138:139], v[134:135], s[78:79], v[138:139] op_sel_hi:[1,0,1]
	v_pk_fma_f32 v[136:137], v[132:133], s[78:79], v[136:137] op_sel_hi:[1,0,1]
	global_store_dwordx4 v[218:219], v[136:139], off
	s_nop 1
	v_sub_f32_e32 v137, v197, v204
	v_sub_f32_e32 v136, v196, v204
	v_sub_f32_e32 v139, v199, v204
	v_sub_f32_e32 v138, v198, v204
	v_pk_mul_f32 v[138:139], v[204:205], v[138:139] op_sel:[1,0]
	v_pk_mul_f32 v[136:137], v[204:205], v[136:137] op_sel:[1,0]
	v_pk_fma_f32 v[138:139], v[148:149], v[138:139], v[106:107]
	v_pk_fma_f32 v[136:137], v[150:151], v[136:137], v[104:105]
	v_add_u32_e32 v196, 0x10010, v194
	v_mov_b32_e32 v197, v159
	v_pk_fma_f32 v[138:139], v[130:131], s[78:79], v[138:139] op_sel_hi:[1,0,1]
	v_pk_fma_f32 v[136:137], v[128:129], s[78:79], v[136:137] op_sel_hi:[1,0,1]
	v_lshl_add_u64 v[196:197], v[196:197], 2, s[90:91]
	global_store_dwordx4 v[196:197], v[136:139], off
	v_add_u32_e32 v196, 0x18000, v194
	v_mov_b32_e32 v197, v159
	v_sub_f32_e32 v137, v209, v216
	v_sub_f32_e32 v136, v208, v216
	v_sub_f32_e32 v139, v211, v216
	v_sub_f32_e32 v138, v210, v216
	v_pk_mul_f32 v[138:139], v[216:217], v[138:139] op_sel:[1,0]
	v_pk_mul_f32 v[136:137], v[216:217], v[136:137] op_sel:[1,0]
	v_pk_fma_f32 v[138:139], v[152:153], v[138:139], v[102:103]
	v_pk_fma_f32 v[136:137], v[154:155], v[136:137], v[100:101]
	v_pk_fma_f32 v[138:139], v[134:135], s[78:79], v[138:139] op_sel_hi:[1,0,1]
	v_pk_fma_f32 v[136:137], v[132:133], s[78:79], v[136:137] op_sel_hi:[1,0,1]
	v_lshl_add_u64 v[196:197], v[196:197], 2, s[90:91]
	global_store_dwordx4 v[196:197], v[136:139], off
	v_add_u32_e32 v196, 0x18010, v194
	v_mov_b32_e32 v197, v159
	v_sub_f32_e32 v137, v213, v216
	v_sub_f32_e32 v136, v212, v216
	v_sub_f32_e32 v139, v215, v216
	v_sub_f32_e32 v138, v214, v216
	v_pk_mul_f32 v[138:139], v[216:217], v[138:139] op_sel:[1,0]
	v_pk_mul_f32 v[136:137], v[216:217], v[136:137] op_sel:[1,0]
	v_pk_fma_f32 v[138:139], v[148:149], v[138:139], v[98:99]
	v_pk_fma_f32 v[136:137], v[150:151], v[136:137], v[96:97]
	v_pk_fma_f32 v[138:139], v[130:131], s[78:79], v[138:139] op_sel_hi:[1,0,1]
	v_pk_fma_f32 v[136:137], v[128:129], s[78:79], v[136:137] op_sel_hi:[1,0,1]
	v_lshl_add_u64 v[196:197], v[196:197], 2, s[90:91]
	global_store_dwordx4 v[196:197], v[136:139], off
	s_nop 1
	v_add_u32_e32 v138, 0x80, v206
	v_lshlrev_b32_e32 v136, 1, v138
	v_mov_b32_e32 v137, v159
	v_lshlrev_b32_e32 v233, 11, v138
	v_lshl_add_u64 v[196:197], v[136:137], 2, s[2:3]
	v_add_u32_e32 v136, v233, v158
	v_lshl_add_u64 v[136:137], v[136:137], 2, s[88:89]
	global_load_dwordx2 v[204:205], v[196:197], off
	v_add_u32_e32 v198, v233, v231
	global_load_dwordx4 v[136:139], v[136:137], off
	v_mov_b32_e32 v199, v159
	v_add_u32_e32 v207, 0x90, v206
	v_lshl_add_u64 v[198:199], v[198:199], 2, s[88:89]
	v_lshlrev_b32_e32 v234, 11, v207
	global_load_dwordx4 v[208:211], v[198:199], off
	v_add_u32_e32 v212, v234, v158
	v_mov_b32_e32 v213, v159
	v_lshl_add_u64 v[212:213], v[212:213], 2, s[88:89]
	global_load_dwordx4 v[212:215], v[212:213], off
	v_lshlrev_b32_e32 v198, 1, v207
	v_mov_b32_e32 v199, v159
	v_lshl_add_u64 v[198:199], v[198:199], 2, s[2:3]
	global_load_dwordx2 v[220:221], v[198:199], off
	v_add_u32_e32 v216, v234, v231
	v_mov_b32_e32 v217, v159
	v_lshl_add_u64 v[216:217], v[216:217], 2, s[88:89]
	global_load_dwordx4 v[216:219], v[216:217], off
	v_add_u32_e32 v238, 0x40000, v194
	v_mov_b32_e32 v239, v159
	v_lshl_add_u64 v[238:239], v[238:239], 2, s[90:91]
	s_waitcnt vmcnt(0)
;     template <bool LN, int BJ, int LO, int HI> DI void batch(const f32x4 (&acc)[2][2][4][2], unsigned row0, unsigned col0, const f32x4 (&gv)[2], const f32x4 (&bv)[2]) const {
;         f32x4 r[HI - LO]; float mean[(HI - LO) / 2], rstd[(HI - LO) / 2];
; #pragma unroll
;         for (int i = LO; i < HI; ++i) { const int ai = i >> 3, m = (i >> 1) & 3, n = i & 1; const unsigned row = row0 + ai * HALF + m * 16;
;             if (n == 0) { mean[(i - LO) >> 1] = 0.f; rstd[(i - LO) >> 1] = 1.f;
;                 if (LN) { const float2 st = *(const float2*)(stats + row * 2u); mean[(i - LO) >> 1] = st.x; rstd[(i - LO) >> 1] = st.y; } }
;             r[i - LO] = *(const f32x4*)(src + (row * (unsigned)DM + col0 + BJ * HALF + n * 16)); }
; #pragma unroll
;         for (int i = LO; i < HI; ++i) { const int ai = i >> 3, m = (i >> 1) & 3, n = i & 1; const unsigned row = row0 + ai * HALF + m * 16;
;             *(f32x4*)(Y + (row * (unsigned)DM + col0 + BJ * HALF + n * 16)) = acc[ai][BJ][m][n] + ((r[i - LO] - mean[(i - LO) >> 1]) * rstd[(i - LO) >> 1]) * gv[n] + bv[n]; }
;         __builtin_amdgcn_sched_barrier(0);
;     }
;     template <bool LN, int BJ> DI void load_gb(unsigned col0, f32x4 (&gv)[2], f32x4 (&bv)[2]) const {
; #pragma unroll
;         for (int n = 0; n < 2; ++n) {
;             if (LN) { gv[n] = *(const f32x4*)(gam + col0 + BJ * HALF + n * 16) * ALPHA; bv[n] = *(const f32x4*)(bet + col0 + BJ * HALF + n * 16) * ALPHA; }
;             else { gv[n] = (f32x4){ALPHA, ALPHA, ALPHA, ALPHA}; bv[n] = (f32x4){0.f, 0.f, 0.f, 0.f}; }
;         }
;     }
;     template <bool LN> DI void run(const f32x4 (&acc)[2][2][4][2], const Unit& u, int wr, int wc, int fr, int fq) const {
;         const unsigned row0 = u.pm * BM + wr * 64 + fr, col0 = u.pn * BM + wc * 32 + 4 * fq;
;         f32x4 gv[2], bv[2];
;         load_gb<LN, 0>(col0, gv, bv);
;         batch<LN, 0, 0, 4>(acc, row0, col0, gv, bv);
;         batch<LN, 0, 4, 8>(acc, row0, col0, gv, bv);
;         batch<LN, 0, 8, 12>(acc, row0, col0, gv, bv);
;         batch<LN, 0, 12, 16>(acc, row0, col0, gv, bv);
	v_sub_f32_e32 v137, v137, v204
	v_sub_f32_e32 v136, v136, v204
	v_sub_f32_e32 v139, v139, v204
	v_sub_f32_e32 v138, v138, v204
	v_pk_mul_f32 v[138:139], v[204:205], v[138:139] op_sel:[1,0]
	v_pk_mul_f32 v[136:137], v[204:205], v[136:137] op_sel:[1,0]
	v_pk_fma_f32 v[138:139], v[152:153], v[138:139], v[94:95]
	v_pk_fma_f32 v[136:137], v[154:155], v[136:137], v[92:93]
	v_pk_fma_f32 v[138:139], v[134:135], s[78:79], v[138:139] op_sel_hi:[1,0,1]
	v_pk_fma_f32 v[136:137], v[132:133], s[78:79], v[136:137] op_sel_hi:[1,0,1]
	global_store_dwordx4 v[238:239], v[136:139], off
	s_nop 1
	v_sub_f32_e32 v137, v209, v204
	v_sub_f32_e32 v136, v208, v204
	v_sub_f32_e32 v139, v211, v204
	v_sub_f32_e32 v138, v210, v204
	v_pk_mul_f32 v[138:139], v[204:205], v[138:139] op_sel:[1,0]
	v_pk_mul_f32 v[136:137], v[204:205], v[136:137] op_sel:[1,0]
	v_pk_fma_f32 v[138:139], v[148:149], v[138:139], v[90:91]
	v_pk_fma_f32 v[136:137], v[150:151], v[136:137], v[88:89]
	v_add_u32_e32 v204, 0x40010, v194
	v_mov_b32_e32 v205, v159
	v_pk_fma_f32 v[138:139], v[130:131], s[78:79], v[138:139] op_sel_hi:[1,0,1]
	v_pk_fma_f32 v[136:137], v[128:129], s[78:79], v[136:137] op_sel_hi:[1,0,1]
	v_lshl_add_u64 v[204:205], v[204:205], 2, s[90:91]
	global_store_dwordx4 v[204:205], v[136:139], off
	v_add_u32_e32 v204, 0x48000, v194
	v_mov_b32_e32 v205, v159
	v_sub_f32_e32 v137, v213, v220
	v_sub_f32_e32 v136, v212, v220
	v_sub_f32_e32 v139, v215, v220
	v_sub_f32_e32 v138, v214, v220
	v_pk_mul_f32 v[138:139], v[220:221], v[138:139] op_sel:[1,0]
	v_pk_mul_f32 v[136:137], v[220:221], v[136:137] op_sel:[1,0]
	v_pk_fma_f32 v[138:139], v[152:153], v[138:139], v[86:87]
	v_pk_fma_f32 v[136:137], v[154:155], v[136:137], v[84:85]
	v_pk_fma_f32 v[138:139], v[134:135], s[78:79], v[138:139] op_sel_hi:[1,0,1]
	v_pk_fma_f32 v[136:137], v[132:133], s[78:79], v[136:137] op_sel_hi:[1,0,1]
	v_lshl_add_u64 v[204:205], v[204:205], 2, s[90:91]
	global_store_dwordx4 v[204:205], v[136:139], off
	v_add_u32_e32 v204, 0x48010, v194
	v_mov_b32_e32 v205, v159
	v_sub_f32_e32 v137, v217, v220
	v_sub_f32_e32 v136, v216, v220
	v_sub_f32_e32 v139, v219, v220
	v_sub_f32_e32 v138, v218, v220
	v_pk_mul_f32 v[138:139], v[220:221], v[138:139] op_sel:[1,0]
	v_pk_mul_f32 v[136:137], v[220:221], v[136:137] op_sel:[1,0]
	v_pk_fma_f32 v[138:139], v[148:149], v[138:139], v[82:83]
	v_pk_fma_f32 v[136:137], v[150:151], v[136:137], v[80:81]
	v_pk_fma_f32 v[138:139], v[130:131], s[78:79], v[138:139] op_sel_hi:[1,0,1]
	v_pk_fma_f32 v[136:137], v[128:129], s[78:79], v[136:137] op_sel_hi:[1,0,1]
	v_lshl_add_u64 v[204:205], v[204:205], 2, s[90:91]
	global_store_dwordx4 v[204:205], v[136:139], off
	s_nop 1
	v_add_u32_e32 v138, 0xa0, v206
	v_lshlrev_b32_e32 v136, 1, v138
	v_mov_b32_e32 v137, v159
	v_lshlrev_b32_e32 v237, 11, v138
	v_lshl_add_u64 v[204:205], v[136:137], 2, s[2:3]
	v_add_u32_e32 v136, v237, v158
	v_lshl_add_u64 v[136:137], v[136:137], 2, s[88:89]
	global_load_dwordx2 v[220:221], v[204:205], off
	v_add_u32_e32 v208, v237, v231
	global_load_dwordx4 v[136:139], v[136:137], off
	v_mov_b32_e32 v209, v159
	v_lshl_add_u64 v[208:209], v[208:209], 2, s[88:89]
	global_load_dwordx4 v[212:215], v[208:209], off
	v_add_u32_e32 v208, 0xb0, v206
	v_lshlrev_b32_e32 v206, 1, v208
	v_mov_b32_e32 v207, v159
	v_lshlrev_b32_e32 v238, 11, v208
	v_lshl_add_u64 v[210:211], v[206:207], 2, s[2:3]
	v_add_u32_e32 v206, v238, v158
	v_lshl_add_u64 v[206:207], v[206:207], 2, s[88:89]
	global_load_dwordx2 v[240:241], v[210:211], off
	v_add_u32_e32 v216, v238, v231
	global_load_dwordx4 v[206:209], v[206:207], off
	v_mov_b32_e32 v217, v159
	v_lshl_add_u64 v[216:217], v[216:217], 2, s[88:89]
	global_load_dwordx4 v[216:219], v[216:217], off
	v_add_u32_e32 v242, 0x50000, v194
	v_mov_b32_e32 v243, v159
	v_lshl_add_u64 v[242:243], v[242:243], 2, s[90:91]
	s_waitcnt vmcnt(0)
	v_sub_f32_e32 v137, v137, v220
	v_sub_f32_e32 v136, v136, v220
	v_sub_f32_e32 v139, v139, v220
	v_sub_f32_e32 v138, v138, v220
	v_pk_mul_f32 v[138:139], v[220:221], v[138:139] op_sel:[1,0]
	v_pk_mul_f32 v[136:137], v[220:221], v[136:137] op_sel:[1,0]
	v_pk_fma_f32 v[138:139], v[152:153], v[138:139], v[78:79]
	v_pk_fma_f32 v[136:137], v[154:155], v[136:137], v[76:77]
	v_pk_fma_f32 v[138:139], v[134:135], s[78:79], v[138:139] op_sel_hi:[1,0,1]
	v_pk_fma_f32 v[136:137], v[132:133], s[78:79], v[136:137] op_sel_hi:[1,0,1]
	global_store_dwordx4 v[242:243], v[136:139], off
	s_nop 1
	v_sub_f32_e32 v137, v213, v220
	v_sub_f32_e32 v136, v212, v220
	v_sub_f32_e32 v139, v215, v220
	v_sub_f32_e32 v138, v214, v220
	v_pk_mul_f32 v[138:139], v[220:221], v[138:139] op_sel:[1,0]
	v_pk_mul_f32 v[136:137], v[220:221], v[136:137] op_sel:[1,0]
	v_pk_fma_f32 v[138:139], v[148:149], v[138:139], v[74:75]
	v_pk_fma_f32 v[136:137], v[150:151], v[136:137], v[72:73]
	v_add_u32_e32 v212, 0x50010, v194
	v_mov_b32_e32 v213, v159
	v_pk_fma_f32 v[138:139], v[130:131], s[78:79], v[138:139] op_sel_hi:[1,0,1]
	v_pk_fma_f32 v[136:137], v[128:129], s[78:79], v[136:137] op_sel_hi:[1,0,1]
	v_lshl_add_u64 v[212:213], v[212:213], 2, s[90:91]
	global_store_dwordx4 v[212:213], v[136:139], off
	s_nop 1
	v_sub_f32_e32 v137, v207, v240
	v_sub_f32_e32 v136, v206, v240
	v_sub_f32_e32 v139, v209, v240
	v_sub_f32_e32 v138, v208, v240
	v_pk_mul_f32 v[136:137], v[240:241], v[136:137] op_sel:[1,0]
	v_pk_mul_f32 v[138:139], v[240:241], v[138:139] op_sel:[1,0]
	v_pk_fma_f32 v[136:137], v[154:155], v[136:137], v[68:69]
	v_pk_fma_f32 v[138:139], v[152:153], v[138:139], v[70:71]
	v_pk_fma_f32 v[132:133], v[132:133], s[78:79], v[136:137] op_sel_hi:[1,0,1]
	v_add_u32_e32 v136, 0x58000, v194
	v_mov_b32_e32 v137, v159
	v_pk_fma_f32 v[134:135], v[134:135], s[78:79], v[138:139] op_sel_hi:[1,0,1]
	v_lshl_add_u64 v[136:137], v[136:137], 2, s[90:91]
	global_store_dwordx4 v[136:137], v[132:135], off
	s_nop 1
	v_sub_f32_e32 v133, v217, v240
	v_sub_f32_e32 v132, v216, v240
	v_sub_f32_e32 v135, v219, v240
	v_sub_f32_e32 v134, v218, v240
	v_pk_mul_f32 v[132:133], v[240:241], v[132:133] op_sel:[1,0]
	v_pk_mul_f32 v[134:135], v[240:241], v[134:135] op_sel:[1,0]
	v_pk_fma_f32 v[132:133], v[150:151], v[132:133], v[64:65]
	v_pk_fma_f32 v[134:135], v[148:149], v[134:135], v[66:67]
	v_pk_fma_f32 v[128:129], v[128:129], s[78:79], v[132:133] op_sel_hi:[1,0,1]
	v_add_u32_e32 v132, 0x58010, v194
	v_mov_b32_e32 v133, v159
	v_pk_fma_f32 v[130:131], v[130:131], s[78:79], v[134:135] op_sel_hi:[1,0,1]
	v_lshl_add_u64 v[132:133], v[132:133], 2, s[90:91]
	global_store_dwordx4 v[132:133], v[128:131], off
	global_load_dwordx4 v[128:131], v[140:141], off offset:512
	v_add_u32_e32 v136, v232, v230
	v_mov_b32_e32 v137, v159
	v_lshl_add_u64 v[136:137], v[136:137], 2, s[88:89]
	s_waitcnt vmcnt(0)
;     template <bool LN, int BJ, int LO, int HI> DI void batch(const f32x4 (&acc)[2][2][4][2], unsigned row0, unsigned col0, const f32x4 (&gv)[2], const f32x4 (&bv)[2]) const {
;         f32x4 r[HI - LO]; float mean[(HI - LO) / 2], rstd[(HI - LO) / 2];
; #pragma unroll
;         for (int i = LO; i < HI; ++i) { const int ai = i >> 3, m = (i >> 1) & 3, n = i & 1; const unsigned row = row0 + ai * HALF + m * 16;
;             if (n == 0) { mean[(i - LO) >> 1] = 0.f; rstd[(i - LO) >> 1] = 1.f;
;                 if (LN) { const float2 st = *(const float2*)(stats + row * 2u); mean[(i - LO) >> 1] = st.x; rstd[(i - LO) >> 1] = st.y; } }
;             r[i - LO] = *(const f32x4*)(src + (row * (unsigned)DM + col0 + BJ * HALF + n * 16)); }
; #pragma unroll
;         for (int i = LO; i < HI; ++i) { const int ai = i >> 3, m = (i >> 1) & 3, n = i & 1; const unsigned row = row0 + ai * HALF + m * 16;
;             *(f32x4*)(Y + (row * (unsigned)DM + col0 + BJ * HALF + n * 16)) = acc[ai][BJ][m][n] + ((r[i - LO] - mean[(i - LO) >> 1]) * rstd[(i - LO) >> 1]) * gv[n] + bv[n]; }
;         __builtin_amdgcn_sched_barrier(0);
;     }
;     template <bool LN, int BJ> DI void load_gb(unsigned col0, f32x4 (&gv)[2], f32x4 (&bv)[2]) const {
; #pragma unroll
;         for (int n = 0; n < 2; ++n) {
;             if (LN) { gv[n] = *(const f32x4*)(gam + col0 + BJ * HALF + n * 16) * ALPHA; bv[n] = *(const f32x4*)(bet + col0 + BJ * HALF + n * 16) * ALPHA; }
;             else { gv[n] = (f32x4){ALPHA, ALPHA, ALPHA, ALPHA}; bv[n] = (f32x4){0.f, 0.f, 0.f, 0.f}; }
;         }
;     }
;     template <bool LN> DI void run(const f32x4 (&acc)[2][2][4][2], const Unit& u, int wr, int wc, int fr, int fq) const {
;         const unsigned row0 = u.pm * BM + wr * 64 + fr, col0 = u.pn * BM + wc * 32 + 4 * fq;
;         f32x4 gv[2], bv[2];
;         load_gb<LN, 0>(col0, gv, bv);
;         batch<LN, 0, 0, 4>(acc, row0, col0, gv, bv);
;         batch<LN, 0, 4, 8>(acc, row0, col0, gv, bv);
;         batch<LN, 0, 8, 12>(acc, row0, col0, gv, bv);
;         batch<LN, 0, 12, 16>(acc, row0, col0, gv, bv);
;         load_gb<LN, 1>(col0, gv, bv);
;         batch<LN, 1, 0, 8>(acc, row0, col0, gv, bv);
;         batch<LN, 1, 8, 16>(acc, row0, col0, gv, bv);
	v_pk_mul_f32 v[212:213], v[130:131], s[78:79] op_sel_hi:[1,0]
	v_pk_mul_f32 v[214:215], v[128:129], s[78:79] op_sel_hi:[1,0]
	global_load_dwordx4 v[132:135], v[142:143], off offset:512
	global_load_dwordx4 v[128:131], v[140:141], off offset:576
	s_waitcnt vmcnt(0)
	v_pk_mul_f32 v[206:207], v[130:131], s[78:79] op_sel_hi:[1,0]
	v_pk_mul_f32 v[208:209], v[128:129], s[78:79] op_sel_hi:[1,0]
	global_load_dwordx4 v[128:131], v[142:143], off offset:576
	global_load_dwordx2 v[220:221], v[144:145], off
	global_load_dwordx4 v[240:243], v[136:137], off
	v_add_u32_e32 v136, v232, v229
	v_mov_b32_e32 v137, v159
	v_lshl_add_u64 v[136:137], v[136:137], 2, s[88:89]
	global_load_dwordx4 v[244:247], v[136:137], off
	global_load_dwordx2 v[218:219], v[146:147], off
	v_add_u32_e32 v136, v195, v230
	v_mov_b32_e32 v137, v159
	v_lshl_add_u64 v[136:137], v[136:137], 2, s[88:89]
	global_load_dwordx4 v[248:251], v[136:137], off
	v_add_u32_e32 v136, v195, v229
	v_mov_b32_e32 v137, v159
	v_lshl_add_u64 v[136:137], v[136:137], 2, s[88:89]
	global_load_dwordx4 v[152:155], v[136:137], off
	global_load_dwordx2 v[216:217], v[200:201], off
	v_add_u32_e32 v136, v236, v230
	v_mov_b32_e32 v137, v159
	v_lshl_add_u64 v[136:137], v[136:137], 2, s[88:89]
	global_load_dwordx4 v[148:151], v[136:137], off
	v_add_u32_e32 v136, v236, v229
	v_mov_b32_e32 v137, v159
	v_lshl_add_u64 v[136:137], v[136:137], 2, s[88:89]
	global_load_dwordx4 v[144:147], v[136:137], off
	global_load_dwordx2 v[200:201], v[202:203], off
	v_add_u32_e32 v136, v235, v230
	v_mov_b32_e32 v137, v159
	v_lshl_add_u64 v[136:137], v[136:137], 2, s[88:89]
	global_load_dwordx4 v[140:143], v[136:137], off
	v_add_u32_e32 v136, v235, v229
	v_mov_b32_e32 v137, v159
	v_lshl_add_u64 v[136:137], v[136:137], 2, s[88:89]
	global_load_dwordx4 v[136:139], v[136:137], off
	v_add_u32_e32 v202, 0x80, v194
	v_mov_b32_e32 v203, v159
	v_lshl_add_u64 v[202:203], v[202:203], 2, s[90:91]
	s_waitcnt vmcnt(0)
	v_sub_f32_e32 v241, v241, v220
	v_sub_f32_e32 v240, v240, v220
	v_sub_f32_e32 v243, v243, v220
	v_sub_f32_e32 v242, v242, v220
	v_pk_mul_f32 v[242:243], v[220:221], v[242:243] op_sel:[1,0]
	v_pk_mul_f32 v[240:241], v[220:221], v[240:241] op_sel:[1,0]
	v_pk_fma_f32 v[242:243], v[212:213], v[242:243], v[62:63]
	v_pk_fma_f32 v[240:241], v[214:215], v[240:241], v[60:61]
	v_pk_fma_f32 v[242:243], v[134:135], s[78:79], v[242:243] op_sel_hi:[1,0,1]
	v_pk_fma_f32 v[240:241], v[132:133], s[78:79], v[240:241] op_sel_hi:[1,0,1]
	global_store_dwordx4 v[202:203], v[240:243], off
	v_sub_f32_e32 v203, v245, v220
	v_sub_f32_e32 v202, v244, v220
	v_sub_f32_e32 v241, v247, v220
	v_sub_f32_e32 v240, v246, v220
	v_pk_mul_f32 v[202:203], v[220:221], v[202:203] op_sel:[1,0]
	v_pk_mul_f32 v[240:241], v[220:221], v[240:241] op_sel:[1,0]
	v_pk_fma_f32 v[202:203], v[208:209], v[202:203], v[56:57]
	v_pk_fma_f32 v[220:221], v[206:207], v[240:241], v[58:59]
	v_pk_fma_f32 v[240:241], v[128:129], s[78:79], v[202:203] op_sel_hi:[1,0,1]
	v_add_u32_e32 v202, 0x90, v194
	v_mov_b32_e32 v203, v159
	v_pk_fma_f32 v[242:243], v[130:131], s[78:79], v[220:221] op_sel_hi:[1,0,1]
	v_lshl_add_u64 v[202:203], v[202:203], 2, s[90:91]
	global_store_dwordx4 v[202:203], v[240:243], off
	v_sub_f32_e32 v203, v249, v218
	v_sub_f32_e32 v202, v248, v218
	v_sub_f32_e32 v221, v251, v218
	v_sub_f32_e32 v220, v250, v218
	v_pk_mul_f32 v[202:203], v[218:219], v[202:203] op_sel:[1,0]
	v_pk_mul_f32 v[220:221], v[218:219], v[220:221] op_sel:[1,0]
	v_pk_fma_f32 v[202:203], v[214:215], v[202:203], v[52:53]
	v_pk_fma_f32 v[220:221], v[212:213], v[220:221], v[54:55]
	v_pk_fma_f32 v[240:241], v[132:133], s[78:79], v[202:203] op_sel_hi:[1,0,1]
	v_add_u32_e32 v202, 0x8080, v194
	v_mov_b32_e32 v203, v159
	v_sub_f32_e32 v153, v153, v218
	v_sub_f32_e32 v152, v152, v218
	v_sub_f32_e32 v155, v155, v218
	v_sub_f32_e32 v154, v154, v218
	v_pk_fma_f32 v[242:243], v[134:135], s[78:79], v[220:221] op_sel_hi:[1,0,1]
	v_lshl_add_u64 v[202:203], v[202:203], 2, s[90:91]
	v_pk_mul_f32 v[154:155], v[218:219], v[154:155] op_sel:[1,0]
	v_pk_mul_f32 v[152:153], v[218:219], v[152:153] op_sel:[1,0]
	global_store_dwordx4 v[202:203], v[240:243], off
	v_pk_fma_f32 v[152:153], v[208:209], v[152:153], v[48:49]
	v_pk_fma_f32 v[154:155], v[206:207], v[154:155], v[50:51]
	v_add_u32_e32 v202, 0x8090, v194
	v_mov_b32_e32 v203, v159
	v_sub_f32_e32 v149, v149, v216
	v_sub_f32_e32 v148, v148, v216
	v_sub_f32_e32 v151, v151, v216
	v_sub_f32_e32 v150, v150, v216
	v_pk_fma_f32 v[154:155], v[130:131], s[78:79], v[154:155] op_sel_hi:[1,0,1]
	v_pk_fma_f32 v[152:153], v[128:129], s[78:79], v[152:153] op_sel_hi:[1,0,1]
	v_lshl_add_u64 v[202:203], v[202:203], 2, s[90:91]
	v_pk_mul_f32 v[150:151], v[216:217], v[150:151] op_sel:[1,0]
	v_pk_mul_f32 v[148:149], v[216:217], v[148:149] op_sel:[1,0]
	global_store_dwordx4 v[202:203], v[152:155], off
	v_pk_fma_f32 v[148:149], v[214:215], v[148:149], v[44:45]
	v_pk_fma_f32 v[150:151], v[212:213], v[150:151], v[46:47]
	v_add_u32_e32 v152, 0x10080, v194
	v_mov_b32_e32 v153, v159
	v_sub_f32_e32 v145, v145, v216
	v_sub_f32_e32 v144, v144, v216
	v_sub_f32_e32 v147, v147, v216
	v_sub_f32_e32 v146, v146, v216
	v_pk_fma_f32 v[150:151], v[134:135], s[78:79], v[150:151] op_sel_hi:[1,0,1]
	v_pk_fma_f32 v[148:149], v[132:133], s[78:79], v[148:149] op_sel_hi:[1,0,1]
	v_lshl_add_u64 v[152:153], v[152:153], 2, s[90:91]
	v_pk_mul_f32 v[146:147], v[216:217], v[146:147] op_sel:[1,0]
	v_pk_mul_f32 v[144:145], v[216:217], v[144:145] op_sel:[1,0]
	global_store_dwordx4 v[152:153], v[148:151], off
	v_pk_fma_f32 v[144:145], v[208:209], v[144:145], v[40:41]
	v_pk_fma_f32 v[146:147], v[206:207], v[146:147], v[42:43]
;     template <bool LN, int BJ, int LO, int HI> DI void batch(const f32x4 (&acc)[2][2][4][2], unsigned row0, unsigned col0, const f32x4 (&gv)[2], const f32x4 (&bv)[2]) const {
;         f32x4 r[HI - LO]; float mean[(HI - LO) / 2], rstd[(HI - LO) / 2];
; #pragma unroll
;         for (int i = LO; i < HI; ++i) { const int ai = i >> 3, m = (i >> 1) & 3, n = i & 1; const unsigned row = row0 + ai * HALF + m * 16;
;             if (n == 0) { mean[(i - LO) >> 1] = 0.f; rstd[(i - LO) >> 1] = 1.f;
;                 if (LN) { const float2 st = *(const float2*)(stats + row * 2u); mean[(i - LO) >> 1] = st.x; rstd[(i - LO) >> 1] = st.y; } }
;             r[i - LO] = *(const f32x4*)(src + (row * (unsigned)DM + col0 + BJ * HALF + n * 16)); }
; #pragma unroll
;         for (int i = LO; i < HI; ++i) { const int ai = i >> 3, m = (i >> 1) & 3, n = i & 1; const unsigned row = row0 + ai * HALF + m * 16;
;             *(f32x4*)(Y + (row * (unsigned)DM + col0 + BJ * HALF + n * 16)) = acc[ai][BJ][m][n] + ((r[i - LO] - mean[(i - LO) >> 1]) * rstd[(i - LO) >> 1]) * gv[n] + bv[n]; }
;         __builtin_amdgcn_sched_barrier(0);
;     }
;     template <bool LN, int BJ> DI void load_gb(unsigned col0, f32x4 (&gv)[2], f32x4 (&bv)[2]) const {
; #pragma unroll
;         for (int n = 0; n < 2; ++n) {
;             if (LN) { gv[n] = *(const f32x4*)(gam + col0 + BJ * HALF + n * 16) * ALPHA; bv[n] = *(const f32x4*)(bet + col0 + BJ * HALF + n * 16) * ALPHA; }
;             else { gv[n] = (f32x4){ALPHA, ALPHA, ALPHA, ALPHA}; bv[n] = (f32x4){0.f, 0.f, 0.f, 0.f}; }
;         }
;     }
;     template <bool LN> DI void run(const f32x4 (&acc)[2][2][4][2], const Unit& u, int wr, int wc, int fr, int fq) const {
;         const unsigned row0 = u.pm * BM + wr * 64 + fr, col0 = u.pn * BM + wc * 32 + 4 * fq;
;         f32x4 gv[2], bv[2];
;         load_gb<LN, 0>(col0, gv, bv);
;         batch<LN, 0, 0, 4>(acc, row0, col0, gv, bv);
;         batch<LN, 0, 4, 8>(acc, row0, col0, gv, bv);
;         batch<LN, 0, 8, 12>(acc, row0, col0, gv, bv);
;         batch<LN, 0, 12, 16>(acc, row0, col0, gv, bv);
;         load_gb<LN, 1>(col0, gv, bv);
;         batch<LN, 1, 0, 8>(acc, row0, col0, gv, bv);
;         batch<LN, 1, 8, 16>(acc, row0, col0, gv, bv);
	v_add_u32_e32 v148, 0x10090, v194
	v_mov_b32_e32 v149, v159
	v_sub_f32_e32 v141, v141, v200
	v_sub_f32_e32 v140, v140, v200
	v_sub_f32_e32 v143, v143, v200
	v_sub_f32_e32 v142, v142, v200
	v_pk_fma_f32 v[146:147], v[130:131], s[78:79], v[146:147] op_sel_hi:[1,0,1]
	v_pk_fma_f32 v[144:145], v[128:129], s[78:79], v[144:145] op_sel_hi:[1,0,1]
	v_lshl_add_u64 v[148:149], v[148:149], 2, s[90:91]
	v_pk_mul_f32 v[142:143], v[200:201], v[142:143] op_sel:[1,0]
	v_pk_mul_f32 v[140:141], v[200:201], v[140:141] op_sel:[1,0]
	global_store_dwordx4 v[148:149], v[144:147], off
	v_pk_fma_f32 v[140:141], v[214:215], v[140:141], v[36:37]
	v_pk_fma_f32 v[142:143], v[212:213], v[142:143], v[38:39]
	v_add_u32_e32 v144, 0x18080, v194
	v_mov_b32_e32 v145, v159
	v_sub_f32_e32 v137, v137, v200
	v_sub_f32_e32 v136, v136, v200
	v_sub_f32_e32 v139, v139, v200
	v_sub_f32_e32 v138, v138, v200
	v_pk_fma_f32 v[142:143], v[134:135], s[78:79], v[142:143] op_sel_hi:[1,0,1]
	v_pk_fma_f32 v[140:141], v[132:133], s[78:79], v[140:141] op_sel_hi:[1,0,1]
	v_lshl_add_u64 v[144:145], v[144:145], 2, s[90:91]
	v_pk_mul_f32 v[138:139], v[200:201], v[138:139] op_sel:[1,0]
	v_pk_mul_f32 v[136:137], v[200:201], v[136:137] op_sel:[1,0]
	global_store_dwordx4 v[144:145], v[140:143], off
	v_pk_fma_f32 v[136:137], v[208:209], v[136:137], v[32:33]
	v_pk_fma_f32 v[138:139], v[206:207], v[138:139], v[34:35]
	v_add_u32_e32 v140, 0x18090, v194
	v_mov_b32_e32 v141, v159
	v_pk_fma_f32 v[138:139], v[130:131], s[78:79], v[138:139] op_sel_hi:[1,0,1]
	v_pk_fma_f32 v[136:137], v[128:129], s[78:79], v[136:137] op_sel_hi:[1,0,1]
	v_lshl_add_u64 v[140:141], v[140:141], 2, s[90:91]
	global_store_dwordx4 v[140:141], v[136:139], off
	s_nop 1
	v_add_u32_e32 v136, v233, v230
	v_mov_b32_e32 v137, v159
	v_lshl_add_u64 v[136:137], v[136:137], 2, s[88:89]
	global_load_dwordx2 v[220:221], v[196:197], off
	global_load_dwordx4 v[216:219], v[136:137], off
	v_add_u32_e32 v136, v233, v229
	v_mov_b32_e32 v137, v159
	v_lshl_add_u64 v[136:137], v[136:137], 2, s[88:89]
	global_load_dwordx4 v[240:243], v[136:137], off
	global_load_dwordx2 v[200:201], v[198:199], off
	v_add_u32_e32 v136, v234, v230
	v_mov_b32_e32 v137, v159
	v_lshl_add_u64 v[136:137], v[136:137], 2, s[88:89]
	global_load_dwordx4 v[244:247], v[136:137], off
	v_add_u32_e32 v136, v234, v229
	v_mov_b32_e32 v137, v159
	v_lshl_add_u64 v[136:137], v[136:137], 2, s[88:89]
	global_load_dwordx4 v[152:155], v[136:137], off
	global_load_dwordx2 v[198:199], v[204:205], off
	v_add_u32_e32 v136, v237, v230
	v_mov_b32_e32 v137, v159
	v_lshl_add_u64 v[136:137], v[136:137], 2, s[88:89]
	global_load_dwordx4 v[148:151], v[136:137], off
	v_add_u32_e32 v136, v237, v229
	v_mov_b32_e32 v137, v159
	v_lshl_add_u64 v[136:137], v[136:137], 2, s[88:89]
	global_load_dwordx4 v[144:147], v[136:137], off
	global_load_dwordx2 v[196:197], v[210:211], off
	v_add_u32_e32 v136, v238, v230
	v_mov_b32_e32 v137, v159
	v_lshl_add_u64 v[136:137], v[136:137], 2, s[88:89]
	global_load_dwordx4 v[140:143], v[136:137], off
	v_add_u32_e32 v136, v238, v229
	v_mov_b32_e32 v137, v159
	v_lshl_add_u64 v[136:137], v[136:137], 2, s[88:89]
	global_load_dwordx4 v[136:139], v[136:137], off
	v_add_u32_e32 v210, 0x40080, v194
	v_mov_b32_e32 v211, v159
	v_lshl_add_u64 v[210:211], v[210:211], 2, s[90:91]
	s_waitcnt vmcnt(0)
;     template <bool LN, int BJ, int LO, int HI> DI void batch(const f32x4 (&acc)[2][2][4][2], unsigned row0, unsigned col0, const f32x4 (&gv)[2], const f32x4 (&bv)[2]) const {
;         f32x4 r[HI - LO]; float mean[(HI - LO) / 2], rstd[(HI - LO) / 2];
; #pragma unroll
;         for (int i = LO; i < HI; ++i) { const int ai = i >> 3, m = (i >> 1) & 3, n = i & 1; const unsigned row = row0 + ai * HALF + m * 16;
;             if (n == 0) { mean[(i - LO) >> 1] = 0.f; rstd[(i - LO) >> 1] = 1.f;
;                 if (LN) { const float2 st = *(const float2*)(stats + row * 2u); mean[(i - LO) >> 1] = st.x; rstd[(i - LO) >> 1] = st.y; } }
;             r[i - LO] = *(const f32x4*)(src + (row * (unsigned)DM + col0 + BJ * HALF + n * 16)); }
; #pragma unroll
;         for (int i = LO; i < HI; ++i) { const int ai = i >> 3, m = (i >> 1) & 3, n = i & 1; const unsigned row = row0 + ai * HALF + m * 16;
;             *(f32x4*)(Y + (row * (unsigned)DM + col0 + BJ * HALF + n * 16)) = acc[ai][BJ][m][n] + ((r[i - LO] - mean[(i - LO) >> 1]) * rstd[(i - LO) >> 1]) * gv[n] + bv[n]; }
;         __builtin_amdgcn_sched_barrier(0);
;     }
;     template <bool LN, int BJ> DI void load_gb(unsigned col0, f32x4 (&gv)[2], f32x4 (&bv)[2]) const {
; #pragma unroll
;         for (int n = 0; n < 2; ++n) {
;             if (LN) { gv[n] = *(const f32x4*)(gam + col0 + BJ * HALF + n * 16) * ALPHA; bv[n] = *(const f32x4*)(bet + col0 + BJ * HALF + n * 16) * ALPHA; }
;             else { gv[n] = (f32x4){ALPHA, ALPHA, ALPHA, ALPHA}; bv[n] = (f32x4){0.f, 0.f, 0.f, 0.f}; }
;         }
;     }
;     template <bool LN> DI void run(const f32x4 (&acc)[2][2][4][2], const Unit& u, int wr, int wc, int fr, int fq) const {
;         const unsigned row0 = u.pm * BM + wr * 64 + fr, col0 = u.pn * BM + wc * 32 + 4 * fq;
;         f32x4 gv[2], bv[2];
;         load_gb<LN, 0>(col0, gv, bv);
;         batch<LN, 0, 0, 4>(acc, row0, col0, gv, bv);
;         batch<LN, 0, 4, 8>(acc, row0, col0, gv, bv);
;         batch<LN, 0, 8, 12>(acc, row0, col0, gv, bv);
;         batch<LN, 0, 12, 16>(acc, row0, col0, gv, bv);
;         load_gb<LN, 1>(col0, gv, bv);
;         batch<LN, 1, 0, 8>(acc, row0, col0, gv, bv);
;         batch<LN, 1, 8, 16>(acc, row0, col0, gv, bv);
	v_sub_f32_e32 v203, v217, v220
	v_sub_f32_e32 v202, v216, v220
	v_sub_f32_e32 v205, v219, v220
	v_sub_f32_e32 v204, v218, v220
	v_pk_mul_f32 v[204:205], v[220:221], v[204:205] op_sel:[1,0]
	v_pk_mul_f32 v[202:203], v[220:221], v[202:203] op_sel:[1,0]
	v_pk_fma_f32 v[204:205], v[212:213], v[204:205], v[30:31]
	v_pk_fma_f32 v[202:203], v[214:215], v[202:203], v[28:29]
	v_pk_fma_f32 v[204:205], v[134:135], s[78:79], v[204:205] op_sel_hi:[1,0,1]
	v_pk_fma_f32 v[202:203], v[132:133], s[78:79], v[202:203] op_sel_hi:[1,0,1]
	global_store_dwordx4 v[210:211], v[202:205], off
	v_add_u32_e32 v210, 0x40090, v194
	v_mov_b32_e32 v211, v159
	v_sub_f32_e32 v203, v241, v220
	v_sub_f32_e32 v202, v240, v220
	v_sub_f32_e32 v205, v243, v220
	v_sub_f32_e32 v204, v242, v220
	v_pk_mul_f32 v[204:205], v[220:221], v[204:205] op_sel:[1,0]
	v_pk_mul_f32 v[202:203], v[220:221], v[202:203] op_sel:[1,0]
	v_pk_fma_f32 v[204:205], v[206:207], v[204:205], v[26:27]
	v_pk_fma_f32 v[202:203], v[208:209], v[202:203], v[24:25]
	v_pk_fma_f32 v[204:205], v[130:131], s[78:79], v[204:205] op_sel_hi:[1,0,1]
	v_pk_fma_f32 v[202:203], v[128:129], s[78:79], v[202:203] op_sel_hi:[1,0,1]
	v_lshl_add_u64 v[210:211], v[210:211], 2, s[90:91]
	global_store_dwordx4 v[210:211], v[202:205], off
	v_sub_f32_e32 v149, v149, v198
	v_sub_f32_e32 v148, v148, v198
	v_sub_f32_e32 v203, v245, v200
	v_sub_f32_e32 v202, v244, v200
	v_sub_f32_e32 v141, v141, v196
	v_sub_f32_e32 v140, v140, v196
	v_sub_f32_e32 v205, v247, v200
	v_sub_f32_e32 v204, v246, v200
	v_pk_mul_f32 v[202:203], v[200:201], v[202:203] op_sel:[1,0]
	v_sub_f32_e32 v151, v151, v198
	v_sub_f32_e32 v150, v150, v198
	v_pk_mul_f32 v[148:149], v[198:199], v[148:149] op_sel:[1,0]
	v_sub_f32_e32 v143, v143, v196
	v_sub_f32_e32 v142, v142, v196
	v_pk_mul_f32 v[140:141], v[196:197], v[140:141] op_sel:[1,0]
	v_pk_mul_f32 v[204:205], v[200:201], v[204:205] op_sel:[1,0]
	v_pk_fma_f32 v[202:203], v[214:215], v[202:203], v[20:21]
	v_sub_f32_e32 v153, v153, v200
	v_sub_f32_e32 v152, v152, v200
	v_sub_f32_e32 v155, v155, v200
	v_sub_f32_e32 v154, v154, v200
	v_pk_mul_f32 v[150:151], v[198:199], v[150:151] op_sel:[1,0]
	v_pk_fma_f32 v[148:149], v[214:215], v[148:149], v[12:13]
	v_pk_mul_f32 v[142:143], v[196:197], v[142:143] op_sel:[1,0]
	v_pk_fma_f32 v[140:141], v[214:215], v[140:141], v[4:5]
	v_pk_fma_f32 v[204:205], v[212:213], v[204:205], v[22:23]
	v_pk_fma_f32 v[202:203], v[132:133], s[78:79], v[202:203] op_sel_hi:[1,0,1]
	v_pk_mul_f32 v[154:155], v[200:201], v[154:155] op_sel:[1,0]
	v_pk_mul_f32 v[152:153], v[200:201], v[152:153] op_sel:[1,0]
	v_pk_fma_f32 v[150:151], v[212:213], v[150:151], v[14:15]
	v_pk_fma_f32 v[148:149], v[132:133], s[78:79], v[148:149] op_sel_hi:[1,0,1]
	v_pk_fma_f32 v[142:143], v[212:213], v[142:143], v[6:7]
	v_pk_fma_f32 v[132:133], v[132:133], s[78:79], v[140:141] op_sel_hi:[1,0,1]
	v_add_u32_e32 v140, 0x58080, v194
	v_mov_b32_e32 v141, v159
	v_pk_fma_f32 v[204:205], v[134:135], s[78:79], v[204:205] op_sel_hi:[1,0,1]
	v_pk_fma_f32 v[152:153], v[208:209], v[152:153], v[16:17]
	v_pk_fma_f32 v[154:155], v[206:207], v[154:155], v[18:19]
	v_add_u32_e32 v200, 0x48090, v194
	v_mov_b32_e32 v201, v159
	v_pk_fma_f32 v[150:151], v[134:135], s[78:79], v[150:151] op_sel_hi:[1,0,1]
	v_pk_fma_f32 v[134:135], v[134:135], s[78:79], v[142:143] op_sel_hi:[1,0,1]
	v_lshl_add_u64 v[140:141], v[140:141], 2, s[90:91]
	v_pk_fma_f32 v[154:155], v[130:131], s[78:79], v[154:155] op_sel_hi:[1,0,1]
	v_pk_fma_f32 v[152:153], v[128:129], s[78:79], v[152:153] op_sel_hi:[1,0,1]
	v_lshl_add_u64 v[200:201], v[200:201], 2, s[90:91]
	v_sub_f32_e32 v145, v145, v198
	v_sub_f32_e32 v144, v144, v198
	global_store_dwordx4 v[140:141], v[132:135], off
	global_store_dwordx4 v[200:201], v[152:155], off
	v_sub_f32_e32 v147, v147, v198
	v_sub_f32_e32 v133, v137, v196
	v_sub_f32_e32 v132, v136, v196
	v_add_u32_e32 v152, 0x50080, v194
	v_mov_b32_e32 v153, v159
	v_sub_f32_e32 v146, v146, v198
	v_pk_mul_f32 v[144:145], v[198:199], v[144:145] op_sel:[1,0]
	v_sub_f32_e32 v135, v139, v196
	v_sub_f32_e32 v134, v138, v196
	v_pk_mul_f32 v[132:133], v[196:197], v[132:133] op_sel:[1,0]
	v_lshl_add_u64 v[152:153], v[152:153], 2, s[90:91]
	v_pk_mul_f32 v[146:147], v[198:199], v[146:147] op_sel:[1,0]
	v_pk_fma_f32 v[144:145], v[208:209], v[144:145], v[8:9]
	v_pk_mul_f32 v[134:135], v[196:197], v[134:135] op_sel:[1,0]
	v_pk_fma_f32 v[132:133], v[208:209], v[132:133], v[0:1]
	v_add_u32_e32 v210, 0x48080, v194
	v_mov_b32_e32 v211, v159
	global_store_dwordx4 v[152:153], v[148:151], off
	v_pk_fma_f32 v[146:147], v[206:207], v[146:147], v[10:11]
	v_pk_fma_f32 v[144:145], v[128:129], s[78:79], v[144:145] op_sel_hi:[1,0,1]
	v_add_u32_e32 v148, 0x50090, v194
	v_mov_b32_e32 v149, v159
	v_pk_fma_f32 v[134:135], v[206:207], v[134:135], v[2:3]
	v_pk_fma_f32 v[128:129], v[128:129], s[78:79], v[132:133] op_sel_hi:[1,0,1]
	v_add_u32_e32 v132, 0x58090, v194
	v_mov_b32_e32 v133, v159
	v_lshl_add_u64 v[210:211], v[210:211], 2, s[90:91]
	v_pk_fma_f32 v[146:147], v[130:131], s[78:79], v[146:147] op_sel_hi:[1,0,1]
	v_lshl_add_u64 v[148:149], v[148:149], 2, s[90:91]
	v_pk_fma_f32 v[130:131], v[130:131], s[78:79], v[134:135] op_sel_hi:[1,0,1]
	v_lshl_add_u64 v[132:133], v[132:133], 2, s[90:91]
	global_store_dwordx4 v[210:211], v[202:205], off
	global_store_dwordx4 v[148:149], v[144:147], off
	global_store_dwordx4 v[132:133], v[128:131], off
	s_mov_b64 s[20:21], 0
	s_branch .LBB0_81

; __device__ __forceinline__ int opaque_tid() { int t = threadIdx.x; asm volatile("" : "+v"(t)); return t; }
; #define PG8_STAGE(bufoff, gbase) do { _Pragma("unroll") for (int _i = 0; _i < 2; ++_i) \
;         __builtin_amdgcn_global_load_lds((const unsigned*)((const char*)(gbase) + voff[_i]), (LAS unsigned*)(lds + (bufoff) + ldsw + _i * 8192), 16, 0, 0); } while (0)
; #define PG8_WAIT_V(n) asm volatile("s_waitcnt vmcnt(" #n ")" ::: "memory")
; #define PG8_BAR __builtin_amdgcn_s_barrier()
; template <class Epi>
; DI void gemm_phase(LAS unsigned char* lds, const Gemm g, const StaticOrder& S, const Epi& E) {
;     const int tid = opaque_tid(), wid = __builtin_amdgcn_readfirstlane(tid >> 6), lane = tid & 63, wr = wid >> 2, wc = wid & 3, fr = lane & 15, fq = lane >> 4;
;     const int K = g.K, nt = K / BK;
;     unsigned voff[2];
; #pragma unroll
;     for (int i = 0; i < 2; ++i) { int R, C; stage_rc(tid * 16 + i * 8192, R, C); voff[i] = (unsigned)(R * K + C) * 2u; }
;     const size_t kstep = (size_t)(BK * 2);
;     const size_t hstep = (size_t)HALF * K * 2;
;     const size_t tstep = 2 * hstep;
;     const unsigned ldsw = (unsigned)wid * 1024u;
;     const int aoff = lds_byte(wr * 64 + fr, fq * 8), boff = lds_byte(wc * 32 + fr, fq * 8);
;     ...
;     Unit cur, nxt; int ui = 0;
;     if (!S.next(0, cur)) return;
;     f32x4 acc[2][2][4][2];
; #pragma unroll
;     for (int a = 0; a < 2; ++a)
; #pragma unroll
;         for (int b = 0; b < 2; ++b)
; #pragma unroll
;             for (int m = 0; m < 4; ++m)
; #pragma unroll
;                 for (int n = 0; n < 2; ++n) acc[a][b][m][n] = (f32x4){0.f, 0.f, 0.f, 0.f};
;     bf16x8 At[4][2], B0[2][2], B1[2][2];
;     const char* cA = (const char*)g.A + (size_t)cur.pm * tstep; const char* cB = (const char*)g.Bt + (size_t)cur.pn * tstep;
;     PG8_STAGE(PG8_SB(0, 0), cB); PG8_STAGE(PG8_SA(0, 0), cA); PG8_STAGE(PG8_SB(0, 1), cB + hstep); PG8_STAGE(PG8_SA(0, 1), cA + hstep);
;     if (wr == 1) PG8_BAR;
;     PG8_WAIT_V(4); PG8_BAR;
;     PG8_STAGE(PG8_SB(1, 0), cB + kstep); PG8_STAGE(PG8_SA(1, 0), cA + kstep); PG8_STAGE(PG8_SB(1, 1), cB + hstep + kstep);
;     PG8_WAIT_V(6); PG8_BAR;
.LBB0_118:
	s_nop 0
	v_readlane_b32 s2, v255, 46
	v_readlane_b32 s3, v255, 47
	s_and_b64 vcc, exec, s[2:3]
	s_cbranch_vccz .LBB0_192
	v_readlane_b32 s2, v254, 46
	v_mov_b32_e32 v4, v156
	v_readlane_b32 s3, v254, 47
	s_lshl_b32 s76, s33, 11
	s_andn2_b64 vcc, exec, s[2:3]
	v_readfirstlane_b32 s24, v4
	s_cbranch_vccnz .LBB0_139
	v_lshlrev_b32_e32 v0, 4, v4
	v_add_u32_e32 v1, 0x2000, v0
	v_ashrrev_i32_e32 v2, 31, v1
	v_lshrrev_b32_e32 v2, 22, v2
	v_add_u32_e32 v2, v1, v2
	v_ashrrev_i32_e32 v5, 10, v2
	v_mul_i32_i24_e32 v2, 0x400, v5
	v_sub_u32_e32 v1, v1, v2
	v_lshrrev_b32_e32 v2, 4, v1
	v_bitop3_b32 v1, v2, v1, 32 bitop3:0x6c
	v_ashrrev_i32_e32 v2, 31, v1
	v_lshrrev_b32_e32 v2, 26, v2
	v_add_u32_e32 v2, v1, v2
	v_ashrrev_i32_e32 v6, 6, v2
	v_and_b32_e32 v2, 0xc0, v2
	v_sub_u32_e32 v1, v1, v2
	v_ashrrev_i16_sdwa v1, v252, sext(v1) dst_sel:DWORD dst_unused:UNUSED_PAD src0_sel:DWORD src1_sel:BYTE_0
	v_bfe_i32 v8, v1, 0, 16
	v_bfe_i32 v1, v4, 27, 1
	v_lshrrev_b32_e32 v1, 22, v1
	v_add_u32_e32 v1, v0, v1
	v_and_b32_e32 v1, 0xfffffc00, v1
	v_sub_u32_e32 v0, v0, v1
	v_lshrrev_b32_e32 v1, 4, v0
	v_bitop3_b32 v1, v1, v0, 32 bitop3:0x6c
	v_ashrrev_i32_e32 v0, 31, v0
	v_lshrrev_b32_e32 v0, 26, v0
	v_add_u32_e32 v0, v1, v0
	v_ashrrev_i32_e32 v9, 6, v0
	v_ashrrev_i32_e32 v0, 31, v4
	v_lshrrev_b32_e32 v0, 26, v0
	v_add_u32_e32 v0, v4, v0
	v_ashrrev_i32_e32 v10, 6, v0
	s_mul_i32 s3, s33, 0x1600000
	v_readlane_b32 s4, v253, 29
	v_lshlrev_b32_e32 v3, 3, v5
	v_lshlrev_b32_e32 v0, 3, v10
	s_mul_hi_u32 s2, s33, 0x1600000
	s_add_u32 s25, s4, s3
	v_readlane_b32 s3, v253, 30
	v_and_b32_e32 v3, 0x7ffff0, v3
	v_and_b32_e32 v0, 0x7ffff0, v0
	v_lshlrev_b32_e32 v2, 5, v10
	s_addc_u32 s26, s3, s2
	s_ashr_i32 s3, s24, 6
	v_add_u32_e32 v3, v6, v3
	s_movk_i32 s4, 0x1600
	v_add_u32_e32 v0, v9, v0
	v_and_b32_e32 v11, 32, v2
	v_mul_i32_i24_e32 v2, 64, v9
	v_readlane_b32 s5, v254, 31
	s_ashr_i32 s2, s24, 8
	s_lshl_b32 s27, s3, 10
	v_mul_lo_u32 v3, v3, s4
	v_mul_lo_u32 v0, v0, s4
	v_sub_u32_e32 v1, v1, v2
	s_mul_i32 s4, s5, 0x2c0000
	v_lshlrev_b32_e32 v7, 5, v5
	v_ashrrev_i16_sdwa v1, v252, sext(v1) dst_sel:DWORD dst_unused:UNUSED_PAD src0_sel:DWORD src1_sel:BYTE_0
	s_add_u32 s18, s25, s4
	s_mul_hi_i32 s4, s5, 0x2c0000
	v_and_b32_e32 v7, 32, v7
	v_or_b32_e32 v0, v0, v11
	v_bfe_i32 v12, v1, 0, 16
	s_addc_u32 s19, s26, s4
	s_add_i32 s28, s27, 0
	v_or_b32_e32 v3, v3, v7
	s_waitcnt vmcnt(0)
	v_add_lshl_u32 v142, v0, v12, 1
	s_add_i32 m0, s28, 0x10000
	v_add_lshl_u32 v140, v3, v8, 1
	global_load_lds_dwordx4 v142, s[18:19]
	s_add_i32 m0, s28, 0x12000
	v_readlane_b32 s4, v254, 42
	global_load_lds_dwordx4 v140, s[18:19]
	s_mov_b32 m0, s28
	v_readlane_b32 s5, v254, 43
	s_add_i32 s29, s28, 0x2000
	v_mov_b32_e32 v143, v159
	v_mov_b32_e32 v141, v159
	v_lshl_add_u64 v[0:1], s[18:19], 0, v[142:143]
	v_lshl_add_u64 v[2:3], s[18:19], 0, v[140:141]
	global_load_lds_dwordx4 v142, s[4:5]
	s_mov_b32 m0, s29
	s_nop 0
	global_load_lds_dwordx4 v140, s[4:5]
	s_add_u32 s4, s18, 0x160000
	s_addc_u32 s5, s19, 0
	s_add_i32 m0, s28, 0x14000
	s_add_i32 s30, s28, 0x4000
	global_load_lds_dwordx4 v142, s[4:5]
	s_add_i32 m0, s28, 0x16000
	s_add_i32 s31, s28, 0x6000
	global_load_lds_dwordx4 v140, s[4:5]
	v_readlane_b32 s4, v254, 44
	s_mov_b32 m0, s30
	v_readlane_b32 s5, v254, 45
	s_cmp_lg_u32 s2, 1
	s_nop 3
	global_load_lds_dwordx4 v142, s[4:5]
	s_mov_b32 m0, s31
	s_nop 0
	global_load_lds_dwordx4 v140, s[4:5]
	s_cbranch_scc1 .LBB0_122
	s_setprio 1
	s_barrier

; #define PG8_STAGE(bufoff, gbase) do { _Pragma("unroll") for (int _i = 0; _i < 2; ++_i) \
;         __builtin_amdgcn_global_load_lds((const unsigned*)((const char*)(gbase) + voff[_i]), (LAS unsigned*)(lds + (bufoff) + ldsw + _i * 8192), 16, 0, 0); } while (0)
; #define PG8_LDA(dst, b, h) do { _Pragma("unroll") for (int m = 0; m < 4; ++m) _Pragma("unroll") for (int k = 0; k < 2; ++k) dst[m][k] = *(const LAS bf16x8*)(lds + PG8_SA(b, h) + aoff + m * 2048 + k * 1024); } while (0)
; #define PG8_LDB(dst, b, h) do { _Pragma("unroll") for (int n = 0; n < 2; ++n) _Pragma("unroll") for (int k = 0; k < 2; ++k) dst[n][k] = *(const LAS bf16x8*)(lds + PG8_SB(b, h) + boff + n * 2048 + k * 1024); } while (0)
; #define PG8_MMA(ai, bj, At, Bt) do { __builtin_amdgcn_s_setprio(1); _Pragma("unroll") for (int m = 0; m < 4; ++m) _Pragma("unroll") for (int n = 0; n < 2; ++n) _Pragma("unroll") for (int k = 0; k < 2; ++k) \
;         acc[ai][bj][m][n] = __builtin_amdgcn_mfma_f32_16x16x32_bf16(Bt[n][k], At[m][k], acc[ai][bj][m][n], 0, 0, 0); __builtin_amdgcn_s_setprio(0); } while (0)
; #define PG8_WAIT_V(n) asm volatile("s_waitcnt vmcnt(" #n ")" ::: "memory")
; #define PG8_WAIT_L(n) asm volatile("s_waitcnt lgkmcnt(" #n ")" ::: "memory")
; #define PG8_BAR __builtin_amdgcn_s_barrier()
; #define PG8_SCHED __builtin_amdgcn_sched_barrier(0)
; template <class Epi>
; DI void gemm_phase(LAS unsigned char* lds, const Gemm g, const StaticOrder& S, const Epi& E) {
;     ...
;         for (int t = 0; t < nt; t += 2) {
;             const bool last = (t == nt - 2);
;             const char* a1 = cA + (size_t)(t + 1) * kstep;
;             const char* a2 = last ? nA : cA + (size_t)(t + 2) * kstep; const char* b2 = last ? nB : cB + (size_t)(t + 2) * kstep;
;             const char* a3 = a2 + kstep; const char* b3 = b2 + kstep;
;             PG8_LDB(B0, 0, 0); PG8_SCHED; PG8_LDA(At, 0, 0); PG8_STAGE(PG8_SA(1, 1), a1 + hstep);
;             PG8_WAIT_L(8); PG8_BAR; PG8_WAIT_L(0); PG8_MMA(0, 0, At, B0); PG8_BAR; PG8_SCHED;
;             PG8_LDB(B1, 0, 1); PG8_STAGE(PG8_SB(0, 0), b2);
;             PG8_BAR; PG8_WAIT_L(0); PG8_MMA(0, 1, At, B1); PG8_BAR;
;             PG8_LDA(At, 0, 1); PG8_STAGE(PG8_SA(0, 0), a2);
;             PG8_BAR; PG8_WAIT_L(0); PG8_MMA(1, 0, At, B0); PG8_BAR; PG8_SCHED;
;             PG8_STAGE(PG8_SB(0, 1), b2 + hstep);
;             PG8_WAIT_V(6); PG8_BAR; PG8_MMA(1, 1, At, B1); PG8_BAR;
.LBB0_134:
	ds_read_b128 v[96:99], v199
	ds_read_b128 v[100:103], v199 offset:1024
	ds_read_b128 v[136:139], v199 offset:2048
	ds_read_b128 v[148:151], v199 offset:3072
	ds_read_b128 v[152:155], v201
	ds_read_b128 v[186:189], v201 offset:1024
	ds_read_b128 v[190:193], v201 offset:2048
	ds_read_b128 v[194:197], v201 offset:3072
	ds_read_b128 v[202:205], v201 offset:4096
	ds_read_b128 v[206:209], v201 offset:5120
	ds_read_b128 v[210:213], v201 offset:6144
	ds_read_b128 v[214:217], v201 offset:7168
	s_add_u32 s18, s16, 0x100
	s_addc_u32 s19, s17, 0
	s_add_i32 s39, 0, 0x10000
	s_cmpk_eq_i32 s33, 0x54
	s_cselect_b32 s23, s9, s19
	s_cselect_b32 s22, s8, s18
	s_cselect_b32 s21, s11, s5
	s_cselect_b32 s20, s10, s4
	s_add_i32 m0, s28, 0xc000
	s_nop 0
	global_load_lds_dwordx4 v144, s[16:17]
	s_add_i32 m0, s28, 0xe000
	s_nop 0
	global_load_lds_dwordx4 v146, s[16:17]
	s_waitcnt lgkmcnt(8)
	s_barrier
	s_waitcnt lgkmcnt(0)
	v_mfma_f32_16x16x32_bf16 v[132:135], v[96:99], v[152:155], v[132:135]
	v_mfma_f32_16x16x32_bf16 v[128:131], v[136:139], v[152:155], v[128:131]
	v_mfma_f32_16x16x32_bf16 v[124:127], v[96:99], v[190:193], v[124:127]
	v_mfma_f32_16x16x32_bf16 v[120:123], v[136:139], v[190:193], v[120:123]
	v_mfma_f32_16x16x32_bf16 v[116:119], v[96:99], v[202:205], v[116:119]
	v_mfma_f32_16x16x32_bf16 v[112:115], v[136:139], v[202:205], v[112:115]
	v_mfma_f32_16x16x32_bf16 v[108:111], v[96:99], v[210:213], v[108:111]
	v_mfma_f32_16x16x32_bf16 v[104:107], v[136:139], v[210:213], v[104:107]
	v_mfma_f32_16x16x32_bf16 v[132:135], v[100:103], v[186:189], v[132:135]
	v_mfma_f32_16x16x32_bf16 v[128:131], v[148:151], v[186:189], v[128:131]
	v_mfma_f32_16x16x32_bf16 v[124:127], v[100:103], v[194:197], v[124:127]
	v_mfma_f32_16x16x32_bf16 v[120:123], v[148:151], v[194:197], v[120:123]
	v_mfma_f32_16x16x32_bf16 v[116:119], v[100:103], v[206:209], v[116:119]
	v_mfma_f32_16x16x32_bf16 v[112:115], v[148:151], v[206:209], v[112:115]
	v_mfma_f32_16x16x32_bf16 v[108:111], v[100:103], v[214:217], v[108:111]
	v_mfma_f32_16x16x32_bf16 v[104:107], v[148:151], v[214:217], v[104:107]
	s_barrier
	ds_read_b128 v[226:229], v199 offset:16384
	ds_read_b128 v[230:233], v199 offset:17408
	ds_read_b128 v[234:237], v199 offset:18432
	ds_read_b128 v[238:241], v199 offset:19456
	s_add_i32 s40, 0, 0x14000
	s_add_i32 s16, s39, s27
	s_mov_b32 m0, s16
	s_nop 0
	global_load_lds_dwordx4 v142, s[20:21]
	s_add_i32 m0, s16, 0x2000
	s_nop 0
	global_load_lds_dwordx4 v140, s[20:21]
	s_waitcnt lgkmcnt(0)
	s_barrier
	v_mfma_f32_16x16x32_bf16 v[60:63], v[226:229], v[152:155], v[60:63]
	v_mfma_f32_16x16x32_bf16 v[56:59], v[234:237], v[152:155], v[56:59]
	v_mfma_f32_16x16x32_bf16 v[52:55], v[226:229], v[190:193], v[52:55]
	v_mfma_f32_16x16x32_bf16 v[48:51], v[234:237], v[190:193], v[48:51]
	v_mfma_f32_16x16x32_bf16 v[44:47], v[226:229], v[202:205], v[44:47]
	v_mfma_f32_16x16x32_bf16 v[40:43], v[234:237], v[202:205], v[40:43]
	v_mfma_f32_16x16x32_bf16 v[36:39], v[226:229], v[210:213], v[36:39]
	v_mfma_f32_16x16x32_bf16 v[32:35], v[234:237], v[210:213], v[32:35]
	v_mfma_f32_16x16x32_bf16 v[60:63], v[230:233], v[186:189], v[60:63]
	s_mov_b32 m0, s28
	v_mfma_f32_16x16x32_bf16 v[56:59], v[238:241], v[186:189], v[56:59]
	v_mfma_f32_16x16x32_bf16 v[52:55], v[230:233], v[194:197], v[52:55]
	v_mfma_f32_16x16x32_bf16 v[48:51], v[238:241], v[194:197], v[48:51]
	v_mfma_f32_16x16x32_bf16 v[44:47], v[230:233], v[206:209], v[44:47]
	v_mfma_f32_16x16x32_bf16 v[40:43], v[238:241], v[206:209], v[40:43]
	v_mfma_f32_16x16x32_bf16 v[36:39], v[230:233], v[214:217], v[36:39]
	v_mfma_f32_16x16x32_bf16 v[32:35], v[238:241], v[214:217], v[32:35]
	s_barrier
	ds_read_b128 v[152:155], v201 offset:16384
	ds_read_b128 v[186:189], v201 offset:17408
	ds_read_b128 v[190:193], v201 offset:18432
	ds_read_b128 v[194:197], v201 offset:19456
	ds_read_b128 v[202:205], v201 offset:20480
	ds_read_b128 v[206:209], v201 offset:21504
	ds_read_b128 v[210:213], v201 offset:22528
	ds_read_b128 v[214:217], v201 offset:23552
	global_load_lds_dwordx4 v142, s[22:23]
	s_mov_b64 s[100:101], s[22:23]
	s_mov_b32 m0, s29
	s_nop 0
	global_load_lds_dwordx4 v140, s[22:23]
	s_waitcnt lgkmcnt(0)
	s_barrier
	v_mfma_f32_16x16x32_bf16 v[92:95], v[96:99], v[152:155], v[92:95]
	v_mfma_f32_16x16x32_bf16 v[88:91], v[136:139], v[152:155], v[88:91]
	v_mfma_f32_16x16x32_bf16 v[84:87], v[96:99], v[190:193], v[84:87]
	v_mfma_f32_16x16x32_bf16 v[80:83], v[136:139], v[190:193], v[80:83]
	v_mfma_f32_16x16x32_bf16 v[76:79], v[96:99], v[202:205], v[76:79]
	v_mfma_f32_16x16x32_bf16 v[72:75], v[136:139], v[202:205], v[72:75]
	v_mfma_f32_16x16x32_bf16 v[68:71], v[96:99], v[210:213], v[68:71]
	v_mfma_f32_16x16x32_bf16 v[64:67], v[136:139], v[210:213], v[64:67]
	v_mfma_f32_16x16x32_bf16 v[92:95], v[100:103], v[186:189], v[92:95]
	v_mfma_f32_16x16x32_bf16 v[88:91], v[148:151], v[186:189], v[88:91]
	v_mfma_f32_16x16x32_bf16 v[84:87], v[100:103], v[194:197], v[84:87]
	v_mfma_f32_16x16x32_bf16 v[80:83], v[148:151], v[194:197], v[80:83]
	v_mfma_f32_16x16x32_bf16 v[76:79], v[100:103], v[206:209], v[76:79]
	v_mfma_f32_16x16x32_bf16 v[72:75], v[148:151], v[206:209], v[72:75]
	v_mfma_f32_16x16x32_bf16 v[68:71], v[100:103], v[214:217], v[68:71]
	v_mfma_f32_16x16x32_bf16 v[64:67], v[148:151], v[214:217], v[64:67]
	s_barrier
	s_add_u32 s16, s20, 0x160000
	s_addc_u32 s17, s21, 0
	s_add_i32 s39, s40, s27
	s_mov_b32 m0, s39
	s_nop 0
	global_load_lds_dwordx4 v142, s[16:17]
	s_add_i32 m0, s39, 0x2000
	s_nop 0
	global_load_lds_dwordx4 v140, s[16:17]
	s_waitcnt vmcnt(6)
	s_barrier
; #define PG8_STAGE(bufoff, gbase) do { _Pragma("unroll") for (int _i = 0; _i < 2; ++_i) \
;         __builtin_amdgcn_global_load_lds((const unsigned*)((const char*)(gbase) + voff[_i]), (LAS unsigned*)(lds + (bufoff) + ldsw + _i * 8192), 16, 0, 0); } while (0)
; #define PG8_LDA(dst, b, h) do { _Pragma("unroll") for (int m = 0; m < 4; ++m) _Pragma("unroll") for (int k = 0; k < 2; ++k) dst[m][k] = *(const LAS bf16x8*)(lds + PG8_SA(b, h) + aoff + m * 2048 + k * 1024); } while (0)
; #define PG8_LDB(dst, b, h) do { _Pragma("unroll") for (int n = 0; n < 2; ++n) _Pragma("unroll") for (int k = 0; k < 2; ++k) dst[n][k] = *(const LAS bf16x8*)(lds + PG8_SB(b, h) + boff + n * 2048 + k * 1024); } while (0)
; #define PG8_MMA(ai, bj, At, Bt) do { __builtin_amdgcn_s_setprio(1); _Pragma("unroll") for (int m = 0; m < 4; ++m) _Pragma("unroll") for (int n = 0; n < 2; ++n) _Pragma("unroll") for (int k = 0; k < 2; ++k) \
;         acc[ai][bj][m][n] = __builtin_amdgcn_mfma_f32_16x16x32_bf16(Bt[n][k], At[m][k], acc[ai][bj][m][n], 0, 0, 0); __builtin_amdgcn_s_setprio(0); } while (0)
; #define PG8_WAIT_V(n) asm volatile("s_waitcnt vmcnt(" #n ")" ::: "memory")
; #define PG8_WAIT_L(n) asm volatile("s_waitcnt lgkmcnt(" #n ")" ::: "memory")
; #define PG8_BAR __builtin_amdgcn_s_barrier()
; #define PG8_SCHED __builtin_amdgcn_sched_barrier(0)
; template <class Epi>
; DI void gemm_phase(LAS unsigned char* lds, const Gemm g, const StaticOrder& S, const Epi& E) {
;     ...
;             PG8_WAIT_V(6); PG8_BAR; PG8_MMA(1, 1, At, B1); PG8_BAR;
;             PG8_LDB(B0, 1, 0); PG8_SCHED; PG8_LDA(At, 1, 0); PG8_STAGE(PG8_SA(0, 1), a2 + hstep);
;             PG8_WAIT_L(8); PG8_BAR; PG8_WAIT_L(0); PG8_MMA(0, 0, At, B0); PG8_BAR; PG8_SCHED;
;             PG8_LDB(B1, 1, 1); PG8_STAGE(PG8_SB(1, 0), b3);
;             PG8_BAR; PG8_WAIT_L(0); PG8_MMA(0, 1, At, B1); PG8_BAR;
;             PG8_LDA(At, 1, 1); PG8_STAGE(PG8_SA(1, 0), a3);
;             PG8_BAR; PG8_WAIT_L(0); PG8_MMA(1, 0, At, B0); PG8_BAR; PG8_SCHED;
	v_mfma_f32_16x16x32_bf16 v[28:31], v[226:229], v[152:155], v[28:31]
	v_mfma_f32_16x16x32_bf16 v[24:27], v[234:237], v[152:155], v[24:27]
	v_mfma_f32_16x16x32_bf16 v[20:23], v[226:229], v[190:193], v[20:23]
	v_mfma_f32_16x16x32_bf16 v[16:19], v[234:237], v[190:193], v[16:19]
	v_mfma_f32_16x16x32_bf16 v[12:15], v[226:229], v[202:205], v[12:15]
	v_mfma_f32_16x16x32_bf16 v[8:11], v[234:237], v[202:205], v[8:11]
	v_mfma_f32_16x16x32_bf16 v[4:7], v[226:229], v[210:213], v[4:7]
	v_mfma_f32_16x16x32_bf16 v[0:3], v[234:237], v[210:213], v[0:3]
	v_mfma_f32_16x16x32_bf16 v[28:31], v[230:233], v[186:189], v[28:31]
	s_add_i32 s39, 0, 0x18000
	v_mfma_f32_16x16x32_bf16 v[24:27], v[238:241], v[186:189], v[24:27]
	v_mfma_f32_16x16x32_bf16 v[20:23], v[230:233], v[194:197], v[20:23]
	v_mfma_f32_16x16x32_bf16 v[16:19], v[238:241], v[194:197], v[16:19]
	v_mfma_f32_16x16x32_bf16 v[12:15], v[230:233], v[206:209], v[12:15]
	v_mfma_f32_16x16x32_bf16 v[8:11], v[238:241], v[206:209], v[8:11]
	v_mfma_f32_16x16x32_bf16 v[4:7], v[230:233], v[214:217], v[4:7]
	v_mfma_f32_16x16x32_bf16 v[0:3], v[238:241], v[214:217], v[0:3]
	s_barrier
	ds_read_b128 v[96:99], v199 offset:32768
	ds_read_b128 v[100:103], v199 offset:33792
	ds_read_b128 v[136:139], v199 offset:34816
	ds_read_b128 v[148:151], v199 offset:35840
	ds_read_b128 v[152:155], v201 offset:32768
	ds_read_b128 v[186:189], v201 offset:33792
	ds_read_b128 v[190:193], v201 offset:34816
	ds_read_b128 v[194:197], v201 offset:35840
	ds_read_b128 v[202:205], v201 offset:36864
	ds_read_b128 v[206:209], v201 offset:37888
	ds_read_b128 v[210:213], v201 offset:38912
	ds_read_b128 v[214:217], v201 offset:39936
	s_add_u32 s16, s22, 0x160000
	s_addc_u32 s17, s23, 0
	s_mov_b32 m0, s30
	s_nop 0
	global_load_lds_dwordx4 v142, s[16:17]
	s_mov_b32 m0, s31
	s_nop 0
	global_load_lds_dwordx4 v140, s[16:17]
	s_waitcnt lgkmcnt(8)
	s_barrier
	s_waitcnt lgkmcnt(0)
	v_mfma_f32_16x16x32_bf16 v[132:135], v[96:99], v[152:155], v[132:135]
	v_mfma_f32_16x16x32_bf16 v[128:131], v[136:139], v[152:155], v[128:131]
	v_mfma_f32_16x16x32_bf16 v[124:127], v[96:99], v[190:193], v[124:127]
	v_mfma_f32_16x16x32_bf16 v[120:123], v[136:139], v[190:193], v[120:123]
	v_mfma_f32_16x16x32_bf16 v[116:119], v[96:99], v[202:205], v[116:119]
	v_mfma_f32_16x16x32_bf16 v[112:115], v[136:139], v[202:205], v[112:115]
	v_mfma_f32_16x16x32_bf16 v[108:111], v[96:99], v[210:213], v[108:111]
	v_mfma_f32_16x16x32_bf16 v[104:107], v[136:139], v[210:213], v[104:107]
	v_mfma_f32_16x16x32_bf16 v[132:135], v[100:103], v[186:189], v[132:135]
	v_mfma_f32_16x16x32_bf16 v[128:131], v[148:151], v[186:189], v[128:131]
	v_mfma_f32_16x16x32_bf16 v[124:127], v[100:103], v[194:197], v[124:127]
	v_mfma_f32_16x16x32_bf16 v[120:123], v[148:151], v[194:197], v[120:123]
	v_mfma_f32_16x16x32_bf16 v[116:119], v[100:103], v[206:209], v[116:119]
	v_mfma_f32_16x16x32_bf16 v[112:115], v[148:151], v[206:209], v[112:115]
	v_mfma_f32_16x16x32_bf16 v[108:111], v[100:103], v[214:217], v[108:111]
	v_mfma_f32_16x16x32_bf16 v[104:107], v[148:151], v[214:217], v[104:107]
	s_barrier
	ds_read_b128 v[226:229], v199 offset:49152
	ds_read_b128 v[230:233], v199 offset:50176
	ds_read_b128 v[234:237], v199 offset:51200
	ds_read_b128 v[238:241], v199 offset:52224
	s_add_i32 s22, 0, 0x1c000
	s_add_i32 s16, s39, s27
	s_add_i32 m0, s16, 0xffffff80
	s_nop 0
	global_load_lds_dwordx4 v142, s[20:21] offset:128
	s_add_i32 m0, s16, 0x1f80
	s_nop 0
	global_load_lds_dwordx4 v140, s[20:21] offset:128
	s_waitcnt lgkmcnt(0)
	s_barrier
	v_mfma_f32_16x16x32_bf16 v[60:63], v[226:229], v[152:155], v[60:63]
	v_mfma_f32_16x16x32_bf16 v[56:59], v[234:237], v[152:155], v[56:59]
	v_mfma_f32_16x16x32_bf16 v[52:55], v[226:229], v[190:193], v[52:55]
	v_mfma_f32_16x16x32_bf16 v[48:51], v[234:237], v[190:193], v[48:51]
	v_mfma_f32_16x16x32_bf16 v[44:47], v[226:229], v[202:205], v[44:47]
	v_mfma_f32_16x16x32_bf16 v[40:43], v[234:237], v[202:205], v[40:43]
	v_mfma_f32_16x16x32_bf16 v[36:39], v[226:229], v[210:213], v[36:39]
	v_mfma_f32_16x16x32_bf16 v[32:35], v[234:237], v[210:213], v[32:35]
	v_mfma_f32_16x16x32_bf16 v[60:63], v[230:233], v[186:189], v[60:63]
	s_add_i32 m0, s34, 0xffffff80
	v_mfma_f32_16x16x32_bf16 v[56:59], v[238:241], v[186:189], v[56:59]
	v_mfma_f32_16x16x32_bf16 v[52:55], v[230:233], v[194:197], v[52:55]
	v_mfma_f32_16x16x32_bf16 v[48:51], v[238:241], v[194:197], v[48:51]
	v_mfma_f32_16x16x32_bf16 v[44:47], v[230:233], v[206:209], v[44:47]
	v_mfma_f32_16x16x32_bf16 v[40:43], v[238:241], v[206:209], v[40:43]
	v_mfma_f32_16x16x32_bf16 v[36:39], v[230:233], v[214:217], v[36:39]
	v_mfma_f32_16x16x32_bf16 v[32:35], v[238:241], v[214:217], v[32:35]
	s_barrier
	ds_read_b128 v[152:155], v201 offset:49152
	ds_read_b128 v[186:189], v201 offset:50176
	ds_read_b128 v[190:193], v201 offset:51200
	ds_read_b128 v[194:197], v201 offset:52224
	ds_read_b128 v[202:205], v201 offset:53248
	ds_read_b128 v[206:209], v201 offset:54272
	ds_read_b128 v[210:213], v201 offset:55296
	ds_read_b128 v[214:217], v201 offset:56320
	global_load_lds_dwordx4 v142, s[100:101] offset:128
	s_add_i32 m0, s35, 0xffffff80
	s_nop 0
	global_load_lds_dwordx4 v140, s[100:101] offset:128
	s_waitcnt lgkmcnt(0)
	s_barrier
; #define PG8_STAGE(bufoff, gbase) do { _Pragma("unroll") for (int _i = 0; _i < 2; ++_i) \
;         __builtin_amdgcn_global_load_lds((const unsigned*)((const char*)(gbase) + voff[_i]), (LAS unsigned*)(lds + (bufoff) + ldsw + _i * 8192), 16, 0, 0); } while (0)
; #define PG8_MMA(ai, bj, At, Bt) do { __builtin_amdgcn_s_setprio(1); _Pragma("unroll") for (int m = 0; m < 4; ++m) _Pragma("unroll") for (int n = 0; n < 2; ++n) _Pragma("unroll") for (int k = 0; k < 2; ++k) \
;         acc[ai][bj][m][n] = __builtin_amdgcn_mfma_f32_16x16x32_bf16(Bt[n][k], At[m][k], acc[ai][bj][m][n], 0, 0, 0); __builtin_amdgcn_s_setprio(0); } while (0)
; #define PG8_WAIT_V(n) asm volatile("s_waitcnt vmcnt(" #n ")" ::: "memory")
; #define PG8_WAIT_L(n) asm volatile("s_waitcnt lgkmcnt(" #n ")" ::: "memory")
; #define PG8_BAR __builtin_amdgcn_s_barrier()
; #define PG8_SCHED __builtin_amdgcn_sched_barrier(0)
; template <class Epi>
; DI void gemm_phase(LAS unsigned char* lds, const Gemm g, const StaticOrder& S, const Epi& E) {
;     ...
;             PG8_BAR; PG8_WAIT_L(0); PG8_MMA(1, 0, At, B0); PG8_BAR; PG8_SCHED;
;             PG8_STAGE(PG8_SB(1, 1), b3 + hstep);
;             PG8_WAIT_V(6); PG8_BAR; PG8_MMA(1, 1, At, B1); PG8_BAR;
;         }
;     template <bool LN, int BJ> DI void load_gb(unsigned col0, f32x4 (&gv)[2], f32x4 (&bv)[2]) const {
; #pragma unroll
;         for (int n = 0; n < 2; ++n) {
;             if (LN) { gv[n] = *(const f32x4*)(gam + col0 + BJ * HALF + n * 16) * ALPHA; bv[n] = *(const f32x4*)(bet + col0 + BJ * HALF + n * 16) * ALPHA; }
;             else { gv[n] = (f32x4){ALPHA, ALPHA, ALPHA, ALPHA}; bv[n] = (f32x4){0.f, 0.f, 0.f, 0.f}; }
;         }
;     }
;     template <bool LN> DI void run(const f32x4 (&acc)[2][2][4][2], const Unit& u, int wr, int wc, int fr, int fq) const {
;         const unsigned row0 = u.pm * BM + wr * 64 + fr, col0 = u.pn * BM + wc * 32 + 4 * fq;
;         f32x4 gv[2], bv[2];
;         load_gb<LN, 0>(col0, gv, bv);
;         batch<LN, 0, 0, 4>(acc, row0, col0, gv, bv);
;         batch<LN, 0, 4, 8>(acc, row0, col0, gv, bv);
;         batch<LN, 0, 8, 12>(acc, row0, col0, gv, bv);
	v_mfma_f32_16x16x32_bf16 v[92:95], v[96:99], v[152:155], v[92:95]
	v_mfma_f32_16x16x32_bf16 v[88:91], v[136:139], v[152:155], v[88:91]
	v_mfma_f32_16x16x32_bf16 v[84:87], v[96:99], v[190:193], v[84:87]
	v_mfma_f32_16x16x32_bf16 v[80:83], v[136:139], v[190:193], v[80:83]
	v_mfma_f32_16x16x32_bf16 v[76:79], v[96:99], v[202:205], v[76:79]
	v_mfma_f32_16x16x32_bf16 v[72:75], v[136:139], v[202:205], v[72:75]
	v_mfma_f32_16x16x32_bf16 v[68:71], v[96:99], v[210:213], v[68:71]
	v_mfma_f32_16x16x32_bf16 v[64:67], v[136:139], v[210:213], v[64:67]
	v_mfma_f32_16x16x32_bf16 v[92:95], v[100:103], v[186:189], v[92:95]
	v_mfma_f32_16x16x32_bf16 v[88:91], v[148:151], v[186:189], v[88:91]
	v_mfma_f32_16x16x32_bf16 v[84:87], v[100:103], v[194:197], v[84:87]
	v_mfma_f32_16x16x32_bf16 v[80:83], v[148:151], v[194:197], v[80:83]
	v_mfma_f32_16x16x32_bf16 v[76:79], v[100:103], v[206:209], v[76:79]
	v_mfma_f32_16x16x32_bf16 v[72:75], v[148:151], v[206:209], v[72:75]
	v_mfma_f32_16x16x32_bf16 v[68:71], v[100:103], v[214:217], v[68:71]
	v_mfma_f32_16x16x32_bf16 v[64:67], v[148:151], v[214:217], v[64:67]
	s_barrier
	s_add_u32 s16, s20, 0x160080
	s_addc_u32 s17, s21, 0
	s_add_i32 s20, s22, s27
	s_mov_b32 m0, s20
	s_nop 0
	global_load_lds_dwordx4 v142, s[16:17]
	s_add_i32 m0, s20, 0x2000
	s_nop 0
	global_load_lds_dwordx4 v140, s[16:17]
	s_waitcnt vmcnt(6)
	s_barrier
	v_mfma_f32_16x16x32_bf16 v[28:31], v[226:229], v[152:155], v[28:31]
	v_mfma_f32_16x16x32_bf16 v[24:27], v[234:237], v[152:155], v[24:27]
	v_mfma_f32_16x16x32_bf16 v[20:23], v[226:229], v[190:193], v[20:23]
	v_mfma_f32_16x16x32_bf16 v[16:19], v[234:237], v[190:193], v[16:19]
	v_mfma_f32_16x16x32_bf16 v[12:15], v[226:229], v[202:205], v[12:15]
	v_mfma_f32_16x16x32_bf16 v[8:11], v[234:237], v[202:205], v[8:11]
	v_mfma_f32_16x16x32_bf16 v[4:7], v[226:229], v[210:213], v[4:7]
	v_mfma_f32_16x16x32_bf16 v[0:3], v[234:237], v[210:213], v[0:3]
	v_mfma_f32_16x16x32_bf16 v[28:31], v[230:233], v[186:189], v[28:31]
	s_add_i32 s33, s33, 2
	v_mfma_f32_16x16x32_bf16 v[24:27], v[238:241], v[186:189], v[24:27]
	s_add_u32 s4, s4, 0x100
	v_mfma_f32_16x16x32_bf16 v[20:23], v[230:233], v[194:197], v[20:23]
	s_addc_u32 s5, s5, 0
	v_mfma_f32_16x16x32_bf16 v[16:19], v[238:241], v[194:197], v[16:19]
	s_cmpk_gt_u32 s33, 0x55
	v_mfma_f32_16x16x32_bf16 v[12:15], v[230:233], v[206:209], v[12:15]
	s_mov_b64 s[16:17], s[18:19]
	v_mfma_f32_16x16x32_bf16 v[8:11], v[238:241], v[206:209], v[8:11]
	v_mfma_f32_16x16x32_bf16 v[4:7], v[230:233], v[214:217], v[4:7]
	v_mfma_f32_16x16x32_bf16 v[0:3], v[238:241], v[214:217], v[0:3]
	s_barrier
	s_cbranch_scc0 .LBB0_134
	v_lshl_or_b32 v158, s2, 8, v200
	v_lshlrev_b64 v[100:101], 2, v[158:159]
	v_lshl_add_u64 v[150:151], s[12:13], 0, v[100:101]
	global_load_dwordx4 v[96:99], v[150:151], off
	v_lshl_add_u64 v[152:153], s[14:15], 0, v[100:101]
	v_lshl_add_u32 v203, s3, 8, v198
	v_lshlrev_b32_e32 v202, 11, v203
	v_add_u32_e32 v148, v202, v158
	v_mov_b32_e32 v149, v159
	v_lshlrev_b32_e32 v136, 1, v203
	v_mov_b32_e32 v137, v159
	v_lshlrev_b64 v[220:221], 2, v[148:149]
	v_lshl_add_u64 v[154:155], v[136:137], 2, s[96:97]
	v_lshl_add_u64 v[136:137], s[90:91], 0, v[220:221]
	v_or_b32_e32 v204, 16, v158
	v_or_b32_e32 v138, 16, v203
	v_lshlrev_b32_e32 v149, 11, v138
	s_waitcnt vmcnt(0)
	v_pk_mul_f32 v[192:193], v[98:99], s[78:79] op_sel_hi:[1,0]
	v_pk_mul_f32 v[194:195], v[96:97], s[78:79] op_sel_hi:[1,0]
	global_load_dwordx4 v[100:103], v[152:153], off
	global_load_dwordx4 v[96:99], v[150:151], off offset:64
	global_load_dwordx2 v[218:219], v[154:155], off
	global_load_dwordx4 v[206:209], v[136:137], off
	v_add_u32_e32 v136, v202, v204
	v_mov_b32_e32 v137, v159
	v_lshl_add_u64 v[136:137], v[136:137], 2, s[90:91]
	global_load_dwordx4 v[210:213], v[136:137], off
	v_lshlrev_b32_e32 v136, 1, v138
	v_mov_b32_e32 v137, v159
	v_lshl_add_u64 v[186:187], v[136:137], 2, s[96:97]
	v_add_u32_e32 v136, v149, v158
	v_lshl_add_u64 v[136:137], v[136:137], 2, s[90:91]
	global_load_dwordx2 v[196:197], v[186:187], off
	global_load_dwordx4 v[214:217], v[136:137], off
	v_add_u32_e32 v136, v149, v204
	v_mov_b32_e32 v137, v159
	v_lshl_add_u64 v[136:137], v[136:137], 2, s[90:91]
	global_load_dwordx4 v[136:139], v[136:137], off
	s_waitcnt vmcnt(0)
	v_pk_mul_f32 v[188:189], v[98:99], s[78:79] op_sel_hi:[1,0]
	v_pk_mul_f32 v[190:191], v[96:97], s[78:79] op_sel_hi:[1,0]
	global_load_dwordx4 v[96:99], v[152:153], off offset:64
	v_sub_f32_e32 v207, v207, v218
	v_sub_f32_e32 v206, v206, v218
	v_sub_f32_e32 v209, v209, v218
	v_sub_f32_e32 v208, v208, v218
	v_pk_mul_f32 v[208:209], v[218:219], v[208:209] op_sel:[1,0]
	v_pk_mul_f32 v[206:207], v[218:219], v[206:207] op_sel:[1,0]
	v_pk_fma_f32 v[134:135], v[192:193], v[208:209], v[134:135]
	v_pk_fma_f32 v[132:133], v[194:195], v[206:207], v[132:133]
	v_pk_fma_f32 v[134:135], v[102:103], s[78:79], v[134:135] op_sel_hi:[1,0,1]
	v_pk_fma_f32 v[132:133], v[100:101], s[78:79], v[132:133] op_sel_hi:[1,0,1]
	v_lshl_add_u64 v[206:207], s[88:89], 0, v[220:221]
	global_store_dwordx4 v[206:207], v[132:135], off
	s_nop 1
	v_sub_f32_e32 v133, v211, v218
	v_sub_f32_e32 v132, v210, v218
	v_sub_f32_e32 v135, v213, v218
	v_sub_f32_e32 v134, v212, v218
	v_pk_mul_f32 v[134:135], v[218:219], v[134:135] op_sel:[1,0]
	v_pk_mul_f32 v[132:133], v[218:219], v[132:133] op_sel:[1,0]
	v_pk_fma_f32 v[130:131], v[188:189], v[134:135], v[130:131]
	v_pk_fma_f32 v[128:129], v[190:191], v[132:133], v[128:129]
	v_or_b32_e32 v132, 16, v148
	v_mov_b32_e32 v133, v159
	v_lshl_add_u64 v[132:133], v[132:133], 2, s[88:89]
	s_waitcnt vmcnt(0)
;     template <bool LN, int BJ, int LO, int HI> DI void batch(const f32x4 (&acc)[2][2][4][2], unsigned row0, unsigned col0, const f32x4 (&gv)[2], const f32x4 (&bv)[2]) const {
;         f32x4 r[HI - LO]; float mean[(HI - LO) / 2], rstd[(HI - LO) / 2];
; #pragma unroll
;         for (int i = LO; i < HI; ++i) { const int ai = i >> 3, m = (i >> 1) & 3, n = i & 1; const unsigned row = row0 + ai * HALF + m * 16;
;             if (n == 0) { mean[(i - LO) >> 1] = 0.f; rstd[(i - LO) >> 1] = 1.f;
;                 if (LN) { const float2 st = *(const float2*)(stats + row * 2u); mean[(i - LO) >> 1] = st.x; rstd[(i - LO) >> 1] = st.y; } }
;             r[i - LO] = *(const f32x4*)(src + (row * (unsigned)DM + col0 + BJ * HALF + n * 16)); }
; #pragma unroll
;         for (int i = LO; i < HI; ++i) { const int ai = i >> 3, m = (i >> 1) & 3, n = i & 1; const unsigned row = row0 + ai * HALF + m * 16;
;             *(f32x4*)(Y + (row * (unsigned)DM + col0 + BJ * HALF + n * 16)) = acc[ai][BJ][m][n] + ((r[i - LO] - mean[(i - LO) >> 1]) * rstd[(i - LO) >> 1]) * gv[n] + bv[n]; }
;         __builtin_amdgcn_sched_barrier(0);
;     }
;     template <bool LN, int BJ> DI void load_gb(unsigned col0, f32x4 (&gv)[2], f32x4 (&bv)[2]) const {
; #pragma unroll
;         for (int n = 0; n < 2; ++n) {
;             if (LN) { gv[n] = *(const f32x4*)(gam + col0 + BJ * HALF + n * 16) * ALPHA; bv[n] = *(const f32x4*)(bet + col0 + BJ * HALF + n * 16) * ALPHA; }
;             else { gv[n] = (f32x4){ALPHA, ALPHA, ALPHA, ALPHA}; bv[n] = (f32x4){0.f, 0.f, 0.f, 0.f}; }
;         }
;     }
;     template <bool LN> DI void run(const f32x4 (&acc)[2][2][4][2], const Unit& u, int wr, int wc, int fr, int fq) const {
;         const unsigned row0 = u.pm * BM + wr * 64 + fr, col0 = u.pn * BM + wc * 32 + 4 * fq;
;         f32x4 gv[2], bv[2];
;         load_gb<LN, 0>(col0, gv, bv);
;         batch<LN, 0, 0, 4>(acc, row0, col0, gv, bv);
;         batch<LN, 0, 4, 8>(acc, row0, col0, gv, bv);
;         batch<LN, 0, 8, 12>(acc, row0, col0, gv, bv);
;         batch<LN, 0, 12, 16>(acc, row0, col0, gv, bv);
	v_pk_fma_f32 v[130:131], v[98:99], s[78:79], v[130:131] op_sel_hi:[1,0,1]
	v_pk_fma_f32 v[128:129], v[96:97], s[78:79], v[128:129] op_sel_hi:[1,0,1]
	global_store_dwordx4 v[132:133], v[128:131], off
	s_nop 1
	v_sub_f32_e32 v129, v215, v196
	v_sub_f32_e32 v128, v214, v196
	v_sub_f32_e32 v131, v217, v196
	v_sub_f32_e32 v130, v216, v196
	v_pk_mul_f32 v[130:131], v[196:197], v[130:131] op_sel:[1,0]
	v_pk_mul_f32 v[128:129], v[196:197], v[128:129] op_sel:[1,0]
	v_pk_fma_f32 v[126:127], v[192:193], v[130:131], v[126:127]
	v_pk_fma_f32 v[124:125], v[194:195], v[128:129], v[124:125]
	v_add_u32_e32 v128, 0x8000, v148
	v_mov_b32_e32 v129, v159
	v_pk_fma_f32 v[126:127], v[102:103], s[78:79], v[126:127] op_sel_hi:[1,0,1]
	v_pk_fma_f32 v[124:125], v[100:101], s[78:79], v[124:125] op_sel_hi:[1,0,1]
	v_lshl_add_u64 v[128:129], v[128:129], 2, s[88:89]
	global_store_dwordx4 v[128:129], v[124:127], off
	s_nop 1
	v_sub_f32_e32 v125, v137, v196
	v_sub_f32_e32 v124, v136, v196
	v_sub_f32_e32 v127, v139, v196
	v_sub_f32_e32 v126, v138, v196
	v_pk_mul_f32 v[126:127], v[196:197], v[126:127] op_sel:[1,0]
	v_pk_mul_f32 v[124:125], v[196:197], v[124:125] op_sel:[1,0]
	v_pk_fma_f32 v[122:123], v[188:189], v[126:127], v[122:123]
	v_pk_fma_f32 v[120:121], v[190:191], v[124:125], v[120:121]
	v_add_u32_e32 v124, 0x8010, v148
	v_mov_b32_e32 v125, v159
	v_pk_fma_f32 v[122:123], v[98:99], s[78:79], v[122:123] op_sel_hi:[1,0,1]
	v_pk_fma_f32 v[120:121], v[96:97], s[78:79], v[120:121] op_sel_hi:[1,0,1]
	v_lshl_add_u64 v[124:125], v[124:125], 2, s[88:89]
	global_store_dwordx4 v[124:125], v[120:123], off
	s_nop 1
	v_or_b32_e32 v122, 32, v203
	v_lshlrev_b32_e32 v124, 11, v122
	v_lshlrev_b32_e32 v120, 1, v122
	v_mov_b32_e32 v121, v159
	v_add_u32_e32 v122, v124, v158
	v_mov_b32_e32 v123, v159
	v_lshl_add_u64 v[120:121], v[120:121], 2, s[96:97]
	v_lshl_add_u64 v[122:123], v[122:123], 2, s[90:91]
	global_load_dwordx2 v[138:139], v[120:121], off
	global_load_dwordx4 v[126:129], v[122:123], off
	v_add_u32_e32 v122, v124, v204
	v_mov_b32_e32 v123, v159
	v_lshl_add_u64 v[122:123], v[122:123], 2, s[90:91]
	global_load_dwordx4 v[130:133], v[122:123], off
	v_or_b32_e32 v125, 48, v203
	v_lshlrev_b32_e32 v122, 1, v125
	v_lshlrev_b32_e32 v125, 11, v125
	v_mov_b32_e32 v123, v159
	v_add_u32_e32 v134, v125, v158
	v_mov_b32_e32 v135, v159
	v_lshl_add_u64 v[122:123], v[122:123], 2, s[96:97]
	v_lshl_add_u64 v[134:135], v[134:135], 2, s[90:91]
	global_load_dwordx2 v[196:197], v[122:123], off
	v_add_u32_e32 v206, v125, v204
	global_load_dwordx4 v[134:137], v[134:135], off
	v_mov_b32_e32 v207, v159
	v_lshl_add_u64 v[206:207], v[206:207], 2, s[90:91]
	global_load_dwordx4 v[206:209], v[206:207], off
	s_waitcnt vmcnt(0)
	v_sub_f32_e32 v127, v127, v138
	v_sub_f32_e32 v126, v126, v138
	v_sub_f32_e32 v129, v129, v138
	v_sub_f32_e32 v128, v128, v138
	v_pk_mul_f32 v[128:129], v[138:139], v[128:129] op_sel:[1,0]
	v_pk_mul_f32 v[126:127], v[138:139], v[126:127] op_sel:[1,0]
	v_pk_fma_f32 v[118:119], v[192:193], v[128:129], v[118:119]
	v_pk_fma_f32 v[116:117], v[194:195], v[126:127], v[116:117]
	v_add_u32_e32 v126, 0x10000, v148
	v_mov_b32_e32 v127, v159
	v_pk_fma_f32 v[118:119], v[102:103], s[78:79], v[118:119] op_sel_hi:[1,0,1]
	v_pk_fma_f32 v[116:117], v[100:101], s[78:79], v[116:117] op_sel_hi:[1,0,1]
	v_lshl_add_u64 v[126:127], v[126:127], 2, s[88:89]
	global_store_dwordx4 v[126:127], v[116:119], off
	s_nop 1
	v_sub_f32_e32 v117, v131, v138
	v_sub_f32_e32 v116, v130, v138
	v_sub_f32_e32 v119, v133, v138
	v_sub_f32_e32 v118, v132, v138
	v_pk_mul_f32 v[118:119], v[138:139], v[118:119] op_sel:[1,0]
	v_pk_mul_f32 v[116:117], v[138:139], v[116:117] op_sel:[1,0]
	v_pk_fma_f32 v[114:115], v[188:189], v[118:119], v[114:115]
	v_pk_fma_f32 v[112:113], v[190:191], v[116:117], v[112:113]
	v_add_u32_e32 v116, 0x10010, v148
	v_mov_b32_e32 v117, v159
	v_pk_fma_f32 v[114:115], v[98:99], s[78:79], v[114:115] op_sel_hi:[1,0,1]
	v_pk_fma_f32 v[112:113], v[96:97], s[78:79], v[112:113] op_sel_hi:[1,0,1]
	v_lshl_add_u64 v[116:117], v[116:117], 2, s[88:89]
	global_store_dwordx4 v[116:117], v[112:115], off
	s_nop 1
	v_sub_f32_e32 v113, v135, v196
	v_sub_f32_e32 v112, v134, v196
	v_sub_f32_e32 v115, v137, v196
	v_sub_f32_e32 v114, v136, v196
	v_pk_mul_f32 v[114:115], v[196:197], v[114:115] op_sel:[1,0]
	v_pk_mul_f32 v[112:113], v[196:197], v[112:113] op_sel:[1,0]
	v_pk_fma_f32 v[110:111], v[192:193], v[114:115], v[110:111]
	v_pk_fma_f32 v[108:109], v[194:195], v[112:113], v[108:109]
	v_add_u32_e32 v112, 0x18000, v148
	v_mov_b32_e32 v113, v159
	v_pk_fma_f32 v[110:111], v[102:103], s[78:79], v[110:111] op_sel_hi:[1,0,1]
	v_pk_fma_f32 v[108:109], v[100:101], s[78:79], v[108:109] op_sel_hi:[1,0,1]
	v_lshl_add_u64 v[112:113], v[112:113], 2, s[88:89]
	global_store_dwordx4 v[112:113], v[108:111], off
	s_nop 1
	v_sub_f32_e32 v109, v207, v196
	v_sub_f32_e32 v108, v206, v196
	v_sub_f32_e32 v111, v209, v196
	v_sub_f32_e32 v110, v208, v196
	v_pk_mul_f32 v[110:111], v[196:197], v[110:111] op_sel:[1,0]
	v_pk_mul_f32 v[108:109], v[196:197], v[108:109] op_sel:[1,0]
	v_pk_fma_f32 v[106:107], v[188:189], v[110:111], v[106:107]
	v_pk_fma_f32 v[104:105], v[190:191], v[108:109], v[104:105]
	v_add_u32_e32 v108, 0x18010, v148
	v_mov_b32_e32 v109, v159
	v_pk_fma_f32 v[106:107], v[98:99], s[78:79], v[106:107] op_sel_hi:[1,0,1]
	v_pk_fma_f32 v[104:105], v[96:97], s[78:79], v[104:105] op_sel_hi:[1,0,1]
	v_lshl_add_u64 v[108:109], v[108:109], 2, s[88:89]
	global_store_dwordx4 v[108:109], v[104:107], off
	s_nop 1
	v_add_u32_e32 v106, 0x80, v203
	v_lshlrev_b32_e32 v114, 11, v106
	v_lshlrev_b32_e32 v104, 1, v106
	v_mov_b32_e32 v105, v159
	v_add_u32_e32 v106, v114, v158
	v_mov_b32_e32 v107, v159
	v_lshl_add_u64 v[104:105], v[104:105], 2, s[96:97]
	v_lshl_add_u64 v[106:107], v[106:107], 2, s[90:91]
	global_load_dwordx2 v[112:113], v[104:105], off
	global_load_dwordx4 v[108:111], v[106:107], off
	v_add_u32_e32 v106, v114, v204
	v_mov_b32_e32 v107, v159
	v_lshl_add_u64 v[106:107], v[106:107], 2, s[90:91]
	global_load_dwordx4 v[116:119], v[106:107], off
	v_add_u32_e32 v115, 0x90, v203
	v_lshlrev_b32_e32 v106, 1, v115
	v_lshlrev_b32_e32 v115, 11, v115
	v_mov_b32_e32 v107, v159
	v_add_u32_e32 v126, v115, v158
	v_mov_b32_e32 v127, v159
	v_lshl_add_u64 v[106:107], v[106:107], 2, s[96:97]
	v_lshl_add_u64 v[126:127], v[126:127], 2, s[90:91]
	global_load_dwordx2 v[134:135], v[106:107], off
	v_add_u32_e32 v130, v115, v204
	global_load_dwordx4 v[126:129], v[126:127], off
	v_mov_b32_e32 v131, v159
	v_lshl_add_u64 v[130:131], v[130:131], 2, s[90:91]
	global_load_dwordx4 v[130:133], v[130:131], off
	s_waitcnt vmcnt(0)
;     template <bool LN, int BJ, int LO, int HI> DI void batch(const f32x4 (&acc)[2][2][4][2], unsigned row0, unsigned col0, const f32x4 (&gv)[2], const f32x4 (&bv)[2]) const {
;         f32x4 r[HI - LO]; float mean[(HI - LO) / 2], rstd[(HI - LO) / 2];
; #pragma unroll
;         for (int i = LO; i < HI; ++i) { const int ai = i >> 3, m = (i >> 1) & 3, n = i & 1; const unsigned row = row0 + ai * HALF + m * 16;
;             if (n == 0) { mean[(i - LO) >> 1] = 0.f; rstd[(i - LO) >> 1] = 1.f;
;                 if (LN) { const float2 st = *(const float2*)(stats + row * 2u); mean[(i - LO) >> 1] = st.x; rstd[(i - LO) >> 1] = st.y; } }
;             r[i - LO] = *(const f32x4*)(src + (row * (unsigned)DM + col0 + BJ * HALF + n * 16)); }
; #pragma unroll
;         for (int i = LO; i < HI; ++i) { const int ai = i >> 3, m = (i >> 1) & 3, n = i & 1; const unsigned row = row0 + ai * HALF + m * 16;
;             *(f32x4*)(Y + (row * (unsigned)DM + col0 + BJ * HALF + n * 16)) = acc[ai][BJ][m][n] + ((r[i - LO] - mean[(i - LO) >> 1]) * rstd[(i - LO) >> 1]) * gv[n] + bv[n]; }
;         __builtin_amdgcn_sched_barrier(0);
;     }
;     template <bool LN, int BJ> DI void load_gb(unsigned col0, f32x4 (&gv)[2], f32x4 (&bv)[2]) const {
; #pragma unroll
;         for (int n = 0; n < 2; ++n) {
;             if (LN) { gv[n] = *(const f32x4*)(gam + col0 + BJ * HALF + n * 16) * ALPHA; bv[n] = *(const f32x4*)(bet + col0 + BJ * HALF + n * 16) * ALPHA; }
;             else { gv[n] = (f32x4){ALPHA, ALPHA, ALPHA, ALPHA}; bv[n] = (f32x4){0.f, 0.f, 0.f, 0.f}; }
;         }
;     }
;     template <bool LN> DI void run(const f32x4 (&acc)[2][2][4][2], const Unit& u, int wr, int wc, int fr, int fq) const {
;         const unsigned row0 = u.pm * BM + wr * 64 + fr, col0 = u.pn * BM + wc * 32 + 4 * fq;
;         f32x4 gv[2], bv[2];
;         load_gb<LN, 0>(col0, gv, bv);
;         batch<LN, 0, 0, 4>(acc, row0, col0, gv, bv);
;         batch<LN, 0, 4, 8>(acc, row0, col0, gv, bv);
;         batch<LN, 0, 8, 12>(acc, row0, col0, gv, bv);
;         batch<LN, 0, 12, 16>(acc, row0, col0, gv, bv);
;         load_gb<LN, 1>(col0, gv, bv);
	v_sub_f32_e32 v109, v109, v112
	v_sub_f32_e32 v108, v108, v112
	v_sub_f32_e32 v111, v111, v112
	v_sub_f32_e32 v110, v110, v112
	v_pk_mul_f32 v[110:111], v[112:113], v[110:111] op_sel:[1,0]
	v_pk_mul_f32 v[108:109], v[112:113], v[108:109] op_sel:[1,0]
	v_pk_fma_f32 v[94:95], v[192:193], v[110:111], v[94:95]
	v_pk_fma_f32 v[92:93], v[194:195], v[108:109], v[92:93]
	v_add_u32_e32 v108, 0x40000, v148
	v_mov_b32_e32 v109, v159
	v_pk_fma_f32 v[94:95], v[102:103], s[78:79], v[94:95] op_sel_hi:[1,0,1]
	v_pk_fma_f32 v[92:93], v[100:101], s[78:79], v[92:93] op_sel_hi:[1,0,1]
	v_lshl_add_u64 v[108:109], v[108:109], 2, s[88:89]
	global_store_dwordx4 v[108:109], v[92:95], off
	s_nop 1
	v_sub_f32_e32 v93, v117, v112
	v_sub_f32_e32 v92, v116, v112
	v_sub_f32_e32 v95, v119, v112
	v_sub_f32_e32 v94, v118, v112
	v_pk_mul_f32 v[94:95], v[112:113], v[94:95] op_sel:[1,0]
	v_pk_mul_f32 v[92:93], v[112:113], v[92:93] op_sel:[1,0]
	v_pk_fma_f32 v[90:91], v[188:189], v[94:95], v[90:91]
	v_pk_fma_f32 v[88:89], v[190:191], v[92:93], v[88:89]
	v_add_u32_e32 v92, 0x40010, v148
	v_mov_b32_e32 v93, v159
	v_pk_fma_f32 v[90:91], v[98:99], s[78:79], v[90:91] op_sel_hi:[1,0,1]
	v_pk_fma_f32 v[88:89], v[96:97], s[78:79], v[88:89] op_sel_hi:[1,0,1]
	v_lshl_add_u64 v[92:93], v[92:93], 2, s[88:89]
	global_store_dwordx4 v[92:93], v[88:91], off
	s_nop 1
	v_sub_f32_e32 v89, v127, v134
	v_sub_f32_e32 v88, v126, v134
	v_sub_f32_e32 v91, v129, v134
	v_sub_f32_e32 v90, v128, v134
	v_pk_mul_f32 v[90:91], v[134:135], v[90:91] op_sel:[1,0]
	v_pk_mul_f32 v[88:89], v[134:135], v[88:89] op_sel:[1,0]
	v_pk_fma_f32 v[86:87], v[192:193], v[90:91], v[86:87]
	v_pk_fma_f32 v[84:85], v[194:195], v[88:89], v[84:85]
	v_add_u32_e32 v88, 0x48000, v148
	v_mov_b32_e32 v89, v159
	v_pk_fma_f32 v[86:87], v[102:103], s[78:79], v[86:87] op_sel_hi:[1,0,1]
	v_pk_fma_f32 v[84:85], v[100:101], s[78:79], v[84:85] op_sel_hi:[1,0,1]
	v_lshl_add_u64 v[88:89], v[88:89], 2, s[88:89]
	global_store_dwordx4 v[88:89], v[84:87], off
	s_nop 1
	v_sub_f32_e32 v85, v131, v134
	v_sub_f32_e32 v84, v130, v134
	v_sub_f32_e32 v87, v133, v134
	v_sub_f32_e32 v86, v132, v134
	v_pk_mul_f32 v[86:87], v[134:135], v[86:87] op_sel:[1,0]
	v_pk_mul_f32 v[84:85], v[134:135], v[84:85] op_sel:[1,0]
	v_pk_fma_f32 v[82:83], v[188:189], v[86:87], v[82:83]
	v_pk_fma_f32 v[80:81], v[190:191], v[84:85], v[80:81]
	v_add_u32_e32 v84, 0x48010, v148
	v_mov_b32_e32 v85, v159
	v_pk_fma_f32 v[82:83], v[98:99], s[78:79], v[82:83] op_sel_hi:[1,0,1]
	v_pk_fma_f32 v[80:81], v[96:97], s[78:79], v[80:81] op_sel_hi:[1,0,1]
	v_lshl_add_u64 v[84:85], v[84:85], 2, s[88:89]
	global_store_dwordx4 v[84:85], v[80:83], off
	s_nop 1
	v_add_u32_e32 v82, 0xa0, v203
	v_lshlrev_b32_e32 v80, 1, v82
	v_mov_b32_e32 v81, v159
	v_lshlrev_b32_e32 v116, 11, v82
	v_lshl_add_u64 v[108:109], v[80:81], 2, s[96:97]
	v_add_u32_e32 v80, v116, v158
	v_lshl_add_u64 v[80:81], v[80:81], 2, s[90:91]
	global_load_dwordx2 v[112:113], v[108:109], off
	v_add_u32_e32 v84, v116, v204
	global_load_dwordx4 v[80:83], v[80:81], off
	v_mov_b32_e32 v85, v159
	v_lshl_add_u64 v[84:85], v[84:85], 2, s[90:91]
	global_load_dwordx4 v[84:87], v[84:85], off
	v_add_u32_e32 v90, 0xb0, v203
	v_lshlrev_b32_e32 v88, 1, v90
	v_mov_b32_e32 v89, v159
	v_lshlrev_b32_e32 v117, 11, v90
	v_lshl_add_u64 v[110:111], v[88:89], 2, s[96:97]
	v_add_u32_e32 v88, v117, v158
	v_lshl_add_u64 v[88:89], v[88:89], 2, s[90:91]
	global_load_dwordx2 v[118:119], v[110:111], off
	v_add_u32_e32 v92, v117, v204
	global_load_dwordx4 v[88:91], v[88:89], off
	v_mov_b32_e32 v93, v159
	v_lshl_add_u64 v[92:93], v[92:93], 2, s[90:91]
	global_load_dwordx4 v[92:95], v[92:93], off
	s_waitcnt vmcnt(0)
	v_sub_f32_e32 v81, v81, v112
	v_sub_f32_e32 v80, v80, v112
	v_sub_f32_e32 v83, v83, v112
	v_sub_f32_e32 v82, v82, v112
	v_pk_mul_f32 v[82:83], v[112:113], v[82:83] op_sel:[1,0]
	v_pk_mul_f32 v[80:81], v[112:113], v[80:81] op_sel:[1,0]
	v_pk_fma_f32 v[78:79], v[192:193], v[82:83], v[78:79]
	v_pk_fma_f32 v[76:77], v[194:195], v[80:81], v[76:77]
	v_add_u32_e32 v80, 0x50000, v148
	v_mov_b32_e32 v81, v159
	v_pk_fma_f32 v[78:79], v[102:103], s[78:79], v[78:79] op_sel_hi:[1,0,1]
	v_pk_fma_f32 v[76:77], v[100:101], s[78:79], v[76:77] op_sel_hi:[1,0,1]
	v_lshl_add_u64 v[80:81], v[80:81], 2, s[88:89]
	global_store_dwordx4 v[80:81], v[76:79], off
	s_nop 1
	v_sub_f32_e32 v77, v85, v112
	v_sub_f32_e32 v76, v84, v112
	v_sub_f32_e32 v79, v87, v112
	v_sub_f32_e32 v78, v86, v112
	v_pk_mul_f32 v[78:79], v[112:113], v[78:79] op_sel:[1,0]
	v_pk_mul_f32 v[76:77], v[112:113], v[76:77] op_sel:[1,0]
	v_pk_fma_f32 v[74:75], v[188:189], v[78:79], v[74:75]
	v_pk_fma_f32 v[72:73], v[190:191], v[76:77], v[72:73]
	v_add_u32_e32 v76, 0x50010, v148
	v_mov_b32_e32 v77, v159
	v_pk_fma_f32 v[74:75], v[98:99], s[78:79], v[74:75] op_sel_hi:[1,0,1]
	v_pk_fma_f32 v[72:73], v[96:97], s[78:79], v[72:73] op_sel_hi:[1,0,1]
	v_lshl_add_u64 v[76:77], v[76:77], 2, s[88:89]
	global_store_dwordx4 v[76:77], v[72:75], off
	s_nop 1
	v_sub_f32_e32 v73, v89, v118
	v_sub_f32_e32 v72, v88, v118
	v_sub_f32_e32 v75, v91, v118
	v_sub_f32_e32 v74, v90, v118
	v_pk_mul_f32 v[74:75], v[118:119], v[74:75] op_sel:[1,0]
	v_pk_mul_f32 v[72:73], v[118:119], v[72:73] op_sel:[1,0]
	v_pk_fma_f32 v[70:71], v[192:193], v[74:75], v[70:71]
	v_pk_fma_f32 v[68:69], v[194:195], v[72:73], v[68:69]
	v_add_u32_e32 v72, 0x58000, v148
	v_mov_b32_e32 v73, v159
	v_pk_fma_f32 v[70:71], v[102:103], s[78:79], v[70:71] op_sel_hi:[1,0,1]
	v_pk_fma_f32 v[68:69], v[100:101], s[78:79], v[68:69] op_sel_hi:[1,0,1]
	v_lshl_add_u64 v[72:73], v[72:73], 2, s[88:89]
	global_store_dwordx4 v[72:73], v[68:71], off
	s_nop 1
	v_sub_f32_e32 v69, v93, v118
	v_sub_f32_e32 v68, v92, v118
	v_sub_f32_e32 v71, v95, v118
	v_sub_f32_e32 v70, v94, v118
	v_pk_mul_f32 v[70:71], v[118:119], v[70:71] op_sel:[1,0]
	v_pk_mul_f32 v[68:69], v[118:119], v[68:69] op_sel:[1,0]
	v_pk_fma_f32 v[66:67], v[188:189], v[70:71], v[66:67]
	v_pk_fma_f32 v[64:65], v[190:191], v[68:69], v[64:65]
	v_add_u32_e32 v68, 0x58010, v148
	v_mov_b32_e32 v69, v159
	v_pk_fma_f32 v[66:67], v[98:99], s[78:79], v[66:67] op_sel_hi:[1,0,1]
	v_pk_fma_f32 v[64:65], v[96:97], s[78:79], v[64:65] op_sel_hi:[1,0,1]
	v_lshl_add_u64 v[68:69], v[68:69], 2, s[88:89]
	global_store_dwordx4 v[68:69], v[64:67], off
	global_load_dwordx4 v[64:67], v[150:151], off offset:512
	v_or_b32_e32 v119, 0x80, v158
	v_add_u32_e32 v72, v202, v119
	v_mov_b32_e32 v73, v159
	v_lshl_add_u64 v[72:73], v[72:73], 2, s[90:91]
	v_or_b32_e32 v118, 0x90, v158
	v_add_u32_e32 v158, v202, v118
	s_waitcnt vmcnt(0)
;     template <bool LN, int BJ, int LO, int HI> DI void batch(const f32x4 (&acc)[2][2][4][2], unsigned row0, unsigned col0, const f32x4 (&gv)[2], const f32x4 (&bv)[2]) const {
;         f32x4 r[HI - LO]; float mean[(HI - LO) / 2], rstd[(HI - LO) / 2];
; #pragma unroll
;         for (int i = LO; i < HI; ++i) { const int ai = i >> 3, m = (i >> 1) & 3, n = i & 1; const unsigned row = row0 + ai * HALF + m * 16;
;             if (n == 0) { mean[(i - LO) >> 1] = 0.f; rstd[(i - LO) >> 1] = 1.f;
;                 if (LN) { const float2 st = *(const float2*)(stats + row * 2u); mean[(i - LO) >> 1] = st.x; rstd[(i - LO) >> 1] = st.y; } }
;             r[i - LO] = *(const f32x4*)(src + (row * (unsigned)DM + col0 + BJ * HALF + n * 16)); }
; #pragma unroll
;         for (int i = LO; i < HI; ++i) { const int ai = i >> 3, m = (i >> 1) & 3, n = i & 1; const unsigned row = row0 + ai * HALF + m * 16;
;             *(f32x4*)(Y + (row * (unsigned)DM + col0 + BJ * HALF + n * 16)) = acc[ai][BJ][m][n] + ((r[i - LO] - mean[(i - LO) >> 1]) * rstd[(i - LO) >> 1]) * gv[n] + bv[n]; }
;         __builtin_amdgcn_sched_barrier(0);
;     }
;     template <bool LN, int BJ> DI void load_gb(unsigned col0, f32x4 (&gv)[2], f32x4 (&bv)[2]) const {
; #pragma unroll
;         for (int n = 0; n < 2; ++n) {
;             if (LN) { gv[n] = *(const f32x4*)(gam + col0 + BJ * HALF + n * 16) * ALPHA; bv[n] = *(const f32x4*)(bet + col0 + BJ * HALF + n * 16) * ALPHA; }
;             else { gv[n] = (f32x4){ALPHA, ALPHA, ALPHA, ALPHA}; bv[n] = (f32x4){0.f, 0.f, 0.f, 0.f}; }
;         }
;     }
;     template <bool LN> DI void run(const f32x4 (&acc)[2][2][4][2], const Unit& u, int wr, int wc, int fr, int fq) const {
;         const unsigned row0 = u.pm * BM + wr * 64 + fr, col0 = u.pn * BM + wc * 32 + 4 * fq;
;         f32x4 gv[2], bv[2];
;         load_gb<LN, 0>(col0, gv, bv);
;         batch<LN, 0, 0, 4>(acc, row0, col0, gv, bv);
;         batch<LN, 0, 4, 8>(acc, row0, col0, gv, bv);
;         batch<LN, 0, 8, 12>(acc, row0, col0, gv, bv);
;         batch<LN, 0, 12, 16>(acc, row0, col0, gv, bv);
;         load_gb<LN, 1>(col0, gv, bv);
;         batch<LN, 1, 0, 8>(acc, row0, col0, gv, bv);
;         batch<LN, 1, 8, 16>(acc, row0, col0, gv, bv);
	v_pk_mul_f32 v[96:97], v[66:67], s[78:79] op_sel_hi:[1,0]
	v_pk_mul_f32 v[98:99], v[64:65], s[78:79] op_sel_hi:[1,0]
	global_load_dwordx4 v[68:71], v[152:153], off offset:512
	global_load_dwordx4 v[64:67], v[150:151], off offset:576
	global_load_dwordx2 v[138:139], v[154:155], off
	global_load_dwordx4 v[126:129], v[72:73], off
	v_lshl_add_u64 v[72:73], v[158:159], 2, s[90:91]
	v_add_u32_e32 v158, v149, v119
	s_waitcnt vmcnt(0)
	v_pk_mul_f32 v[92:93], v[66:67], s[78:79] op_sel_hi:[1,0]
	v_pk_mul_f32 v[94:95], v[64:65], s[78:79] op_sel_hi:[1,0]
	global_load_dwordx4 v[64:67], v[152:153], off offset:576
	global_load_dwordx4 v[130:133], v[72:73], off
	global_load_dwordx2 v[112:113], v[186:187], off
	v_lshl_add_u64 v[72:73], v[158:159], 2, s[90:91]
	global_load_dwordx4 v[134:137], v[72:73], off
	v_add_u32_e32 v158, v149, v118
	v_lshl_add_u64 v[72:73], v[158:159], 2, s[90:91]
	global_load_dwordx4 v[88:91], v[72:73], off
	global_load_dwordx2 v[102:103], v[120:121], off
	v_add_u32_e32 v158, v124, v119
	v_lshl_add_u64 v[72:73], v[158:159], 2, s[90:91]
	global_load_dwordx4 v[84:87], v[72:73], off
	v_add_u32_e32 v158, v124, v118
	v_lshl_add_u64 v[72:73], v[158:159], 2, s[90:91]
	global_load_dwordx4 v[80:83], v[72:73], off
	global_load_dwordx2 v[100:101], v[122:123], off
	v_add_u32_e32 v158, v125, v119
	v_lshl_add_u64 v[72:73], v[158:159], 2, s[90:91]
	global_load_dwordx4 v[76:79], v[72:73], off
	v_add_u32_e32 v158, v125, v118
	v_lshl_add_u64 v[72:73], v[158:159], 2, s[90:91]
	global_load_dwordx4 v[72:75], v[72:73], off
	v_sub_f32_e32 v121, v127, v138
	v_sub_f32_e32 v120, v126, v138
	v_sub_f32_e32 v123, v129, v138
	v_sub_f32_e32 v122, v128, v138
	v_pk_mul_f32 v[122:123], v[138:139], v[122:123] op_sel:[1,0]
	v_pk_mul_f32 v[120:121], v[138:139], v[120:121] op_sel:[1,0]
	v_or_b32_e32 v158, 0x80, v148
	v_pk_fma_f32 v[60:61], v[98:99], v[120:121], v[60:61]
	v_pk_fma_f32 v[62:63], v[96:97], v[122:123], v[62:63]
	v_pk_fma_f32 v[60:61], v[68:69], s[78:79], v[60:61] op_sel_hi:[1,0,1]
	v_pk_fma_f32 v[62:63], v[70:71], s[78:79], v[62:63] op_sel_hi:[1,0,1]
	v_lshl_add_u64 v[120:121], v[158:159], 2, s[88:89]
	global_store_dwordx4 v[120:121], v[60:63], off
	v_or_b32_e32 v158, 0x90, v148
	s_waitcnt vmcnt(0)
	v_sub_f32_e32 v61, v131, v138
	v_sub_f32_e32 v60, v130, v138
	v_sub_f32_e32 v63, v133, v138
	v_sub_f32_e32 v62, v132, v138
	v_pk_mul_f32 v[62:63], v[138:139], v[62:63] op_sel:[1,0]
	v_pk_mul_f32 v[60:61], v[138:139], v[60:61] op_sel:[1,0]
	v_pk_fma_f32 v[58:59], v[92:93], v[62:63], v[58:59]
	v_pk_fma_f32 v[56:57], v[94:95], v[60:61], v[56:57]
	v_pk_fma_f32 v[58:59], v[66:67], s[78:79], v[58:59] op_sel_hi:[1,0,1]
	v_pk_fma_f32 v[56:57], v[64:65], s[78:79], v[56:57] op_sel_hi:[1,0,1]
	v_lshl_add_u64 v[60:61], v[158:159], 2, s[88:89]
	global_store_dwordx4 v[60:61], v[56:59], off
	v_add_u32_e32 v158, 0x8080, v148
	s_nop 0
	v_sub_f32_e32 v57, v135, v112
	v_sub_f32_e32 v56, v134, v112
	v_sub_f32_e32 v59, v137, v112
	v_sub_f32_e32 v58, v136, v112
	v_pk_mul_f32 v[58:59], v[112:113], v[58:59] op_sel:[1,0]
	v_pk_mul_f32 v[56:57], v[112:113], v[56:57] op_sel:[1,0]
	v_pk_fma_f32 v[54:55], v[96:97], v[58:59], v[54:55]
	v_pk_fma_f32 v[52:53], v[98:99], v[56:57], v[52:53]
	v_pk_fma_f32 v[54:55], v[70:71], s[78:79], v[54:55] op_sel_hi:[1,0,1]
	v_pk_fma_f32 v[52:53], v[68:69], s[78:79], v[52:53] op_sel_hi:[1,0,1]
	v_lshl_add_u64 v[56:57], v[158:159], 2, s[88:89]
	global_store_dwordx4 v[56:57], v[52:55], off
	v_add_u32_e32 v158, 0x8090, v148
	s_nop 0
	v_sub_f32_e32 v53, v89, v112
	v_sub_f32_e32 v52, v88, v112
	v_sub_f32_e32 v55, v91, v112
	v_sub_f32_e32 v54, v90, v112
	v_pk_mul_f32 v[54:55], v[112:113], v[54:55] op_sel:[1,0]
	v_pk_mul_f32 v[52:53], v[112:113], v[52:53] op_sel:[1,0]
	v_pk_fma_f32 v[50:51], v[92:93], v[54:55], v[50:51]
	v_pk_fma_f32 v[48:49], v[94:95], v[52:53], v[48:49]
	v_pk_fma_f32 v[50:51], v[66:67], s[78:79], v[50:51] op_sel_hi:[1,0,1]
	v_pk_fma_f32 v[48:49], v[64:65], s[78:79], v[48:49] op_sel_hi:[1,0,1]
	v_lshl_add_u64 v[52:53], v[158:159], 2, s[88:89]
	global_store_dwordx4 v[52:53], v[48:51], off
	v_add_u32_e32 v158, 0x10080, v148
	s_nop 0
	v_sub_f32_e32 v49, v85, v102
	v_sub_f32_e32 v48, v84, v102
	v_sub_f32_e32 v51, v87, v102
	v_sub_f32_e32 v50, v86, v102
	v_pk_mul_f32 v[50:51], v[102:103], v[50:51] op_sel:[1,0]
	v_pk_mul_f32 v[48:49], v[102:103], v[48:49] op_sel:[1,0]
	v_pk_fma_f32 v[46:47], v[96:97], v[50:51], v[46:47]
	v_pk_fma_f32 v[44:45], v[98:99], v[48:49], v[44:45]
	v_pk_fma_f32 v[46:47], v[70:71], s[78:79], v[46:47] op_sel_hi:[1,0,1]
	v_pk_fma_f32 v[44:45], v[68:69], s[78:79], v[44:45] op_sel_hi:[1,0,1]
	v_lshl_add_u64 v[48:49], v[158:159], 2, s[88:89]
	global_store_dwordx4 v[48:49], v[44:47], off
	v_add_u32_e32 v158, 0x10090, v148
	s_nop 0
	v_sub_f32_e32 v45, v81, v102
	v_sub_f32_e32 v44, v80, v102
	v_sub_f32_e32 v47, v83, v102
	v_sub_f32_e32 v46, v82, v102
	v_pk_mul_f32 v[46:47], v[102:103], v[46:47] op_sel:[1,0]
	v_pk_mul_f32 v[44:45], v[102:103], v[44:45] op_sel:[1,0]
	v_pk_fma_f32 v[42:43], v[92:93], v[46:47], v[42:43]
	v_pk_fma_f32 v[40:41], v[94:95], v[44:45], v[40:41]
	v_pk_fma_f32 v[42:43], v[66:67], s[78:79], v[42:43] op_sel_hi:[1,0,1]
	v_pk_fma_f32 v[40:41], v[64:65], s[78:79], v[40:41] op_sel_hi:[1,0,1]
	v_lshl_add_u64 v[44:45], v[158:159], 2, s[88:89]
	global_store_dwordx4 v[44:45], v[40:43], off
	v_add_u32_e32 v158, 0x18080, v148
	s_nop 0
	v_sub_f32_e32 v41, v77, v100
	v_sub_f32_e32 v40, v76, v100
	v_sub_f32_e32 v43, v79, v100
	v_sub_f32_e32 v42, v78, v100
	v_pk_mul_f32 v[42:43], v[100:101], v[42:43] op_sel:[1,0]
	v_pk_mul_f32 v[40:41], v[100:101], v[40:41] op_sel:[1,0]
	v_pk_fma_f32 v[38:39], v[96:97], v[42:43], v[38:39]
;     template <bool LN, int BJ, int LO, int HI> DI void batch(const f32x4 (&acc)[2][2][4][2], unsigned row0, unsigned col0, const f32x4 (&gv)[2], const f32x4 (&bv)[2]) const {
;         f32x4 r[HI - LO]; float mean[(HI - LO) / 2], rstd[(HI - LO) / 2];
; #pragma unroll
;         for (int i = LO; i < HI; ++i) { const int ai = i >> 3, m = (i >> 1) & 3, n = i & 1; const unsigned row = row0 + ai * HALF + m * 16;
;             if (n == 0) { mean[(i - LO) >> 1] = 0.f; rstd[(i - LO) >> 1] = 1.f;
;                 if (LN) { const float2 st = *(const float2*)(stats + row * 2u); mean[(i - LO) >> 1] = st.x; rstd[(i - LO) >> 1] = st.y; } }
;             r[i - LO] = *(const f32x4*)(src + (row * (unsigned)DM + col0 + BJ * HALF + n * 16)); }
; #pragma unroll
;         for (int i = LO; i < HI; ++i) { const int ai = i >> 3, m = (i >> 1) & 3, n = i & 1; const unsigned row = row0 + ai * HALF + m * 16;
;             *(f32x4*)(Y + (row * (unsigned)DM + col0 + BJ * HALF + n * 16)) = acc[ai][BJ][m][n] + ((r[i - LO] - mean[(i - LO) >> 1]) * rstd[(i - LO) >> 1]) * gv[n] + bv[n]; }
;         __builtin_amdgcn_sched_barrier(0);
;     }
;     template <bool LN, int BJ> DI void load_gb(unsigned col0, f32x4 (&gv)[2], f32x4 (&bv)[2]) const {
; #pragma unroll
;         for (int n = 0; n < 2; ++n) {
;             if (LN) { gv[n] = *(const f32x4*)(gam + col0 + BJ * HALF + n * 16) * ALPHA; bv[n] = *(const f32x4*)(bet + col0 + BJ * HALF + n * 16) * ALPHA; }
;             else { gv[n] = (f32x4){ALPHA, ALPHA, ALPHA, ALPHA}; bv[n] = (f32x4){0.f, 0.f, 0.f, 0.f}; }
;         }
;     }
;     template <bool LN> DI void run(const f32x4 (&acc)[2][2][4][2], const Unit& u, int wr, int wc, int fr, int fq) const {
;         const unsigned row0 = u.pm * BM + wr * 64 + fr, col0 = u.pn * BM + wc * 32 + 4 * fq;
;         f32x4 gv[2], bv[2];
;         load_gb<LN, 0>(col0, gv, bv);
;         batch<LN, 0, 0, 4>(acc, row0, col0, gv, bv);
;         batch<LN, 0, 4, 8>(acc, row0, col0, gv, bv);
;         batch<LN, 0, 8, 12>(acc, row0, col0, gv, bv);
;         batch<LN, 0, 12, 16>(acc, row0, col0, gv, bv);
;         load_gb<LN, 1>(col0, gv, bv);
;         batch<LN, 1, 0, 8>(acc, row0, col0, gv, bv);
;         batch<LN, 1, 8, 16>(acc, row0, col0, gv, bv);
	v_pk_fma_f32 v[36:37], v[98:99], v[40:41], v[36:37]
	v_pk_fma_f32 v[38:39], v[70:71], s[78:79], v[38:39] op_sel_hi:[1,0,1]
	v_pk_fma_f32 v[36:37], v[68:69], s[78:79], v[36:37] op_sel_hi:[1,0,1]
	v_lshl_add_u64 v[40:41], v[158:159], 2, s[88:89]
	global_store_dwordx4 v[40:41], v[36:39], off
	v_add_u32_e32 v158, 0x18090, v148
	s_nop 0
	v_sub_f32_e32 v37, v73, v100
	v_sub_f32_e32 v36, v72, v100
	v_sub_f32_e32 v39, v75, v100
	v_sub_f32_e32 v38, v74, v100
	v_pk_mul_f32 v[38:39], v[100:101], v[38:39] op_sel:[1,0]
	v_pk_mul_f32 v[36:37], v[100:101], v[36:37] op_sel:[1,0]
	v_pk_fma_f32 v[34:35], v[92:93], v[38:39], v[34:35]
	v_pk_fma_f32 v[32:33], v[94:95], v[36:37], v[32:33]
	v_pk_fma_f32 v[34:35], v[66:67], s[78:79], v[34:35] op_sel_hi:[1,0,1]
	v_pk_fma_f32 v[32:33], v[64:65], s[78:79], v[32:33] op_sel_hi:[1,0,1]
	v_lshl_add_u64 v[36:37], v[158:159], 2, s[88:89]
	global_store_dwordx4 v[36:37], v[32:35], off
	v_add_u32_e32 v158, v114, v119
	s_nop 0
	v_lshl_add_u64 v[32:33], v[158:159], 2, s[90:91]
	global_load_dwordx2 v[62:63], v[104:105], off
	global_load_dwordx4 v[54:57], v[32:33], off
	v_add_u32_e32 v158, v114, v118
	v_lshl_add_u64 v[32:33], v[158:159], 2, s[90:91]
	global_load_dwordx4 v[58:61], v[32:33], off
	global_load_dwordx2 v[52:53], v[106:107], off
	v_add_u32_e32 v158, v115, v119
	v_lshl_add_u64 v[32:33], v[158:159], 2, s[90:91]
	global_load_dwordx4 v[72:75], v[32:33], off
	v_add_u32_e32 v158, v115, v118
	v_lshl_add_u64 v[32:33], v[158:159], 2, s[90:91]
	global_load_dwordx4 v[76:79], v[32:33], off
	global_load_dwordx2 v[50:51], v[108:109], off
	v_add_u32_e32 v158, v116, v119
	v_lshl_add_u64 v[32:33], v[158:159], 2, s[90:91]
	global_load_dwordx4 v[44:47], v[32:33], off
	v_add_u32_e32 v158, v116, v118
	v_lshl_add_u64 v[32:33], v[158:159], 2, s[90:91]
	global_load_dwordx4 v[40:43], v[32:33], off
	global_load_dwordx2 v[48:49], v[110:111], off
	v_add_u32_e32 v158, v117, v119
	v_lshl_add_u64 v[32:33], v[158:159], 2, s[90:91]
	global_load_dwordx4 v[36:39], v[32:33], off
	v_add_u32_e32 v158, v117, v118
	v_lshl_add_u64 v[32:33], v[158:159], 2, s[90:91]
	global_load_dwordx4 v[32:35], v[32:33], off
	v_add_u32_e32 v158, 0x40080, v148
	s_waitcnt vmcnt(0)
; template <class Epi>
; DI void gemm_phase(LAS unsigned char* lds, const Gemm g, const StaticOrder& S, const Epi& E) {
;     ...
;         E(acc, cur, wr, wc, fr, fq);
;     template <bool LN, int BJ, int LO, int HI> DI void batch(const f32x4 (&acc)[2][2][4][2], unsigned row0, unsigned col0, const f32x4 (&gv)[2], const f32x4 (&bv)[2]) const {
;         f32x4 r[HI - LO]; float mean[(HI - LO) / 2], rstd[(HI - LO) / 2];
; #pragma unroll
;         for (int i = LO; i < HI; ++i) { const int ai = i >> 3, m = (i >> 1) & 3, n = i & 1; const unsigned row = row0 + ai * HALF + m * 16;
;             if (n == 0) { mean[(i - LO) >> 1] = 0.f; rstd[(i - LO) >> 1] = 1.f;
;                 if (LN) { const float2 st = *(const float2*)(stats + row * 2u); mean[(i - LO) >> 1] = st.x; rstd[(i - LO) >> 1] = st.y; } }
;             r[i - LO] = *(const f32x4*)(src + (row * (unsigned)DM + col0 + BJ * HALF + n * 16)); }
; #pragma unroll
;         for (int i = LO; i < HI; ++i) { const int ai = i >> 3, m = (i >> 1) & 3, n = i & 1; const unsigned row = row0 + ai * HALF + m * 16;
;             *(f32x4*)(Y + (row * (unsigned)DM + col0 + BJ * HALF + n * 16)) = acc[ai][BJ][m][n] + ((r[i - LO] - mean[(i - LO) >> 1]) * rstd[(i - LO) >> 1]) * gv[n] + bv[n]; }
;         __builtin_amdgcn_sched_barrier(0);
;     }
;     template <bool LN, int BJ> DI void load_gb(unsigned col0, f32x4 (&gv)[2], f32x4 (&bv)[2]) const {
; #pragma unroll
;         for (int n = 0; n < 2; ++n) {
;             if (LN) { gv[n] = *(const f32x4*)(gam + col0 + BJ * HALF + n * 16) * ALPHA; bv[n] = *(const f32x4*)(bet + col0 + BJ * HALF + n * 16) * ALPHA; }
;             else { gv[n] = (f32x4){ALPHA, ALPHA, ALPHA, ALPHA}; bv[n] = (f32x4){0.f, 0.f, 0.f, 0.f}; }
;         }
;     }
;     template <bool LN> DI void run(const f32x4 (&acc)[2][2][4][2], const Unit& u, int wr, int wc, int fr, int fq) const {
;         const unsigned row0 = u.pm * BM + wr * 64 + fr, col0 = u.pn * BM + wc * 32 + 4 * fq;
;         f32x4 gv[2], bv[2];
;         load_gb<LN, 0>(col0, gv, bv);
;         batch<LN, 0, 0, 4>(acc, row0, col0, gv, bv);
;         batch<LN, 0, 4, 8>(acc, row0, col0, gv, bv);
;         batch<LN, 0, 8, 12>(acc, row0, col0, gv, bv);
;         batch<LN, 0, 12, 16>(acc, row0, col0, gv, bv);
;         load_gb<LN, 1>(col0, gv, bv);
;         batch<LN, 1, 0, 8>(acc, row0, col0, gv, bv);
;         batch<LN, 1, 8, 16>(acc, row0, col0, gv, bv);
	v_sub_f32_e32 v55, v55, v62
	v_sub_f32_e32 v54, v54, v62
	v_sub_f32_e32 v57, v57, v62
	v_sub_f32_e32 v56, v56, v62
	v_pk_mul_f32 v[56:57], v[62:63], v[56:57] op_sel:[1,0]
	v_pk_mul_f32 v[54:55], v[62:63], v[54:55] op_sel:[1,0]
	v_pk_fma_f32 v[30:31], v[96:97], v[56:57], v[30:31]
	v_pk_fma_f32 v[28:29], v[98:99], v[54:55], v[28:29]
	v_pk_fma_f32 v[30:31], v[70:71], s[78:79], v[30:31] op_sel_hi:[1,0,1]
	v_pk_fma_f32 v[28:29], v[68:69], s[78:79], v[28:29] op_sel_hi:[1,0,1]
	v_lshl_add_u64 v[54:55], v[158:159], 2, s[88:89]
	global_store_dwordx4 v[54:55], v[28:31], off
	v_add_u32_e32 v158, 0x40090, v148
	s_nop 0
	v_sub_f32_e32 v29, v59, v62
	v_sub_f32_e32 v28, v58, v62
	v_sub_f32_e32 v31, v61, v62
	v_sub_f32_e32 v30, v60, v62
	v_pk_mul_f32 v[30:31], v[62:63], v[30:31] op_sel:[1,0]
	v_pk_mul_f32 v[28:29], v[62:63], v[28:29] op_sel:[1,0]
	v_pk_fma_f32 v[26:27], v[92:93], v[30:31], v[26:27]
	v_pk_fma_f32 v[24:25], v[94:95], v[28:29], v[24:25]
	v_pk_fma_f32 v[26:27], v[66:67], s[78:79], v[26:27] op_sel_hi:[1,0,1]
	v_pk_fma_f32 v[24:25], v[64:65], s[78:79], v[24:25] op_sel_hi:[1,0,1]
	v_lshl_add_u64 v[28:29], v[158:159], 2, s[88:89]
	global_store_dwordx4 v[28:29], v[24:27], off
	v_add_u32_e32 v158, 0x48080, v148
	s_nop 0
	v_sub_f32_e32 v25, v73, v52
	v_sub_f32_e32 v24, v72, v52
	v_sub_f32_e32 v27, v75, v52
	v_sub_f32_e32 v26, v74, v52
	v_pk_mul_f32 v[26:27], v[52:53], v[26:27] op_sel:[1,0]
	v_pk_mul_f32 v[24:25], v[52:53], v[24:25] op_sel:[1,0]
	v_pk_fma_f32 v[22:23], v[96:97], v[26:27], v[22:23]
	v_pk_fma_f32 v[20:21], v[98:99], v[24:25], v[20:21]
	v_pk_fma_f32 v[22:23], v[70:71], s[78:79], v[22:23] op_sel_hi:[1,0,1]
	v_pk_fma_f32 v[20:21], v[68:69], s[78:79], v[20:21] op_sel_hi:[1,0,1]
	v_lshl_add_u64 v[24:25], v[158:159], 2, s[88:89]
	global_store_dwordx4 v[24:25], v[20:23], off
	v_add_u32_e32 v158, 0x48090, v148
	s_nop 0
	v_sub_f32_e32 v21, v77, v52
	v_sub_f32_e32 v20, v76, v52
	v_sub_f32_e32 v23, v79, v52
	v_sub_f32_e32 v22, v78, v52
	v_pk_mul_f32 v[22:23], v[52:53], v[22:23] op_sel:[1,0]
	v_pk_mul_f32 v[20:21], v[52:53], v[20:21] op_sel:[1,0]
	v_pk_fma_f32 v[18:19], v[92:93], v[22:23], v[18:19]
	v_pk_fma_f32 v[16:17], v[94:95], v[20:21], v[16:17]
	v_pk_fma_f32 v[18:19], v[66:67], s[78:79], v[18:19] op_sel_hi:[1,0,1]
	v_pk_fma_f32 v[16:17], v[64:65], s[78:79], v[16:17] op_sel_hi:[1,0,1]
	v_lshl_add_u64 v[20:21], v[158:159], 2, s[88:89]
	global_store_dwordx4 v[20:21], v[16:19], off
	v_add_u32_e32 v158, 0x50080, v148
	s_nop 0
	v_sub_f32_e32 v17, v45, v50
	v_sub_f32_e32 v16, v44, v50
	v_sub_f32_e32 v19, v47, v50
	v_sub_f32_e32 v18, v46, v50
	v_pk_mul_f32 v[18:19], v[50:51], v[18:19] op_sel:[1,0]
	v_pk_mul_f32 v[16:17], v[50:51], v[16:17] op_sel:[1,0]
	v_pk_fma_f32 v[14:15], v[96:97], v[18:19], v[14:15]
	v_pk_fma_f32 v[12:13], v[98:99], v[16:17], v[12:13]
	v_pk_fma_f32 v[14:15], v[70:71], s[78:79], v[14:15] op_sel_hi:[1,0,1]
	v_pk_fma_f32 v[12:13], v[68:69], s[78:79], v[12:13] op_sel_hi:[1,0,1]
	v_lshl_add_u64 v[16:17], v[158:159], 2, s[88:89]
	global_store_dwordx4 v[16:17], v[12:15], off
	v_add_u32_e32 v158, 0x50090, v148
	s_nop 0
	v_sub_f32_e32 v13, v41, v50
	v_sub_f32_e32 v12, v40, v50
	v_sub_f32_e32 v15, v43, v50
	v_sub_f32_e32 v14, v42, v50
	v_pk_mul_f32 v[14:15], v[50:51], v[14:15] op_sel:[1,0]
	v_pk_mul_f32 v[12:13], v[50:51], v[12:13] op_sel:[1,0]
	v_pk_fma_f32 v[10:11], v[92:93], v[14:15], v[10:11]
	v_pk_fma_f32 v[8:9], v[94:95], v[12:13], v[8:9]
	v_pk_fma_f32 v[10:11], v[66:67], s[78:79], v[10:11] op_sel_hi:[1,0,1]
	v_pk_fma_f32 v[8:9], v[64:65], s[78:79], v[8:9] op_sel_hi:[1,0,1]
	v_lshl_add_u64 v[12:13], v[158:159], 2, s[88:89]
	global_store_dwordx4 v[12:13], v[8:11], off
	v_add_u32_e32 v158, 0x58080, v148
	s_nop 0
	v_sub_f32_e32 v9, v37, v48
	v_sub_f32_e32 v8, v36, v48
	v_sub_f32_e32 v11, v39, v48
	v_sub_f32_e32 v10, v38, v48
	v_pk_mul_f32 v[10:11], v[48:49], v[10:11] op_sel:[1,0]
	v_pk_mul_f32 v[8:9], v[48:49], v[8:9] op_sel:[1,0]
	v_pk_fma_f32 v[6:7], v[96:97], v[10:11], v[6:7]
	v_pk_fma_f32 v[4:5], v[98:99], v[8:9], v[4:5]
	v_pk_fma_f32 v[6:7], v[70:71], s[78:79], v[6:7] op_sel_hi:[1,0,1]
	v_pk_fma_f32 v[4:5], v[68:69], s[78:79], v[4:5] op_sel_hi:[1,0,1]
	v_lshl_add_u64 v[8:9], v[158:159], 2, s[88:89]
	global_store_dwordx4 v[8:9], v[4:7], off
	v_add_u32_e32 v158, 0x58090, v148
	s_nop 0
	v_sub_f32_e32 v5, v33, v48
	v_sub_f32_e32 v4, v32, v48
	v_sub_f32_e32 v7, v35, v48
	v_sub_f32_e32 v6, v34, v48
	v_pk_mul_f32 v[6:7], v[48:49], v[6:7] op_sel:[1,0]
	v_pk_mul_f32 v[4:5], v[48:49], v[4:5] op_sel:[1,0]
	v_pk_fma_f32 v[2:3], v[92:93], v[6:7], v[2:3]
	v_pk_fma_f32 v[0:1], v[94:95], v[4:5], v[0:1]
	v_pk_fma_f32 v[2:3], v[66:67], s[78:79], v[2:3] op_sel_hi:[1,0,1]
	v_pk_fma_f32 v[0:1], v[64:65], s[78:79], v[0:1] op_sel_hi:[1,0,1]
	v_lshl_add_u64 v[4:5], v[158:159], 2, s[88:89]
	global_store_dwordx4 v[4:5], v[0:3], off
	s_and_b64 vcc, exec, s[6:7]
	s_mov_b32 s2, s37
	s_mov_b32 s3, s38
	s_mov_b64 s[18:19], s[10:11]
	s_mov_b64 s[16:17], s[8:9]
	v_readlane_b32 s33, v255, 39
	s_cbranch_vccz .LBB0_123
	s_waitcnt vmcnt(0)
	s_cmpk_gt_u32 s24, 0xff
	s_cbranch_scc1 .LBB0_138
	s_barrier

; __device__ __forceinline__ int opaque_tid() { int t = threadIdx.x; asm volatile("" : "+v"(t)); return t; }
; #define PG8_STAGE(bufoff, gbase) do { _Pragma("unroll") for (int _i = 0; _i < 2; ++_i) \
;         __builtin_amdgcn_global_load_lds((const unsigned*)((const char*)(gbase) + voff[_i]), (LAS unsigned*)(lds + (bufoff) + ldsw + _i * 8192), 16, 0, 0); } while (0)
; #define PG8_WAIT_V(n) asm volatile("s_waitcnt vmcnt(" #n ")" ::: "memory")
; #define PG8_BAR __builtin_amdgcn_s_barrier()
; template <class Epi>
; DI void gemm_phase(LAS unsigned char* lds, const Gemm g, const StaticOrder& S, const Epi& E) {
;     const int tid = opaque_tid(), wid = __builtin_amdgcn_readfirstlane(tid >> 6), lane = tid & 63, wr = wid >> 2, wc = wid & 3, fr = lane & 15, fq = lane >> 4;
;     const int K = g.K, nt = K / BK;
;     unsigned voff[2];
; #pragma unroll
;     for (int i = 0; i < 2; ++i) { int R, C; stage_rc(tid * 16 + i * 8192, R, C); voff[i] = (unsigned)(R * K + C) * 2u; }
;     const size_t kstep = (size_t)(BK * 2);
;     const size_t hstep = (size_t)HALF * K * 2;
;     const size_t tstep = 2 * hstep;
;     const unsigned ldsw = (unsigned)wid * 1024u;
;     const int aoff = lds_byte(wr * 64 + fr, fq * 8), boff = lds_byte(wc * 32 + fr, fq * 8);
;     ...
;     Unit cur, nxt; int ui = 0;
;     if (!S.next(0, cur)) return;
;     f32x4 acc[2][2][4][2];
; #pragma unroll
;     for (int a = 0; a < 2; ++a)
; #pragma unroll
;         for (int b = 0; b < 2; ++b)
; #pragma unroll
;             for (int m = 0; m < 4; ++m)
; #pragma unroll
;                 for (int n = 0; n < 2; ++n) acc[a][b][m][n] = (f32x4){0.f, 0.f, 0.f, 0.f};
;     bf16x8 At[4][2], B0[2][2], B1[2][2];
;     const char* cA = (const char*)g.A + (size_t)cur.pm * tstep; const char* cB = (const char*)g.Bt + (size_t)cur.pn * tstep;
;     PG8_STAGE(PG8_SB(0, 0), cB); PG8_STAGE(PG8_SA(0, 0), cA); PG8_STAGE(PG8_SB(0, 1), cB + hstep); PG8_STAGE(PG8_SA(0, 1), cA + hstep);
;     if (wr == 1) PG8_BAR;
;     PG8_WAIT_V(4); PG8_BAR;
;     PG8_STAGE(PG8_SB(1, 0), cB + kstep); PG8_STAGE(PG8_SA(1, 0), cA + kstep); PG8_STAGE(PG8_SB(1, 1), cB + hstep + kstep);
;     PG8_WAIT_V(6); PG8_BAR;
.LBB0_192:
	s_and_b64 vcc, exec, s[12:13]
	v_readlane_b32 s33, v255, 40
	s_cbranch_vccz .LBB0_236
	v_readlane_b32 s2, v255, 41
	v_readlane_b32 s3, v255, 42
	s_mov_b64 s[6:7], -1
	s_and_b64 vcc, exec, s[2:3]
	s_cbranch_vccz .LBB0_223
	v_readlane_b32 s2, v253, 25
	v_mov_b32_e32 v0, v156
	v_readlane_b32 s3, v253, 26
	s_andn2_b64 vcc, exec, s[2:3]
	v_readfirstlane_b32 s22, v0
	s_cbranch_vccnz .LBB0_222
	v_lshlrev_b32_e32 v5, 4, v0
	v_add_u32_e32 v2, 0x2000, v5
	v_ashrrev_i32_e32 v1, 31, v2
	v_lshrrev_b32_e32 v1, 22, v1
	v_add_u32_e32 v1, v2, v1
	v_ashrrev_i32_e32 v1, 10, v1
	v_lshlrev_b32_e32 v3, 5, v1
	v_and_b32_e32 v4, 32, v3
	v_mul_i32_i24_e32 v3, 0x400, v1
	v_sub_u32_e32 v2, v2, v3
	v_lshrrev_b32_e32 v3, 4, v2
	v_bitop3_b32 v3, v3, v2, 32 bitop3:0x6c
	v_ashrrev_i32_e32 v2, 31, v3
	v_lshrrev_b32_e32 v2, 26, v2
	v_add_u32_e32 v6, v3, v2
	v_ashrrev_i32_e32 v2, 6, v6
	v_and_b32_e32 v6, 0xc0, v6
	v_sub_u32_e32 v3, v3, v6
	v_ashrrev_i16_sdwa v3, v252, sext(v3) dst_sel:DWORD dst_unused:UNUSED_PAD src0_sel:DWORD src1_sel:BYTE_0
	v_lshlrev_b32_e32 v6, 3, v1
	v_bfe_i32 v3, v3, 0, 16
	v_and_b32_e32 v6, 0xffff0, v6
	v_add_u32_e32 v4, v4, v3
	v_add_lshl_u32 v6, v2, v6, 12
	s_waitcnt vmcnt(0)
	v_lshl_add_u32 v142, v4, 1, v6
	v_ashrrev_i32_e32 v4, 31, v0
	v_lshrrev_b32_e32 v4, 26, v4
	v_add_u32_e32 v4, v0, v4
	v_ashrrev_i32_e32 v4, 6, v4
	v_lshlrev_b32_e32 v6, 5, v4
	v_and_b32_e32 v7, 32, v6
	v_bfe_i32 v6, v0, 27, 1
	v_lshrrev_b32_e32 v6, 22, v6
	v_add_u32_e32 v6, v5, v6
	v_and_b32_e32 v6, 0xfffffc00, v6
	v_sub_u32_e32 v5, v5, v6
	v_lshrrev_b32_e32 v6, 4, v5
	v_bitop3_b32 v6, v6, v5, 32 bitop3:0x6c
	v_ashrrev_i32_e32 v5, 31, v5
	v_readlane_b32 s2, v255, 43
	v_lshrrev_b32_e32 v5, 26, v5
	v_readlane_b32 s3, v255, 44
	s_mov_b32 s4, s2
	v_add_u32_e32 v5, v6, v5
	s_mul_i32 s3, s4, 0x1b00000
	v_readlane_b32 s4, v253, 23
	v_ashrrev_i32_e32 v5, 6, v5
	s_mul_hi_u32 s2, s2, 0x1b00000
	s_add_u32 s23, s4, s3
	v_readlane_b32 s3, v253, 24
	v_mul_i32_i24_e32 v8, 64, v5
	s_addc_u32 s24, s3, s2
	s_ashr_i32 s3, s22, 6
	v_sub_u32_e32 v6, v6, v8
	s_ashr_i32 s2, s22, 8
	s_lshl_b32 s25, s3, 10
	v_ashrrev_i16_sdwa v6, v252, sext(v6) dst_sel:DWORD dst_unused:UNUSED_PAD src0_sel:DWORD src1_sel:BYTE_0
	v_lshlrev_b32_e32 v8, 3, v4
	v_readlane_b32 s4, v254, 52
	v_bfe_i32 v6, v6, 0, 16
	v_and_b32_e32 v8, 0xffff0, v8
	v_readlane_b32 s5, v254, 53
	s_add_u32 s18, s23, s4
	v_add_u32_e32 v7, v7, v6
	v_add_lshl_u32 v8, v5, v8, 12
	s_addc_u32 s19, s24, s5
	s_add_i32 s26, s25, 0
	v_lshl_add_u32 v144, v7, 1, v8
	s_add_i32 m0, s26, 0x10000
	v_readlane_b32 s4, v254, 57
	global_load_lds_dwordx4 v144, s[18:19]
	s_add_i32 m0, s26, 0x12000
	v_readlane_b32 s5, v254, 58
	global_load_lds_dwordx4 v142, s[18:19]
	s_mov_b32 m0, s26
	s_add_i32 s27, s26, 0x2000
	s_nop 1
	global_load_lds_dwordx4 v144, s[4:5]
	s_mov_b32 m0, s27
	s_nop 0
	global_load_lds_dwordx4 v142, s[4:5]
	s_add_u32 s4, s18, 0x80000
	s_addc_u32 s5, s19, 0
	s_add_i32 m0, s26, 0x14000
	s_add_i32 s28, s26, 0x4000
	global_load_lds_dwordx4 v144, s[4:5]
	s_add_i32 m0, s26, 0x16000
	s_add_i32 s29, s26, 0x6000
	global_load_lds_dwordx4 v142, s[4:5]
	v_readlane_b32 s4, v254, 59
	s_mov_b32 m0, s28
	v_readlane_b32 s5, v254, 60
	s_cmp_lg_u32 s2, 1
	s_nop 3
	global_load_lds_dwordx4 v144, s[4:5]
	s_mov_b32 m0, s29
	s_nop 0
	global_load_lds_dwordx4 v142, s[4:5]
	s_cbranch_scc1 .LBB0_197
	s_setprio 1
	s_barrier

; #define PG8_STAGE(bufoff, gbase) do { _Pragma("unroll") for (int _i = 0; _i < 2; ++_i) \
;         __builtin_amdgcn_global_load_lds((const unsigned*)((const char*)(gbase) + voff[_i]), (LAS unsigned*)(lds + (bufoff) + ldsw + _i * 8192), 16, 0, 0); } while (0)
; #define PG8_LDA(dst, b, h) do { _Pragma("unroll") for (int m = 0; m < 4; ++m) _Pragma("unroll") for (int k = 0; k < 2; ++k) dst[m][k] = *(const LAS bf16x8*)(lds + PG8_SA(b, h) + aoff + m * 2048 + k * 1024); } while (0)
; #define PG8_LDB(dst, b, h) do { _Pragma("unroll") for (int n = 0; n < 2; ++n) _Pragma("unroll") for (int k = 0; k < 2; ++k) dst[n][k] = *(const LAS bf16x8*)(lds + PG8_SB(b, h) + boff + n * 2048 + k * 1024); } while (0)
; #define PG8_MMA(ai, bj, At, Bt) do { __builtin_amdgcn_s_setprio(1); _Pragma("unroll") for (int m = 0; m < 4; ++m) _Pragma("unroll") for (int n = 0; n < 2; ++n) _Pragma("unroll") for (int k = 0; k < 2; ++k) \
;         acc[ai][bj][m][n] = __builtin_amdgcn_mfma_f32_16x16x32_bf16(Bt[n][k], At[m][k], acc[ai][bj][m][n], 0, 0, 0); __builtin_amdgcn_s_setprio(0); } while (0)
; #define PG8_WAIT_V(n) asm volatile("s_waitcnt vmcnt(" #n ")" ::: "memory")
; #define PG8_WAIT_L(n) asm volatile("s_waitcnt lgkmcnt(" #n ")" ::: "memory")
; #define PG8_BAR __builtin_amdgcn_s_barrier()
; #define PG8_SCHED __builtin_amdgcn_sched_barrier(0)
; template <class Epi>
; DI void gemm_phase(LAS unsigned char* lds, const Gemm g, const StaticOrder& S, const Epi& E) {
;     ...
;         for (int t = 0; t < nt; t += 2) {
;             const bool last = (t == nt - 2);
;             const char* a1 = cA + (size_t)(t + 1) * kstep;
;             const char* a2 = last ? nA : cA + (size_t)(t + 2) * kstep; const char* b2 = last ? nB : cB + (size_t)(t + 2) * kstep;
;             const char* a3 = a2 + kstep; const char* b3 = b2 + kstep;
;             PG8_LDB(B0, 0, 0); PG8_SCHED; PG8_LDA(At, 0, 0); PG8_STAGE(PG8_SA(1, 1), a1 + hstep);
;             PG8_WAIT_L(8); PG8_BAR; PG8_WAIT_L(0); PG8_MMA(0, 0, At, B0); PG8_BAR; PG8_SCHED;
;             PG8_LDB(B1, 0, 1); PG8_STAGE(PG8_SB(0, 0), b2);
;             PG8_BAR; PG8_WAIT_L(0); PG8_MMA(0, 1, At, B1); PG8_BAR;
;             PG8_LDA(At, 0, 1); PG8_STAGE(PG8_SA(0, 0), a2);
;             PG8_BAR; PG8_WAIT_L(0); PG8_MMA(1, 0, At, B0); PG8_BAR; PG8_SCHED;
;             PG8_STAGE(PG8_SB(0, 1), b2 + hstep);
;             PG8_WAIT_V(6); PG8_BAR; PG8_MMA(1, 1, At, B1); PG8_BAR;
.LBB0_202:
	s_add_u32 s18, s8, 0xfff80080
	s_addc_u32 s19, s9, -1
	s_add_i32 s37, 0, 0x10000
	s_waitcnt lgkmcnt(0)
	ds_read_b128 v[128:131], v187
	ds_read_b128 v[132:135], v187 offset:1024
	ds_read_b128 v[136:139], v187 offset:2048
	ds_read_b128 v[190:193], v187 offset:3072
	s_cmp_eq_u32 s36, 28
	s_cselect_b32 s21, s4, s19
	s_cselect_b32 s20, s5, s18
	s_cselect_b32 s19, s11, s35
	s_cselect_b32 s18, s13, s33
	s_add_i32 m0, s26, 0xc000
	ds_read_b128 v[194:197], v189
	ds_read_b128 v[198:201], v189 offset:1024
	ds_read_b128 v[202:205], v189 offset:2048
	ds_read_b128 v[206:209], v189 offset:3072
	ds_read_b128 v[210:213], v189 offset:4096
	ds_read_b128 v[214:217], v189 offset:5120
	ds_read_b128 v[226:229], v189 offset:6144
	ds_read_b128 v[230:233], v189 offset:7168
	global_load_lds_dwordx4 v150, s[8:9]
	s_add_i32 m0, s26, 0xe000
	s_nop 0
	global_load_lds_dwordx4 v152, s[8:9]
	s_waitcnt lgkmcnt(8)
	s_barrier
	s_waitcnt lgkmcnt(0)
	v_mfma_f32_16x16x32_bf16 v[124:127], v[128:131], v[194:197], v[124:127]
	v_mfma_f32_16x16x32_bf16 v[120:123], v[136:139], v[194:197], v[120:123]
	v_mfma_f32_16x16x32_bf16 v[108:111], v[128:131], v[202:205], v[108:111]
	v_mfma_f32_16x16x32_bf16 v[104:107], v[136:139], v[202:205], v[104:107]
	v_mfma_f32_16x16x32_bf16 v[92:95], v[128:131], v[210:213], v[92:95]
	v_mfma_f32_16x16x32_bf16 v[88:91], v[136:139], v[210:213], v[88:91]
	v_mfma_f32_16x16x32_bf16 v[76:79], v[128:131], v[226:229], v[76:79]
	v_mfma_f32_16x16x32_bf16 v[72:75], v[136:139], v[226:229], v[72:75]
	v_mfma_f32_16x16x32_bf16 v[124:127], v[132:135], v[198:201], v[124:127]
	v_mfma_f32_16x16x32_bf16 v[120:123], v[190:193], v[198:201], v[120:123]
	v_mfma_f32_16x16x32_bf16 v[108:111], v[132:135], v[206:209], v[108:111]
	v_mfma_f32_16x16x32_bf16 v[104:107], v[190:193], v[206:209], v[104:107]
	v_mfma_f32_16x16x32_bf16 v[92:95], v[132:135], v[214:217], v[92:95]
	v_mfma_f32_16x16x32_bf16 v[88:91], v[190:193], v[214:217], v[88:91]
	v_mfma_f32_16x16x32_bf16 v[76:79], v[132:135], v[230:233], v[76:79]
	v_mfma_f32_16x16x32_bf16 v[72:75], v[190:193], v[230:233], v[72:75]
	s_barrier
	ds_read_b128 v[234:237], v187 offset:16384
	ds_read_b128 v[238:241], v187 offset:17408
	ds_read_b128 v[242:245], v187 offset:18432
	ds_read_b128 v[246:249], v187 offset:19456
	s_add_i32 s40, 0, 0x14000
	s_add_i32 s37, s37, s25
	s_mov_b32 m0, s37
	s_nop 0
	global_load_lds_dwordx4 v144, s[18:19]
	s_add_i32 m0, s37, 0x2000
	s_nop 0
	global_load_lds_dwordx4 v142, s[18:19]
	s_waitcnt lgkmcnt(0)
	s_barrier
	v_mfma_f32_16x16x32_bf16 v[116:119], v[234:237], v[194:197], v[116:119]
	v_mfma_f32_16x16x32_bf16 v[112:115], v[242:245], v[194:197], v[112:115]
	v_mfma_f32_16x16x32_bf16 v[100:103], v[234:237], v[202:205], v[100:103]
	v_mfma_f32_16x16x32_bf16 v[96:99], v[242:245], v[202:205], v[96:99]
	v_mfma_f32_16x16x32_bf16 v[84:87], v[234:237], v[210:213], v[84:87]
	v_mfma_f32_16x16x32_bf16 v[80:83], v[242:245], v[210:213], v[80:83]
	v_mfma_f32_16x16x32_bf16 v[68:71], v[234:237], v[226:229], v[68:71]
	v_mfma_f32_16x16x32_bf16 v[64:67], v[242:245], v[226:229], v[64:67]
	v_mfma_f32_16x16x32_bf16 v[116:119], v[238:241], v[198:201], v[116:119]
	s_mov_b32 m0, s26
	v_mfma_f32_16x16x32_bf16 v[112:115], v[246:249], v[198:201], v[112:115]
	v_mfma_f32_16x16x32_bf16 v[100:103], v[238:241], v[206:209], v[100:103]
	v_mfma_f32_16x16x32_bf16 v[96:99], v[246:249], v[206:209], v[96:99]
	v_mfma_f32_16x16x32_bf16 v[84:87], v[238:241], v[214:217], v[84:87]
	v_mfma_f32_16x16x32_bf16 v[80:83], v[246:249], v[214:217], v[80:83]
	v_mfma_f32_16x16x32_bf16 v[68:71], v[238:241], v[230:233], v[68:71]
	v_mfma_f32_16x16x32_bf16 v[64:67], v[246:249], v[230:233], v[64:67]
	s_barrier
	ds_read_b128 v[194:197], v189 offset:16384
	ds_read_b128 v[198:201], v189 offset:17408
	ds_read_b128 v[202:205], v189 offset:18432
	ds_read_b128 v[206:209], v189 offset:19456
	ds_read_b128 v[210:213], v189 offset:20480
	ds_read_b128 v[214:217], v189 offset:21504
	ds_read_b128 v[226:229], v189 offset:22528
	ds_read_b128 v[230:233], v189 offset:23552
	global_load_lds_dwordx4 v144, s[20:21]
	s_mov_b64 s[100:101], s[20:21]
	s_mov_b32 m0, s27
	s_nop 0
	global_load_lds_dwordx4 v142, s[20:21]
	s_waitcnt lgkmcnt(0)
	s_barrier
	v_mfma_f32_16x16x32_bf16 v[60:63], v[128:131], v[194:197], v[60:63]
	v_mfma_f32_16x16x32_bf16 v[56:59], v[136:139], v[194:197], v[56:59]
	v_mfma_f32_16x16x32_bf16 v[44:47], v[128:131], v[202:205], v[44:47]
	v_mfma_f32_16x16x32_bf16 v[40:43], v[136:139], v[202:205], v[40:43]
	v_mfma_f32_16x16x32_bf16 v[28:31], v[128:131], v[210:213], v[28:31]
	v_mfma_f32_16x16x32_bf16 v[24:27], v[136:139], v[210:213], v[24:27]
	v_mfma_f32_16x16x32_bf16 v[12:15], v[128:131], v[226:229], v[12:15]
	v_mfma_f32_16x16x32_bf16 v[8:11], v[136:139], v[226:229], v[8:11]
	v_mfma_f32_16x16x32_bf16 v[60:63], v[132:135], v[198:201], v[60:63]
	v_mfma_f32_16x16x32_bf16 v[56:59], v[190:193], v[198:201], v[56:59]
	v_mfma_f32_16x16x32_bf16 v[44:47], v[132:135], v[206:209], v[44:47]
	v_mfma_f32_16x16x32_bf16 v[40:43], v[190:193], v[206:209], v[40:43]
	v_mfma_f32_16x16x32_bf16 v[28:31], v[132:135], v[214:217], v[28:31]
	v_mfma_f32_16x16x32_bf16 v[24:27], v[190:193], v[214:217], v[24:27]
	v_mfma_f32_16x16x32_bf16 v[12:15], v[132:135], v[230:233], v[12:15]
	v_mfma_f32_16x16x32_bf16 v[8:11], v[190:193], v[230:233], v[8:11]
	s_barrier
	s_add_u32 s38, s18, 0x80000
	s_addc_u32 s39, s19, 0
	s_add_i32 s37, s40, s25
	s_mov_b32 m0, s37
	s_nop 0
	global_load_lds_dwordx4 v144, s[38:39]
	s_add_i32 m0, s37, 0x2000
	s_nop 0
	global_load_lds_dwordx4 v142, s[38:39]
	s_waitcnt vmcnt(6)
	s_barrier
; #define PG8_STAGE(bufoff, gbase) do { _Pragma("unroll") for (int _i = 0; _i < 2; ++_i) \
;         __builtin_amdgcn_global_load_lds((const unsigned*)((const char*)(gbase) + voff[_i]), (LAS unsigned*)(lds + (bufoff) + ldsw + _i * 8192), 16, 0, 0); } while (0)
; #define PG8_LDA(dst, b, h) do { _Pragma("unroll") for (int m = 0; m < 4; ++m) _Pragma("unroll") for (int k = 0; k < 2; ++k) dst[m][k] = *(const LAS bf16x8*)(lds + PG8_SA(b, h) + aoff + m * 2048 + k * 1024); } while (0)
; #define PG8_LDB(dst, b, h) do { _Pragma("unroll") for (int n = 0; n < 2; ++n) _Pragma("unroll") for (int k = 0; k < 2; ++k) dst[n][k] = *(const LAS bf16x8*)(lds + PG8_SB(b, h) + boff + n * 2048 + k * 1024); } while (0)
; #define PG8_MMA(ai, bj, At, Bt) do { __builtin_amdgcn_s_setprio(1); _Pragma("unroll") for (int m = 0; m < 4; ++m) _Pragma("unroll") for (int n = 0; n < 2; ++n) _Pragma("unroll") for (int k = 0; k < 2; ++k) \
;         acc[ai][bj][m][n] = __builtin_amdgcn_mfma_f32_16x16x32_bf16(Bt[n][k], At[m][k], acc[ai][bj][m][n], 0, 0, 0); __builtin_amdgcn_s_setprio(0); } while (0)
; #define PG8_WAIT_V(n) asm volatile("s_waitcnt vmcnt(" #n ")" ::: "memory")
; #define PG8_WAIT_L(n) asm volatile("s_waitcnt lgkmcnt(" #n ")" ::: "memory")
; #define PG8_BAR __builtin_amdgcn_s_barrier()
; #define PG8_SCHED __builtin_amdgcn_sched_barrier(0)
; template <class Epi>
; DI void gemm_phase(LAS unsigned char* lds, const Gemm g, const StaticOrder& S, const Epi& E) {
;     ...
;             PG8_WAIT_V(6); PG8_BAR; PG8_MMA(1, 1, At, B1); PG8_BAR;
;             PG8_LDB(B0, 1, 0); PG8_SCHED; PG8_LDA(At, 1, 0); PG8_STAGE(PG8_SA(0, 1), a2 + hstep);
;             PG8_WAIT_L(8); PG8_BAR; PG8_WAIT_L(0); PG8_MMA(0, 0, At, B0); PG8_BAR; PG8_SCHED;
;             PG8_LDB(B1, 1, 1); PG8_STAGE(PG8_SB(1, 0), b3);
;             PG8_BAR; PG8_WAIT_L(0); PG8_MMA(0, 1, At, B1); PG8_BAR;
;             PG8_LDA(At, 1, 1); PG8_STAGE(PG8_SA(1, 0), a3);
;             PG8_BAR; PG8_WAIT_L(0); PG8_MMA(1, 0, At, B0); PG8_BAR; PG8_SCHED;
	v_mfma_f32_16x16x32_bf16 v[52:55], v[234:237], v[194:197], v[52:55]
	v_mfma_f32_16x16x32_bf16 v[48:51], v[242:245], v[194:197], v[48:51]
	v_mfma_f32_16x16x32_bf16 v[36:39], v[234:237], v[202:205], v[36:39]
	v_mfma_f32_16x16x32_bf16 v[32:35], v[242:245], v[202:205], v[32:35]
	v_mfma_f32_16x16x32_bf16 v[20:23], v[234:237], v[210:213], v[20:23]
	v_mfma_f32_16x16x32_bf16 v[16:19], v[242:245], v[210:213], v[16:19]
	v_mfma_f32_16x16x32_bf16 v[4:7], v[234:237], v[226:229], v[4:7]
	v_mfma_f32_16x16x32_bf16 v[0:3], v[242:245], v[226:229], v[0:3]
	v_mfma_f32_16x16x32_bf16 v[52:55], v[238:241], v[198:201], v[52:55]
	s_add_i32 s37, 0, 0x18000
	v_mfma_f32_16x16x32_bf16 v[48:51], v[246:249], v[198:201], v[48:51]
	v_mfma_f32_16x16x32_bf16 v[36:39], v[238:241], v[206:209], v[36:39]
	v_mfma_f32_16x16x32_bf16 v[32:35], v[246:249], v[206:209], v[32:35]
	v_mfma_f32_16x16x32_bf16 v[20:23], v[238:241], v[214:217], v[20:23]
	v_mfma_f32_16x16x32_bf16 v[16:19], v[246:249], v[214:217], v[16:19]
	v_mfma_f32_16x16x32_bf16 v[4:7], v[238:241], v[230:233], v[4:7]
	v_mfma_f32_16x16x32_bf16 v[0:3], v[246:249], v[230:233], v[0:3]
	s_barrier
	ds_read_b128 v[128:131], v187 offset:32768
	ds_read_b128 v[132:135], v187 offset:33792
	ds_read_b128 v[136:139], v187 offset:34816
	ds_read_b128 v[190:193], v187 offset:35840
	ds_read_b128 v[194:197], v189 offset:32768
	ds_read_b128 v[198:201], v189 offset:33792
	ds_read_b128 v[202:205], v189 offset:34816
	ds_read_b128 v[206:209], v189 offset:35840
	ds_read_b128 v[210:213], v189 offset:36864
	ds_read_b128 v[214:217], v189 offset:37888
	ds_read_b128 v[226:229], v189 offset:38912
	ds_read_b128 v[230:233], v189 offset:39936
	s_add_u32 s20, s20, 0x80000
	s_addc_u32 s21, s21, 0
	s_mov_b32 m0, s28
	s_nop 0
	global_load_lds_dwordx4 v144, s[20:21]
	s_mov_b32 m0, s29
	s_nop 0
	global_load_lds_dwordx4 v142, s[20:21]
	s_waitcnt lgkmcnt(8)
	s_barrier
	s_waitcnt lgkmcnt(0)
	v_mfma_f32_16x16x32_bf16 v[124:127], v[128:131], v[194:197], v[124:127]
	v_mfma_f32_16x16x32_bf16 v[120:123], v[136:139], v[194:197], v[120:123]
	v_mfma_f32_16x16x32_bf16 v[108:111], v[128:131], v[202:205], v[108:111]
	v_mfma_f32_16x16x32_bf16 v[104:107], v[136:139], v[202:205], v[104:107]
	v_mfma_f32_16x16x32_bf16 v[92:95], v[128:131], v[210:213], v[92:95]
	v_mfma_f32_16x16x32_bf16 v[88:91], v[136:139], v[210:213], v[88:91]
	v_mfma_f32_16x16x32_bf16 v[76:79], v[128:131], v[226:229], v[76:79]
	v_mfma_f32_16x16x32_bf16 v[72:75], v[136:139], v[226:229], v[72:75]
	v_mfma_f32_16x16x32_bf16 v[124:127], v[132:135], v[198:201], v[124:127]
	v_mfma_f32_16x16x32_bf16 v[120:123], v[190:193], v[198:201], v[120:123]
	v_mfma_f32_16x16x32_bf16 v[108:111], v[132:135], v[206:209], v[108:111]
	v_mfma_f32_16x16x32_bf16 v[104:107], v[190:193], v[206:209], v[104:107]
	v_mfma_f32_16x16x32_bf16 v[92:95], v[132:135], v[214:217], v[92:95]
	v_mfma_f32_16x16x32_bf16 v[88:91], v[190:193], v[214:217], v[88:91]
	v_mfma_f32_16x16x32_bf16 v[76:79], v[132:135], v[230:233], v[76:79]
	v_mfma_f32_16x16x32_bf16 v[72:75], v[190:193], v[230:233], v[72:75]
	s_barrier
	ds_read_b128 v[234:237], v187 offset:49152
	ds_read_b128 v[238:241], v187 offset:50176
	ds_read_b128 v[242:245], v187 offset:51200
	ds_read_b128 v[246:249], v187 offset:52224
	s_add_i32 s20, 0, 0x1c000
	s_add_i32 s21, s37, s25
	s_add_i32 m0, s21, 0xffffff80
	s_nop 0
	global_load_lds_dwordx4 v144, s[18:19] offset:128
	s_add_i32 m0, s21, 0x1f80
	s_nop 0
	global_load_lds_dwordx4 v142, s[18:19] offset:128
	s_waitcnt lgkmcnt(0)
	s_barrier
	v_mfma_f32_16x16x32_bf16 v[116:119], v[234:237], v[194:197], v[116:119]
	v_mfma_f32_16x16x32_bf16 v[112:115], v[242:245], v[194:197], v[112:115]
	v_mfma_f32_16x16x32_bf16 v[100:103], v[234:237], v[202:205], v[100:103]
	v_mfma_f32_16x16x32_bf16 v[96:99], v[242:245], v[202:205], v[96:99]
	v_mfma_f32_16x16x32_bf16 v[84:87], v[234:237], v[210:213], v[84:87]
	v_mfma_f32_16x16x32_bf16 v[80:83], v[242:245], v[210:213], v[80:83]
	v_mfma_f32_16x16x32_bf16 v[68:71], v[234:237], v[226:229], v[68:71]
	v_mfma_f32_16x16x32_bf16 v[64:67], v[242:245], v[226:229], v[64:67]
	v_mfma_f32_16x16x32_bf16 v[116:119], v[238:241], v[198:201], v[116:119]
	s_add_i32 m0, s30, 0xffffff80
	v_mfma_f32_16x16x32_bf16 v[112:115], v[246:249], v[198:201], v[112:115]
	v_mfma_f32_16x16x32_bf16 v[100:103], v[238:241], v[206:209], v[100:103]
	v_mfma_f32_16x16x32_bf16 v[96:99], v[246:249], v[206:209], v[96:99]
	v_mfma_f32_16x16x32_bf16 v[84:87], v[238:241], v[214:217], v[84:87]
	v_mfma_f32_16x16x32_bf16 v[80:83], v[246:249], v[214:217], v[80:83]
	v_mfma_f32_16x16x32_bf16 v[68:71], v[238:241], v[230:233], v[68:71]
	v_mfma_f32_16x16x32_bf16 v[64:67], v[246:249], v[230:233], v[64:67]
	s_barrier
; #define PG8_STAGE(bufoff, gbase) do { _Pragma("unroll") for (int _i = 0; _i < 2; ++_i) \
;         __builtin_amdgcn_global_load_lds((const unsigned*)((const char*)(gbase) + voff[_i]), (LAS unsigned*)(lds + (bufoff) + ldsw + _i * 8192), 16, 0, 0); } while (0)
; #define PG8_MMA(ai, bj, At, Bt) do { __builtin_amdgcn_s_setprio(1); _Pragma("unroll") for (int m = 0; m < 4; ++m) _Pragma("unroll") for (int n = 0; n < 2; ++n) _Pragma("unroll") for (int k = 0; k < 2; ++k) \
;         acc[ai][bj][m][n] = __builtin_amdgcn_mfma_f32_16x16x32_bf16(Bt[n][k], At[m][k], acc[ai][bj][m][n], 0, 0, 0); __builtin_amdgcn_s_setprio(0); } while (0)
; #define PG8_WAIT_V(n) asm volatile("s_waitcnt vmcnt(" #n ")" ::: "memory")
; #define PG8_WAIT_L(n) asm volatile("s_waitcnt lgkmcnt(" #n ")" ::: "memory")
; #define PG8_BAR __builtin_amdgcn_s_barrier()
; #define PG8_SCHED __builtin_amdgcn_sched_barrier(0)
; template <class Epi>
; DI void gemm_phase(LAS unsigned char* lds, const Gemm g, const StaticOrder& S, const Epi& E) {
;     ...
;             PG8_BAR; PG8_WAIT_L(0); PG8_MMA(1, 0, At, B0); PG8_BAR; PG8_SCHED;
;             PG8_STAGE(PG8_SB(1, 1), b3 + hstep);
;             PG8_WAIT_V(6); PG8_BAR; PG8_MMA(1, 1, At, B1); PG8_BAR;
;         }
;     DI void operator()(const f32x4 (&acc)[2][2][4][2], const Unit& u, int wr, int wc, int fr, int fq) const {
;         const int row0 = u.pm * BM + wr * 64 + fr, col0 = u.pn * BM + wc * 16 + 4 * fq;
;         const bool rot = u.pn < 18;
; #pragma unroll
;         for (int ai = 0; ai < 2; ++ai)
; #pragma unroll
;             for (int m = 0; m < 4; ++m) { const int row = row0 + ai * HALF + m * 16; u16* rowp = O + (size_t)row * NQKV_DIL + col0;
;                 f32x4 c4 = (f32x4){1.f, 1.f, 1.f, 1.f}, s4 = (f32x4){0.f, 0.f, 0.f, 0.f};
;                 if (rot) { const int pos = row & (SEQ - 1); c4 = *(const f32x4*)(cs + pos * 64 + wc * 16 + 4 * fq); s4 = *(const f32x4*)(sn + pos * 64 + wc * 16 + 4 * fq); }
	ds_read_b128 v[194:197], v189 offset:49152
	ds_read_b128 v[198:201], v189 offset:50176
	ds_read_b128 v[202:205], v189 offset:51200
	ds_read_b128 v[206:209], v189 offset:52224
	ds_read_b128 v[210:213], v189 offset:53248
	ds_read_b128 v[214:217], v189 offset:54272
	ds_read_b128 v[226:229], v189 offset:55296
	ds_read_b128 v[230:233], v189 offset:56320
	global_load_lds_dwordx4 v144, s[100:101] offset:128
	s_add_i32 m0, s31, 0xffffff80
	s_nop 0
	global_load_lds_dwordx4 v142, s[100:101] offset:128
	s_waitcnt lgkmcnt(0)
	s_barrier
	v_mfma_f32_16x16x32_bf16 v[60:63], v[128:131], v[194:197], v[60:63]
	v_mfma_f32_16x16x32_bf16 v[56:59], v[136:139], v[194:197], v[56:59]
	v_mfma_f32_16x16x32_bf16 v[44:47], v[128:131], v[202:205], v[44:47]
	v_mfma_f32_16x16x32_bf16 v[40:43], v[136:139], v[202:205], v[40:43]
	v_mfma_f32_16x16x32_bf16 v[28:31], v[128:131], v[210:213], v[28:31]
	v_mfma_f32_16x16x32_bf16 v[24:27], v[136:139], v[210:213], v[24:27]
	v_mfma_f32_16x16x32_bf16 v[12:15], v[128:131], v[226:229], v[12:15]
	v_mfma_f32_16x16x32_bf16 v[8:11], v[136:139], v[226:229], v[8:11]
	v_mfma_f32_16x16x32_bf16 v[60:63], v[132:135], v[198:201], v[60:63]
	v_mfma_f32_16x16x32_bf16 v[56:59], v[190:193], v[198:201], v[56:59]
	v_mfma_f32_16x16x32_bf16 v[44:47], v[132:135], v[206:209], v[44:47]
	v_mfma_f32_16x16x32_bf16 v[40:43], v[190:193], v[206:209], v[40:43]
	v_mfma_f32_16x16x32_bf16 v[28:31], v[132:135], v[214:217], v[28:31]
	v_mfma_f32_16x16x32_bf16 v[24:27], v[190:193], v[214:217], v[24:27]
	v_mfma_f32_16x16x32_bf16 v[12:15], v[132:135], v[230:233], v[12:15]
	v_mfma_f32_16x16x32_bf16 v[8:11], v[190:193], v[230:233], v[8:11]
	s_barrier
	s_add_u32 s18, s18, 0x80080
	s_addc_u32 s19, s19, 0
	s_add_i32 s20, s20, s25
	s_mov_b32 m0, s20
	s_nop 0
	global_load_lds_dwordx4 v144, s[18:19]
	s_add_i32 m0, s20, 0x2000
	s_nop 0
	global_load_lds_dwordx4 v142, s[18:19]
	s_waitcnt vmcnt(6)
	s_barrier
	v_mfma_f32_16x16x32_bf16 v[52:55], v[234:237], v[194:197], v[52:55]
	v_mfma_f32_16x16x32_bf16 v[48:51], v[242:245], v[194:197], v[48:51]
	v_mfma_f32_16x16x32_bf16 v[36:39], v[234:237], v[202:205], v[36:39]
	v_mfma_f32_16x16x32_bf16 v[32:35], v[242:245], v[202:205], v[32:35]
	v_mfma_f32_16x16x32_bf16 v[20:23], v[234:237], v[210:213], v[20:23]
	v_mfma_f32_16x16x32_bf16 v[16:19], v[242:245], v[210:213], v[16:19]
	v_mfma_f32_16x16x32_bf16 v[4:7], v[234:237], v[226:229], v[4:7]
	v_mfma_f32_16x16x32_bf16 v[0:3], v[242:245], v[226:229], v[0:3]
	v_mfma_f32_16x16x32_bf16 v[52:55], v[238:241], v[198:201], v[52:55]
	s_add_i32 s36, s36, 2
	v_mfma_f32_16x16x32_bf16 v[48:51], v[246:249], v[198:201], v[48:51]
	s_add_u32 s8, s8, 0x100
	v_mfma_f32_16x16x32_bf16 v[36:39], v[238:241], v[206:209], v[36:39]
	s_addc_u32 s9, s9, 0
	v_mfma_f32_16x16x32_bf16 v[32:35], v[246:249], v[206:209], v[32:35]
	s_add_u32 s33, s33, 0x100
	v_mfma_f32_16x16x32_bf16 v[20:23], v[238:241], v[214:217], v[20:23]
	s_addc_u32 s35, s35, 0
	v_mfma_f32_16x16x32_bf16 v[16:19], v[246:249], v[214:217], v[16:19]
	s_cmp_gt_u32 s36, 29
	v_mfma_f32_16x16x32_bf16 v[4:7], v[238:241], v[230:233], v[4:7]
	v_mfma_f32_16x16x32_bf16 v[0:3], v[246:249], v[230:233], v[0:3]
	s_barrier
	s_cbranch_scc0 .LBB0_202
	s_cmp_lt_i32 s2, 18
	v_lshl_add_u32 v190, s3, 8, v186
	v_mov_b32_e32 v128, 1.0
	v_mov_b32_e32 v132, 0
	s_cselect_b64 s[18:19], -1, 0
	s_cmp_gt_i32 s2, 17
	v_mov_b32_e32 v134, 0
	v_mov_b32_e32 v135, 0
	v_mov_b32_e32 v136, 0
	v_mov_b32_e32 v137, 0
	v_mov_b32_e32 v138, 1.0
	v_mov_b32_e32 v139, 1.0
	v_mov_b32_e32 v140, 1.0
	v_mov_b32_e32 v141, 1.0
	s_cbranch_scc1 .LBB0_205
	v_lshlrev_b32_e32 v129, 8, v190
	v_and_b32_e32 v158, 0xfcf00, v129
	v_lshl_add_u64 v[130:131], v[146:147], 0, v[158:159]
	v_lshl_add_u64 v[134:135], v[148:149], 0, v[158:159]
	global_load_dwordx4 v[138:141], v[130:131], off
	s_nop 0
	global_load_dwordx4 v[134:137], v[134:135], off

; __device__ __forceinline__ int opaque_tid() { int t = threadIdx.x; asm volatile("" : "+v"(t)); return t; }
; #define PG8_STAGE(bufoff, gbase) do { _Pragma("unroll") for (int _i = 0; _i < 2; ++_i) \
;         __builtin_amdgcn_global_load_lds((const unsigned*)((const char*)(gbase) + voff[_i]), (LAS unsigned*)(lds + (bufoff) + ldsw + _i * 8192), 16, 0, 0); } while (0)
; #define PG8_WAIT_V(n) asm volatile("s_waitcnt vmcnt(" #n ")" ::: "memory")
; #define PG8_BAR __builtin_amdgcn_s_barrier()
; template <class Epi>
; DI void gemm_phase(LAS unsigned char* lds, const Gemm g, const StaticOrder& S, const Epi& E) {
;     const int tid = opaque_tid(), wid = __builtin_amdgcn_readfirstlane(tid >> 6), lane = tid & 63, wr = wid >> 2, wc = wid & 3, fr = lane & 15, fq = lane >> 4;
;     const int K = g.K, nt = K / BK;
;     unsigned voff[2];
; #pragma unroll
;     for (int i = 0; i < 2; ++i) { int R, C; stage_rc(tid * 16 + i * 8192, R, C); voff[i] = (unsigned)(R * K + C) * 2u; }
;     const size_t kstep = (size_t)(BK * 2);
;     const size_t hstep = (size_t)HALF * K * 2;
;     const size_t tstep = 2 * hstep;
;     const unsigned ldsw = (unsigned)wid * 1024u;
;     const int aoff = lds_byte(wr * 64 + fr, fq * 8), boff = lds_byte(wc * 32 + fr, fq * 8);
;     ...
;     Unit cur, nxt; int ui = 0;
;     if (!S.next(0, cur)) return;
;     f32x4 acc[2][2][4][2];
; #pragma unroll
;     for (int a = 0; a < 2; ++a)
; #pragma unroll
;         for (int b = 0; b < 2; ++b)
; #pragma unroll
;             for (int m = 0; m < 4; ++m)
; #pragma unroll
;                 for (int n = 0; n < 2; ++n) acc[a][b][m][n] = (f32x4){0.f, 0.f, 0.f, 0.f};
;     bf16x8 At[4][2], B0[2][2], B1[2][2];
;     const char* cA = (const char*)g.A + (size_t)cur.pm * tstep; const char* cB = (const char*)g.Bt + (size_t)cur.pn * tstep;
;     PG8_STAGE(PG8_SB(0, 0), cB); PG8_STAGE(PG8_SA(0, 0), cA); PG8_STAGE(PG8_SB(0, 1), cB + hstep); PG8_STAGE(PG8_SA(0, 1), cA + hstep);
;     if (wr == 1) PG8_BAR;
;     PG8_WAIT_V(4); PG8_BAR;
;     PG8_STAGE(PG8_SB(1, 0), cB + kstep); PG8_STAGE(PG8_SA(1, 0), cA + kstep); PG8_STAGE(PG8_SB(1, 1), cB + hstep + kstep);
;     PG8_WAIT_V(6); PG8_BAR;
.LBB0_223:
	s_andn2_b64 vcc, exec, s[6:7]
	s_cbranch_vccnz .LBB0_236
	v_readlane_b32 s2, v253, 27
	v_mov_b32_e32 v0, v156
	v_readlane_b32 s3, v253, 28
	s_andn2_b64 vcc, exec, s[2:3]
	v_readfirstlane_b32 s2, v0
	s_cbranch_vccnz .LBB0_236
	v_lshlrev_b32_e32 v5, 4, v0
	v_add_u32_e32 v2, 0x2000, v5
	v_ashrrev_i32_e32 v1, 31, v2
	v_lshrrev_b32_e32 v1, 22, v1
	v_add_u32_e32 v1, v2, v1
	v_ashrrev_i32_e32 v1, 10, v1
	v_lshlrev_b32_e32 v3, 5, v1
	v_and_b32_e32 v4, 32, v3
	v_mul_i32_i24_e32 v3, 0x400, v1
	v_sub_u32_e32 v2, v2, v3
	v_lshrrev_b32_e32 v3, 4, v2
	v_bitop3_b32 v3, v3, v2, 32 bitop3:0x6c
	v_ashrrev_i32_e32 v2, 31, v3
	v_lshrrev_b32_e32 v2, 26, v2
	v_add_u32_e32 v6, v3, v2
	v_ashrrev_i32_e32 v2, 6, v6
	v_and_b32_e32 v6, 0xc0, v6
	v_sub_u32_e32 v3, v3, v6
	v_ashrrev_i16_sdwa v3, v252, sext(v3) dst_sel:DWORD dst_unused:UNUSED_PAD src0_sel:DWORD src1_sel:BYTE_0
	v_lshlrev_b32_e32 v6, 3, v1
	v_bfe_i32 v3, v3, 0, 16
	v_and_b32_e32 v6, 0xffff0, v6
	v_add_u32_e32 v4, v4, v3
	v_add_lshl_u32 v6, v2, v6, 12
	v_lshl_add_u32 v128, v4, 1, v6
	v_ashrrev_i32_e32 v4, 31, v0
	v_lshrrev_b32_e32 v4, 26, v4
	v_add_u32_e32 v4, v0, v4
	v_ashrrev_i32_e32 v4, 6, v4
	v_lshlrev_b32_e32 v6, 5, v4
	v_and_b32_e32 v7, 32, v6
	v_bfe_i32 v6, v0, 27, 1
	v_lshrrev_b32_e32 v6, 22, v6
	v_add_u32_e32 v6, v5, v6
	v_and_b32_e32 v6, 0xfffffc00, v6
	v_sub_u32_e32 v5, v5, v6
	v_lshrrev_b32_e32 v6, 4, v5
	v_bitop3_b32 v6, v6, v5, 32 bitop3:0x6c
	v_ashrrev_i32_e32 v5, 31, v5
	v_readlane_b32 s4, v255, 43
	v_lshrrev_b32_e32 v5, 26, v5
	s_mov_b32 s6, s4
	v_add_u32_e32 v5, v6, v5
	s_mul_i32 s3, s6, 0x1800000
	v_ashrrev_i32_e32 v5, 6, v5
	v_readlane_b32 s5, v255, 44
	s_mul_hi_u32 s4, s4, 0x1800000
	s_add_u32 s3, s84, s3
	v_mul_i32_i24_e32 v8, 64, v5
	s_addc_u32 s22, s85, s4
	s_ashr_i32 s5, s2, 6
	v_sub_u32_e32 v6, v6, v8
	s_ashr_i32 s4, s2, 8
	s_lshl_b32 s23, s5, 10
	v_ashrrev_i16_sdwa v6, v252, sext(v6) dst_sel:DWORD dst_unused:UNUSED_PAD src0_sel:DWORD src1_sel:BYTE_0
	v_lshlrev_b32_e32 v8, 3, v4
	v_readlane_b32 s6, v254, 33
	v_bfe_i32 v6, v6, 0, 16
	v_and_b32_e32 v8, 0xffff0, v8
	v_readlane_b32 s7, v254, 34
	s_add_u32 s18, s3, s6
	v_add_u32_e32 v7, v7, v6
	v_add_lshl_u32 v8, v5, v8, 12
	s_addc_u32 s19, s22, s7
	s_add_i32 s24, s23, 0
	v_lshl_add_u32 v158, v7, 1, v8
	s_add_i32 m0, s24, 0x10000
	v_readlane_b32 s6, v254, 38
	global_load_lds_dwordx4 v158, s[18:19]
	s_add_i32 m0, s24, 0x12000
	v_readlane_b32 s7, v254, 39
	global_load_lds_dwordx4 v128, s[18:19]
	s_mov_b32 m0, s24
	s_add_i32 s25, s24, 0x2000
	s_nop 1
	global_load_lds_dwordx4 v158, s[6:7]
	s_mov_b32 m0, s25
	s_nop 0
	global_load_lds_dwordx4 v128, s[6:7]
	s_add_u32 s6, s18, 0x80000
	s_addc_u32 s7, s19, 0
	s_add_i32 m0, s24, 0x14000
	s_add_i32 s26, s24, 0x4000
	global_load_lds_dwordx4 v158, s[6:7]
	s_add_i32 m0, s24, 0x16000
	s_add_i32 s27, s24, 0x6000
	global_load_lds_dwordx4 v128, s[6:7]
	v_readlane_b32 s6, v254, 40
	s_mov_b32 m0, s26
	v_readlane_b32 s7, v254, 41
	s_cmp_lg_u32 s4, 1
	s_nop 3
	global_load_lds_dwordx4 v158, s[6:7]
	s_mov_b32 m0, s27
	s_nop 0
	global_load_lds_dwordx4 v128, s[6:7]
	s_cbranch_scc1 .LBB0_227
	s_setprio 1
	s_barrier

; #define PG8_STAGE(bufoff, gbase) do { _Pragma("unroll") for (int _i = 0; _i < 2; ++_i) \
;         __builtin_amdgcn_global_load_lds((const unsigned*)((const char*)(gbase) + voff[_i]), (LAS unsigned*)(lds + (bufoff) + ldsw + _i * 8192), 16, 0, 0); } while (0)
; #define PG8_LDA(dst, b, h) do { _Pragma("unroll") for (int m = 0; m < 4; ++m) _Pragma("unroll") for (int k = 0; k < 2; ++k) dst[m][k] = *(const LAS bf16x8*)(lds + PG8_SA(b, h) + aoff + m * 2048 + k * 1024); } while (0)
; #define PG8_LDB(dst, b, h) do { _Pragma("unroll") for (int n = 0; n < 2; ++n) _Pragma("unroll") for (int k = 0; k < 2; ++k) dst[n][k] = *(const LAS bf16x8*)(lds + PG8_SB(b, h) + boff + n * 2048 + k * 1024); } while (0)
; #define PG8_MMA(ai, bj, At, Bt) do { __builtin_amdgcn_s_setprio(1); _Pragma("unroll") for (int m = 0; m < 4; ++m) _Pragma("unroll") for (int n = 0; n < 2; ++n) _Pragma("unroll") for (int k = 0; k < 2; ++k) \
;         acc[ai][bj][m][n] = __builtin_amdgcn_mfma_f32_16x16x32_bf16(Bt[n][k], At[m][k], acc[ai][bj][m][n], 0, 0, 0); __builtin_amdgcn_s_setprio(0); } while (0)
; #define PG8_WAIT_V(n) asm volatile("s_waitcnt vmcnt(" #n ")" ::: "memory")
; #define PG8_WAIT_L(n) asm volatile("s_waitcnt lgkmcnt(" #n ")" ::: "memory")
; #define PG8_BAR __builtin_amdgcn_s_barrier()
; #define PG8_SCHED __builtin_amdgcn_sched_barrier(0)
; template <class Epi>
; DI void gemm_phase(LAS unsigned char* lds, const Gemm g, const StaticOrder& S, const Epi& E) {
;     ...
;         for (int t = 0; t < nt; t += 2) {
;             const bool last = (t == nt - 2);
;             const char* a1 = cA + (size_t)(t + 1) * kstep;
;             const char* a2 = last ? nA : cA + (size_t)(t + 2) * kstep; const char* b2 = last ? nB : cB + (size_t)(t + 2) * kstep;
;             const char* a3 = a2 + kstep; const char* b3 = b2 + kstep;
;             PG8_LDB(B0, 0, 0); PG8_SCHED; PG8_LDA(At, 0, 0); PG8_STAGE(PG8_SA(1, 1), a1 + hstep);
;             PG8_WAIT_L(8); PG8_BAR; PG8_WAIT_L(0); PG8_MMA(0, 0, At, B0); PG8_BAR; PG8_SCHED;
;             PG8_LDB(B1, 0, 1); PG8_STAGE(PG8_SB(0, 0), b2);
;             PG8_BAR; PG8_WAIT_L(0); PG8_MMA(0, 1, At, B1); PG8_BAR;
;             PG8_LDA(At, 0, 1); PG8_STAGE(PG8_SA(0, 0), a2);
;             PG8_BAR; PG8_WAIT_L(0); PG8_MMA(1, 0, At, B0); PG8_BAR; PG8_SCHED;
;             PG8_STAGE(PG8_SB(0, 1), b2 + hstep);
;             PG8_WAIT_V(6); PG8_BAR; PG8_MMA(1, 1, At, B1); PG8_BAR;
.LBB0_231:
	ds_read_b128 v[138:141], v135
	ds_read_b128 v[142:145], v135 offset:1024
	ds_read_b128 v[146:149], v135 offset:2048
	ds_read_b128 v[150:153], v135 offset:3072
	ds_read_b128 v[186:189], v137
	ds_read_b128 v[190:193], v137 offset:1024
	ds_read_b128 v[194:197], v137 offset:2048
	ds_read_b128 v[198:201], v137 offset:3072
	ds_read_b128 v[202:205], v137 offset:4096
	ds_read_b128 v[206:209], v137 offset:5120
	ds_read_b128 v[210:213], v137 offset:6144
	ds_read_b128 v[214:217], v137 offset:7168
	s_add_u32 s18, s16, 0xfff80080
	s_addc_u32 s19, s17, -1
	s_add_i32 s37, 0, 0x10000
	s_cmp_eq_u32 s36, 28
	s_cselect_b32 s21, s4, s19
	s_cselect_b32 s20, s5, s18
	s_cselect_b32 s19, s9, s35
	s_cselect_b32 s18, s11, s34
	s_add_i32 m0, s24, 0xc000
	s_nop 0
	global_load_lds_dwordx4 v130, s[16:17]
	s_add_i32 m0, s24, 0xe000
	s_nop 0
	global_load_lds_dwordx4 v132, s[16:17]
	s_waitcnt lgkmcnt(8)
	s_barrier
	s_waitcnt lgkmcnt(0)
	v_mfma_f32_16x16x32_bf16 v[124:127], v[138:141], v[186:189], v[124:127]
	v_mfma_f32_16x16x32_bf16 v[120:123], v[146:149], v[186:189], v[120:123]
	v_mfma_f32_16x16x32_bf16 v[116:119], v[138:141], v[194:197], v[116:119]
	v_mfma_f32_16x16x32_bf16 v[112:115], v[146:149], v[194:197], v[112:115]
	v_mfma_f32_16x16x32_bf16 v[100:103], v[138:141], v[202:205], v[100:103]
	v_mfma_f32_16x16x32_bf16 v[96:99], v[146:149], v[202:205], v[96:99]
	v_mfma_f32_16x16x32_bf16 v[84:87], v[138:141], v[210:213], v[84:87]
	v_mfma_f32_16x16x32_bf16 v[80:83], v[146:149], v[210:213], v[80:83]
	v_mfma_f32_16x16x32_bf16 v[124:127], v[142:145], v[190:193], v[124:127]
	v_mfma_f32_16x16x32_bf16 v[120:123], v[150:153], v[190:193], v[120:123]
	v_mfma_f32_16x16x32_bf16 v[116:119], v[142:145], v[198:201], v[116:119]
	v_mfma_f32_16x16x32_bf16 v[112:115], v[150:153], v[198:201], v[112:115]
	v_mfma_f32_16x16x32_bf16 v[100:103], v[142:145], v[206:209], v[100:103]
	v_mfma_f32_16x16x32_bf16 v[96:99], v[150:153], v[206:209], v[96:99]
	v_mfma_f32_16x16x32_bf16 v[84:87], v[142:145], v[214:217], v[84:87]
	v_mfma_f32_16x16x32_bf16 v[80:83], v[150:153], v[214:217], v[80:83]
	s_barrier
	ds_read_b128 v[226:229], v135 offset:16384
	ds_read_b128 v[230:233], v135 offset:17408
	ds_read_b128 v[234:237], v135 offset:18432
	ds_read_b128 v[238:241], v135 offset:19456
	s_add_i32 s40, 0, 0x14000
	s_add_i32 s37, s37, s23
	s_mov_b32 m0, s37
	s_nop 0
	global_load_lds_dwordx4 v158, s[18:19]
	s_add_i32 m0, s37, 0x2000
	s_nop 0
	global_load_lds_dwordx4 v128, s[18:19]
	s_waitcnt lgkmcnt(0)
	s_barrier
	v_mfma_f32_16x16x32_bf16 v[108:111], v[226:229], v[186:189], v[108:111]
	v_mfma_f32_16x16x32_bf16 v[104:107], v[234:237], v[186:189], v[104:107]
	v_mfma_f32_16x16x32_bf16 v[92:95], v[226:229], v[194:197], v[92:95]
	v_mfma_f32_16x16x32_bf16 v[88:91], v[234:237], v[194:197], v[88:91]
	v_mfma_f32_16x16x32_bf16 v[76:79], v[226:229], v[202:205], v[76:79]
	v_mfma_f32_16x16x32_bf16 v[72:75], v[234:237], v[202:205], v[72:75]
	v_mfma_f32_16x16x32_bf16 v[68:71], v[226:229], v[210:213], v[68:71]
	v_mfma_f32_16x16x32_bf16 v[64:67], v[234:237], v[210:213], v[64:67]
	v_mfma_f32_16x16x32_bf16 v[108:111], v[230:233], v[190:193], v[108:111]
	s_mov_b32 m0, s24
	v_mfma_f32_16x16x32_bf16 v[104:107], v[238:241], v[190:193], v[104:107]
	v_mfma_f32_16x16x32_bf16 v[92:95], v[230:233], v[198:201], v[92:95]
	v_mfma_f32_16x16x32_bf16 v[88:91], v[238:241], v[198:201], v[88:91]
	v_mfma_f32_16x16x32_bf16 v[76:79], v[230:233], v[206:209], v[76:79]
	v_mfma_f32_16x16x32_bf16 v[72:75], v[238:241], v[206:209], v[72:75]
	v_mfma_f32_16x16x32_bf16 v[68:71], v[230:233], v[214:217], v[68:71]
	v_mfma_f32_16x16x32_bf16 v[64:67], v[238:241], v[214:217], v[64:67]
	s_barrier
	ds_read_b128 v[186:189], v137 offset:16384
	ds_read_b128 v[190:193], v137 offset:17408
	ds_read_b128 v[194:197], v137 offset:18432
	ds_read_b128 v[198:201], v137 offset:19456
	ds_read_b128 v[202:205], v137 offset:20480
	ds_read_b128 v[206:209], v137 offset:21504
	ds_read_b128 v[210:213], v137 offset:22528
	ds_read_b128 v[214:217], v137 offset:23552
	global_load_lds_dwordx4 v158, s[20:21]
	s_mov_b64 s[100:101], s[20:21]
	s_mov_b32 m0, s25
	s_nop 0
	global_load_lds_dwordx4 v128, s[20:21]
	s_waitcnt lgkmcnt(0)
	s_barrier
	v_mfma_f32_16x16x32_bf16 v[60:63], v[138:141], v[186:189], v[60:63]
	v_mfma_f32_16x16x32_bf16 v[56:59], v[146:149], v[186:189], v[56:59]
	v_mfma_f32_16x16x32_bf16 v[52:55], v[138:141], v[194:197], v[52:55]
	v_mfma_f32_16x16x32_bf16 v[48:51], v[146:149], v[194:197], v[48:51]
	v_mfma_f32_16x16x32_bf16 v[36:39], v[138:141], v[202:205], v[36:39]
	v_mfma_f32_16x16x32_bf16 v[32:35], v[146:149], v[202:205], v[32:35]
	v_mfma_f32_16x16x32_bf16 v[20:23], v[138:141], v[210:213], v[20:23]
	v_mfma_f32_16x16x32_bf16 v[16:19], v[146:149], v[210:213], v[16:19]
	v_mfma_f32_16x16x32_bf16 v[60:63], v[142:145], v[190:193], v[60:63]
	v_mfma_f32_16x16x32_bf16 v[56:59], v[150:153], v[190:193], v[56:59]
	v_mfma_f32_16x16x32_bf16 v[52:55], v[142:145], v[198:201], v[52:55]
	v_mfma_f32_16x16x32_bf16 v[48:51], v[150:153], v[198:201], v[48:51]
	v_mfma_f32_16x16x32_bf16 v[36:39], v[142:145], v[206:209], v[36:39]
	v_mfma_f32_16x16x32_bf16 v[32:35], v[150:153], v[206:209], v[32:35]
	v_mfma_f32_16x16x32_bf16 v[20:23], v[142:145], v[214:217], v[20:23]
	v_mfma_f32_16x16x32_bf16 v[16:19], v[150:153], v[214:217], v[16:19]
	s_barrier
	s_add_u32 s38, s18, 0x80000
	s_addc_u32 s39, s19, 0
	s_add_i32 s37, s40, s23
	s_mov_b32 m0, s37
	s_nop 0
	global_load_lds_dwordx4 v158, s[38:39]
	s_add_i32 m0, s37, 0x2000
	s_nop 0
	global_load_lds_dwordx4 v128, s[38:39]
	s_waitcnt vmcnt(6)
	s_barrier
; #define PG8_STAGE(bufoff, gbase) do { _Pragma("unroll") for (int _i = 0; _i < 2; ++_i) \
;         __builtin_amdgcn_global_load_lds((const unsigned*)((const char*)(gbase) + voff[_i]), (LAS unsigned*)(lds + (bufoff) + ldsw + _i * 8192), 16, 0, 0); } while (0)
; #define PG8_LDA(dst, b, h) do { _Pragma("unroll") for (int m = 0; m < 4; ++m) _Pragma("unroll") for (int k = 0; k < 2; ++k) dst[m][k] = *(const LAS bf16x8*)(lds + PG8_SA(b, h) + aoff + m * 2048 + k * 1024); } while (0)
; #define PG8_LDB(dst, b, h) do { _Pragma("unroll") for (int n = 0; n < 2; ++n) _Pragma("unroll") for (int k = 0; k < 2; ++k) dst[n][k] = *(const LAS bf16x8*)(lds + PG8_SB(b, h) + boff + n * 2048 + k * 1024); } while (0)
; #define PG8_MMA(ai, bj, At, Bt) do { __builtin_amdgcn_s_setprio(1); _Pragma("unroll") for (int m = 0; m < 4; ++m) _Pragma("unroll") for (int n = 0; n < 2; ++n) _Pragma("unroll") for (int k = 0; k < 2; ++k) \
;         acc[ai][bj][m][n] = __builtin_amdgcn_mfma_f32_16x16x32_bf16(Bt[n][k], At[m][k], acc[ai][bj][m][n], 0, 0, 0); __builtin_amdgcn_s_setprio(0); } while (0)
; #define PG8_WAIT_V(n) asm volatile("s_waitcnt vmcnt(" #n ")" ::: "memory")
; #define PG8_WAIT_L(n) asm volatile("s_waitcnt lgkmcnt(" #n ")" ::: "memory")
; #define PG8_BAR __builtin_amdgcn_s_barrier()
; #define PG8_SCHED __builtin_amdgcn_sched_barrier(0)
; template <class Epi>
; DI void gemm_phase(LAS unsigned char* lds, const Gemm g, const StaticOrder& S, const Epi& E) {
;     ...
;             PG8_WAIT_V(6); PG8_BAR; PG8_MMA(1, 1, At, B1); PG8_BAR;
;             PG8_LDB(B0, 1, 0); PG8_SCHED; PG8_LDA(At, 1, 0); PG8_STAGE(PG8_SA(0, 1), a2 + hstep);
;             PG8_WAIT_L(8); PG8_BAR; PG8_WAIT_L(0); PG8_MMA(0, 0, At, B0); PG8_BAR; PG8_SCHED;
;             PG8_LDB(B1, 1, 1); PG8_STAGE(PG8_SB(1, 0), b3);
;             PG8_BAR; PG8_WAIT_L(0); PG8_MMA(0, 1, At, B1); PG8_BAR;
;             PG8_LDA(At, 1, 1); PG8_STAGE(PG8_SA(1, 0), a3);
;             PG8_BAR; PG8_WAIT_L(0); PG8_MMA(1, 0, At, B0); PG8_BAR; PG8_SCHED;
	v_mfma_f32_16x16x32_bf16 v[44:47], v[226:229], v[186:189], v[44:47]
	v_mfma_f32_16x16x32_bf16 v[40:43], v[234:237], v[186:189], v[40:43]
	v_mfma_f32_16x16x32_bf16 v[28:31], v[226:229], v[194:197], v[28:31]
	v_mfma_f32_16x16x32_bf16 v[24:27], v[234:237], v[194:197], v[24:27]
	v_mfma_f32_16x16x32_bf16 v[12:15], v[226:229], v[202:205], v[12:15]
	v_mfma_f32_16x16x32_bf16 v[8:11], v[234:237], v[202:205], v[8:11]
	v_mfma_f32_16x16x32_bf16 v[4:7], v[226:229], v[210:213], v[4:7]
	v_mfma_f32_16x16x32_bf16 v[0:3], v[234:237], v[210:213], v[0:3]
	v_mfma_f32_16x16x32_bf16 v[44:47], v[230:233], v[190:193], v[44:47]
	s_add_i32 s37, 0, 0x18000
	v_mfma_f32_16x16x32_bf16 v[40:43], v[238:241], v[190:193], v[40:43]
	v_mfma_f32_16x16x32_bf16 v[28:31], v[230:233], v[198:201], v[28:31]
	v_mfma_f32_16x16x32_bf16 v[24:27], v[238:241], v[198:201], v[24:27]
	v_mfma_f32_16x16x32_bf16 v[12:15], v[230:233], v[206:209], v[12:15]
	v_mfma_f32_16x16x32_bf16 v[8:11], v[238:241], v[206:209], v[8:11]
	v_mfma_f32_16x16x32_bf16 v[4:7], v[230:233], v[214:217], v[4:7]
	v_mfma_f32_16x16x32_bf16 v[0:3], v[238:241], v[214:217], v[0:3]
	s_barrier
	ds_read_b128 v[138:141], v135 offset:32768
	ds_read_b128 v[142:145], v135 offset:33792
	ds_read_b128 v[146:149], v135 offset:34816
	ds_read_b128 v[150:153], v135 offset:35840
	ds_read_b128 v[186:189], v137 offset:32768
	ds_read_b128 v[190:193], v137 offset:33792
	ds_read_b128 v[194:197], v137 offset:34816
	ds_read_b128 v[198:201], v137 offset:35840
	ds_read_b128 v[202:205], v137 offset:36864
	ds_read_b128 v[206:209], v137 offset:37888
	ds_read_b128 v[210:213], v137 offset:38912
	ds_read_b128 v[214:217], v137 offset:39936
	s_add_u32 s20, s20, 0x80000
	s_addc_u32 s21, s21, 0
	s_mov_b32 m0, s26
	s_nop 0
	global_load_lds_dwordx4 v158, s[20:21]
	s_mov_b32 m0, s27
	s_nop 0
	global_load_lds_dwordx4 v128, s[20:21]
	s_waitcnt lgkmcnt(8)
	s_barrier
	s_waitcnt lgkmcnt(0)
	v_mfma_f32_16x16x32_bf16 v[124:127], v[138:141], v[186:189], v[124:127]
	v_mfma_f32_16x16x32_bf16 v[120:123], v[146:149], v[186:189], v[120:123]
	v_mfma_f32_16x16x32_bf16 v[116:119], v[138:141], v[194:197], v[116:119]
	v_mfma_f32_16x16x32_bf16 v[112:115], v[146:149], v[194:197], v[112:115]
	v_mfma_f32_16x16x32_bf16 v[100:103], v[138:141], v[202:205], v[100:103]
	v_mfma_f32_16x16x32_bf16 v[96:99], v[146:149], v[202:205], v[96:99]
	v_mfma_f32_16x16x32_bf16 v[84:87], v[138:141], v[210:213], v[84:87]
	v_mfma_f32_16x16x32_bf16 v[80:83], v[146:149], v[210:213], v[80:83]
	v_mfma_f32_16x16x32_bf16 v[124:127], v[142:145], v[190:193], v[124:127]
	v_mfma_f32_16x16x32_bf16 v[120:123], v[150:153], v[190:193], v[120:123]
	v_mfma_f32_16x16x32_bf16 v[116:119], v[142:145], v[198:201], v[116:119]
	v_mfma_f32_16x16x32_bf16 v[112:115], v[150:153], v[198:201], v[112:115]
	v_mfma_f32_16x16x32_bf16 v[100:103], v[142:145], v[206:209], v[100:103]
	v_mfma_f32_16x16x32_bf16 v[96:99], v[150:153], v[206:209], v[96:99]
	v_mfma_f32_16x16x32_bf16 v[84:87], v[142:145], v[214:217], v[84:87]
	v_mfma_f32_16x16x32_bf16 v[80:83], v[150:153], v[214:217], v[80:83]
	s_barrier
	ds_read_b128 v[226:229], v135 offset:49152
	ds_read_b128 v[230:233], v135 offset:50176
	ds_read_b128 v[234:237], v135 offset:51200
	ds_read_b128 v[238:241], v135 offset:52224
	s_add_i32 s20, 0, 0x1c000
	s_add_i32 s21, s37, s23
	s_add_i32 m0, s21, 0xffffff80
	s_nop 0
	global_load_lds_dwordx4 v158, s[18:19] offset:128
	s_add_i32 m0, s21, 0x1f80
	s_nop 0
	global_load_lds_dwordx4 v128, s[18:19] offset:128
	s_waitcnt lgkmcnt(0)
	s_barrier
	v_mfma_f32_16x16x32_bf16 v[108:111], v[226:229], v[186:189], v[108:111]
	v_mfma_f32_16x16x32_bf16 v[104:107], v[234:237], v[186:189], v[104:107]
	v_mfma_f32_16x16x32_bf16 v[92:95], v[226:229], v[194:197], v[92:95]
	v_mfma_f32_16x16x32_bf16 v[88:91], v[234:237], v[194:197], v[88:91]
	v_mfma_f32_16x16x32_bf16 v[76:79], v[226:229], v[202:205], v[76:79]
	v_mfma_f32_16x16x32_bf16 v[72:75], v[234:237], v[202:205], v[72:75]
	v_mfma_f32_16x16x32_bf16 v[68:71], v[226:229], v[210:213], v[68:71]
	v_mfma_f32_16x16x32_bf16 v[64:67], v[234:237], v[210:213], v[64:67]
	v_mfma_f32_16x16x32_bf16 v[108:111], v[230:233], v[190:193], v[108:111]
	s_add_i32 m0, s28, 0xffffff80
	v_mfma_f32_16x16x32_bf16 v[104:107], v[238:241], v[190:193], v[104:107]
	v_mfma_f32_16x16x32_bf16 v[92:95], v[230:233], v[198:201], v[92:95]
	v_mfma_f32_16x16x32_bf16 v[88:91], v[238:241], v[198:201], v[88:91]
	v_mfma_f32_16x16x32_bf16 v[76:79], v[230:233], v[206:209], v[76:79]
	v_mfma_f32_16x16x32_bf16 v[72:75], v[238:241], v[206:209], v[72:75]
	v_mfma_f32_16x16x32_bf16 v[68:71], v[230:233], v[214:217], v[68:71]
	v_mfma_f32_16x16x32_bf16 v[64:67], v[238:241], v[214:217], v[64:67]
	s_barrier
	ds_read_b128 v[186:189], v137 offset:49152
	ds_read_b128 v[190:193], v137 offset:50176
	ds_read_b128 v[194:197], v137 offset:51200
	ds_read_b128 v[198:201], v137 offset:52224
	ds_read_b128 v[202:205], v137 offset:53248
	ds_read_b128 v[206:209], v137 offset:54272
	ds_read_b128 v[210:213], v137 offset:55296
	ds_read_b128 v[214:217], v137 offset:56320
	global_load_lds_dwordx4 v158, s[100:101] offset:128
	s_add_i32 m0, s29, 0xffffff80
	s_nop 0
	global_load_lds_dwordx4 v128, s[100:101] offset:128
	s_waitcnt lgkmcnt(0)
	s_barrier
; #define PG8_STAGE(bufoff, gbase) do { _Pragma("unroll") for (int _i = 0; _i < 2; ++_i) \
;         __builtin_amdgcn_global_load_lds((const unsigned*)((const char*)(gbase) + voff[_i]), (LAS unsigned*)(lds + (bufoff) + ldsw + _i * 8192), 16, 0, 0); } while (0)
; #define PG8_MMA(ai, bj, At, Bt) do { __builtin_amdgcn_s_setprio(1); _Pragma("unroll") for (int m = 0; m < 4; ++m) _Pragma("unroll") for (int n = 0; n < 2; ++n) _Pragma("unroll") for (int k = 0; k < 2; ++k) \
;         acc[ai][bj][m][n] = __builtin_amdgcn_mfma_f32_16x16x32_bf16(Bt[n][k], At[m][k], acc[ai][bj][m][n], 0, 0, 0); __builtin_amdgcn_s_setprio(0); } while (0)
; #define PG8_WAIT_V(n) asm volatile("s_waitcnt vmcnt(" #n ")" ::: "memory")
; #define PG8_WAIT_L(n) asm volatile("s_waitcnt lgkmcnt(" #n ")" ::: "memory")
; #define PG8_BAR __builtin_amdgcn_s_barrier()
; #define PG8_SCHED __builtin_amdgcn_sched_barrier(0)
; template <class Epi>
; DI void gemm_phase(LAS unsigned char* lds, const Gemm g, const StaticOrder& S, const Epi& E) {
;     ...
;             PG8_BAR; PG8_WAIT_L(0); PG8_MMA(1, 0, At, B0); PG8_BAR; PG8_SCHED;
;             PG8_STAGE(PG8_SB(1, 1), b3 + hstep);
;             PG8_WAIT_V(6); PG8_BAR; PG8_MMA(1, 1, At, B1); PG8_BAR;
;         }
	v_mfma_f32_16x16x32_bf16 v[60:63], v[138:141], v[186:189], v[60:63]
	v_mfma_f32_16x16x32_bf16 v[56:59], v[146:149], v[186:189], v[56:59]
	v_mfma_f32_16x16x32_bf16 v[52:55], v[138:141], v[194:197], v[52:55]
	v_mfma_f32_16x16x32_bf16 v[48:51], v[146:149], v[194:197], v[48:51]
	v_mfma_f32_16x16x32_bf16 v[36:39], v[138:141], v[202:205], v[36:39]
	v_mfma_f32_16x16x32_bf16 v[32:35], v[146:149], v[202:205], v[32:35]
	v_mfma_f32_16x16x32_bf16 v[20:23], v[138:141], v[210:213], v[20:23]
	v_mfma_f32_16x16x32_bf16 v[16:19], v[146:149], v[210:213], v[16:19]
	v_mfma_f32_16x16x32_bf16 v[60:63], v[142:145], v[190:193], v[60:63]
	v_mfma_f32_16x16x32_bf16 v[56:59], v[150:153], v[190:193], v[56:59]
	v_mfma_f32_16x16x32_bf16 v[52:55], v[142:145], v[198:201], v[52:55]
	v_mfma_f32_16x16x32_bf16 v[48:51], v[150:153], v[198:201], v[48:51]
	v_mfma_f32_16x16x32_bf16 v[36:39], v[142:145], v[206:209], v[36:39]
	v_mfma_f32_16x16x32_bf16 v[32:35], v[150:153], v[206:209], v[32:35]
	v_mfma_f32_16x16x32_bf16 v[20:23], v[142:145], v[214:217], v[20:23]
	v_mfma_f32_16x16x32_bf16 v[16:19], v[150:153], v[214:217], v[16:19]
	s_barrier
	s_add_u32 s18, s18, 0x80080
	s_addc_u32 s19, s19, 0
	s_add_i32 s20, s20, s23
	s_mov_b32 m0, s20
	s_nop 0
	global_load_lds_dwordx4 v158, s[18:19]
	s_add_i32 m0, s20, 0x2000
	s_nop 0
	global_load_lds_dwordx4 v128, s[18:19]
	s_waitcnt vmcnt(6)
	s_barrier
	v_mfma_f32_16x16x32_bf16 v[44:47], v[226:229], v[186:189], v[44:47]
	v_mfma_f32_16x16x32_bf16 v[40:43], v[234:237], v[186:189], v[40:43]
	v_mfma_f32_16x16x32_bf16 v[28:31], v[226:229], v[194:197], v[28:31]
	v_mfma_f32_16x16x32_bf16 v[24:27], v[234:237], v[194:197], v[24:27]
	v_mfma_f32_16x16x32_bf16 v[12:15], v[226:229], v[202:205], v[12:15]
	v_mfma_f32_16x16x32_bf16 v[8:11], v[234:237], v[202:205], v[8:11]
	v_mfma_f32_16x16x32_bf16 v[4:7], v[226:229], v[210:213], v[4:7]
	v_mfma_f32_16x16x32_bf16 v[0:3], v[234:237], v[210:213], v[0:3]
	v_mfma_f32_16x16x32_bf16 v[44:47], v[230:233], v[190:193], v[44:47]
	s_add_i32 s36, s36, 2
	v_mfma_f32_16x16x32_bf16 v[40:43], v[238:241], v[190:193], v[40:43]
	s_add_u32 s16, s16, 0x100
	v_mfma_f32_16x16x32_bf16 v[28:31], v[230:233], v[198:201], v[28:31]
	s_addc_u32 s17, s17, 0
	v_mfma_f32_16x16x32_bf16 v[24:27], v[238:241], v[198:201], v[24:27]
	s_add_u32 s34, s34, 0x100
	v_mfma_f32_16x16x32_bf16 v[12:15], v[230:233], v[206:209], v[12:15]
	s_addc_u32 s35, s35, 0
	v_mfma_f32_16x16x32_bf16 v[8:11], v[238:241], v[206:209], v[8:11]
	s_cmp_gt_u32 s36, 29
	v_mfma_f32_16x16x32_bf16 v[4:7], v[230:233], v[214:217], v[4:7]
	v_mfma_f32_16x16x32_bf16 v[0:3], v[238:241], v[214:217], v[0:3]
	s_barrier
	s_cbranch_scc0 .LBB0_231
; #define PG8_WAIT_V(n) asm volatile("s_waitcnt vmcnt(" #n ")" ::: "memory")
; #define PG8_BAR __builtin_amdgcn_s_barrier()
; template <class Epi>
; DI void gemm_phase(LAS unsigned char* lds, const Gemm g, const StaticOrder& S, const Epi& E) {
;     ...
;         E(acc, cur, wr, wc, fr, fq);
;         if (!has_next) break;
; #pragma unroll
;         for (int a = 0; a < 2; ++a)
; #pragma unroll
;             for (int b = 0; b < 2; ++b)
; #pragma unroll
;                 for (int m = 0; m < 4; ++m)
; #pragma unroll
;                     for (int n = 0; n < 2; ++n) acc[a][b][m][n] = (f32x4){0.f, 0.f, 0.f, 0.f};
;         cur = nxt; cA = nA; cB = nB; ++ui;
;     }
;     PG8_WAIT_V(0);
;     if (wr == 0) PG8_BAR;
;     DI void operator()(const f32x4 (&acc)[2][2][4][2], const Unit& u, int wr, int wc, int fr, int fq) const {
;         const int row0 = u.pm * BM + wr * 64 + fr, col0 = u.pn * BM + wc * 32 + 8 * fq;
; #pragma unroll
;         for (int ai = 0; ai < 2; ++ai)
; #pragma unroll
;             for (int m = 0; m < 4; ++m) { u16* rowp = O + (size_t)(row0 + ai * HALF + m * 16) * ldc + col0;
; #pragma unroll
;                 for (int bj = 0; bj < 2; ++bj) { const f32x4 v0 = acc[ai][bj][m][0], v1 = acc[ai][bj][m][1];
;                     *(u32x4*)(rowp + bj * HALF) = (u32x4){pk(v0[0], v0[1]), pk(v0[2], v0[3]), pk(v1[0], v1[1]), pk(v1[2], v1[3])}; } }
	v_lshl_add_u32 v144, s33, 8, v134
	v_lshl_or_b32 v138, s31, 8, v136
	v_ashrrev_i32_e32 v139, 31, v138
	v_mov_b64_e32 v[140:141], s[50:51]
	s_movk_i32 s9, 0x3000
	v_cvt_pk_bf16_f32 v68, v68, v69
	v_cvt_pk_bf16_f32 v69, v70, v71
	v_cvt_pk_bf16_f32 v70, v64, v65
	v_add_u32_e32 v64, 0x80, v144
	v_mad_i64_i32 v[142:143], s[4:5], v144, s9, v[140:141]
	v_lshlrev_b64 v[138:139], 1, v[138:139]
	v_cvt_pk_bf16_f32 v108, v108, v109
	v_cvt_pk_bf16_f32 v109, v110, v111
	v_cvt_pk_bf16_f32 v110, v104, v105
	v_or_b32_e32 v104, 16, v144
	v_mad_i64_i32 v[64:65], s[4:5], v64, s9, v[140:141]
	v_cvt_pk_bf16_f32 v44, v44, v45
	v_cvt_pk_bf16_f32 v45, v46, v47
	v_cvt_pk_bf16_f32 v46, v40, v41
	v_add_u32_e32 v40, 0x90, v144
	v_lshl_add_u64 v[142:143], v[142:143], 0, v[138:139]
	v_cvt_pk_bf16_f32 v111, v106, v107
	v_mad_i64_i32 v[104:105], s[4:5], v104, s9, v[140:141]
	v_cvt_pk_bf16_f32 v92, v92, v93
	v_cvt_pk_bf16_f32 v93, v94, v95
	v_cvt_pk_bf16_f32 v94, v88, v89
	v_or_b32_e32 v88, 32, v144
	v_lshl_add_u64 v[64:65], v[64:65], 0, v[138:139]
	v_cvt_pk_bf16_f32 v47, v42, v43
	v_mad_i64_i32 v[40:41], s[4:5], v40, s9, v[140:141]
	v_cvt_pk_bf16_f32 v28, v28, v29
	v_cvt_pk_bf16_f32 v29, v30, v31
	v_cvt_pk_bf16_f32 v30, v24, v25
	v_add_u32_e32 v24, 0xa0, v144
	global_store_dwordx4 v[142:143], v[108:111], off offset:256
	v_cvt_pk_bf16_f32 v95, v90, v91
	v_mad_i64_i32 v[88:89], s[4:5], v88, s9, v[140:141]
	v_lshl_add_u64 v[108:109], v[104:105], 0, v[138:139]
	v_cvt_pk_bf16_f32 v76, v76, v77
	v_cvt_pk_bf16_f32 v77, v78, v79
	v_cvt_pk_bf16_f32 v78, v72, v73
	v_or_b32_e32 v72, 48, v144
	global_store_dwordx4 v[64:65], v[44:47], off offset:256
	v_cvt_pk_bf16_f32 v31, v26, v27
	v_mad_i64_i32 v[24:25], s[4:5], v24, s9, v[140:141]
	v_lshl_add_u64 v[44:45], v[40:41], 0, v[138:139]
	v_cvt_pk_bf16_f32 v12, v12, v13
	v_cvt_pk_bf16_f32 v13, v14, v15
	v_cvt_pk_bf16_f32 v14, v8, v9
	v_add_u32_e32 v8, 0xb0, v144
	global_store_dwordx4 v[108:109], v[92:95], off offset:256
	v_cvt_pk_bf16_f32 v79, v74, v75
	v_mad_i64_i32 v[72:73], s[4:5], v72, s9, v[140:141]
	v_lshl_add_u64 v[92:93], v[88:89], 0, v[138:139]
	global_store_dwordx4 v[44:45], v[28:31], off offset:256
	v_cvt_pk_bf16_f32 v15, v10, v11
	v_mad_i64_i32 v[8:9], s[4:5], v8, s9, v[140:141]
	v_lshl_add_u64 v[28:29], v[24:25], 0, v[138:139]
	v_cvt_pk_bf16_f32 v124, v124, v125
	v_cvt_pk_bf16_f32 v125, v126, v127
	v_cvt_pk_bf16_f32 v126, v120, v121
	v_cvt_pk_bf16_f32 v127, v122, v123
	v_cvt_pk_bf16_f32 v104, v116, v117
	v_cvt_pk_bf16_f32 v105, v118, v119
	v_cvt_pk_bf16_f32 v106, v112, v113
	v_cvt_pk_bf16_f32 v107, v114, v115
	v_cvt_pk_bf16_f32 v88, v100, v101
	v_cvt_pk_bf16_f32 v89, v102, v103
	v_cvt_pk_bf16_f32 v90, v96, v97
	v_cvt_pk_bf16_f32 v91, v98, v99
	global_store_dwordx4 v[92:93], v[76:79], off offset:256
	v_cvt_pk_bf16_f32 v74, v80, v81
	v_cvt_pk_bf16_f32 v75, v82, v83
	v_lshl_add_u64 v[76:77], v[72:73], 0, v[138:139]
	v_cvt_pk_bf16_f32 v72, v84, v85
	v_cvt_pk_bf16_f32 v73, v86, v87
	v_cvt_pk_bf16_f32 v71, v66, v67
	v_cvt_pk_bf16_f32 v60, v60, v61
	v_cvt_pk_bf16_f32 v61, v62, v63
	v_cvt_pk_bf16_f32 v62, v56, v57
	v_cvt_pk_bf16_f32 v63, v58, v59
	v_cvt_pk_bf16_f32 v40, v52, v53
	v_cvt_pk_bf16_f32 v41, v54, v55
	v_cvt_pk_bf16_f32 v42, v48, v49
	v_cvt_pk_bf16_f32 v43, v50, v51
	v_cvt_pk_bf16_f32 v24, v36, v37
	v_cvt_pk_bf16_f32 v25, v38, v39
	v_cvt_pk_bf16_f32 v26, v32, v33
	v_cvt_pk_bf16_f32 v27, v34, v35
	global_store_dwordx4 v[28:29], v[12:15], off offset:256
	v_cvt_pk_bf16_f32 v10, v16, v17
	v_cvt_pk_bf16_f32 v11, v18, v19
	v_lshl_add_u64 v[12:13], v[8:9], 0, v[138:139]
	v_cvt_pk_bf16_f32 v8, v20, v21
	v_cvt_pk_bf16_f32 v9, v22, v23
	v_cvt_pk_bf16_f32 v4, v4, v5
	v_cvt_pk_bf16_f32 v5, v6, v7
	v_cvt_pk_bf16_f32 v6, v0, v1
	v_cvt_pk_bf16_f32 v7, v2, v3
	s_and_b64 vcc, exec, s[6:7]
	s_mov_b32 s31, s8
	s_mov_b32 s33, s10
	s_mov_b64 s[18:19], s[14:15]
	s_mov_b64 s[16:17], s[12:13]
	global_store_dwordx4 v[142:143], v[124:127], off
	global_store_dwordx4 v[108:109], v[104:107], off
	global_store_dwordx4 v[92:93], v[88:91], off
	global_store_dwordx4 v[76:77], v[72:75], off
	global_store_dwordx4 v[76:77], v[68:71], off offset:256
	global_store_dwordx4 v[64:65], v[60:63], off
	global_store_dwordx4 v[44:45], v[40:43], off
	global_store_dwordx4 v[28:29], v[24:27], off
	global_store_dwordx4 v[12:13], v[8:11], off
	global_store_dwordx4 v[12:13], v[4:7], off offset:256
	s_cbranch_vccz .LBB0_228
	s_waitcnt vmcnt(0)
	s_cmpk_gt_u32 s2, 0xff
	s_cbranch_scc1 .LBB0_235
	s_barrier

; __global__ void __launch_bounds__(512, 2) mega_fwd(Params p) {
;     ...
;         if (ph + 1 < p.ph_hi) {
;             if (ph == p.ph_lo) { grid.sync(); gb = xcd_barrier_post(barw, bst); }
;             else xcd_barrier(gb);
.LBB0_258:
	s_setprio 0
	s_load_dwordx2 s[4:5], s[0:1], 0x238
	s_add_i32 s2, s33, 1
	s_mov_b64 s[6:7], -1
	s_waitcnt lgkmcnt(0)
	s_cmp_ge_i32 s2, s5
	s_cbranch_scc1 .LBB0_20
	s_load_dwordx2 s[4:5], s[0:1], 0x238
	s_waitcnt lgkmcnt(0)
	s_cmp_lg_u32 s33, s4
	s_cbranch_scc0 .LBB0_360
	s_waitcnt vmcnt(0)
	s_waitcnt vmcnt(0)
	s_barrier
	s_mov_b64 s[6:7], exec
	v_readlane_b32 s4, v253, 6
	v_readlane_b32 s5, v253, 7
	s_and_b64 s[4:5], s[6:7], s[4:5]
	s_mov_b64 exec, s[4:5]
	s_cbranch_execz .LBB0_359
	v_readlane_b32 s3, v255, 7
	s_waitcnt vmcnt(0) expcnt(0) lgkmcnt(0)
	s_nop 0
	v_mov_b32_e32 v0, s3
	ds_read_b32 v2, v0
	v_readlane_b32 s3, v255, 8
	s_waitcnt lgkmcnt(0)
	v_cmp_ne_u32_e32 vcc, 0, v2
	v_mov_b32_e32 v0, s3
	ds_read_b32 v0, v0
	s_cbranch_vccnz .LBB0_276
	s_mov_b32 s3, 1
	s_branch .LBB0_264

; __device__ __forceinline__ int opaque_tid() { int t = threadIdx.x; asm volatile("" : "+v"(t)); return t; }
; #define PG8_STAGE(bufoff, gbase) do { _Pragma("unroll") for (int _i = 0; _i < 2; ++_i) \
;         __builtin_amdgcn_global_load_lds((const unsigned*)((const char*)(gbase) + voff[_i]), (LAS unsigned*)(lds + (bufoff) + ldsw + _i * 8192), 16, 0, 0); } while (0)
; #define PG8_WAIT_V(n) asm volatile("s_waitcnt vmcnt(" #n ")" ::: "memory")
; #define PG8_BAR __builtin_amdgcn_s_barrier()
; template <class Epi>
; DI void gemm_phase(LAS unsigned char* lds, const Gemm g, const StaticOrder& S, const Epi& E) {
;     const int tid = opaque_tid(), wid = __builtin_amdgcn_readfirstlane(tid >> 6), lane = tid & 63, wr = wid >> 2, wc = wid & 3, fr = lane & 15, fq = lane >> 4;
;     const int K = g.K, nt = K / BK;
;     unsigned voff[2];
; #pragma unroll
;     for (int i = 0; i < 2; ++i) { int R, C; stage_rc(tid * 16 + i * 8192, R, C); voff[i] = (unsigned)(R * K + C) * 2u; }
;     const size_t kstep = (size_t)(BK * 2);
;     const size_t hstep = (size_t)HALF * K * 2;
;     const size_t tstep = 2 * hstep;
;     const unsigned ldsw = (unsigned)wid * 1024u;
;     const int aoff = lds_byte(wr * 64 + fr, fq * 8), boff = lds_byte(wc * 32 + fr, fq * 8);
;     ...
;     Unit cur, nxt; int ui = 0;
;     if (!S.next(0, cur)) return;
;     f32x4 acc[2][2][4][2];
; #pragma unroll
;     for (int a = 0; a < 2; ++a)
; #pragma unroll
;         for (int b = 0; b < 2; ++b)
; #pragma unroll
;             for (int m = 0; m < 4; ++m)
; #pragma unroll
;                 for (int n = 0; n < 2; ++n) acc[a][b][m][n] = (f32x4){0.f, 0.f, 0.f, 0.f};
;     bf16x8 At[4][2], B0[2][2], B1[2][2];
;     const char* cA = (const char*)g.A + (size_t)cur.pm * tstep; const char* cB = (const char*)g.Bt + (size_t)cur.pn * tstep;
;     PG8_STAGE(PG8_SB(0, 0), cB); PG8_STAGE(PG8_SA(0, 0), cA); PG8_STAGE(PG8_SB(0, 1), cB + hstep); PG8_STAGE(PG8_SA(0, 1), cA + hstep);
;     if (wr == 1) PG8_BAR;
;     PG8_WAIT_V(4); PG8_BAR;
;     PG8_STAGE(PG8_SB(1, 0), cB + kstep); PG8_STAGE(PG8_SA(1, 0), cA + kstep); PG8_STAGE(PG8_SB(1, 1), cB + hstep + kstep);
;     PG8_WAIT_V(6); PG8_BAR;
.LBB0_307:
	s_andn2_b64 vcc, exec, s[6:7]
	s_cbranch_vccnz .LBB0_329
	v_readlane_b32 s2, v254, 46
	v_mov_b32_e32 v0, v156
	v_readlane_b32 s3, v254, 47
	s_andn2_b64 vcc, exec, s[2:3]
	v_readfirstlane_b32 s34, v0
	s_cbranch_vccnz .LBB0_329
	v_lshlrev_b32_e32 v5, 4, v0
	v_add_u32_e32 v2, 0x2000, v5
	v_ashrrev_i32_e32 v1, 31, v2
	v_lshrrev_b32_e32 v1, 22, v1
	v_add_u32_e32 v1, v2, v1
	v_ashrrev_i32_e32 v1, 10, v1
	v_mul_i32_i24_e32 v3, 0x400, v1
	v_sub_u32_e32 v2, v2, v3
	v_lshrrev_b32_e32 v3, 4, v2
	v_bitop3_b32 v4, v3, v2, 32 bitop3:0x6c
	v_ashrrev_i32_e32 v2, 31, v4
	v_lshrrev_b32_e32 v2, 26, v2
	v_add_u32_e32 v6, v4, v2
	v_ashrrev_i32_e32 v2, 6, v6
	v_and_b32_e32 v6, 0xc0, v6
	v_sub_u32_e32 v4, v4, v6
	v_bfe_i32 v6, v0, 27, 1
	v_lshrrev_b32_e32 v6, 22, v6
	v_add_u32_e32 v6, v5, v6
	v_and_b32_e32 v6, 0xfffffc00, v6
	v_sub_u32_e32 v5, v5, v6
	v_lshlrev_b32_e32 v3, 3, v1
	v_lshrrev_b32_e32 v6, 4, v5
	v_and_b32_e32 v3, 0xffff0, v3
	v_bitop3_b32 v8, v6, v5, 32 bitop3:0x6c
	v_ashrrev_i32_e32 v6, 31, v0
	v_readlane_b32 s2, v255, 43
	v_add_u32_e32 v7, v2, v3
	v_lshlrev_b32_e32 v3, 5, v1
	v_ashrrev_i32_e32 v5, 31, v5
	v_lshrrev_b32_e32 v6, 26, v6
	v_readlane_b32 s3, v255, 44
	v_and_b32_e32 v3, 32, v3
	v_ashrrev_i16_sdwa v4, v252, sext(v4) dst_sel:DWORD dst_unused:UNUSED_PAD src0_sel:DWORD src1_sel:BYTE_0
	v_lshrrev_b32_e32 v5, 26, v5
	v_add_u32_e32 v6, v0, v6
	s_lshl_b64 s[2:3], s[2:3], 23
	v_readlane_b32 s4, v253, 16
	v_lshl_or_b32 v7, v7, 11, v3
	v_bfe_i32 v4, v4, 0, 16
	v_add_u32_e32 v5, v8, v5
	v_ashrrev_i32_e32 v6, 6, v6
	s_add_u32 s35, s4, s2
	v_readlane_b32 s2, v253, 17
	v_add_lshl_u32 v186, v7, v4, 1
	v_ashrrev_i32_e32 v5, 6, v5
	v_lshlrev_b32_e32 v7, 3, v6
	s_addc_u32 s36, s2, s3
	s_ashr_i32 s3, s34, 6
	v_and_b32_e32 v7, 0xffff0, v7
	v_mul_i32_i24_e32 v10, 64, v5
	s_ashr_i32 s2, s34, 8
	s_lshl_b32 s37, s3, 10
	v_add_u32_e32 v9, v5, v7
	v_lshlrev_b32_e32 v7, 5, v6
	v_sub_u32_e32 v8, v8, v10
	v_readlane_b32 s4, v254, 25
	v_and_b32_e32 v7, 32, v7
	v_ashrrev_i16_sdwa v8, v252, sext(v8) dst_sel:DWORD dst_unused:UNUSED_PAD src0_sel:DWORD src1_sel:BYTE_0
	v_readlane_b32 s5, v254, 26
	s_add_u32 s26, s35, s4
	v_lshl_or_b32 v9, v9, 11, v7
	v_bfe_i32 v8, v8, 0, 16
	s_addc_u32 s27, s36, s5
	s_add_i32 s38, s37, 0
	v_add_lshl_u32 v188, v9, v8, 1
	s_add_i32 m0, s38, 0x10000
	v_readlane_b32 s4, v254, 27
	global_load_lds_dwordx4 v188, s[26:27]
	s_add_i32 m0, s38, 0x12000
	v_readlane_b32 s5, v254, 28
	global_load_lds_dwordx4 v186, s[26:27]
	s_mov_b32 m0, s38
	s_add_i32 s39, s38, 0x2000
	s_nop 1
	global_load_lds_dwordx4 v188, s[4:5]
	s_mov_b32 m0, s39
	s_nop 0
	global_load_lds_dwordx4 v186, s[4:5]
	s_add_u32 s4, s26, 0x80000
	s_addc_u32 s5, s27, 0
	s_add_i32 m0, s38, 0x14000
	s_add_i32 s40, s38, 0x4000
	global_load_lds_dwordx4 v188, s[4:5]
	s_add_i32 m0, s38, 0x16000
	s_add_i32 s41, s38, 0x6000
	global_load_lds_dwordx4 v186, s[4:5]
	v_readlane_b32 s4, v254, 29
	s_mov_b32 m0, s40
	v_readlane_b32 s5, v254, 30
	s_cmp_lg_u32 s2, 1
	s_nop 3
	global_load_lds_dwordx4 v188, s[4:5]
	s_mov_b32 m0, s41
	s_nop 0
	global_load_lds_dwordx4 v186, s[4:5]
	s_cbranch_scc1 .LBB0_311
	s_setprio 1
	s_barrier

; #define PG8_STAGE(bufoff, gbase) do { _Pragma("unroll") for (int _i = 0; _i < 2; ++_i) \
;         __builtin_amdgcn_global_load_lds((const unsigned*)((const char*)(gbase) + voff[_i]), (LAS unsigned*)(lds + (bufoff) + ldsw + _i * 8192), 16, 0, 0); } while (0)
; #define PG8_LDA(dst, b, h) do { _Pragma("unroll") for (int m = 0; m < 4; ++m) _Pragma("unroll") for (int k = 0; k < 2; ++k) dst[m][k] = *(const LAS bf16x8*)(lds + PG8_SA(b, h) + aoff + m * 2048 + k * 1024); } while (0)
; #define PG8_LDB(dst, b, h) do { _Pragma("unroll") for (int n = 0; n < 2; ++n) _Pragma("unroll") for (int k = 0; k < 2; ++k) dst[n][k] = *(const LAS bf16x8*)(lds + PG8_SB(b, h) + boff + n * 2048 + k * 1024); } while (0)
; #define PG8_MMA(ai, bj, At, Bt) do { __builtin_amdgcn_s_setprio(1); _Pragma("unroll") for (int m = 0; m < 4; ++m) _Pragma("unroll") for (int n = 0; n < 2; ++n) _Pragma("unroll") for (int k = 0; k < 2; ++k) \
;         acc[ai][bj][m][n] = __builtin_amdgcn_mfma_f32_16x16x32_bf16(Bt[n][k], At[m][k], acc[ai][bj][m][n], 0, 0, 0); __builtin_amdgcn_s_setprio(0); } while (0)
; #define PG8_WAIT_V(n) asm volatile("s_waitcnt vmcnt(" #n ")" ::: "memory")
; #define PG8_WAIT_L(n) asm volatile("s_waitcnt lgkmcnt(" #n ")" ::: "memory")
; #define PG8_BAR __builtin_amdgcn_s_barrier()
; #define PG8_SCHED __builtin_amdgcn_sched_barrier(0)
; template <class Epi>
; DI void gemm_phase(LAS unsigned char* lds, const Gemm g, const StaticOrder& S, const Epi& E) {
;     ...
;         for (int t = 0; t < nt; t += 2) {
;             const bool last = (t == nt - 2);
;             const char* a1 = cA + (size_t)(t + 1) * kstep;
;             const char* a2 = last ? nA : cA + (size_t)(t + 2) * kstep; const char* b2 = last ? nB : cB + (size_t)(t + 2) * kstep;
;             const char* a3 = a2 + kstep; const char* b3 = b2 + kstep;
;             PG8_LDB(B0, 0, 0); PG8_SCHED; PG8_LDA(At, 0, 0); PG8_STAGE(PG8_SA(1, 1), a1 + hstep);
;             PG8_WAIT_L(8); PG8_BAR; PG8_WAIT_L(0); PG8_MMA(0, 0, At, B0); PG8_BAR; PG8_SCHED;
;             PG8_LDB(B1, 0, 1); PG8_STAGE(PG8_SB(0, 0), b2);
;             PG8_BAR; PG8_WAIT_L(0); PG8_MMA(0, 1, At, B1); PG8_BAR;
;             PG8_LDA(At, 0, 1); PG8_STAGE(PG8_SA(0, 0), a2);
;             PG8_BAR; PG8_WAIT_L(0); PG8_MMA(1, 0, At, B0); PG8_BAR; PG8_SCHED;
;             PG8_STAGE(PG8_SB(0, 1), b2 + hstep);
;             PG8_WAIT_V(6); PG8_BAR; PG8_MMA(1, 1, At, B1); PG8_BAR;
.LBB0_320:
	s_add_u32 s26, s24, 0x100
	s_addc_u32 s27, s25, 0
	s_add_i32 s47, 0, 0x10000
	ds_read_b128 v[128:131], v226
	ds_read_b128 v[132:135], v226 offset:1024
	ds_read_b128 v[136:139], v226 offset:2048
	ds_read_b128 v[140:143], v226 offset:3072
	s_cmp_eq_u32 s46, 28
	s_cselect_b32 s31, s4, s27
	s_cselect_b32 s30, s5, s26
	s_cselect_b32 s29, s9, s45
	s_cselect_b32 s28, s11, s33
	v_lshl_add_u64 v[214:215], s[24:25], 0, v[190:191]
	s_add_i32 m0, s38, 0xc000
	ds_read_b128 v[144:147], v228
	ds_read_b128 v[148:151], v228 offset:1024
	ds_read_b128 v[152:155], v228 offset:2048
	ds_read_b128 v[194:197], v228 offset:3072
	ds_read_b128 v[198:201], v228 offset:4096
	ds_read_b128 v[202:205], v228 offset:5120
	ds_read_b128 v[206:209], v228 offset:6144
	ds_read_b128 v[210:213], v228 offset:7168
	global_load_lds_dwordx4 v[214:215], off
	v_lshl_add_u64 v[214:215], s[24:25], 0, v[192:193]
	s_add_i32 m0, s38, 0xe000
	s_nop 0
	global_load_lds_dwordx4 v[214:215], off
	s_waitcnt lgkmcnt(8)
	s_barrier
	s_waitcnt lgkmcnt(0)
	v_mfma_f32_16x16x32_bf16 v[124:127], v[128:131], v[144:147], v[124:127]
	v_mfma_f32_16x16x32_bf16 v[120:123], v[136:139], v[144:147], v[120:123]
	v_mfma_f32_16x16x32_bf16 v[116:119], v[128:131], v[152:155], v[116:119]
	v_mfma_f32_16x16x32_bf16 v[112:115], v[136:139], v[152:155], v[112:115]
	v_mfma_f32_16x16x32_bf16 v[108:111], v[128:131], v[198:201], v[108:111]
	v_mfma_f32_16x16x32_bf16 v[104:107], v[136:139], v[198:201], v[104:107]
	v_mfma_f32_16x16x32_bf16 v[100:103], v[128:131], v[206:209], v[100:103]
	v_mfma_f32_16x16x32_bf16 v[96:99], v[136:139], v[206:209], v[96:99]
	v_mfma_f32_16x16x32_bf16 v[124:127], v[132:135], v[148:151], v[124:127]
	v_mfma_f32_16x16x32_bf16 v[120:123], v[140:143], v[148:151], v[120:123]
	v_mfma_f32_16x16x32_bf16 v[116:119], v[132:135], v[194:197], v[116:119]
	v_mfma_f32_16x16x32_bf16 v[112:115], v[140:143], v[194:197], v[112:115]
	v_mfma_f32_16x16x32_bf16 v[108:111], v[132:135], v[202:205], v[108:111]
	v_mfma_f32_16x16x32_bf16 v[104:107], v[140:143], v[202:205], v[104:107]
	v_mfma_f32_16x16x32_bf16 v[100:103], v[132:135], v[210:213], v[100:103]
	v_mfma_f32_16x16x32_bf16 v[96:99], v[140:143], v[210:213], v[96:99]
	s_barrier
	ds_read_b128 v[214:217], v226 offset:16384
	ds_read_b128 v[230:233], v226 offset:17408
	ds_read_b128 v[234:237], v226 offset:18432
	ds_read_b128 v[238:241], v226 offset:19456
	s_add_i32 s48, 0, 0x14000
	s_add_i32 s24, s47, s37
	s_mov_b32 m0, s24
	s_nop 0
	global_load_lds_dwordx4 v188, s[28:29]
	s_add_i32 m0, s24, 0x2000
	s_nop 0
	global_load_lds_dwordx4 v186, s[28:29]
	s_waitcnt lgkmcnt(0)
	s_barrier
	v_mfma_f32_16x16x32_bf16 v[60:63], v[214:217], v[144:147], v[60:63]
	v_mfma_f32_16x16x32_bf16 v[56:59], v[234:237], v[144:147], v[56:59]
	v_mfma_f32_16x16x32_bf16 v[52:55], v[214:217], v[152:155], v[52:55]
	v_mfma_f32_16x16x32_bf16 v[48:51], v[234:237], v[152:155], v[48:51]
	v_mfma_f32_16x16x32_bf16 v[44:47], v[214:217], v[198:201], v[44:47]
	v_mfma_f32_16x16x32_bf16 v[40:43], v[234:237], v[198:201], v[40:43]
	v_mfma_f32_16x16x32_bf16 v[36:39], v[214:217], v[206:209], v[36:39]
	v_mfma_f32_16x16x32_bf16 v[32:35], v[234:237], v[206:209], v[32:35]
	v_mfma_f32_16x16x32_bf16 v[60:63], v[230:233], v[148:151], v[60:63]
	s_mov_b32 m0, s38
	v_mfma_f32_16x16x32_bf16 v[56:59], v[238:241], v[148:151], v[56:59]
	v_mfma_f32_16x16x32_bf16 v[52:55], v[230:233], v[194:197], v[52:55]
	v_mfma_f32_16x16x32_bf16 v[48:51], v[238:241], v[194:197], v[48:51]
	v_mfma_f32_16x16x32_bf16 v[44:47], v[230:233], v[202:205], v[44:47]
	v_mfma_f32_16x16x32_bf16 v[40:43], v[238:241], v[202:205], v[40:43]
	v_mfma_f32_16x16x32_bf16 v[36:39], v[230:233], v[210:213], v[36:39]
	v_mfma_f32_16x16x32_bf16 v[32:35], v[238:241], v[210:213], v[32:35]
	s_barrier
	ds_read_b128 v[144:147], v228 offset:16384
	ds_read_b128 v[148:151], v228 offset:17408
	ds_read_b128 v[152:155], v228 offset:18432
	ds_read_b128 v[194:197], v228 offset:19456
	ds_read_b128 v[198:201], v228 offset:20480
	ds_read_b128 v[202:205], v228 offset:21504
	ds_read_b128 v[206:209], v228 offset:22528
	ds_read_b128 v[210:213], v228 offset:23552
	global_load_lds_dwordx4 v188, s[30:31]
	s_mov_b64 s[100:101], s[30:31]
	s_mov_b32 m0, s39
	s_nop 0
	global_load_lds_dwordx4 v186, s[30:31]
	s_waitcnt lgkmcnt(0)
	s_barrier
	v_mfma_f32_16x16x32_bf16 v[92:95], v[128:131], v[144:147], v[92:95]
	v_mfma_f32_16x16x32_bf16 v[88:91], v[136:139], v[144:147], v[88:91]
	v_mfma_f32_16x16x32_bf16 v[84:87], v[128:131], v[152:155], v[84:87]
	v_mfma_f32_16x16x32_bf16 v[80:83], v[136:139], v[152:155], v[80:83]
	v_mfma_f32_16x16x32_bf16 v[76:79], v[128:131], v[198:201], v[76:79]
	v_mfma_f32_16x16x32_bf16 v[72:75], v[136:139], v[198:201], v[72:75]
	v_mfma_f32_16x16x32_bf16 v[68:71], v[128:131], v[206:209], v[68:71]
	v_mfma_f32_16x16x32_bf16 v[64:67], v[136:139], v[206:209], v[64:67]
	v_mfma_f32_16x16x32_bf16 v[92:95], v[132:135], v[148:151], v[92:95]
	v_mfma_f32_16x16x32_bf16 v[88:91], v[140:143], v[148:151], v[88:91]
	v_mfma_f32_16x16x32_bf16 v[84:87], v[132:135], v[194:197], v[84:87]
	v_mfma_f32_16x16x32_bf16 v[80:83], v[140:143], v[194:197], v[80:83]
	v_mfma_f32_16x16x32_bf16 v[76:79], v[132:135], v[202:205], v[76:79]
	v_mfma_f32_16x16x32_bf16 v[72:75], v[140:143], v[202:205], v[72:75]
	v_mfma_f32_16x16x32_bf16 v[68:71], v[132:135], v[210:213], v[68:71]
	v_mfma_f32_16x16x32_bf16 v[64:67], v[140:143], v[210:213], v[64:67]
	s_barrier
	s_add_u32 s24, s28, 0x80000
	s_addc_u32 s25, s29, 0
	s_add_i32 s47, s48, s37
	s_mov_b32 m0, s47
	s_nop 0
	global_load_lds_dwordx4 v188, s[24:25]
	s_add_i32 m0, s47, 0x2000
	s_nop 0
	global_load_lds_dwordx4 v186, s[24:25]
	s_waitcnt vmcnt(6)
	s_barrier
; #define PG8_STAGE(bufoff, gbase) do { _Pragma("unroll") for (int _i = 0; _i < 2; ++_i) \
;         __builtin_amdgcn_global_load_lds((const unsigned*)((const char*)(gbase) + voff[_i]), (LAS unsigned*)(lds + (bufoff) + ldsw + _i * 8192), 16, 0, 0); } while (0)
; #define PG8_LDA(dst, b, h) do { _Pragma("unroll") for (int m = 0; m < 4; ++m) _Pragma("unroll") for (int k = 0; k < 2; ++k) dst[m][k] = *(const LAS bf16x8*)(lds + PG8_SA(b, h) + aoff + m * 2048 + k * 1024); } while (0)
; #define PG8_LDB(dst, b, h) do { _Pragma("unroll") for (int n = 0; n < 2; ++n) _Pragma("unroll") for (int k = 0; k < 2; ++k) dst[n][k] = *(const LAS bf16x8*)(lds + PG8_SB(b, h) + boff + n * 2048 + k * 1024); } while (0)
; #define PG8_MMA(ai, bj, At, Bt) do { __builtin_amdgcn_s_setprio(1); _Pragma("unroll") for (int m = 0; m < 4; ++m) _Pragma("unroll") for (int n = 0; n < 2; ++n) _Pragma("unroll") for (int k = 0; k < 2; ++k) \
;         acc[ai][bj][m][n] = __builtin_amdgcn_mfma_f32_16x16x32_bf16(Bt[n][k], At[m][k], acc[ai][bj][m][n], 0, 0, 0); __builtin_amdgcn_s_setprio(0); } while (0)
; #define PG8_WAIT_V(n) asm volatile("s_waitcnt vmcnt(" #n ")" ::: "memory")
; #define PG8_WAIT_L(n) asm volatile("s_waitcnt lgkmcnt(" #n ")" ::: "memory")
; #define PG8_BAR __builtin_amdgcn_s_barrier()
; #define PG8_SCHED __builtin_amdgcn_sched_barrier(0)
; template <class Epi>
; DI void gemm_phase(LAS unsigned char* lds, const Gemm g, const StaticOrder& S, const Epi& E) {
;     ...
;             PG8_WAIT_V(6); PG8_BAR; PG8_MMA(1, 1, At, B1); PG8_BAR;
;             PG8_LDB(B0, 1, 0); PG8_SCHED; PG8_LDA(At, 1, 0); PG8_STAGE(PG8_SA(0, 1), a2 + hstep);
;             PG8_WAIT_L(8); PG8_BAR; PG8_WAIT_L(0); PG8_MMA(0, 0, At, B0); PG8_BAR; PG8_SCHED;
;             PG8_LDB(B1, 1, 1); PG8_STAGE(PG8_SB(1, 0), b3);
;             PG8_BAR; PG8_WAIT_L(0); PG8_MMA(0, 1, At, B1); PG8_BAR;
;             PG8_LDA(At, 1, 1); PG8_STAGE(PG8_SA(1, 0), a3);
;             PG8_BAR; PG8_WAIT_L(0); PG8_MMA(1, 0, At, B0); PG8_BAR; PG8_SCHED;
	v_mfma_f32_16x16x32_bf16 v[28:31], v[214:217], v[144:147], v[28:31]
	v_mfma_f32_16x16x32_bf16 v[24:27], v[234:237], v[144:147], v[24:27]
	v_mfma_f32_16x16x32_bf16 v[20:23], v[214:217], v[152:155], v[20:23]
	v_mfma_f32_16x16x32_bf16 v[16:19], v[234:237], v[152:155], v[16:19]
	v_mfma_f32_16x16x32_bf16 v[12:15], v[214:217], v[198:201], v[12:15]
	v_mfma_f32_16x16x32_bf16 v[8:11], v[234:237], v[198:201], v[8:11]
	v_mfma_f32_16x16x32_bf16 v[4:7], v[214:217], v[206:209], v[4:7]
	v_mfma_f32_16x16x32_bf16 v[0:3], v[234:237], v[206:209], v[0:3]
	v_mfma_f32_16x16x32_bf16 v[28:31], v[230:233], v[148:151], v[28:31]
	s_add_i32 s47, 0, 0x18000
	v_mfma_f32_16x16x32_bf16 v[24:27], v[238:241], v[148:151], v[24:27]
	v_mfma_f32_16x16x32_bf16 v[20:23], v[230:233], v[194:197], v[20:23]
	v_mfma_f32_16x16x32_bf16 v[16:19], v[238:241], v[194:197], v[16:19]
	v_mfma_f32_16x16x32_bf16 v[12:15], v[230:233], v[202:205], v[12:15]
	v_mfma_f32_16x16x32_bf16 v[8:11], v[238:241], v[202:205], v[8:11]
	v_mfma_f32_16x16x32_bf16 v[4:7], v[230:233], v[210:213], v[4:7]
	v_mfma_f32_16x16x32_bf16 v[0:3], v[238:241], v[210:213], v[0:3]
	s_barrier
	ds_read_b128 v[128:131], v226 offset:32768
	ds_read_b128 v[132:135], v226 offset:33792
	ds_read_b128 v[136:139], v226 offset:34816
	ds_read_b128 v[140:143], v226 offset:35840
	ds_read_b128 v[144:147], v228 offset:32768
	ds_read_b128 v[148:151], v228 offset:33792
	ds_read_b128 v[152:155], v228 offset:34816
	ds_read_b128 v[194:197], v228 offset:35840
	ds_read_b128 v[198:201], v228 offset:36864
	ds_read_b128 v[202:205], v228 offset:37888
	ds_read_b128 v[206:209], v228 offset:38912
	ds_read_b128 v[210:213], v228 offset:39936
	s_add_u32 s24, s30, 0x80000
	s_addc_u32 s25, s31, 0
	s_mov_b32 m0, s40
	s_nop 0
	global_load_lds_dwordx4 v188, s[24:25]
	s_mov_b32 m0, s41
	s_nop 0
	global_load_lds_dwordx4 v186, s[24:25]
	s_waitcnt lgkmcnt(8)
	s_barrier
	s_waitcnt lgkmcnt(0)
	v_mfma_f32_16x16x32_bf16 v[124:127], v[128:131], v[144:147], v[124:127]
	v_mfma_f32_16x16x32_bf16 v[120:123], v[136:139], v[144:147], v[120:123]
	v_mfma_f32_16x16x32_bf16 v[116:119], v[128:131], v[152:155], v[116:119]
	v_mfma_f32_16x16x32_bf16 v[112:115], v[136:139], v[152:155], v[112:115]
	v_mfma_f32_16x16x32_bf16 v[108:111], v[128:131], v[198:201], v[108:111]
	v_mfma_f32_16x16x32_bf16 v[104:107], v[136:139], v[198:201], v[104:107]
	v_mfma_f32_16x16x32_bf16 v[100:103], v[128:131], v[206:209], v[100:103]
	v_mfma_f32_16x16x32_bf16 v[96:99], v[136:139], v[206:209], v[96:99]
	v_mfma_f32_16x16x32_bf16 v[124:127], v[132:135], v[148:151], v[124:127]
	v_mfma_f32_16x16x32_bf16 v[120:123], v[140:143], v[148:151], v[120:123]
	v_mfma_f32_16x16x32_bf16 v[116:119], v[132:135], v[194:197], v[116:119]
	v_mfma_f32_16x16x32_bf16 v[112:115], v[140:143], v[194:197], v[112:115]
	v_mfma_f32_16x16x32_bf16 v[108:111], v[132:135], v[202:205], v[108:111]
	v_mfma_f32_16x16x32_bf16 v[104:107], v[140:143], v[202:205], v[104:107]
	v_mfma_f32_16x16x32_bf16 v[100:103], v[132:135], v[210:213], v[100:103]
	v_mfma_f32_16x16x32_bf16 v[96:99], v[140:143], v[210:213], v[96:99]
	s_barrier
	ds_read_b128 v[214:217], v226 offset:49152
	ds_read_b128 v[230:233], v226 offset:50176
	ds_read_b128 v[234:237], v226 offset:51200
	ds_read_b128 v[238:241], v226 offset:52224
	s_add_i32 s30, 0, 0x1c000
	s_add_i32 s24, s47, s37
	s_add_i32 m0, s24, 0xffffff80
	s_nop 0
	global_load_lds_dwordx4 v188, s[28:29] offset:128
	s_add_i32 m0, s24, 0x1f80
	s_nop 0
	global_load_lds_dwordx4 v186, s[28:29] offset:128
	s_waitcnt lgkmcnt(0)
	s_barrier
	v_mfma_f32_16x16x32_bf16 v[60:63], v[214:217], v[144:147], v[60:63]
	v_mfma_f32_16x16x32_bf16 v[56:59], v[234:237], v[144:147], v[56:59]
	v_mfma_f32_16x16x32_bf16 v[52:55], v[214:217], v[152:155], v[52:55]
	v_mfma_f32_16x16x32_bf16 v[48:51], v[234:237], v[152:155], v[48:51]
	v_mfma_f32_16x16x32_bf16 v[44:47], v[214:217], v[198:201], v[44:47]
	v_mfma_f32_16x16x32_bf16 v[40:43], v[234:237], v[198:201], v[40:43]
	v_mfma_f32_16x16x32_bf16 v[36:39], v[214:217], v[206:209], v[36:39]
	v_mfma_f32_16x16x32_bf16 v[32:35], v[234:237], v[206:209], v[32:35]
	v_mfma_f32_16x16x32_bf16 v[60:63], v[230:233], v[148:151], v[60:63]
	s_add_i32 m0, s42, 0xffffff80
	v_mfma_f32_16x16x32_bf16 v[56:59], v[238:241], v[148:151], v[56:59]
	v_mfma_f32_16x16x32_bf16 v[52:55], v[230:233], v[194:197], v[52:55]
	v_mfma_f32_16x16x32_bf16 v[48:51], v[238:241], v[194:197], v[48:51]
	v_mfma_f32_16x16x32_bf16 v[44:47], v[230:233], v[202:205], v[44:47]
	v_mfma_f32_16x16x32_bf16 v[40:43], v[238:241], v[202:205], v[40:43]
	v_mfma_f32_16x16x32_bf16 v[36:39], v[230:233], v[210:213], v[36:39]
	v_mfma_f32_16x16x32_bf16 v[32:35], v[238:241], v[210:213], v[32:35]
	s_barrier
	ds_read_b128 v[144:147], v228 offset:49152
	ds_read_b128 v[148:151], v228 offset:50176
	ds_read_b128 v[152:155], v228 offset:51200
	ds_read_b128 v[194:197], v228 offset:52224
	ds_read_b128 v[198:201], v228 offset:53248
	ds_read_b128 v[202:205], v228 offset:54272
	ds_read_b128 v[206:209], v228 offset:55296
	ds_read_b128 v[210:213], v228 offset:56320
	global_load_lds_dwordx4 v188, s[100:101] offset:128
	s_add_i32 m0, s43, 0xffffff80
	s_nop 0
	global_load_lds_dwordx4 v186, s[100:101] offset:128
	s_waitcnt lgkmcnt(0)
	s_barrier
; template <class Epi>
; DI void gemm_phase(LAS unsigned char* lds, const Gemm g, const StaticOrder& S, const Epi& E) {
;     ...
;             PG8_BAR; PG8_WAIT_L(0); PG8_MMA(1, 0, At, B0); PG8_BAR; PG8_SCHED;
;             PG8_STAGE(PG8_SB(1, 1), b3 + hstep);
;             PG8_WAIT_V(6); PG8_BAR; PG8_MMA(1, 1, At, B1); PG8_BAR;
;         }
;         E(acc, cur, wr, wc, fr, fq);
;     template <bool LN, int BJ, int LO, int HI> DI void batch(const f32x4 (&acc)[2][2][4][2], unsigned row0, unsigned col0, const f32x4 (&gv)[2], const f32x4 (&bv)[2]) const {
;         f32x4 r[HI - LO]; float mean[(HI - LO) / 2], rstd[(HI - LO) / 2];
; #pragma unroll
;         for (int i = LO; i < HI; ++i) { const int ai = i >> 3, m = (i >> 1) & 3, n = i & 1; const unsigned row = row0 + ai * HALF + m * 16;
;             if (n == 0) { mean[(i - LO) >> 1] = 0.f; rstd[(i - LO) >> 1] = 1.f;
;                 if (LN) { const float2 st = *(const float2*)(stats + row * 2u); mean[(i - LO) >> 1] = st.x; rstd[(i - LO) >> 1] = st.y; } }
;             r[i - LO] = *(const f32x4*)(src + (row * (unsigned)DM + col0 + BJ * HALF + n * 16)); }
; #pragma unroll
;         for (int i = LO; i < HI; ++i) { const int ai = i >> 3, m = (i >> 1) & 3, n = i & 1; const unsigned row = row0 + ai * HALF + m * 16;
;             *(f32x4*)(Y + (row * (unsigned)DM + col0 + BJ * HALF + n * 16)) = acc[ai][BJ][m][n] + ((r[i - LO] - mean[(i - LO) >> 1]) * rstd[(i - LO) >> 1]) * gv[n] + bv[n]; }
;         __builtin_amdgcn_sched_barrier(0);
;     }
;     template <bool LN, int BJ> DI void load_gb(unsigned col0, f32x4 (&gv)[2], f32x4 (&bv)[2]) const {
; #pragma unroll
;         for (int n = 0; n < 2; ++n) {
;             if (LN) { gv[n] = *(const f32x4*)(gam + col0 + BJ * HALF + n * 16) * ALPHA; bv[n] = *(const f32x4*)(bet + col0 + BJ * HALF + n * 16) * ALPHA; }
;             else { gv[n] = (f32x4){ALPHA, ALPHA, ALPHA, ALPHA}; bv[n] = (f32x4){0.f, 0.f, 0.f, 0.f}; }
;         }
;     }
;     template <bool LN> DI void run(const f32x4 (&acc)[2][2][4][2], const Unit& u, int wr, int wc, int fr, int fq) const {
;         const unsigned row0 = u.pm * BM + wr * 64 + fr, col0 = u.pn * BM + wc * 32 + 4 * fq;
;         f32x4 gv[2], bv[2];
;         load_gb<LN, 0>(col0, gv, bv);
;         batch<LN, 0, 0, 4>(acc, row0, col0, gv, bv);
;         batch<LN, 0, 4, 8>(acc, row0, col0, gv, bv);
;         batch<LN, 0, 8, 12>(acc, row0, col0, gv, bv);
	v_mfma_f32_16x16x32_bf16 v[92:95], v[128:131], v[144:147], v[92:95]
	v_mfma_f32_16x16x32_bf16 v[88:91], v[136:139], v[144:147], v[88:91]
	v_mfma_f32_16x16x32_bf16 v[84:87], v[128:131], v[152:155], v[84:87]
	v_mfma_f32_16x16x32_bf16 v[80:83], v[136:139], v[152:155], v[80:83]
	v_mfma_f32_16x16x32_bf16 v[76:79], v[128:131], v[198:201], v[76:79]
	v_mfma_f32_16x16x32_bf16 v[72:75], v[136:139], v[198:201], v[72:75]
	v_mfma_f32_16x16x32_bf16 v[68:71], v[128:131], v[206:209], v[68:71]
	v_mfma_f32_16x16x32_bf16 v[64:67], v[136:139], v[206:209], v[64:67]
	v_mfma_f32_16x16x32_bf16 v[92:95], v[132:135], v[148:151], v[92:95]
	v_mfma_f32_16x16x32_bf16 v[88:91], v[140:143], v[148:151], v[88:91]
	v_mfma_f32_16x16x32_bf16 v[84:87], v[132:135], v[194:197], v[84:87]
	v_mfma_f32_16x16x32_bf16 v[80:83], v[140:143], v[194:197], v[80:83]
	v_mfma_f32_16x16x32_bf16 v[76:79], v[132:135], v[202:205], v[76:79]
	v_mfma_f32_16x16x32_bf16 v[72:75], v[140:143], v[202:205], v[72:75]
	v_mfma_f32_16x16x32_bf16 v[68:71], v[132:135], v[210:213], v[68:71]
	v_mfma_f32_16x16x32_bf16 v[64:67], v[140:143], v[210:213], v[64:67]
	s_barrier
	s_add_u32 s24, s28, 0x80080
	s_addc_u32 s25, s29, 0
	s_add_i32 s28, s30, s37
	s_mov_b32 m0, s28
	s_nop 0
	global_load_lds_dwordx4 v188, s[24:25]
	s_add_i32 m0, s28, 0x2000
	s_nop 0
	global_load_lds_dwordx4 v186, s[24:25]
	s_waitcnt vmcnt(6)
	s_barrier
	v_mfma_f32_16x16x32_bf16 v[28:31], v[214:217], v[144:147], v[28:31]
	v_mfma_f32_16x16x32_bf16 v[24:27], v[234:237], v[144:147], v[24:27]
	v_mfma_f32_16x16x32_bf16 v[20:23], v[214:217], v[152:155], v[20:23]
	v_mfma_f32_16x16x32_bf16 v[16:19], v[234:237], v[152:155], v[16:19]
	v_mfma_f32_16x16x32_bf16 v[12:15], v[214:217], v[198:201], v[12:15]
	v_mfma_f32_16x16x32_bf16 v[8:11], v[234:237], v[198:201], v[8:11]
	v_mfma_f32_16x16x32_bf16 v[4:7], v[214:217], v[206:209], v[4:7]
	v_mfma_f32_16x16x32_bf16 v[0:3], v[234:237], v[206:209], v[0:3]
	v_mfma_f32_16x16x32_bf16 v[28:31], v[230:233], v[148:151], v[28:31]
	s_add_i32 s46, s46, 2
	v_mfma_f32_16x16x32_bf16 v[24:27], v[238:241], v[148:151], v[24:27]
	s_add_u32 s33, s33, 0x100
	v_mfma_f32_16x16x32_bf16 v[20:23], v[230:233], v[194:197], v[20:23]
	s_addc_u32 s45, s45, 0
	v_mfma_f32_16x16x32_bf16 v[16:19], v[238:241], v[194:197], v[16:19]
	s_cmp_gt_u32 s46, 29
	v_mfma_f32_16x16x32_bf16 v[12:15], v[230:233], v[202:205], v[12:15]
	s_mov_b64 s[24:25], s[26:27]
	v_mfma_f32_16x16x32_bf16 v[8:11], v[238:241], v[202:205], v[8:11]
	v_mfma_f32_16x16x32_bf16 v[4:7], v[230:233], v[210:213], v[4:7]
	v_mfma_f32_16x16x32_bf16 v[0:3], v[238:241], v[210:213], v[0:3]
	s_barrier
	s_cbranch_scc0 .LBB0_320
	v_lshl_add_u32 v206, s3, 8, v225
	v_lshl_or_b32 v158, s2, 8, v227
	v_lshlrev_b32_e32 v232, 11, v206
	s_andn2_b64 vcc, exec, s[14:15]
	v_or_b32_e32 v231, 16, v158
	v_add_u32_e32 v194, v232, v158
	v_or_b32_e32 v230, 0x80, v158
	v_or_b32_e32 v229, 0x90, v158
	s_cbranch_vccnz .LBB0_323
	v_lshlrev_b64 v[132:133], 2, v[158:159]
	v_lshl_add_u64 v[140:141], s[16:17], 0, v[132:133]
	global_load_dwordx4 v[128:131], v[140:141], off
	v_lshl_add_u64 v[142:143], s[18:19], 0, v[132:133]
	v_readlane_b32 s2, v253, 8
	v_mov_b32_e32 v195, v159
	v_lshlrev_b32_e32 v136, 1, v206
	v_mov_b32_e32 v137, v159
	v_readlane_b32 s3, v253, 9
	v_lshlrev_b64 v[212:213], 2, v[194:195]
	v_add_u32_e32 v146, v232, v231
	v_lshl_add_u64 v[144:145], v[136:137], 2, s[2:3]
	v_lshl_add_u64 v[136:137], s[88:89], 0, v[212:213]
	v_mov_b32_e32 v147, v159
	v_lshl_add_u64 v[146:147], v[146:147], 2, s[88:89]
	v_or_b32_e32 v195, 16, v206
	v_mov_b32_e32 v201, v159
	v_mov_b32_e32 v209, v159
	v_lshl_add_u64 v[212:213], s[90:91], 0, v[212:213]
	s_waitcnt vmcnt(0)
	v_pk_mul_f32 v[152:153], v[130:131], s[78:79] op_sel_hi:[1,0]
	v_pk_mul_f32 v[154:155], v[128:129], s[78:79] op_sel_hi:[1,0]
	global_load_dwordx4 v[132:135], v[142:143], off
	global_load_dwordx4 v[128:131], v[140:141], off offset:64
	global_load_dwordx2 v[204:205], v[144:145], off
	global_load_dwordx4 v[196:199], v[146:147], off
	v_lshlrev_b32_e32 v146, 1, v195
	global_load_dwordx4 v[136:139], v[136:137], off
	v_lshlrev_b32_e32 v195, 11, v195
	v_mov_b32_e32 v147, v159
	v_add_u32_e32 v200, v195, v158
	v_lshl_add_u64 v[146:147], v[146:147], 2, s[2:3]
	v_lshl_add_u64 v[200:201], v[200:201], 2, s[88:89]
	global_load_dwordx2 v[214:215], v[146:147], off
	v_add_u32_e32 v208, v195, v231
	global_load_dwordx4 v[200:203], v[200:201], off
	v_lshl_add_u64 v[208:209], v[208:209], 2, s[88:89]
	global_load_dwordx4 v[208:211], v[208:209], off
	s_waitcnt vmcnt(0)
	v_pk_mul_f32 v[148:149], v[130:131], s[78:79] op_sel_hi:[1,0]
	v_pk_mul_f32 v[150:151], v[128:129], s[78:79] op_sel_hi:[1,0]
	global_load_dwordx4 v[128:131], v[142:143], off offset:64
	v_sub_f32_e32 v137, v137, v204
	v_sub_f32_e32 v136, v136, v204
	v_sub_f32_e32 v139, v139, v204
	v_sub_f32_e32 v138, v138, v204
	v_pk_mul_f32 v[138:139], v[204:205], v[138:139] op_sel:[1,0]
	v_pk_mul_f32 v[136:137], v[204:205], v[136:137] op_sel:[1,0]
	v_pk_fma_f32 v[138:139], v[152:153], v[138:139], v[126:127]
	v_pk_fma_f32 v[136:137], v[154:155], v[136:137], v[124:125]
	v_pk_fma_f32 v[138:139], v[134:135], s[78:79], v[138:139] op_sel_hi:[1,0,1]
	v_pk_fma_f32 v[136:137], v[132:133], s[78:79], v[136:137] op_sel_hi:[1,0,1]
	global_store_dwordx4 v[212:213], v[136:139], off
	s_nop 1
	v_sub_f32_e32 v137, v197, v204
	v_sub_f32_e32 v136, v196, v204
	v_sub_f32_e32 v139, v199, v204
	v_sub_f32_e32 v138, v198, v204
	v_pk_mul_f32 v[138:139], v[204:205], v[138:139] op_sel:[1,0]
	v_pk_mul_f32 v[136:137], v[204:205], v[136:137] op_sel:[1,0]
	v_pk_fma_f32 v[138:139], v[148:149], v[138:139], v[122:123]
	v_pk_fma_f32 v[136:137], v[150:151], v[136:137], v[120:121]
	v_or_b32_e32 v196, 16, v194
	v_mov_b32_e32 v197, v159
	v_lshl_add_u64 v[196:197], v[196:197], 2, s[90:91]
	s_waitcnt vmcnt(0)
;     template <bool LN, int BJ, int LO, int HI> DI void batch(const f32x4 (&acc)[2][2][4][2], unsigned row0, unsigned col0, const f32x4 (&gv)[2], const f32x4 (&bv)[2]) const {
;         f32x4 r[HI - LO]; float mean[(HI - LO) / 2], rstd[(HI - LO) / 2];
; #pragma unroll
;         for (int i = LO; i < HI; ++i) { const int ai = i >> 3, m = (i >> 1) & 3, n = i & 1; const unsigned row = row0 + ai * HALF + m * 16;
;             if (n == 0) { mean[(i - LO) >> 1] = 0.f; rstd[(i - LO) >> 1] = 1.f;
;                 if (LN) { const float2 st = *(const float2*)(stats + row * 2u); mean[(i - LO) >> 1] = st.x; rstd[(i - LO) >> 1] = st.y; } }
;             r[i - LO] = *(const f32x4*)(src + (row * (unsigned)DM + col0 + BJ * HALF + n * 16)); }
; #pragma unroll
;         for (int i = LO; i < HI; ++i) { const int ai = i >> 3, m = (i >> 1) & 3, n = i & 1; const unsigned row = row0 + ai * HALF + m * 16;
;             *(f32x4*)(Y + (row * (unsigned)DM + col0 + BJ * HALF + n * 16)) = acc[ai][BJ][m][n] + ((r[i - LO] - mean[(i - LO) >> 1]) * rstd[(i - LO) >> 1]) * gv[n] + bv[n]; }
	v_pk_fma_f32 v[138:139], v[130:131], s[78:79], v[138:139] op_sel_hi:[1,0,1]
	v_pk_fma_f32 v[136:137], v[128:129], s[78:79], v[136:137] op_sel_hi:[1,0,1]
	global_store_dwordx4 v[196:197], v[136:139], off
	v_add_u32_e32 v196, 0x8000, v194
	v_mov_b32_e32 v197, v159
	v_sub_f32_e32 v137, v201, v214
	v_sub_f32_e32 v136, v200, v214
	v_sub_f32_e32 v139, v203, v214
	v_sub_f32_e32 v138, v202, v214
	v_pk_mul_f32 v[138:139], v[214:215], v[138:139] op_sel:[1,0]
	v_pk_mul_f32 v[136:137], v[214:215], v[136:137] op_sel:[1,0]
	v_pk_fma_f32 v[138:139], v[152:153], v[138:139], v[118:119]
	v_pk_fma_f32 v[136:137], v[154:155], v[136:137], v[116:117]
	v_pk_fma_f32 v[138:139], v[134:135], s[78:79], v[138:139] op_sel_hi:[1,0,1]
	v_pk_fma_f32 v[136:137], v[132:133], s[78:79], v[136:137] op_sel_hi:[1,0,1]
	v_lshl_add_u64 v[196:197], v[196:197], 2, s[90:91]
	global_store_dwordx4 v[196:197], v[136:139], off
	v_add_u32_e32 v196, 0x8010, v194
	v_mov_b32_e32 v197, v159
	v_sub_f32_e32 v137, v209, v214
	v_sub_f32_e32 v136, v208, v214
	v_sub_f32_e32 v139, v211, v214
	v_sub_f32_e32 v138, v210, v214
	v_pk_mul_f32 v[138:139], v[214:215], v[138:139] op_sel:[1,0]
	v_pk_mul_f32 v[136:137], v[214:215], v[136:137] op_sel:[1,0]
	v_pk_fma_f32 v[138:139], v[148:149], v[138:139], v[114:115]
	v_pk_fma_f32 v[136:137], v[150:151], v[136:137], v[112:113]
	v_pk_fma_f32 v[138:139], v[130:131], s[78:79], v[138:139] op_sel_hi:[1,0,1]
	v_pk_fma_f32 v[136:137], v[128:129], s[78:79], v[136:137] op_sel_hi:[1,0,1]
	v_lshl_add_u64 v[196:197], v[196:197], 2, s[90:91]
	global_store_dwordx4 v[196:197], v[136:139], off
	s_nop 1
	v_or_b32_e32 v138, 32, v206
	v_lshlrev_b32_e32 v136, 1, v138
	v_mov_b32_e32 v137, v159
	v_lshlrev_b32_e32 v236, 11, v138
	v_lshl_add_u64 v[200:201], v[136:137], 2, s[2:3]
	v_add_u32_e32 v136, v236, v158
	v_lshl_add_u64 v[136:137], v[136:137], 2, s[88:89]
	global_load_dwordx2 v[204:205], v[200:201], off
	v_add_u32_e32 v196, v236, v231
	global_load_dwordx4 v[136:139], v[136:137], off
	v_mov_b32_e32 v197, v159
	v_lshl_add_u64 v[196:197], v[196:197], 2, s[88:89]
	global_load_dwordx4 v[196:199], v[196:197], off
	v_or_b32_e32 v207, 48, v206
	v_lshlrev_b32_e32 v235, 11, v207
	v_lshlrev_b32_e32 v202, 1, v207
	v_mov_b32_e32 v203, v159
	v_add_u32_e32 v208, v235, v158
	v_mov_b32_e32 v209, v159
	v_lshl_add_u64 v[202:203], v[202:203], 2, s[2:3]
	v_lshl_add_u64 v[208:209], v[208:209], 2, s[88:89]
	global_load_dwordx2 v[216:217], v[202:203], off
	v_add_u32_e32 v212, v235, v231
	global_load_dwordx4 v[208:211], v[208:209], off
	v_mov_b32_e32 v213, v159
	v_lshl_add_u64 v[212:213], v[212:213], 2, s[88:89]
	global_load_dwordx4 v[212:215], v[212:213], off
	v_add_u32_e32 v218, 0x10000, v194
	v_mov_b32_e32 v219, v159
	v_lshl_add_u64 v[218:219], v[218:219], 2, s[90:91]
	s_waitcnt vmcnt(0)
	v_sub_f32_e32 v137, v137, v204
	v_sub_f32_e32 v136, v136, v204
	v_sub_f32_e32 v139, v139, v204
	v_sub_f32_e32 v138, v138, v204
	v_pk_mul_f32 v[138:139], v[204:205], v[138:139] op_sel:[1,0]
	v_pk_mul_f32 v[136:137], v[204:205], v[136:137] op_sel:[1,0]
	v_pk_fma_f32 v[138:139], v[152:153], v[138:139], v[110:111]
	v_pk_fma_f32 v[136:137], v[154:155], v[136:137], v[108:109]
	v_pk_fma_f32 v[138:139], v[134:135], s[78:79], v[138:139] op_sel_hi:[1,0,1]
	v_pk_fma_f32 v[136:137], v[132:133], s[78:79], v[136:137] op_sel_hi:[1,0,1]
	global_store_dwordx4 v[218:219], v[136:139], off
	s_nop 1
	v_sub_f32_e32 v137, v197, v204
	v_sub_f32_e32 v136, v196, v204
	v_sub_f32_e32 v139, v199, v204
	v_sub_f32_e32 v138, v198, v204
	v_pk_mul_f32 v[138:139], v[204:205], v[138:139] op_sel:[1,0]
	v_pk_mul_f32 v[136:137], v[204:205], v[136:137] op_sel:[1,0]
	v_pk_fma_f32 v[138:139], v[148:149], v[138:139], v[106:107]
	v_pk_fma_f32 v[136:137], v[150:151], v[136:137], v[104:105]
	v_add_u32_e32 v196, 0x10010, v194
	v_mov_b32_e32 v197, v159
	v_pk_fma_f32 v[138:139], v[130:131], s[78:79], v[138:139] op_sel_hi:[1,0,1]
	v_pk_fma_f32 v[136:137], v[128:129], s[78:79], v[136:137] op_sel_hi:[1,0,1]
	v_lshl_add_u64 v[196:197], v[196:197], 2, s[90:91]
	global_store_dwordx4 v[196:197], v[136:139], off
	v_add_u32_e32 v196, 0x18000, v194
	v_mov_b32_e32 v197, v159
	v_sub_f32_e32 v137, v209, v216
	v_sub_f32_e32 v136, v208, v216
	v_sub_f32_e32 v139, v211, v216
	v_sub_f32_e32 v138, v210, v216
	v_pk_mul_f32 v[138:139], v[216:217], v[138:139] op_sel:[1,0]
	v_pk_mul_f32 v[136:137], v[216:217], v[136:137] op_sel:[1,0]
	v_pk_fma_f32 v[138:139], v[152:153], v[138:139], v[102:103]
	v_pk_fma_f32 v[136:137], v[154:155], v[136:137], v[100:101]
	v_pk_fma_f32 v[138:139], v[134:135], s[78:79], v[138:139] op_sel_hi:[1,0,1]
	v_pk_fma_f32 v[136:137], v[132:133], s[78:79], v[136:137] op_sel_hi:[1,0,1]
	v_lshl_add_u64 v[196:197], v[196:197], 2, s[90:91]
	global_store_dwordx4 v[196:197], v[136:139], off
	v_add_u32_e32 v196, 0x18010, v194
	v_mov_b32_e32 v197, v159
	v_sub_f32_e32 v137, v213, v216
	v_sub_f32_e32 v136, v212, v216
	v_sub_f32_e32 v139, v215, v216
	v_sub_f32_e32 v138, v214, v216
	v_pk_mul_f32 v[138:139], v[216:217], v[138:139] op_sel:[1,0]
	v_pk_mul_f32 v[136:137], v[216:217], v[136:137] op_sel:[1,0]
	v_pk_fma_f32 v[138:139], v[148:149], v[138:139], v[98:99]
	v_pk_fma_f32 v[136:137], v[150:151], v[136:137], v[96:97]
	v_pk_fma_f32 v[138:139], v[130:131], s[78:79], v[138:139] op_sel_hi:[1,0,1]
	v_pk_fma_f32 v[136:137], v[128:129], s[78:79], v[136:137] op_sel_hi:[1,0,1]
	v_lshl_add_u64 v[196:197], v[196:197], 2, s[90:91]
	global_store_dwordx4 v[196:197], v[136:139], off
	s_nop 1
	v_add_u32_e32 v138, 0x80, v206
	v_lshlrev_b32_e32 v136, 1, v138
	v_mov_b32_e32 v137, v159
	v_lshlrev_b32_e32 v233, 11, v138
	v_lshl_add_u64 v[196:197], v[136:137], 2, s[2:3]
	v_add_u32_e32 v136, v233, v158
	v_lshl_add_u64 v[136:137], v[136:137], 2, s[88:89]
	global_load_dwordx2 v[204:205], v[196:197], off
	v_add_u32_e32 v198, v233, v231
	global_load_dwordx4 v[136:139], v[136:137], off
	v_mov_b32_e32 v199, v159
	v_add_u32_e32 v207, 0x90, v206
	v_lshl_add_u64 v[198:199], v[198:199], 2, s[88:89]
	v_lshlrev_b32_e32 v234, 11, v207
	global_load_dwordx4 v[208:211], v[198:199], off
	v_add_u32_e32 v212, v234, v158
	v_mov_b32_e32 v213, v159
	v_lshl_add_u64 v[212:213], v[212:213], 2, s[88:89]
	global_load_dwordx4 v[212:215], v[212:213], off
	v_lshlrev_b32_e32 v198, 1, v207
	v_mov_b32_e32 v199, v159
	v_lshl_add_u64 v[198:199], v[198:199], 2, s[2:3]
	global_load_dwordx2 v[238:239], v[198:199], off
	v_add_u32_e32 v216, v234, v231
	v_mov_b32_e32 v217, v159
	v_lshl_add_u64 v[216:217], v[216:217], 2, s[88:89]
	global_load_dwordx4 v[216:219], v[216:217], off
	v_add_u32_e32 v240, 0x40000, v194
	v_mov_b32_e32 v241, v159
	v_lshl_add_u64 v[240:241], v[240:241], 2, s[90:91]
	s_waitcnt vmcnt(0)
;     template <bool LN, int BJ, int LO, int HI> DI void batch(const f32x4 (&acc)[2][2][4][2], unsigned row0, unsigned col0, const f32x4 (&gv)[2], const f32x4 (&bv)[2]) const {
;         f32x4 r[HI - LO]; float mean[(HI - LO) / 2], rstd[(HI - LO) / 2];
; #pragma unroll
;         for (int i = LO; i < HI; ++i) { const int ai = i >> 3, m = (i >> 1) & 3, n = i & 1; const unsigned row = row0 + ai * HALF + m * 16;
;             if (n == 0) { mean[(i - LO) >> 1] = 0.f; rstd[(i - LO) >> 1] = 1.f;
;                 if (LN) { const float2 st = *(const float2*)(stats + row * 2u); mean[(i - LO) >> 1] = st.x; rstd[(i - LO) >> 1] = st.y; } }
;             r[i - LO] = *(const f32x4*)(src + (row * (unsigned)DM + col0 + BJ * HALF + n * 16)); }
; #pragma unroll
;         for (int i = LO; i < HI; ++i) { const int ai = i >> 3, m = (i >> 1) & 3, n = i & 1; const unsigned row = row0 + ai * HALF + m * 16;
;             *(f32x4*)(Y + (row * (unsigned)DM + col0 + BJ * HALF + n * 16)) = acc[ai][BJ][m][n] + ((r[i - LO] - mean[(i - LO) >> 1]) * rstd[(i - LO) >> 1]) * gv[n] + bv[n]; }
	v_sub_f32_e32 v137, v137, v204
	v_sub_f32_e32 v136, v136, v204
	v_sub_f32_e32 v139, v139, v204
	v_sub_f32_e32 v138, v138, v204
	v_pk_mul_f32 v[138:139], v[204:205], v[138:139] op_sel:[1,0]
	v_pk_mul_f32 v[136:137], v[204:205], v[136:137] op_sel:[1,0]
	v_pk_fma_f32 v[138:139], v[152:153], v[138:139], v[94:95]
	v_pk_fma_f32 v[136:137], v[154:155], v[136:137], v[92:93]
	v_pk_fma_f32 v[138:139], v[134:135], s[78:79], v[138:139] op_sel_hi:[1,0,1]
	v_pk_fma_f32 v[136:137], v[132:133], s[78:79], v[136:137] op_sel_hi:[1,0,1]
	global_store_dwordx4 v[240:241], v[136:139], off
	s_nop 1
	v_sub_f32_e32 v137, v209, v204
	v_sub_f32_e32 v136, v208, v204
	v_sub_f32_e32 v139, v211, v204
	v_sub_f32_e32 v138, v210, v204
	v_pk_mul_f32 v[138:139], v[204:205], v[138:139] op_sel:[1,0]
	v_pk_mul_f32 v[136:137], v[204:205], v[136:137] op_sel:[1,0]
	v_pk_fma_f32 v[138:139], v[148:149], v[138:139], v[90:91]
	v_pk_fma_f32 v[136:137], v[150:151], v[136:137], v[88:89]
	v_add_u32_e32 v204, 0x40010, v194
	v_mov_b32_e32 v205, v159
	v_pk_fma_f32 v[138:139], v[130:131], s[78:79], v[138:139] op_sel_hi:[1,0,1]
	v_pk_fma_f32 v[136:137], v[128:129], s[78:79], v[136:137] op_sel_hi:[1,0,1]
	v_lshl_add_u64 v[204:205], v[204:205], 2, s[90:91]
	global_store_dwordx4 v[204:205], v[136:139], off
	v_add_u32_e32 v204, 0x48000, v194
	v_mov_b32_e32 v205, v159
	v_sub_f32_e32 v137, v213, v238
	v_sub_f32_e32 v136, v212, v238
	v_sub_f32_e32 v139, v215, v238
	v_sub_f32_e32 v138, v214, v238
	v_pk_mul_f32 v[138:139], v[238:239], v[138:139] op_sel:[1,0]
	v_pk_mul_f32 v[136:137], v[238:239], v[136:137] op_sel:[1,0]
	v_pk_fma_f32 v[138:139], v[152:153], v[138:139], v[86:87]
	v_pk_fma_f32 v[136:137], v[154:155], v[136:137], v[84:85]
	v_pk_fma_f32 v[138:139], v[134:135], s[78:79], v[138:139] op_sel_hi:[1,0,1]
	v_pk_fma_f32 v[136:137], v[132:133], s[78:79], v[136:137] op_sel_hi:[1,0,1]
	v_lshl_add_u64 v[204:205], v[204:205], 2, s[90:91]
	global_store_dwordx4 v[204:205], v[136:139], off
	v_add_u32_e32 v204, 0x48010, v194
	v_mov_b32_e32 v205, v159
	v_sub_f32_e32 v137, v217, v238
	v_sub_f32_e32 v136, v216, v238
	v_sub_f32_e32 v139, v219, v238
	v_sub_f32_e32 v138, v218, v238
	v_pk_mul_f32 v[138:139], v[238:239], v[138:139] op_sel:[1,0]
	v_pk_mul_f32 v[136:137], v[238:239], v[136:137] op_sel:[1,0]
	v_pk_fma_f32 v[138:139], v[148:149], v[138:139], v[82:83]
	v_pk_fma_f32 v[136:137], v[150:151], v[136:137], v[80:81]
	v_pk_fma_f32 v[138:139], v[130:131], s[78:79], v[138:139] op_sel_hi:[1,0,1]
	v_pk_fma_f32 v[136:137], v[128:129], s[78:79], v[136:137] op_sel_hi:[1,0,1]
	v_lshl_add_u64 v[204:205], v[204:205], 2, s[90:91]
	global_store_dwordx4 v[204:205], v[136:139], off
	s_nop 1
	v_add_u32_e32 v138, 0xa0, v206
	v_lshlrev_b32_e32 v136, 1, v138
	v_mov_b32_e32 v137, v159
	v_lshlrev_b32_e32 v237, 11, v138
	v_lshl_add_u64 v[204:205], v[136:137], 2, s[2:3]
	v_add_u32_e32 v136, v237, v158
	v_lshl_add_u64 v[136:137], v[136:137], 2, s[88:89]
	global_load_dwordx2 v[240:241], v[204:205], off
	v_add_u32_e32 v208, v237, v231
	global_load_dwordx4 v[136:139], v[136:137], off
	v_mov_b32_e32 v209, v159
	v_lshl_add_u64 v[208:209], v[208:209], 2, s[88:89]
	global_load_dwordx4 v[212:215], v[208:209], off
	v_add_u32_e32 v208, 0xb0, v206
	v_lshlrev_b32_e32 v206, 1, v208
	v_mov_b32_e32 v207, v159
	v_lshlrev_b32_e32 v238, 11, v208
	v_lshl_add_u64 v[210:211], v[206:207], 2, s[2:3]
	v_add_u32_e32 v206, v238, v158
	v_lshl_add_u64 v[206:207], v[206:207], 2, s[88:89]
	global_load_dwordx2 v[242:243], v[210:211], off
	v_add_u32_e32 v216, v238, v231
	global_load_dwordx4 v[206:209], v[206:207], off
	v_mov_b32_e32 v217, v159
	v_lshl_add_u64 v[216:217], v[216:217], 2, s[88:89]
	global_load_dwordx4 v[216:219], v[216:217], off
	v_add_u32_e32 v244, 0x50000, v194
	v_mov_b32_e32 v245, v159
	v_lshl_add_u64 v[244:245], v[244:245], 2, s[90:91]
	s_waitcnt vmcnt(0)
	v_sub_f32_e32 v137, v137, v240
	v_sub_f32_e32 v136, v136, v240
	v_sub_f32_e32 v139, v139, v240
	v_sub_f32_e32 v138, v138, v240
	v_pk_mul_f32 v[138:139], v[240:241], v[138:139] op_sel:[1,0]
	v_pk_mul_f32 v[136:137], v[240:241], v[136:137] op_sel:[1,0]
	v_pk_fma_f32 v[138:139], v[152:153], v[138:139], v[78:79]
	v_pk_fma_f32 v[136:137], v[154:155], v[136:137], v[76:77]
	v_pk_fma_f32 v[138:139], v[134:135], s[78:79], v[138:139] op_sel_hi:[1,0,1]
	v_pk_fma_f32 v[136:137], v[132:133], s[78:79], v[136:137] op_sel_hi:[1,0,1]
	global_store_dwordx4 v[244:245], v[136:139], off
	s_nop 1
	v_sub_f32_e32 v137, v213, v240
	v_sub_f32_e32 v136, v212, v240
	v_sub_f32_e32 v139, v215, v240
	v_sub_f32_e32 v138, v214, v240
	v_pk_mul_f32 v[138:139], v[240:241], v[138:139] op_sel:[1,0]
	v_pk_mul_f32 v[136:137], v[240:241], v[136:137] op_sel:[1,0]
	v_pk_fma_f32 v[138:139], v[148:149], v[138:139], v[74:75]
	v_pk_fma_f32 v[136:137], v[150:151], v[136:137], v[72:73]
	v_add_u32_e32 v212, 0x50010, v194
	v_mov_b32_e32 v213, v159
	v_pk_fma_f32 v[138:139], v[130:131], s[78:79], v[138:139] op_sel_hi:[1,0,1]
	v_pk_fma_f32 v[136:137], v[128:129], s[78:79], v[136:137] op_sel_hi:[1,0,1]
	v_lshl_add_u64 v[212:213], v[212:213], 2, s[90:91]
	global_store_dwordx4 v[212:213], v[136:139], off
	s_nop 1
	v_sub_f32_e32 v137, v207, v242
	v_sub_f32_e32 v136, v206, v242
	v_sub_f32_e32 v139, v209, v242
	v_sub_f32_e32 v138, v208, v242
	v_pk_mul_f32 v[136:137], v[242:243], v[136:137] op_sel:[1,0]
	v_pk_mul_f32 v[138:139], v[242:243], v[138:139] op_sel:[1,0]
	v_pk_fma_f32 v[136:137], v[154:155], v[136:137], v[68:69]
	v_pk_fma_f32 v[138:139], v[152:153], v[138:139], v[70:71]
	v_pk_fma_f32 v[132:133], v[132:133], s[78:79], v[136:137] op_sel_hi:[1,0,1]
	v_add_u32_e32 v136, 0x58000, v194
	v_mov_b32_e32 v137, v159
	v_pk_fma_f32 v[134:135], v[134:135], s[78:79], v[138:139] op_sel_hi:[1,0,1]
	v_lshl_add_u64 v[136:137], v[136:137], 2, s[90:91]
	global_store_dwordx4 v[136:137], v[132:135], off
	s_nop 1
	v_sub_f32_e32 v133, v217, v242
	v_sub_f32_e32 v132, v216, v242
	v_sub_f32_e32 v135, v219, v242
	v_sub_f32_e32 v134, v218, v242
	v_pk_mul_f32 v[132:133], v[242:243], v[132:133] op_sel:[1,0]
	v_pk_mul_f32 v[134:135], v[242:243], v[134:135] op_sel:[1,0]
	v_pk_fma_f32 v[132:133], v[150:151], v[132:133], v[64:65]
	v_pk_fma_f32 v[134:135], v[148:149], v[134:135], v[66:67]
	v_pk_fma_f32 v[128:129], v[128:129], s[78:79], v[132:133] op_sel_hi:[1,0,1]
	v_add_u32_e32 v132, 0x58010, v194
	v_mov_b32_e32 v133, v159
	v_pk_fma_f32 v[130:131], v[130:131], s[78:79], v[134:135] op_sel_hi:[1,0,1]
	v_lshl_add_u64 v[132:133], v[132:133], 2, s[90:91]
	global_store_dwordx4 v[132:133], v[128:131], off
	global_load_dwordx4 v[128:131], v[140:141], off offset:512
	v_add_u32_e32 v136, v232, v230
	v_mov_b32_e32 v137, v159
	v_lshl_add_u64 v[136:137], v[136:137], 2, s[88:89]
	s_waitcnt vmcnt(0)
;     template <bool LN, int BJ, int LO, int HI> DI void batch(const f32x4 (&acc)[2][2][4][2], unsigned row0, unsigned col0, const f32x4 (&gv)[2], const f32x4 (&bv)[2]) const {
;         f32x4 r[HI - LO]; float mean[(HI - LO) / 2], rstd[(HI - LO) / 2];
; #pragma unroll
;         for (int i = LO; i < HI; ++i) { const int ai = i >> 3, m = (i >> 1) & 3, n = i & 1; const unsigned row = row0 + ai * HALF + m * 16;
;             if (n == 0) { mean[(i - LO) >> 1] = 0.f; rstd[(i - LO) >> 1] = 1.f;
;                 if (LN) { const float2 st = *(const float2*)(stats + row * 2u); mean[(i - LO) >> 1] = st.x; rstd[(i - LO) >> 1] = st.y; } }
;             r[i - LO] = *(const f32x4*)(src + (row * (unsigned)DM + col0 + BJ * HALF + n * 16)); }
; #pragma unroll
;         for (int i = LO; i < HI; ++i) { const int ai = i >> 3, m = (i >> 1) & 3, n = i & 1; const unsigned row = row0 + ai * HALF + m * 16;
;             *(f32x4*)(Y + (row * (unsigned)DM + col0 + BJ * HALF + n * 16)) = acc[ai][BJ][m][n] + ((r[i - LO] - mean[(i - LO) >> 1]) * rstd[(i - LO) >> 1]) * gv[n] + bv[n]; }
;     template <bool LN, int BJ> DI void load_gb(unsigned col0, f32x4 (&gv)[2], f32x4 (&bv)[2]) const {
; #pragma unroll
;         for (int n = 0; n < 2; ++n) {
;             if (LN) { gv[n] = *(const f32x4*)(gam + col0 + BJ * HALF + n * 16) * ALPHA; bv[n] = *(const f32x4*)(bet + col0 + BJ * HALF + n * 16) * ALPHA; }
;             else { gv[n] = (f32x4){ALPHA, ALPHA, ALPHA, ALPHA}; bv[n] = (f32x4){0.f, 0.f, 0.f, 0.f}; }
;         }
;     }
;     template <bool LN> DI void run(const f32x4 (&acc)[2][2][4][2], const Unit& u, int wr, int wc, int fr, int fq) const {
;         const unsigned row0 = u.pm * BM + wr * 64 + fr, col0 = u.pn * BM + wc * 32 + 4 * fq;
;         f32x4 gv[2], bv[2];
;         load_gb<LN, 0>(col0, gv, bv);
;         batch<LN, 0, 0, 4>(acc, row0, col0, gv, bv);
;         batch<LN, 0, 4, 8>(acc, row0, col0, gv, bv);
;         batch<LN, 0, 8, 12>(acc, row0, col0, gv, bv);
;         batch<LN, 0, 12, 16>(acc, row0, col0, gv, bv);
;         load_gb<LN, 1>(col0, gv, bv);
	v_pk_mul_f32 v[212:213], v[130:131], s[78:79] op_sel_hi:[1,0]
	v_pk_mul_f32 v[214:215], v[128:129], s[78:79] op_sel_hi:[1,0]
	global_load_dwordx4 v[132:135], v[142:143], off offset:512
	global_load_dwordx4 v[128:131], v[140:141], off offset:576
	s_waitcnt vmcnt(0)
	v_pk_mul_f32 v[206:207], v[130:131], s[78:79] op_sel_hi:[1,0]
	v_pk_mul_f32 v[208:209], v[128:129], s[78:79] op_sel_hi:[1,0]
	global_load_dwordx4 v[128:131], v[142:143], off offset:576
	global_load_dwordx2 v[220:221], v[144:145], off
	global_load_dwordx4 v[240:243], v[136:137], off
	v_add_u32_e32 v136, v232, v229
	v_mov_b32_e32 v137, v159
	v_lshl_add_u64 v[136:137], v[136:137], 2, s[88:89]
	global_load_dwordx4 v[244:247], v[136:137], off
	global_load_dwordx2 v[218:219], v[146:147], off
	v_add_u32_e32 v136, v195, v230
	v_mov_b32_e32 v137, v159
	v_lshl_add_u64 v[136:137], v[136:137], 2, s[88:89]
	global_load_dwordx4 v[248:251], v[136:137], off
	v_add_u32_e32 v136, v195, v229
	v_mov_b32_e32 v137, v159
	v_lshl_add_u64 v[136:137], v[136:137], 2, s[88:89]
	global_load_dwordx4 v[152:155], v[136:137], off
	global_load_dwordx2 v[216:217], v[200:201], off
	v_add_u32_e32 v136, v236, v230
	v_mov_b32_e32 v137, v159
	v_lshl_add_u64 v[136:137], v[136:137], 2, s[88:89]
	global_load_dwordx4 v[148:151], v[136:137], off
	v_add_u32_e32 v136, v236, v229
	v_mov_b32_e32 v137, v159
	v_lshl_add_u64 v[136:137], v[136:137], 2, s[88:89]
	global_load_dwordx4 v[144:147], v[136:137], off
	global_load_dwordx2 v[200:201], v[202:203], off
	v_add_u32_e32 v136, v235, v230
	v_mov_b32_e32 v137, v159
	v_lshl_add_u64 v[136:137], v[136:137], 2, s[88:89]
	global_load_dwordx4 v[140:143], v[136:137], off
	v_add_u32_e32 v136, v235, v229
	v_mov_b32_e32 v137, v159
	v_lshl_add_u64 v[136:137], v[136:137], 2, s[88:89]
	global_load_dwordx4 v[136:139], v[136:137], off
	v_add_u32_e32 v202, 0x80, v194
	v_mov_b32_e32 v203, v159
	v_lshl_add_u64 v[202:203], v[202:203], 2, s[90:91]
	s_waitcnt vmcnt(0)
	v_sub_f32_e32 v241, v241, v220
	v_sub_f32_e32 v240, v240, v220
	v_sub_f32_e32 v243, v243, v220
	v_sub_f32_e32 v242, v242, v220
	v_pk_mul_f32 v[242:243], v[220:221], v[242:243] op_sel:[1,0]
	v_pk_mul_f32 v[240:241], v[220:221], v[240:241] op_sel:[1,0]
	v_pk_fma_f32 v[242:243], v[212:213], v[242:243], v[62:63]
	v_pk_fma_f32 v[240:241], v[214:215], v[240:241], v[60:61]
	v_pk_fma_f32 v[242:243], v[134:135], s[78:79], v[242:243] op_sel_hi:[1,0,1]
	v_pk_fma_f32 v[240:241], v[132:133], s[78:79], v[240:241] op_sel_hi:[1,0,1]
	global_store_dwordx4 v[202:203], v[240:243], off
	v_sub_f32_e32 v203, v245, v220
	v_sub_f32_e32 v202, v244, v220
	v_sub_f32_e32 v241, v247, v220
	v_sub_f32_e32 v240, v246, v220
	v_pk_mul_f32 v[202:203], v[220:221], v[202:203] op_sel:[1,0]
	v_pk_mul_f32 v[240:241], v[220:221], v[240:241] op_sel:[1,0]
	v_pk_fma_f32 v[202:203], v[208:209], v[202:203], v[56:57]
	v_pk_fma_f32 v[220:221], v[206:207], v[240:241], v[58:59]
	v_pk_fma_f32 v[240:241], v[128:129], s[78:79], v[202:203] op_sel_hi:[1,0,1]
	v_add_u32_e32 v202, 0x90, v194
	v_mov_b32_e32 v203, v159
	v_pk_fma_f32 v[242:243], v[130:131], s[78:79], v[220:221] op_sel_hi:[1,0,1]
	v_lshl_add_u64 v[202:203], v[202:203], 2, s[90:91]
	global_store_dwordx4 v[202:203], v[240:243], off
	v_sub_f32_e32 v203, v249, v218
	v_sub_f32_e32 v202, v248, v218
	v_sub_f32_e32 v221, v251, v218
	v_sub_f32_e32 v220, v250, v218
	v_pk_mul_f32 v[202:203], v[218:219], v[202:203] op_sel:[1,0]
	v_pk_mul_f32 v[220:221], v[218:219], v[220:221] op_sel:[1,0]
	v_pk_fma_f32 v[202:203], v[214:215], v[202:203], v[52:53]
	v_pk_fma_f32 v[220:221], v[212:213], v[220:221], v[54:55]
	v_pk_fma_f32 v[240:241], v[132:133], s[78:79], v[202:203] op_sel_hi:[1,0,1]
	v_add_u32_e32 v202, 0x8080, v194
	v_mov_b32_e32 v203, v159
	v_sub_f32_e32 v153, v153, v218
	v_sub_f32_e32 v152, v152, v218
	v_sub_f32_e32 v155, v155, v218
	v_sub_f32_e32 v154, v154, v218
	v_pk_fma_f32 v[242:243], v[134:135], s[78:79], v[220:221] op_sel_hi:[1,0,1]
	v_lshl_add_u64 v[202:203], v[202:203], 2, s[90:91]
	v_pk_mul_f32 v[154:155], v[218:219], v[154:155] op_sel:[1,0]
	v_pk_mul_f32 v[152:153], v[218:219], v[152:153] op_sel:[1,0]
	global_store_dwordx4 v[202:203], v[240:243], off
	v_pk_fma_f32 v[152:153], v[208:209], v[152:153], v[48:49]
	v_pk_fma_f32 v[154:155], v[206:207], v[154:155], v[50:51]
	v_add_u32_e32 v202, 0x8090, v194
	v_mov_b32_e32 v203, v159
	v_sub_f32_e32 v149, v149, v216
	v_sub_f32_e32 v148, v148, v216
	v_sub_f32_e32 v151, v151, v216
	v_sub_f32_e32 v150, v150, v216
	v_pk_fma_f32 v[154:155], v[130:131], s[78:79], v[154:155] op_sel_hi:[1,0,1]
	v_pk_fma_f32 v[152:153], v[128:129], s[78:79], v[152:153] op_sel_hi:[1,0,1]
	v_lshl_add_u64 v[202:203], v[202:203], 2, s[90:91]
	v_pk_mul_f32 v[150:151], v[216:217], v[150:151] op_sel:[1,0]
	v_pk_mul_f32 v[148:149], v[216:217], v[148:149] op_sel:[1,0]
	global_store_dwordx4 v[202:203], v[152:155], off
	v_pk_fma_f32 v[148:149], v[214:215], v[148:149], v[44:45]
	v_pk_fma_f32 v[150:151], v[212:213], v[150:151], v[46:47]
	v_add_u32_e32 v152, 0x10080, v194
	v_mov_b32_e32 v153, v159
	v_sub_f32_e32 v145, v145, v216
	v_sub_f32_e32 v144, v144, v216
	v_sub_f32_e32 v147, v147, v216
	v_sub_f32_e32 v146, v146, v216
	v_pk_fma_f32 v[150:151], v[134:135], s[78:79], v[150:151] op_sel_hi:[1,0,1]
	v_pk_fma_f32 v[148:149], v[132:133], s[78:79], v[148:149] op_sel_hi:[1,0,1]
	v_lshl_add_u64 v[152:153], v[152:153], 2, s[90:91]
	v_pk_mul_f32 v[146:147], v[216:217], v[146:147] op_sel:[1,0]
	v_pk_mul_f32 v[144:145], v[216:217], v[144:145] op_sel:[1,0]
	global_store_dwordx4 v[152:153], v[148:151], off
	v_pk_fma_f32 v[144:145], v[208:209], v[144:145], v[40:41]
	v_pk_fma_f32 v[146:147], v[206:207], v[146:147], v[42:43]
;     template <bool LN, int BJ, int LO, int HI> DI void batch(const f32x4 (&acc)[2][2][4][2], unsigned row0, unsigned col0, const f32x4 (&gv)[2], const f32x4 (&bv)[2]) const {
;         f32x4 r[HI - LO]; float mean[(HI - LO) / 2], rstd[(HI - LO) / 2];
; #pragma unroll
;         for (int i = LO; i < HI; ++i) { const int ai = i >> 3, m = (i >> 1) & 3, n = i & 1; const unsigned row = row0 + ai * HALF + m * 16;
;             if (n == 0) { mean[(i - LO) >> 1] = 0.f; rstd[(i - LO) >> 1] = 1.f;
;                 if (LN) { const float2 st = *(const float2*)(stats + row * 2u); mean[(i - LO) >> 1] = st.x; rstd[(i - LO) >> 1] = st.y; } }
;             r[i - LO] = *(const f32x4*)(src + (row * (unsigned)DM + col0 + BJ * HALF + n * 16)); }
; #pragma unroll
;         for (int i = LO; i < HI; ++i) { const int ai = i >> 3, m = (i >> 1) & 3, n = i & 1; const unsigned row = row0 + ai * HALF + m * 16;
;             *(f32x4*)(Y + (row * (unsigned)DM + col0 + BJ * HALF + n * 16)) = acc[ai][BJ][m][n] + ((r[i - LO] - mean[(i - LO) >> 1]) * rstd[(i - LO) >> 1]) * gv[n] + bv[n]; }
	v_add_u32_e32 v148, 0x10090, v194
	v_mov_b32_e32 v149, v159
	v_sub_f32_e32 v141, v141, v200
	v_sub_f32_e32 v140, v140, v200
	v_sub_f32_e32 v143, v143, v200
	v_sub_f32_e32 v142, v142, v200
	v_pk_fma_f32 v[146:147], v[130:131], s[78:79], v[146:147] op_sel_hi:[1,0,1]
	v_pk_fma_f32 v[144:145], v[128:129], s[78:79], v[144:145] op_sel_hi:[1,0,1]
	v_lshl_add_u64 v[148:149], v[148:149], 2, s[90:91]
	v_pk_mul_f32 v[142:143], v[200:201], v[142:143] op_sel:[1,0]
	v_pk_mul_f32 v[140:141], v[200:201], v[140:141] op_sel:[1,0]
	global_store_dwordx4 v[148:149], v[144:147], off
	v_pk_fma_f32 v[140:141], v[214:215], v[140:141], v[36:37]
	v_pk_fma_f32 v[142:143], v[212:213], v[142:143], v[38:39]
	v_add_u32_e32 v144, 0x18080, v194
	v_mov_b32_e32 v145, v159
	v_sub_f32_e32 v137, v137, v200
	v_sub_f32_e32 v136, v136, v200
	v_sub_f32_e32 v139, v139, v200
	v_sub_f32_e32 v138, v138, v200
	v_pk_fma_f32 v[142:143], v[134:135], s[78:79], v[142:143] op_sel_hi:[1,0,1]
	v_pk_fma_f32 v[140:141], v[132:133], s[78:79], v[140:141] op_sel_hi:[1,0,1]
	v_lshl_add_u64 v[144:145], v[144:145], 2, s[90:91]
	v_pk_mul_f32 v[138:139], v[200:201], v[138:139] op_sel:[1,0]
	v_pk_mul_f32 v[136:137], v[200:201], v[136:137] op_sel:[1,0]
	global_store_dwordx4 v[144:145], v[140:143], off
	v_pk_fma_f32 v[136:137], v[208:209], v[136:137], v[32:33]
	v_pk_fma_f32 v[138:139], v[206:207], v[138:139], v[34:35]
	v_add_u32_e32 v140, 0x18090, v194
	v_mov_b32_e32 v141, v159
	v_pk_fma_f32 v[138:139], v[130:131], s[78:79], v[138:139] op_sel_hi:[1,0,1]
	v_pk_fma_f32 v[136:137], v[128:129], s[78:79], v[136:137] op_sel_hi:[1,0,1]
	v_lshl_add_u64 v[140:141], v[140:141], 2, s[90:91]
	global_store_dwordx4 v[140:141], v[136:139], off
	s_nop 1
	v_add_u32_e32 v136, v233, v230
	v_mov_b32_e32 v137, v159
	v_lshl_add_u64 v[136:137], v[136:137], 2, s[88:89]
	global_load_dwordx2 v[220:221], v[196:197], off
	global_load_dwordx4 v[216:219], v[136:137], off
	v_add_u32_e32 v136, v233, v229
	v_mov_b32_e32 v137, v159
	v_lshl_add_u64 v[136:137], v[136:137], 2, s[88:89]
	global_load_dwordx4 v[240:243], v[136:137], off
	global_load_dwordx2 v[200:201], v[198:199], off
	v_add_u32_e32 v136, v234, v230
	v_mov_b32_e32 v137, v159
	v_lshl_add_u64 v[136:137], v[136:137], 2, s[88:89]
	global_load_dwordx4 v[244:247], v[136:137], off
	v_add_u32_e32 v136, v234, v229
	v_mov_b32_e32 v137, v159
	v_lshl_add_u64 v[136:137], v[136:137], 2, s[88:89]
	global_load_dwordx4 v[152:155], v[136:137], off
	global_load_dwordx2 v[198:199], v[204:205], off
	v_add_u32_e32 v136, v237, v230
	v_mov_b32_e32 v137, v159
	v_lshl_add_u64 v[136:137], v[136:137], 2, s[88:89]
	global_load_dwordx4 v[148:151], v[136:137], off
	v_add_u32_e32 v136, v237, v229
	v_mov_b32_e32 v137, v159
	v_lshl_add_u64 v[136:137], v[136:137], 2, s[88:89]
	global_load_dwordx4 v[144:147], v[136:137], off
	global_load_dwordx2 v[196:197], v[210:211], off
	v_add_u32_e32 v136, v238, v230
	v_mov_b32_e32 v137, v159
	v_lshl_add_u64 v[136:137], v[136:137], 2, s[88:89]
	global_load_dwordx4 v[140:143], v[136:137], off
	v_add_u32_e32 v136, v238, v229
	v_mov_b32_e32 v137, v159
	v_lshl_add_u64 v[136:137], v[136:137], 2, s[88:89]
	global_load_dwordx4 v[136:139], v[136:137], off
	v_add_u32_e32 v210, 0x40080, v194
	v_mov_b32_e32 v211, v159
	v_lshl_add_u64 v[210:211], v[210:211], 2, s[90:91]
	s_waitcnt vmcnt(0)
;     template <bool LN, int BJ, int LO, int HI> DI void batch(const f32x4 (&acc)[2][2][4][2], unsigned row0, unsigned col0, const f32x4 (&gv)[2], const f32x4 (&bv)[2]) const {
;         f32x4 r[HI - LO]; float mean[(HI - LO) / 2], rstd[(HI - LO) / 2];
; #pragma unroll
;         for (int i = LO; i < HI; ++i) { const int ai = i >> 3, m = (i >> 1) & 3, n = i & 1; const unsigned row = row0 + ai * HALF + m * 16;
;             if (n == 0) { mean[(i - LO) >> 1] = 0.f; rstd[(i - LO) >> 1] = 1.f;
;                 if (LN) { const float2 st = *(const float2*)(stats + row * 2u); mean[(i - LO) >> 1] = st.x; rstd[(i - LO) >> 1] = st.y; } }
;             r[i - LO] = *(const f32x4*)(src + (row * (unsigned)DM + col0 + BJ * HALF + n * 16)); }
; #pragma unroll
;         for (int i = LO; i < HI; ++i) { const int ai = i >> 3, m = (i >> 1) & 3, n = i & 1; const unsigned row = row0 + ai * HALF + m * 16;
;             *(f32x4*)(Y + (row * (unsigned)DM + col0 + BJ * HALF + n * 16)) = acc[ai][BJ][m][n] + ((r[i - LO] - mean[(i - LO) >> 1]) * rstd[(i - LO) >> 1]) * gv[n] + bv[n]; }
	v_sub_f32_e32 v203, v217, v220
	v_sub_f32_e32 v202, v216, v220
	v_sub_f32_e32 v205, v219, v220
	v_sub_f32_e32 v204, v218, v220
	v_pk_mul_f32 v[204:205], v[220:221], v[204:205] op_sel:[1,0]
	v_pk_mul_f32 v[202:203], v[220:221], v[202:203] op_sel:[1,0]
	v_pk_fma_f32 v[204:205], v[212:213], v[204:205], v[30:31]
	v_pk_fma_f32 v[202:203], v[214:215], v[202:203], v[28:29]
	v_pk_fma_f32 v[204:205], v[134:135], s[78:79], v[204:205] op_sel_hi:[1,0,1]
	v_pk_fma_f32 v[202:203], v[132:133], s[78:79], v[202:203] op_sel_hi:[1,0,1]
	global_store_dwordx4 v[210:211], v[202:205], off
	v_add_u32_e32 v210, 0x40090, v194
	v_mov_b32_e32 v211, v159
	v_sub_f32_e32 v203, v241, v220
	v_sub_f32_e32 v202, v240, v220
	v_sub_f32_e32 v205, v243, v220
	v_sub_f32_e32 v204, v242, v220
	v_pk_mul_f32 v[204:205], v[220:221], v[204:205] op_sel:[1,0]
	v_pk_mul_f32 v[202:203], v[220:221], v[202:203] op_sel:[1,0]
	v_pk_fma_f32 v[204:205], v[206:207], v[204:205], v[26:27]
	v_pk_fma_f32 v[202:203], v[208:209], v[202:203], v[24:25]
	v_pk_fma_f32 v[204:205], v[130:131], s[78:79], v[204:205] op_sel_hi:[1,0,1]
	v_pk_fma_f32 v[202:203], v[128:129], s[78:79], v[202:203] op_sel_hi:[1,0,1]
	v_lshl_add_u64 v[210:211], v[210:211], 2, s[90:91]
	global_store_dwordx4 v[210:211], v[202:205], off
	v_sub_f32_e32 v149, v149, v198
	v_sub_f32_e32 v148, v148, v198
	v_sub_f32_e32 v203, v245, v200
	v_sub_f32_e32 v202, v244, v200
	v_sub_f32_e32 v141, v141, v196
	v_sub_f32_e32 v140, v140, v196
	v_sub_f32_e32 v205, v247, v200
	v_sub_f32_e32 v204, v246, v200
	v_pk_mul_f32 v[202:203], v[200:201], v[202:203] op_sel:[1,0]
	v_sub_f32_e32 v151, v151, v198
	v_sub_f32_e32 v150, v150, v198
	v_pk_mul_f32 v[148:149], v[198:199], v[148:149] op_sel:[1,0]
	v_sub_f32_e32 v143, v143, v196
	v_sub_f32_e32 v142, v142, v196
	v_pk_mul_f32 v[140:141], v[196:197], v[140:141] op_sel:[1,0]
	v_pk_mul_f32 v[204:205], v[200:201], v[204:205] op_sel:[1,0]
	v_pk_fma_f32 v[202:203], v[214:215], v[202:203], v[20:21]
	v_sub_f32_e32 v153, v153, v200
	v_sub_f32_e32 v152, v152, v200
	v_sub_f32_e32 v155, v155, v200
	v_sub_f32_e32 v154, v154, v200
	v_pk_mul_f32 v[150:151], v[198:199], v[150:151] op_sel:[1,0]
	v_pk_fma_f32 v[148:149], v[214:215], v[148:149], v[12:13]
	v_pk_mul_f32 v[142:143], v[196:197], v[142:143] op_sel:[1,0]
	v_pk_fma_f32 v[140:141], v[214:215], v[140:141], v[4:5]
	v_pk_fma_f32 v[204:205], v[212:213], v[204:205], v[22:23]
	v_pk_fma_f32 v[202:203], v[132:133], s[78:79], v[202:203] op_sel_hi:[1,0,1]
	v_pk_mul_f32 v[154:155], v[200:201], v[154:155] op_sel:[1,0]
	v_pk_mul_f32 v[152:153], v[200:201], v[152:153] op_sel:[1,0]
	v_pk_fma_f32 v[150:151], v[212:213], v[150:151], v[14:15]
	v_pk_fma_f32 v[148:149], v[132:133], s[78:79], v[148:149] op_sel_hi:[1,0,1]
	v_pk_fma_f32 v[142:143], v[212:213], v[142:143], v[6:7]
	v_pk_fma_f32 v[132:133], v[132:133], s[78:79], v[140:141] op_sel_hi:[1,0,1]
	v_add_u32_e32 v140, 0x58080, v194
	v_mov_b32_e32 v141, v159
	v_pk_fma_f32 v[204:205], v[134:135], s[78:79], v[204:205] op_sel_hi:[1,0,1]
	v_pk_fma_f32 v[152:153], v[208:209], v[152:153], v[16:17]
	v_pk_fma_f32 v[154:155], v[206:207], v[154:155], v[18:19]
	v_add_u32_e32 v200, 0x48090, v194
	v_mov_b32_e32 v201, v159
	v_pk_fma_f32 v[150:151], v[134:135], s[78:79], v[150:151] op_sel_hi:[1,0,1]
	v_pk_fma_f32 v[134:135], v[134:135], s[78:79], v[142:143] op_sel_hi:[1,0,1]
	v_lshl_add_u64 v[140:141], v[140:141], 2, s[90:91]
	v_pk_fma_f32 v[154:155], v[130:131], s[78:79], v[154:155] op_sel_hi:[1,0,1]
	v_pk_fma_f32 v[152:153], v[128:129], s[78:79], v[152:153] op_sel_hi:[1,0,1]
	v_lshl_add_u64 v[200:201], v[200:201], 2, s[90:91]
	v_sub_f32_e32 v145, v145, v198
	v_sub_f32_e32 v144, v144, v198
	global_store_dwordx4 v[140:141], v[132:135], off
	global_store_dwordx4 v[200:201], v[152:155], off
	v_sub_f32_e32 v147, v147, v198
	v_sub_f32_e32 v133, v137, v196
	v_sub_f32_e32 v132, v136, v196
	v_add_u32_e32 v152, 0x50080, v194
	v_mov_b32_e32 v153, v159
	v_sub_f32_e32 v146, v146, v198
	v_pk_mul_f32 v[144:145], v[198:199], v[144:145] op_sel:[1,0]
	v_sub_f32_e32 v135, v139, v196
	v_sub_f32_e32 v134, v138, v196
	v_pk_mul_f32 v[132:133], v[196:197], v[132:133] op_sel:[1,0]
	v_lshl_add_u64 v[152:153], v[152:153], 2, s[90:91]
	v_pk_mul_f32 v[146:147], v[198:199], v[146:147] op_sel:[1,0]
	v_pk_fma_f32 v[144:145], v[208:209], v[144:145], v[8:9]
	v_pk_mul_f32 v[134:135], v[196:197], v[134:135] op_sel:[1,0]
	v_pk_fma_f32 v[132:133], v[208:209], v[132:133], v[0:1]
	v_add_u32_e32 v210, 0x48080, v194
	v_mov_b32_e32 v211, v159
	global_store_dwordx4 v[152:153], v[148:151], off
	v_pk_fma_f32 v[146:147], v[206:207], v[146:147], v[10:11]
	v_pk_fma_f32 v[144:145], v[128:129], s[78:79], v[144:145] op_sel_hi:[1,0,1]
	v_add_u32_e32 v148, 0x50090, v194
	v_mov_b32_e32 v149, v159
	v_pk_fma_f32 v[134:135], v[206:207], v[134:135], v[2:3]
	v_pk_fma_f32 v[128:129], v[128:129], s[78:79], v[132:133] op_sel_hi:[1,0,1]
	v_add_u32_e32 v132, 0x58090, v194
	v_mov_b32_e32 v133, v159
	v_lshl_add_u64 v[210:211], v[210:211], 2, s[90:91]
	v_pk_fma_f32 v[146:147], v[130:131], s[78:79], v[146:147] op_sel_hi:[1,0,1]
	v_lshl_add_u64 v[148:149], v[148:149], 2, s[90:91]
	v_pk_fma_f32 v[130:131], v[130:131], s[78:79], v[134:135] op_sel_hi:[1,0,1]
	v_lshl_add_u64 v[132:133], v[132:133], 2, s[90:91]
	global_store_dwordx4 v[210:211], v[202:205], off
	global_store_dwordx4 v[148:149], v[144:147], off
	global_store_dwordx4 v[132:133], v[128:131], off
	s_mov_b64 s[24:25], 0
	s_branch .LBB0_324
